# s_setprio 2 during the outproj pipelined loops
# baseline (speedup 1.0000x reference)
.LBB0_315:
	s_ashr_i32 s34, s52, 31
	s_lshr_b32 s34, s34, 23
	s_add_i32 s34, s52, s34
	s_ashr_i32 s34, s34, 9
	s_lshl_b32 s55, s34, 6
	s_lshl_b32 s34, s52, 3
	s_and_b32 s34, s34, 56
	s_or_b32 s54, s55, s34
	s_bfe_u32 s56, s52, 0x30003
	s_or_b32 s34, s54, s56
	s_ashr_i32 s35, s34, 31
	s_lshl_b64 s[38:39], s[34:35], 19
	v_lshl_add_u64 v[0:1], v[86:87], 0, s[38:39]
	v_readfirstlane_b32 s38, v129
	s_mov_b32 m0, s38
	v_readfirstlane_b32 s38, v119
	s_barrier
	s_setprio 2
	s_bfe_u32 s53, s52, 0x30006
	s_lshl_b64 s[98:99], s[34:35], 19
	s_add_u32 s98, s98, s50
	s_addc_u32 s99, s99, s51
	s_add_u32 s98, s98, 0x5a00000
	s_addc_u32 s99, s99, 0
	s_lshl_b32 s100, s53, 19
	s_add_u32 s100, s100, s50
	s_addc_u32 s101, s51, 0
	s_add_u32 s100, s100, 0x2800000
	s_addc_u32 s101, s101, 0
	v_readfirstlane_b32 s38, v129
	v_and_b32_e32 v80, 15, v131
	v_bfe_u32 v81, v131, 4, 2
	v_bfe_u32 v82, v131, 1, 3
	v_xor_b32_e32 v82, v81, v82
	v_lshlrev_b32_e32 v82, 4, v82
	v_lshl_or_b32 v210, v80, 7, v82
	v_xor_b32_e32 v211, 64, v210
	v_lshrrev_b32_e32 v82, 6, v131
	v_lshl_add_u32 v208, v82, 12, v210
	v_lshl_add_u32 v209, v82, 12, v211
	v_bfe_u32 v80, v131, 4, 3
	v_and_b32_e32 v81, 7, v131
	v_xor_b32_e32 v80, v80, v81
	v_lshlrev_b32_e32 v80, 4, v80
	v_lshrrev_b32_e32 v81, 3, v131
	v_lshl_or_b32 v212, v81, 12, v80
	v_add_u32_e32 v213, 131072, v212
	v_add_u32_e32 v214, 262144, v212
	v_add_u32_e32 v215, 393216, v212
	s_add_u32 m0, s38, 0
	v_mov_b32_e32 v40, 0
	v_mov_b32_e32 v41, 0
	global_load_lds_dwordx4 v212, s[98:99]
	s_add_u32 m0, s38, 4096
	v_mov_b32_e32 v42, 0
	v_mov_b32_e32 v43, 0
	global_load_lds_dwordx4 v213, s[98:99]
	s_add_u32 m0, s38, 8192
	v_mov_b32_e32 v28, 0
	v_mov_b32_e32 v29, 0
	global_load_lds_dwordx4 v214, s[98:99]
	s_add_u32 m0, s38, 12288
	v_mov_b32_e32 v30, 0
	v_mov_b32_e32 v31, 0
	global_load_lds_dwordx4 v215, s[98:99]
	s_add_u32 s98, s98, 128
	s_addc_u32 s99, s99, 0
	s_add_u32 m0, s38, 16384
	v_mov_b32_e32 v60, 0
	v_mov_b32_e32 v61, 0
	global_load_lds_dwordx4 v212, s[100:101]
	s_add_u32 m0, s38, 20480
	v_mov_b32_e32 v62, 0
	v_mov_b32_e32 v63, 0
	global_load_lds_dwordx4 v213, s[100:101]
	s_add_u32 m0, s38, 24576
	v_mov_b32_e32 v20, 0
	v_mov_b32_e32 v21, 0
	global_load_lds_dwordx4 v214, s[100:101]
	s_add_u32 m0, s38, 28672
	v_mov_b32_e32 v22, 0
	v_mov_b32_e32 v23, 0
	global_load_lds_dwordx4 v215, s[100:101]
	s_add_u32 s100, s100, 128
	s_addc_u32 s101, s101, 0
	s_add_u32 m0, s38, 32768
	v_mov_b32_e32 v44, 0
	v_mov_b32_e32 v45, 0
	global_load_lds_dwordx4 v212, s[98:99]
	s_add_u32 m0, s38, 36864
	v_mov_b32_e32 v46, 0
	v_mov_b32_e32 v47, 0
	global_load_lds_dwordx4 v213, s[98:99]
	s_add_u32 m0, s38, 40960
	v_mov_b32_e32 v24, 0
	v_mov_b32_e32 v25, 0
	global_load_lds_dwordx4 v214, s[98:99]
	s_add_u32 m0, s38, 45056
	v_mov_b32_e32 v26, 0
	v_mov_b32_e32 v27, 0
	global_load_lds_dwordx4 v215, s[98:99]
	s_add_u32 s98, s98, 128
	s_addc_u32 s99, s99, 0
	s_add_u32 m0, s38, 49152
	v_mov_b32_e32 v56, 0
	v_mov_b32_e32 v57, 0
	global_load_lds_dwordx4 v212, s[100:101]
	s_add_u32 m0, s38, 53248
	v_mov_b32_e32 v58, 0
	v_mov_b32_e32 v59, 0
	global_load_lds_dwordx4 v213, s[100:101]
	s_add_u32 m0, s38, 57344
	v_mov_b32_e32 v12, 0
	v_mov_b32_e32 v13, 0
	global_load_lds_dwordx4 v214, s[100:101]
	s_add_u32 m0, s38, 61440
	v_mov_b32_e32 v14, 0
	v_mov_b32_e32 v15, 0
	global_load_lds_dwordx4 v215, s[100:101]
	s_add_u32 s100, s100, 128
	s_addc_u32 s101, s101, 0
	v_mov_b32_e32 v52, 0
	v_mov_b32_e32 v53, 0
	v_mov_b32_e32 v54, 0
	v_mov_b32_e32 v55, 0
	v_mov_b32_e32 v16, 0
	v_mov_b32_e32 v17, 0
	v_mov_b32_e32 v18, 0
	v_mov_b32_e32 v19, 0
	v_mov_b32_e32 v48, 0
	v_mov_b32_e32 v49, 0
	v_mov_b32_e32 v50, 0
	v_mov_b32_e32 v51, 0
	v_mov_b32_e32 v0, 0
	v_mov_b32_e32 v1, 0
	v_mov_b32_e32 v2, 0
	v_mov_b32_e32 v3, 0
	v_mov_b32_e32 v36, 0
	v_mov_b32_e32 v37, 0
	v_mov_b32_e32 v38, 0
	v_mov_b32_e32 v39, 0
	v_mov_b32_e32 v8, 0
	v_mov_b32_e32 v9, 0
	v_mov_b32_e32 v10, 0
	v_mov_b32_e32 v11, 0
	v_mov_b32_e32 v32, 0
	v_mov_b32_e32 v33, 0
	v_mov_b32_e32 v34, 0
	v_mov_b32_e32 v35, 0
	v_mov_b32_e32 v4, 0
	v_mov_b32_e32 v5, 0
	v_mov_b32_e32 v6, 0
	v_mov_b32_e32 v7, 0
	s_waitcnt vmcnt(8)
	s_barrier
	ds_read_b128 v[64:67], v208 offset:0
	ds_read_b128 v[68:71], v208 offset:2048
	ds_read_b128 v[160:163], v210 offset:16384
	ds_read_b128 v[164:167], v210 offset:18432
	ds_read_b128 v[168:171], v210 offset:20480
	ds_read_b128 v[172:175], v210 offset:22528
	ds_read_b128 v[176:179], v210 offset:24576
	ds_read_b128 v[180:183], v210 offset:26624
	ds_read_b128 v[184:187], v210 offset:28672
	s_waitcnt lgkmcnt(6)
	v_mfma_f32_16x16x32_bf16 v[40:43], v[64:67], v[160:163], v[40:43]
	v_mfma_f32_16x16x32_bf16 v[52:55], v[68:71], v[160:163], v[52:55]
	ds_read_b128 v[188:191], v210 offset:30720
	s_waitcnt lgkmcnt(6)
	v_mfma_f32_16x16x32_bf16 v[28:31], v[64:67], v[164:167], v[28:31]
	v_mfma_f32_16x16x32_bf16 v[16:19], v[68:71], v[164:167], v[16:19]
	ds_read_b128 v[72:75], v209 offset:0
	ds_read_b128 v[76:79], v209 offset:2048
	ds_read_b128 v[192:195], v211 offset:16384
	s_waitcnt lgkmcnt(8)
	v_mfma_f32_16x16x32_bf16 v[60:63], v[64:67], v[168:171], v[60:63]
	v_mfma_f32_16x16x32_bf16 v[48:51], v[68:71], v[168:171], v[48:51]
	ds_read_b128 v[196:199], v211 offset:18432
	s_waitcnt lgkmcnt(8)
	v_mfma_f32_16x16x32_bf16 v[20:23], v[64:67], v[172:175], v[20:23]
	v_mfma_f32_16x16x32_bf16 v[0:3], v[68:71], v[172:175], v[0:3]
	ds_read_b128 v[200:203], v211 offset:20480
	s_waitcnt lgkmcnt(8)
	v_mfma_f32_16x16x32_bf16 v[44:47], v[64:67], v[176:179], v[44:47]
	v_mfma_f32_16x16x32_bf16 v[36:39], v[68:71], v[176:179], v[36:39]
	ds_read_b128 v[204:207], v211 offset:22528
	s_waitcnt lgkmcnt(8)
	v_mfma_f32_16x16x32_bf16 v[24:27], v[64:67], v[180:183], v[24:27]
	v_mfma_f32_16x16x32_bf16 v[8:11], v[68:71], v[180:183], v[8:11]
	ds_read_b128 v[160:163], v211 offset:24576
	s_waitcnt lgkmcnt(8)
	v_mfma_f32_16x16x32_bf16 v[56:59], v[64:67], v[184:187], v[56:59]
	v_mfma_f32_16x16x32_bf16 v[32:35], v[68:71], v[184:187], v[32:35]
	ds_read_b128 v[164:167], v211 offset:26624
	s_waitcnt lgkmcnt(8)
	v_mfma_f32_16x16x32_bf16 v[12:15], v[64:67], v[188:191], v[12:15]
	v_mfma_f32_16x16x32_bf16 v[4:7], v[68:71], v[188:191], v[4:7]
	ds_read_b128 v[168:171], v211 offset:28672
	s_waitcnt lgkmcnt(6)
	v_mfma_f32_16x16x32_bf16 v[40:43], v[72:75], v[192:195], v[40:43]
	v_mfma_f32_16x16x32_bf16 v[52:55], v[76:79], v[192:195], v[52:55]
	ds_read_b128 v[172:175], v211 offset:30720
	s_waitcnt vmcnt(0) lgkmcnt(0)
	s_barrier
	s_add_u32 m0, s38, 0
	s_nop 0
	global_load_lds_dwordx4 v212, s[98:99]
	s_waitcnt lgkmcnt(6)
	v_mfma_f32_16x16x32_bf16 v[28:31], v[72:75], v[196:199], v[28:31]
	v_mfma_f32_16x16x32_bf16 v[16:19], v[76:79], v[196:199], v[16:19]
	ds_read_b128 v[64:67], v208 offset:32768
	ds_read_b128 v[68:71], v208 offset:34816
	ds_read_b128 v[176:179], v210 offset:49152
	s_add_u32 m0, s38, 4096
	s_nop 0
	global_load_lds_dwordx4 v213, s[98:99]
	s_waitcnt lgkmcnt(8)
	v_mfma_f32_16x16x32_bf16 v[60:63], v[72:75], v[200:203], v[60:63]
	v_mfma_f32_16x16x32_bf16 v[48:51], v[76:79], v[200:203], v[48:51]
	ds_read_b128 v[180:183], v210 offset:51200
	s_add_u32 m0, s38, 8192
	s_nop 0
	global_load_lds_dwordx4 v214, s[98:99]
	s_waitcnt lgkmcnt(8)
	v_mfma_f32_16x16x32_bf16 v[20:23], v[72:75], v[204:207], v[20:23]
	v_mfma_f32_16x16x32_bf16 v[0:3], v[76:79], v[204:207], v[0:3]
	ds_read_b128 v[184:187], v210 offset:53248
	s_add_u32 m0, s38, 12288
	s_nop 0
	global_load_lds_dwordx4 v215, s[98:99]
	s_add_u32 s98, s98, 128
	s_addc_u32 s99, s99, 0
	s_waitcnt lgkmcnt(8)
	v_mfma_f32_16x16x32_bf16 v[44:47], v[72:75], v[160:163], v[44:47]
	v_mfma_f32_16x16x32_bf16 v[36:39], v[76:79], v[160:163], v[36:39]
	ds_read_b128 v[188:191], v210 offset:55296
	s_add_u32 m0, s38, 16384
	s_nop 0
	global_load_lds_dwordx4 v212, s[100:101]
	s_waitcnt lgkmcnt(8)
	v_mfma_f32_16x16x32_bf16 v[24:27], v[72:75], v[164:167], v[24:27]
	v_mfma_f32_16x16x32_bf16 v[8:11], v[76:79], v[164:167], v[8:11]
	ds_read_b128 v[192:195], v210 offset:57344
	s_add_u32 m0, s38, 20480
	s_nop 0
	global_load_lds_dwordx4 v213, s[100:101]
	s_waitcnt lgkmcnt(8)
	v_mfma_f32_16x16x32_bf16 v[56:59], v[72:75], v[168:171], v[56:59]
	v_mfma_f32_16x16x32_bf16 v[32:35], v[76:79], v[168:171], v[32:35]
	ds_read_b128 v[196:199], v210 offset:59392
	s_add_u32 m0, s38, 24576
	s_nop 0
	global_load_lds_dwordx4 v214, s[100:101]
	s_waitcnt lgkmcnt(8)
	v_mfma_f32_16x16x32_bf16 v[12:15], v[72:75], v[172:175], v[12:15]
	v_mfma_f32_16x16x32_bf16 v[4:7], v[76:79], v[172:175], v[4:7]
	ds_read_b128 v[200:203], v210 offset:61440
	s_add_u32 m0, s38, 28672
	s_nop 0
	global_load_lds_dwordx4 v215, s[100:101]
	s_add_u32 s100, s100, 128
	s_addc_u32 s101, s101, 0
	s_waitcnt lgkmcnt(6)
	v_mfma_f32_16x16x32_bf16 v[40:43], v[64:67], v[176:179], v[40:43]
	v_mfma_f32_16x16x32_bf16 v[52:55], v[68:71], v[176:179], v[52:55]
	ds_read_b128 v[204:207], v210 offset:63488
	s_waitcnt lgkmcnt(6)
	v_mfma_f32_16x16x32_bf16 v[28:31], v[64:67], v[180:183], v[28:31]
	v_mfma_f32_16x16x32_bf16 v[16:19], v[68:71], v[180:183], v[16:19]
	ds_read_b128 v[72:75], v209 offset:32768
	ds_read_b128 v[76:79], v209 offset:34816
	ds_read_b128 v[160:163], v211 offset:49152
	s_waitcnt lgkmcnt(8)
	v_mfma_f32_16x16x32_bf16 v[60:63], v[64:67], v[184:187], v[60:63]
	v_mfma_f32_16x16x32_bf16 v[48:51], v[68:71], v[184:187], v[48:51]
	ds_read_b128 v[164:167], v211 offset:51200
	s_waitcnt lgkmcnt(8)
	v_mfma_f32_16x16x32_bf16 v[20:23], v[64:67], v[188:191], v[20:23]
	v_mfma_f32_16x16x32_bf16 v[0:3], v[68:71], v[188:191], v[0:3]
	ds_read_b128 v[168:171], v211 offset:53248
	s_waitcnt lgkmcnt(8)
	v_mfma_f32_16x16x32_bf16 v[44:47], v[64:67], v[192:195], v[44:47]
	v_mfma_f32_16x16x32_bf16 v[36:39], v[68:71], v[192:195], v[36:39]
	ds_read_b128 v[172:175], v211 offset:55296
	s_waitcnt lgkmcnt(8)
	v_mfma_f32_16x16x32_bf16 v[24:27], v[64:67], v[196:199], v[24:27]
	v_mfma_f32_16x16x32_bf16 v[8:11], v[68:71], v[196:199], v[8:11]
	ds_read_b128 v[176:179], v211 offset:57344
	s_waitcnt lgkmcnt(8)
	v_mfma_f32_16x16x32_bf16 v[56:59], v[64:67], v[200:203], v[56:59]
	v_mfma_f32_16x16x32_bf16 v[32:35], v[68:71], v[200:203], v[32:35]
	ds_read_b128 v[180:183], v211 offset:59392
	s_waitcnt lgkmcnt(8)
	v_mfma_f32_16x16x32_bf16 v[12:15], v[64:67], v[204:207], v[12:15]
	v_mfma_f32_16x16x32_bf16 v[4:7], v[68:71], v[204:207], v[4:7]
	ds_read_b128 v[184:187], v211 offset:61440
	s_waitcnt lgkmcnt(6)
	v_mfma_f32_16x16x32_bf16 v[40:43], v[72:75], v[160:163], v[40:43]
	v_mfma_f32_16x16x32_bf16 v[52:55], v[76:79], v[160:163], v[52:55]
	ds_read_b128 v[188:191], v211 offset:63488
	s_waitcnt vmcnt(0) lgkmcnt(0)
	s_barrier
	s_add_u32 m0, s38, 32768
	s_nop 0
	global_load_lds_dwordx4 v212, s[98:99]
	s_waitcnt lgkmcnt(6)
	v_mfma_f32_16x16x32_bf16 v[28:31], v[72:75], v[164:167], v[28:31]
	v_mfma_f32_16x16x32_bf16 v[16:19], v[76:79], v[164:167], v[16:19]
	ds_read_b128 v[64:67], v208 offset:0
	ds_read_b128 v[68:71], v208 offset:2048
	ds_read_b128 v[192:195], v210 offset:16384
	s_add_u32 m0, s38, 36864
	s_nop 0
	global_load_lds_dwordx4 v213, s[98:99]
	s_waitcnt lgkmcnt(8)
	v_mfma_f32_16x16x32_bf16 v[60:63], v[72:75], v[168:171], v[60:63]
	v_mfma_f32_16x16x32_bf16 v[48:51], v[76:79], v[168:171], v[48:51]
	ds_read_b128 v[196:199], v210 offset:18432
	s_add_u32 m0, s38, 40960
	s_nop 0
	global_load_lds_dwordx4 v214, s[98:99]
	s_waitcnt lgkmcnt(8)
	v_mfma_f32_16x16x32_bf16 v[20:23], v[72:75], v[172:175], v[20:23]
	v_mfma_f32_16x16x32_bf16 v[0:3], v[76:79], v[172:175], v[0:3]
	ds_read_b128 v[200:203], v210 offset:20480
	s_add_u32 m0, s38, 45056
	s_nop 0
	global_load_lds_dwordx4 v215, s[98:99]
	s_add_u32 s98, s98, 128
	s_addc_u32 s99, s99, 0
	s_waitcnt lgkmcnt(8)
	v_mfma_f32_16x16x32_bf16 v[44:47], v[72:75], v[176:179], v[44:47]
	v_mfma_f32_16x16x32_bf16 v[36:39], v[76:79], v[176:179], v[36:39]
	ds_read_b128 v[204:207], v210 offset:22528
	s_add_u32 m0, s38, 49152
	s_nop 0
	global_load_lds_dwordx4 v212, s[100:101]
	s_waitcnt lgkmcnt(8)
	v_mfma_f32_16x16x32_bf16 v[24:27], v[72:75], v[180:183], v[24:27]
	v_mfma_f32_16x16x32_bf16 v[8:11], v[76:79], v[180:183], v[8:11]
	ds_read_b128 v[160:163], v210 offset:24576
	s_add_u32 m0, s38, 53248
	s_nop 0
	global_load_lds_dwordx4 v213, s[100:101]
	s_waitcnt lgkmcnt(8)
	v_mfma_f32_16x16x32_bf16 v[56:59], v[72:75], v[184:187], v[56:59]
	v_mfma_f32_16x16x32_bf16 v[32:35], v[76:79], v[184:187], v[32:35]
	ds_read_b128 v[164:167], v210 offset:26624
	s_add_u32 m0, s38, 57344
	s_nop 0
	global_load_lds_dwordx4 v214, s[100:101]
	s_waitcnt lgkmcnt(8)
	v_mfma_f32_16x16x32_bf16 v[12:15], v[72:75], v[188:191], v[12:15]
	v_mfma_f32_16x16x32_bf16 v[4:7], v[76:79], v[188:191], v[4:7]
	ds_read_b128 v[168:171], v210 offset:28672
	s_add_u32 m0, s38, 61440
	s_nop 0
	global_load_lds_dwordx4 v215, s[100:101]
	s_add_u32 s100, s100, 128
	s_addc_u32 s101, s101, 0
	s_waitcnt lgkmcnt(6)
	v_mfma_f32_16x16x32_bf16 v[40:43], v[64:67], v[192:195], v[40:43]
	v_mfma_f32_16x16x32_bf16 v[52:55], v[68:71], v[192:195], v[52:55]
	ds_read_b128 v[172:175], v210 offset:30720
	s_waitcnt lgkmcnt(6)
	v_mfma_f32_16x16x32_bf16 v[28:31], v[64:67], v[196:199], v[28:31]
	v_mfma_f32_16x16x32_bf16 v[16:19], v[68:71], v[196:199], v[16:19]
	ds_read_b128 v[72:75], v209 offset:0
	ds_read_b128 v[76:79], v209 offset:2048
	ds_read_b128 v[176:179], v211 offset:16384
	s_waitcnt lgkmcnt(8)
	v_mfma_f32_16x16x32_bf16 v[60:63], v[64:67], v[200:203], v[60:63]
	v_mfma_f32_16x16x32_bf16 v[48:51], v[68:71], v[200:203], v[48:51]
	ds_read_b128 v[180:183], v211 offset:18432
	s_waitcnt lgkmcnt(8)
	v_mfma_f32_16x16x32_bf16 v[20:23], v[64:67], v[204:207], v[20:23]
	v_mfma_f32_16x16x32_bf16 v[0:3], v[68:71], v[204:207], v[0:3]
	ds_read_b128 v[184:187], v211 offset:20480
	s_waitcnt lgkmcnt(8)
	v_mfma_f32_16x16x32_bf16 v[44:47], v[64:67], v[160:163], v[44:47]
	v_mfma_f32_16x16x32_bf16 v[36:39], v[68:71], v[160:163], v[36:39]
	ds_read_b128 v[188:191], v211 offset:22528
	s_waitcnt lgkmcnt(8)
	v_mfma_f32_16x16x32_bf16 v[24:27], v[64:67], v[164:167], v[24:27]
	v_mfma_f32_16x16x32_bf16 v[8:11], v[68:71], v[164:167], v[8:11]
	ds_read_b128 v[192:195], v211 offset:24576
	s_waitcnt lgkmcnt(8)
	v_mfma_f32_16x16x32_bf16 v[56:59], v[64:67], v[168:171], v[56:59]
	v_mfma_f32_16x16x32_bf16 v[32:35], v[68:71], v[168:171], v[32:35]
	ds_read_b128 v[196:199], v211 offset:26624
	s_waitcnt lgkmcnt(8)
	v_mfma_f32_16x16x32_bf16 v[12:15], v[64:67], v[172:175], v[12:15]
	v_mfma_f32_16x16x32_bf16 v[4:7], v[68:71], v[172:175], v[4:7]
	ds_read_b128 v[200:203], v211 offset:28672
	s_waitcnt lgkmcnt(6)
	v_mfma_f32_16x16x32_bf16 v[40:43], v[72:75], v[176:179], v[40:43]
	v_mfma_f32_16x16x32_bf16 v[52:55], v[76:79], v[176:179], v[52:55]
	ds_read_b128 v[204:207], v211 offset:30720
	s_waitcnt vmcnt(0) lgkmcnt(0)
	s_barrier
	s_add_u32 m0, s38, 0
	s_nop 0
	global_load_lds_dwordx4 v212, s[98:99]
	s_waitcnt lgkmcnt(6)
	v_mfma_f32_16x16x32_bf16 v[28:31], v[72:75], v[180:183], v[28:31]
	v_mfma_f32_16x16x32_bf16 v[16:19], v[76:79], v[180:183], v[16:19]
	ds_read_b128 v[64:67], v208 offset:32768
	ds_read_b128 v[68:71], v208 offset:34816
	ds_read_b128 v[160:163], v210 offset:49152
	s_add_u32 m0, s38, 4096
	s_nop 0
	global_load_lds_dwordx4 v213, s[98:99]
	s_waitcnt lgkmcnt(8)
	v_mfma_f32_16x16x32_bf16 v[60:63], v[72:75], v[184:187], v[60:63]
	v_mfma_f32_16x16x32_bf16 v[48:51], v[76:79], v[184:187], v[48:51]
	ds_read_b128 v[164:167], v210 offset:51200
	s_add_u32 m0, s38, 8192
	s_nop 0
	global_load_lds_dwordx4 v214, s[98:99]
	s_waitcnt lgkmcnt(8)
	v_mfma_f32_16x16x32_bf16 v[20:23], v[72:75], v[188:191], v[20:23]
	v_mfma_f32_16x16x32_bf16 v[0:3], v[76:79], v[188:191], v[0:3]
	ds_read_b128 v[168:171], v210 offset:53248
	s_add_u32 m0, s38, 12288
	s_nop 0
	global_load_lds_dwordx4 v215, s[98:99]
	s_add_u32 s98, s98, 128
	s_addc_u32 s99, s99, 0
	s_waitcnt lgkmcnt(8)
	v_mfma_f32_16x16x32_bf16 v[44:47], v[72:75], v[192:195], v[44:47]
	v_mfma_f32_16x16x32_bf16 v[36:39], v[76:79], v[192:195], v[36:39]
	ds_read_b128 v[172:175], v210 offset:55296
	s_add_u32 m0, s38, 16384
	s_nop 0
	global_load_lds_dwordx4 v212, s[100:101]
	s_waitcnt lgkmcnt(8)
	v_mfma_f32_16x16x32_bf16 v[24:27], v[72:75], v[196:199], v[24:27]
	v_mfma_f32_16x16x32_bf16 v[8:11], v[76:79], v[196:199], v[8:11]
	ds_read_b128 v[176:179], v210 offset:57344
	s_add_u32 m0, s38, 20480
	s_nop 0
	global_load_lds_dwordx4 v213, s[100:101]
	s_waitcnt lgkmcnt(8)
	v_mfma_f32_16x16x32_bf16 v[56:59], v[72:75], v[200:203], v[56:59]
	v_mfma_f32_16x16x32_bf16 v[32:35], v[76:79], v[200:203], v[32:35]
	ds_read_b128 v[180:183], v210 offset:59392
	s_add_u32 m0, s38, 24576
	s_nop 0
	global_load_lds_dwordx4 v214, s[100:101]
	s_waitcnt lgkmcnt(8)
	v_mfma_f32_16x16x32_bf16 v[12:15], v[72:75], v[204:207], v[12:15]
	v_mfma_f32_16x16x32_bf16 v[4:7], v[76:79], v[204:207], v[4:7]
	ds_read_b128 v[184:187], v210 offset:61440
	s_add_u32 m0, s38, 28672
	s_nop 0
	global_load_lds_dwordx4 v215, s[100:101]
	s_add_u32 s100, s100, 128
	s_addc_u32 s101, s101, 0
	s_waitcnt lgkmcnt(6)
	v_mfma_f32_16x16x32_bf16 v[40:43], v[64:67], v[160:163], v[40:43]
	v_mfma_f32_16x16x32_bf16 v[52:55], v[68:71], v[160:163], v[52:55]
	ds_read_b128 v[188:191], v210 offset:63488
	s_waitcnt lgkmcnt(6)
	v_mfma_f32_16x16x32_bf16 v[28:31], v[64:67], v[164:167], v[28:31]
	v_mfma_f32_16x16x32_bf16 v[16:19], v[68:71], v[164:167], v[16:19]
	ds_read_b128 v[72:75], v209 offset:32768
	ds_read_b128 v[76:79], v209 offset:34816
	ds_read_b128 v[192:195], v211 offset:49152
	s_waitcnt lgkmcnt(8)
	v_mfma_f32_16x16x32_bf16 v[60:63], v[64:67], v[168:171], v[60:63]
	v_mfma_f32_16x16x32_bf16 v[48:51], v[68:71], v[168:171], v[48:51]
	ds_read_b128 v[196:199], v211 offset:51200
	s_waitcnt lgkmcnt(8)
	v_mfma_f32_16x16x32_bf16 v[20:23], v[64:67], v[172:175], v[20:23]
	v_mfma_f32_16x16x32_bf16 v[0:3], v[68:71], v[172:175], v[0:3]
	ds_read_b128 v[200:203], v211 offset:53248
	s_waitcnt lgkmcnt(8)
	v_mfma_f32_16x16x32_bf16 v[44:47], v[64:67], v[176:179], v[44:47]
	v_mfma_f32_16x16x32_bf16 v[36:39], v[68:71], v[176:179], v[36:39]
	ds_read_b128 v[204:207], v211 offset:55296
	s_waitcnt lgkmcnt(8)
	v_mfma_f32_16x16x32_bf16 v[24:27], v[64:67], v[180:183], v[24:27]
	v_mfma_f32_16x16x32_bf16 v[8:11], v[68:71], v[180:183], v[8:11]
	ds_read_b128 v[160:163], v211 offset:57344
	s_waitcnt lgkmcnt(8)
	v_mfma_f32_16x16x32_bf16 v[56:59], v[64:67], v[184:187], v[56:59]
	v_mfma_f32_16x16x32_bf16 v[32:35], v[68:71], v[184:187], v[32:35]
	ds_read_b128 v[164:167], v211 offset:59392
	s_waitcnt lgkmcnt(8)
	v_mfma_f32_16x16x32_bf16 v[12:15], v[64:67], v[188:191], v[12:15]
	v_mfma_f32_16x16x32_bf16 v[4:7], v[68:71], v[188:191], v[4:7]
	ds_read_b128 v[168:171], v211 offset:61440
	s_waitcnt lgkmcnt(6)
	v_mfma_f32_16x16x32_bf16 v[40:43], v[72:75], v[192:195], v[40:43]
	v_mfma_f32_16x16x32_bf16 v[52:55], v[76:79], v[192:195], v[52:55]
	ds_read_b128 v[172:175], v211 offset:63488
	s_waitcnt vmcnt(0) lgkmcnt(0)
	s_barrier
	s_add_u32 m0, s38, 32768
	s_nop 0
	global_load_lds_dwordx4 v212, s[98:99]
	s_waitcnt lgkmcnt(6)
	v_mfma_f32_16x16x32_bf16 v[28:31], v[72:75], v[196:199], v[28:31]
	v_mfma_f32_16x16x32_bf16 v[16:19], v[76:79], v[196:199], v[16:19]
	ds_read_b128 v[64:67], v208 offset:0
	ds_read_b128 v[68:71], v208 offset:2048
	ds_read_b128 v[176:179], v210 offset:16384
	s_add_u32 m0, s38, 36864
	s_nop 0
	global_load_lds_dwordx4 v213, s[98:99]
	s_waitcnt lgkmcnt(8)
	v_mfma_f32_16x16x32_bf16 v[60:63], v[72:75], v[200:203], v[60:63]
	v_mfma_f32_16x16x32_bf16 v[48:51], v[76:79], v[200:203], v[48:51]
	ds_read_b128 v[180:183], v210 offset:18432
	s_add_u32 m0, s38, 40960
	s_nop 0
	global_load_lds_dwordx4 v214, s[98:99]
	s_waitcnt lgkmcnt(8)
	v_mfma_f32_16x16x32_bf16 v[20:23], v[72:75], v[204:207], v[20:23]
	v_mfma_f32_16x16x32_bf16 v[0:3], v[76:79], v[204:207], v[0:3]
	ds_read_b128 v[184:187], v210 offset:20480
	s_add_u32 m0, s38, 45056
	s_nop 0
	global_load_lds_dwordx4 v215, s[98:99]
	s_add_u32 s98, s98, 128
	s_addc_u32 s99, s99, 0
	s_waitcnt lgkmcnt(8)
	v_mfma_f32_16x16x32_bf16 v[44:47], v[72:75], v[160:163], v[44:47]
	v_mfma_f32_16x16x32_bf16 v[36:39], v[76:79], v[160:163], v[36:39]
	ds_read_b128 v[188:191], v210 offset:22528
	s_add_u32 m0, s38, 49152
	s_nop 0
	global_load_lds_dwordx4 v212, s[100:101]
	s_waitcnt lgkmcnt(8)
	v_mfma_f32_16x16x32_bf16 v[24:27], v[72:75], v[164:167], v[24:27]
	v_mfma_f32_16x16x32_bf16 v[8:11], v[76:79], v[164:167], v[8:11]
	ds_read_b128 v[192:195], v210 offset:24576
	s_add_u32 m0, s38, 53248
	s_nop 0
	global_load_lds_dwordx4 v213, s[100:101]
	s_waitcnt lgkmcnt(8)
	v_mfma_f32_16x16x32_bf16 v[56:59], v[72:75], v[168:171], v[56:59]
	v_mfma_f32_16x16x32_bf16 v[32:35], v[76:79], v[168:171], v[32:35]
	ds_read_b128 v[196:199], v210 offset:26624
	s_add_u32 m0, s38, 57344
	s_nop 0
	global_load_lds_dwordx4 v214, s[100:101]
	s_waitcnt lgkmcnt(8)
	v_mfma_f32_16x16x32_bf16 v[12:15], v[72:75], v[172:175], v[12:15]
	v_mfma_f32_16x16x32_bf16 v[4:7], v[76:79], v[172:175], v[4:7]
	ds_read_b128 v[200:203], v210 offset:28672
	s_add_u32 m0, s38, 61440
	s_nop 0
	global_load_lds_dwordx4 v215, s[100:101]
	s_add_u32 s100, s100, 128
	s_addc_u32 s101, s101, 0
	s_waitcnt lgkmcnt(6)
	v_mfma_f32_16x16x32_bf16 v[40:43], v[64:67], v[176:179], v[40:43]
	v_mfma_f32_16x16x32_bf16 v[52:55], v[68:71], v[176:179], v[52:55]
	ds_read_b128 v[204:207], v210 offset:30720
	s_waitcnt lgkmcnt(6)
	v_mfma_f32_16x16x32_bf16 v[28:31], v[64:67], v[180:183], v[28:31]
	v_mfma_f32_16x16x32_bf16 v[16:19], v[68:71], v[180:183], v[16:19]
	ds_read_b128 v[72:75], v209 offset:0
	ds_read_b128 v[76:79], v209 offset:2048
	ds_read_b128 v[160:163], v211 offset:16384
	s_waitcnt lgkmcnt(8)
	v_mfma_f32_16x16x32_bf16 v[60:63], v[64:67], v[184:187], v[60:63]
	v_mfma_f32_16x16x32_bf16 v[48:51], v[68:71], v[184:187], v[48:51]
	ds_read_b128 v[164:167], v211 offset:18432
	s_waitcnt lgkmcnt(8)
	v_mfma_f32_16x16x32_bf16 v[20:23], v[64:67], v[188:191], v[20:23]
	v_mfma_f32_16x16x32_bf16 v[0:3], v[68:71], v[188:191], v[0:3]
	ds_read_b128 v[168:171], v211 offset:20480
	s_waitcnt lgkmcnt(8)
	v_mfma_f32_16x16x32_bf16 v[44:47], v[64:67], v[192:195], v[44:47]
	v_mfma_f32_16x16x32_bf16 v[36:39], v[68:71], v[192:195], v[36:39]
	ds_read_b128 v[172:175], v211 offset:22528
	s_waitcnt lgkmcnt(8)
	v_mfma_f32_16x16x32_bf16 v[24:27], v[64:67], v[196:199], v[24:27]
	v_mfma_f32_16x16x32_bf16 v[8:11], v[68:71], v[196:199], v[8:11]
	ds_read_b128 v[176:179], v211 offset:24576
	s_waitcnt lgkmcnt(8)
	v_mfma_f32_16x16x32_bf16 v[56:59], v[64:67], v[200:203], v[56:59]
	v_mfma_f32_16x16x32_bf16 v[32:35], v[68:71], v[200:203], v[32:35]
	ds_read_b128 v[180:183], v211 offset:26624
	s_waitcnt lgkmcnt(8)
	v_mfma_f32_16x16x32_bf16 v[12:15], v[64:67], v[204:207], v[12:15]
	v_mfma_f32_16x16x32_bf16 v[4:7], v[68:71], v[204:207], v[4:7]
	ds_read_b128 v[184:187], v211 offset:28672
	s_waitcnt lgkmcnt(6)
	v_mfma_f32_16x16x32_bf16 v[40:43], v[72:75], v[160:163], v[40:43]
	v_mfma_f32_16x16x32_bf16 v[52:55], v[76:79], v[160:163], v[52:55]
	ds_read_b128 v[188:191], v211 offset:30720
	s_waitcnt vmcnt(0) lgkmcnt(0)
	s_barrier
	s_add_u32 m0, s38, 0
	s_nop 0
	global_load_lds_dwordx4 v212, s[98:99]
	s_waitcnt lgkmcnt(6)
	v_mfma_f32_16x16x32_bf16 v[28:31], v[72:75], v[164:167], v[28:31]
	v_mfma_f32_16x16x32_bf16 v[16:19], v[76:79], v[164:167], v[16:19]
	ds_read_b128 v[64:67], v208 offset:32768
	ds_read_b128 v[68:71], v208 offset:34816
	ds_read_b128 v[192:195], v210 offset:49152
	s_add_u32 m0, s38, 4096
	s_nop 0
	global_load_lds_dwordx4 v213, s[98:99]
	s_waitcnt lgkmcnt(8)
	v_mfma_f32_16x16x32_bf16 v[60:63], v[72:75], v[168:171], v[60:63]
	v_mfma_f32_16x16x32_bf16 v[48:51], v[76:79], v[168:171], v[48:51]
	ds_read_b128 v[196:199], v210 offset:51200
	s_add_u32 m0, s38, 8192
	s_nop 0
	global_load_lds_dwordx4 v214, s[98:99]
	s_waitcnt lgkmcnt(8)
	v_mfma_f32_16x16x32_bf16 v[20:23], v[72:75], v[172:175], v[20:23]
	v_mfma_f32_16x16x32_bf16 v[0:3], v[76:79], v[172:175], v[0:3]
	ds_read_b128 v[200:203], v210 offset:53248
	s_add_u32 m0, s38, 12288
	s_nop 0
	global_load_lds_dwordx4 v215, s[98:99]
	s_add_u32 s98, s98, 128
	s_addc_u32 s99, s99, 0
	s_waitcnt lgkmcnt(8)
	v_mfma_f32_16x16x32_bf16 v[44:47], v[72:75], v[176:179], v[44:47]
	v_mfma_f32_16x16x32_bf16 v[36:39], v[76:79], v[176:179], v[36:39]
	ds_read_b128 v[204:207], v210 offset:55296
	s_add_u32 m0, s38, 16384
	s_nop 0
	global_load_lds_dwordx4 v212, s[100:101]
	s_waitcnt lgkmcnt(8)
	v_mfma_f32_16x16x32_bf16 v[24:27], v[72:75], v[180:183], v[24:27]
	v_mfma_f32_16x16x32_bf16 v[8:11], v[76:79], v[180:183], v[8:11]
	ds_read_b128 v[160:163], v210 offset:57344
	s_add_u32 m0, s38, 20480
	s_nop 0
	global_load_lds_dwordx4 v213, s[100:101]
	s_waitcnt lgkmcnt(8)
	v_mfma_f32_16x16x32_bf16 v[56:59], v[72:75], v[184:187], v[56:59]
	v_mfma_f32_16x16x32_bf16 v[32:35], v[76:79], v[184:187], v[32:35]
	ds_read_b128 v[164:167], v210 offset:59392
	s_add_u32 m0, s38, 24576
	s_nop 0
	global_load_lds_dwordx4 v214, s[100:101]
	s_waitcnt lgkmcnt(8)
	v_mfma_f32_16x16x32_bf16 v[12:15], v[72:75], v[188:191], v[12:15]
	v_mfma_f32_16x16x32_bf16 v[4:7], v[76:79], v[188:191], v[4:7]
	ds_read_b128 v[168:171], v210 offset:61440
	s_add_u32 m0, s38, 28672
	s_nop 0
	global_load_lds_dwordx4 v215, s[100:101]
	s_add_u32 s100, s100, 128
	s_addc_u32 s101, s101, 0
	s_waitcnt lgkmcnt(6)
	v_mfma_f32_16x16x32_bf16 v[40:43], v[64:67], v[192:195], v[40:43]
	v_mfma_f32_16x16x32_bf16 v[52:55], v[68:71], v[192:195], v[52:55]
	ds_read_b128 v[172:175], v210 offset:63488
	s_waitcnt lgkmcnt(6)
	v_mfma_f32_16x16x32_bf16 v[28:31], v[64:67], v[196:199], v[28:31]
	v_mfma_f32_16x16x32_bf16 v[16:19], v[68:71], v[196:199], v[16:19]
	ds_read_b128 v[72:75], v209 offset:32768
	ds_read_b128 v[76:79], v209 offset:34816
	ds_read_b128 v[176:179], v211 offset:49152
	s_waitcnt lgkmcnt(8)
	v_mfma_f32_16x16x32_bf16 v[60:63], v[64:67], v[200:203], v[60:63]
	v_mfma_f32_16x16x32_bf16 v[48:51], v[68:71], v[200:203], v[48:51]
	ds_read_b128 v[180:183], v211 offset:51200
	s_waitcnt lgkmcnt(8)
	v_mfma_f32_16x16x32_bf16 v[20:23], v[64:67], v[204:207], v[20:23]
	v_mfma_f32_16x16x32_bf16 v[0:3], v[68:71], v[204:207], v[0:3]
	ds_read_b128 v[184:187], v211 offset:53248
	s_waitcnt lgkmcnt(8)
	v_mfma_f32_16x16x32_bf16 v[44:47], v[64:67], v[160:163], v[44:47]
	v_mfma_f32_16x16x32_bf16 v[36:39], v[68:71], v[160:163], v[36:39]
	ds_read_b128 v[188:191], v211 offset:55296
	s_waitcnt lgkmcnt(8)
	v_mfma_f32_16x16x32_bf16 v[24:27], v[64:67], v[164:167], v[24:27]
	v_mfma_f32_16x16x32_bf16 v[8:11], v[68:71], v[164:167], v[8:11]
	ds_read_b128 v[192:195], v211 offset:57344
	s_waitcnt lgkmcnt(8)
	v_mfma_f32_16x16x32_bf16 v[56:59], v[64:67], v[168:171], v[56:59]
	v_mfma_f32_16x16x32_bf16 v[32:35], v[68:71], v[168:171], v[32:35]
	ds_read_b128 v[196:199], v211 offset:59392
	s_waitcnt lgkmcnt(8)
	v_mfma_f32_16x16x32_bf16 v[12:15], v[64:67], v[172:175], v[12:15]
	v_mfma_f32_16x16x32_bf16 v[4:7], v[68:71], v[172:175], v[4:7]
	ds_read_b128 v[200:203], v211 offset:61440
	s_waitcnt lgkmcnt(6)
	v_mfma_f32_16x16x32_bf16 v[40:43], v[72:75], v[176:179], v[40:43]
	v_mfma_f32_16x16x32_bf16 v[52:55], v[76:79], v[176:179], v[52:55]
	ds_read_b128 v[204:207], v211 offset:63488
	s_waitcnt vmcnt(0) lgkmcnt(0)
	s_barrier
	s_add_u32 m0, s38, 32768
	s_nop 0
	global_load_lds_dwordx4 v212, s[98:99]
	s_waitcnt lgkmcnt(6)
	v_mfma_f32_16x16x32_bf16 v[28:31], v[72:75], v[180:183], v[28:31]
	v_mfma_f32_16x16x32_bf16 v[16:19], v[76:79], v[180:183], v[16:19]
	ds_read_b128 v[64:67], v208 offset:0
	ds_read_b128 v[68:71], v208 offset:2048
	ds_read_b128 v[160:163], v210 offset:16384
	s_add_u32 m0, s38, 36864
	s_nop 0
	global_load_lds_dwordx4 v213, s[98:99]
	s_waitcnt lgkmcnt(8)
	v_mfma_f32_16x16x32_bf16 v[60:63], v[72:75], v[184:187], v[60:63]
	v_mfma_f32_16x16x32_bf16 v[48:51], v[76:79], v[184:187], v[48:51]
	ds_read_b128 v[164:167], v210 offset:18432
	s_add_u32 m0, s38, 40960
	s_nop 0
	global_load_lds_dwordx4 v214, s[98:99]
	s_waitcnt lgkmcnt(8)
	v_mfma_f32_16x16x32_bf16 v[20:23], v[72:75], v[188:191], v[20:23]
	v_mfma_f32_16x16x32_bf16 v[0:3], v[76:79], v[188:191], v[0:3]
	ds_read_b128 v[168:171], v210 offset:20480
	s_add_u32 m0, s38, 45056
	s_nop 0
	global_load_lds_dwordx4 v215, s[98:99]
	s_add_u32 s98, s98, 128
	s_addc_u32 s99, s99, 0
	s_waitcnt lgkmcnt(8)
	v_mfma_f32_16x16x32_bf16 v[44:47], v[72:75], v[192:195], v[44:47]
	v_mfma_f32_16x16x32_bf16 v[36:39], v[76:79], v[192:195], v[36:39]
	ds_read_b128 v[172:175], v210 offset:22528
	s_add_u32 m0, s38, 49152
	s_nop 0
	global_load_lds_dwordx4 v212, s[100:101]
	s_waitcnt lgkmcnt(8)
	v_mfma_f32_16x16x32_bf16 v[24:27], v[72:75], v[196:199], v[24:27]
	v_mfma_f32_16x16x32_bf16 v[8:11], v[76:79], v[196:199], v[8:11]
	ds_read_b128 v[176:179], v210 offset:24576
	s_add_u32 m0, s38, 53248
	s_nop 0
	global_load_lds_dwordx4 v213, s[100:101]
	s_waitcnt lgkmcnt(8)
	v_mfma_f32_16x16x32_bf16 v[56:59], v[72:75], v[200:203], v[56:59]
	v_mfma_f32_16x16x32_bf16 v[32:35], v[76:79], v[200:203], v[32:35]
	ds_read_b128 v[180:183], v210 offset:26624
	s_add_u32 m0, s38, 57344
	s_nop 0
	global_load_lds_dwordx4 v214, s[100:101]
	s_waitcnt lgkmcnt(8)
	v_mfma_f32_16x16x32_bf16 v[12:15], v[72:75], v[204:207], v[12:15]
	v_mfma_f32_16x16x32_bf16 v[4:7], v[76:79], v[204:207], v[4:7]
	ds_read_b128 v[184:187], v210 offset:28672
	s_add_u32 m0, s38, 61440
	s_nop 0
	global_load_lds_dwordx4 v215, s[100:101]
	s_add_u32 s100, s100, 128
	s_addc_u32 s101, s101, 0
	s_waitcnt lgkmcnt(6)
	v_mfma_f32_16x16x32_bf16 v[40:43], v[64:67], v[160:163], v[40:43]
	v_mfma_f32_16x16x32_bf16 v[52:55], v[68:71], v[160:163], v[52:55]
	ds_read_b128 v[188:191], v210 offset:30720
	s_waitcnt lgkmcnt(6)
	v_mfma_f32_16x16x32_bf16 v[28:31], v[64:67], v[164:167], v[28:31]
	v_mfma_f32_16x16x32_bf16 v[16:19], v[68:71], v[164:167], v[16:19]
	ds_read_b128 v[72:75], v209 offset:0
	ds_read_b128 v[76:79], v209 offset:2048
	ds_read_b128 v[192:195], v211 offset:16384
	s_waitcnt lgkmcnt(8)
	v_mfma_f32_16x16x32_bf16 v[60:63], v[64:67], v[168:171], v[60:63]
	v_mfma_f32_16x16x32_bf16 v[48:51], v[68:71], v[168:171], v[48:51]
	ds_read_b128 v[196:199], v211 offset:18432
	s_waitcnt lgkmcnt(8)
	v_mfma_f32_16x16x32_bf16 v[20:23], v[64:67], v[172:175], v[20:23]
	v_mfma_f32_16x16x32_bf16 v[0:3], v[68:71], v[172:175], v[0:3]
	ds_read_b128 v[200:203], v211 offset:20480
	s_waitcnt lgkmcnt(8)
	v_mfma_f32_16x16x32_bf16 v[44:47], v[64:67], v[176:179], v[44:47]
	v_mfma_f32_16x16x32_bf16 v[36:39], v[68:71], v[176:179], v[36:39]
	ds_read_b128 v[204:207], v211 offset:22528
	s_waitcnt lgkmcnt(8)
	v_mfma_f32_16x16x32_bf16 v[24:27], v[64:67], v[180:183], v[24:27]
	v_mfma_f32_16x16x32_bf16 v[8:11], v[68:71], v[180:183], v[8:11]
	ds_read_b128 v[160:163], v211 offset:24576
	s_waitcnt lgkmcnt(8)
	v_mfma_f32_16x16x32_bf16 v[56:59], v[64:67], v[184:187], v[56:59]
	v_mfma_f32_16x16x32_bf16 v[32:35], v[68:71], v[184:187], v[32:35]
	ds_read_b128 v[164:167], v211 offset:26624
	s_waitcnt lgkmcnt(8)
	v_mfma_f32_16x16x32_bf16 v[12:15], v[64:67], v[188:191], v[12:15]
	v_mfma_f32_16x16x32_bf16 v[4:7], v[68:71], v[188:191], v[4:7]
	ds_read_b128 v[168:171], v211 offset:28672
	s_waitcnt lgkmcnt(6)
	v_mfma_f32_16x16x32_bf16 v[40:43], v[72:75], v[192:195], v[40:43]
	v_mfma_f32_16x16x32_bf16 v[52:55], v[76:79], v[192:195], v[52:55]
	ds_read_b128 v[172:175], v211 offset:30720
	s_waitcnt vmcnt(0) lgkmcnt(0)
	s_barrier
	s_add_u32 m0, s38, 0
	s_nop 0
	global_load_lds_dwordx4 v212, s[98:99]
	s_waitcnt lgkmcnt(6)
	v_mfma_f32_16x16x32_bf16 v[28:31], v[72:75], v[196:199], v[28:31]
	v_mfma_f32_16x16x32_bf16 v[16:19], v[76:79], v[196:199], v[16:19]
	ds_read_b128 v[64:67], v208 offset:32768
	ds_read_b128 v[68:71], v208 offset:34816
	ds_read_b128 v[176:179], v210 offset:49152
	s_add_u32 m0, s38, 4096
	s_nop 0
	global_load_lds_dwordx4 v213, s[98:99]
	s_waitcnt lgkmcnt(8)
	v_mfma_f32_16x16x32_bf16 v[60:63], v[72:75], v[200:203], v[60:63]
	v_mfma_f32_16x16x32_bf16 v[48:51], v[76:79], v[200:203], v[48:51]
	ds_read_b128 v[180:183], v210 offset:51200
	s_add_u32 m0, s38, 8192
	s_nop 0
	global_load_lds_dwordx4 v214, s[98:99]
	s_waitcnt lgkmcnt(8)
	v_mfma_f32_16x16x32_bf16 v[20:23], v[72:75], v[204:207], v[20:23]
	v_mfma_f32_16x16x32_bf16 v[0:3], v[76:79], v[204:207], v[0:3]
	ds_read_b128 v[184:187], v210 offset:53248
	s_add_u32 m0, s38, 12288
	s_nop 0
	global_load_lds_dwordx4 v215, s[98:99]
	s_add_u32 s98, s98, 128
	s_addc_u32 s99, s99, 0
	s_waitcnt lgkmcnt(8)
	v_mfma_f32_16x16x32_bf16 v[44:47], v[72:75], v[160:163], v[44:47]
	v_mfma_f32_16x16x32_bf16 v[36:39], v[76:79], v[160:163], v[36:39]
	ds_read_b128 v[188:191], v210 offset:55296
	s_add_u32 m0, s38, 16384
	s_nop 0
	global_load_lds_dwordx4 v212, s[100:101]
	s_waitcnt lgkmcnt(8)
	v_mfma_f32_16x16x32_bf16 v[24:27], v[72:75], v[164:167], v[24:27]
	v_mfma_f32_16x16x32_bf16 v[8:11], v[76:79], v[164:167], v[8:11]
	ds_read_b128 v[192:195], v210 offset:57344
	s_add_u32 m0, s38, 20480
	s_nop 0
	global_load_lds_dwordx4 v213, s[100:101]
	s_waitcnt lgkmcnt(8)
	v_mfma_f32_16x16x32_bf16 v[56:59], v[72:75], v[168:171], v[56:59]
	v_mfma_f32_16x16x32_bf16 v[32:35], v[76:79], v[168:171], v[32:35]
	ds_read_b128 v[196:199], v210 offset:59392
	s_add_u32 m0, s38, 24576
	s_nop 0
	global_load_lds_dwordx4 v214, s[100:101]
	s_waitcnt lgkmcnt(8)
	v_mfma_f32_16x16x32_bf16 v[12:15], v[72:75], v[172:175], v[12:15]
	v_mfma_f32_16x16x32_bf16 v[4:7], v[76:79], v[172:175], v[4:7]
	ds_read_b128 v[200:203], v210 offset:61440
	s_add_u32 m0, s38, 28672
	s_nop 0
	global_load_lds_dwordx4 v215, s[100:101]
	s_add_u32 s100, s100, 128
	s_addc_u32 s101, s101, 0
	s_waitcnt lgkmcnt(6)
	v_mfma_f32_16x16x32_bf16 v[40:43], v[64:67], v[176:179], v[40:43]
	v_mfma_f32_16x16x32_bf16 v[52:55], v[68:71], v[176:179], v[52:55]
	ds_read_b128 v[204:207], v210 offset:63488
	s_waitcnt lgkmcnt(6)
	v_mfma_f32_16x16x32_bf16 v[28:31], v[64:67], v[180:183], v[28:31]
	v_mfma_f32_16x16x32_bf16 v[16:19], v[68:71], v[180:183], v[16:19]
	ds_read_b128 v[72:75], v209 offset:32768
	ds_read_b128 v[76:79], v209 offset:34816
	ds_read_b128 v[160:163], v211 offset:49152
	s_waitcnt lgkmcnt(8)
	v_mfma_f32_16x16x32_bf16 v[60:63], v[64:67], v[184:187], v[60:63]
	v_mfma_f32_16x16x32_bf16 v[48:51], v[68:71], v[184:187], v[48:51]
	ds_read_b128 v[164:167], v211 offset:51200
	s_waitcnt lgkmcnt(8)
	v_mfma_f32_16x16x32_bf16 v[20:23], v[64:67], v[188:191], v[20:23]
	v_mfma_f32_16x16x32_bf16 v[0:3], v[68:71], v[188:191], v[0:3]
	ds_read_b128 v[168:171], v211 offset:53248
	s_waitcnt lgkmcnt(8)
	v_mfma_f32_16x16x32_bf16 v[44:47], v[64:67], v[192:195], v[44:47]
	v_mfma_f32_16x16x32_bf16 v[36:39], v[68:71], v[192:195], v[36:39]
	ds_read_b128 v[172:175], v211 offset:55296
	s_waitcnt lgkmcnt(8)
	v_mfma_f32_16x16x32_bf16 v[24:27], v[64:67], v[196:199], v[24:27]
	v_mfma_f32_16x16x32_bf16 v[8:11], v[68:71], v[196:199], v[8:11]
	ds_read_b128 v[176:179], v211 offset:57344
	s_waitcnt lgkmcnt(8)
	v_mfma_f32_16x16x32_bf16 v[56:59], v[64:67], v[200:203], v[56:59]
	v_mfma_f32_16x16x32_bf16 v[32:35], v[68:71], v[200:203], v[32:35]
	ds_read_b128 v[180:183], v211 offset:59392
	s_waitcnt lgkmcnt(8)
	v_mfma_f32_16x16x32_bf16 v[12:15], v[64:67], v[204:207], v[12:15]
	v_mfma_f32_16x16x32_bf16 v[4:7], v[68:71], v[204:207], v[4:7]
	ds_read_b128 v[184:187], v211 offset:61440
	s_waitcnt lgkmcnt(6)
	v_mfma_f32_16x16x32_bf16 v[40:43], v[72:75], v[160:163], v[40:43]
	v_mfma_f32_16x16x32_bf16 v[52:55], v[76:79], v[160:163], v[52:55]
	ds_read_b128 v[188:191], v211 offset:63488
	s_waitcnt vmcnt(0) lgkmcnt(0)
	s_barrier
	s_add_u32 m0, s38, 32768
	s_nop 0
	global_load_lds_dwordx4 v212, s[98:99]
	s_waitcnt lgkmcnt(6)
	v_mfma_f32_16x16x32_bf16 v[28:31], v[72:75], v[164:167], v[28:31]
	v_mfma_f32_16x16x32_bf16 v[16:19], v[76:79], v[164:167], v[16:19]
	ds_read_b128 v[64:67], v208 offset:0
	ds_read_b128 v[68:71], v208 offset:2048
	ds_read_b128 v[192:195], v210 offset:16384
	s_add_u32 m0, s38, 36864
	s_nop 0
	global_load_lds_dwordx4 v213, s[98:99]
	s_waitcnt lgkmcnt(8)
	v_mfma_f32_16x16x32_bf16 v[60:63], v[72:75], v[168:171], v[60:63]
	v_mfma_f32_16x16x32_bf16 v[48:51], v[76:79], v[168:171], v[48:51]
	ds_read_b128 v[196:199], v210 offset:18432
	s_add_u32 m0, s38, 40960
	s_nop 0
	global_load_lds_dwordx4 v214, s[98:99]
	s_waitcnt lgkmcnt(8)
	v_mfma_f32_16x16x32_bf16 v[20:23], v[72:75], v[172:175], v[20:23]
	v_mfma_f32_16x16x32_bf16 v[0:3], v[76:79], v[172:175], v[0:3]
	ds_read_b128 v[200:203], v210 offset:20480
	s_add_u32 m0, s38, 45056
	s_nop 0
	global_load_lds_dwordx4 v215, s[98:99]
	s_add_u32 s98, s98, 128
	s_addc_u32 s99, s99, 0
	s_waitcnt lgkmcnt(8)
	v_mfma_f32_16x16x32_bf16 v[44:47], v[72:75], v[176:179], v[44:47]
	v_mfma_f32_16x16x32_bf16 v[36:39], v[76:79], v[176:179], v[36:39]
	ds_read_b128 v[204:207], v210 offset:22528
	s_add_u32 m0, s38, 49152
	s_nop 0
	global_load_lds_dwordx4 v212, s[100:101]
	s_waitcnt lgkmcnt(8)
	v_mfma_f32_16x16x32_bf16 v[24:27], v[72:75], v[180:183], v[24:27]
	v_mfma_f32_16x16x32_bf16 v[8:11], v[76:79], v[180:183], v[8:11]
	ds_read_b128 v[160:163], v210 offset:24576
	s_add_u32 m0, s38, 53248
	s_nop 0
	global_load_lds_dwordx4 v213, s[100:101]
	s_waitcnt lgkmcnt(8)
	v_mfma_f32_16x16x32_bf16 v[56:59], v[72:75], v[184:187], v[56:59]
	v_mfma_f32_16x16x32_bf16 v[32:35], v[76:79], v[184:187], v[32:35]
	ds_read_b128 v[164:167], v210 offset:26624
	s_add_u32 m0, s38, 57344
	s_nop 0
	global_load_lds_dwordx4 v214, s[100:101]
	s_waitcnt lgkmcnt(8)
	v_mfma_f32_16x16x32_bf16 v[12:15], v[72:75], v[188:191], v[12:15]
	v_mfma_f32_16x16x32_bf16 v[4:7], v[76:79], v[188:191], v[4:7]
	ds_read_b128 v[168:171], v210 offset:28672
	s_add_u32 m0, s38, 61440
	s_nop 0
	global_load_lds_dwordx4 v215, s[100:101]
	s_add_u32 s100, s100, 128
	s_addc_u32 s101, s101, 0
	s_waitcnt lgkmcnt(6)
	v_mfma_f32_16x16x32_bf16 v[40:43], v[64:67], v[192:195], v[40:43]
	v_mfma_f32_16x16x32_bf16 v[52:55], v[68:71], v[192:195], v[52:55]
	ds_read_b128 v[172:175], v210 offset:30720
	s_waitcnt lgkmcnt(6)
	v_mfma_f32_16x16x32_bf16 v[28:31], v[64:67], v[196:199], v[28:31]
	v_mfma_f32_16x16x32_bf16 v[16:19], v[68:71], v[196:199], v[16:19]
	ds_read_b128 v[72:75], v209 offset:0
	ds_read_b128 v[76:79], v209 offset:2048
	ds_read_b128 v[176:179], v211 offset:16384
	s_waitcnt lgkmcnt(8)
	v_mfma_f32_16x16x32_bf16 v[60:63], v[64:67], v[200:203], v[60:63]
	v_mfma_f32_16x16x32_bf16 v[48:51], v[68:71], v[200:203], v[48:51]
	ds_read_b128 v[180:183], v211 offset:18432
	s_waitcnt lgkmcnt(8)
	v_mfma_f32_16x16x32_bf16 v[20:23], v[64:67], v[204:207], v[20:23]
	v_mfma_f32_16x16x32_bf16 v[0:3], v[68:71], v[204:207], v[0:3]
	ds_read_b128 v[184:187], v211 offset:20480
	s_waitcnt lgkmcnt(8)
	v_mfma_f32_16x16x32_bf16 v[44:47], v[64:67], v[160:163], v[44:47]
	v_mfma_f32_16x16x32_bf16 v[36:39], v[68:71], v[160:163], v[36:39]
	ds_read_b128 v[188:191], v211 offset:22528
	s_waitcnt lgkmcnt(8)
	v_mfma_f32_16x16x32_bf16 v[24:27], v[64:67], v[164:167], v[24:27]
	v_mfma_f32_16x16x32_bf16 v[8:11], v[68:71], v[164:167], v[8:11]
	ds_read_b128 v[192:195], v211 offset:24576
	s_waitcnt lgkmcnt(8)
	v_mfma_f32_16x16x32_bf16 v[56:59], v[64:67], v[168:171], v[56:59]
	v_mfma_f32_16x16x32_bf16 v[32:35], v[68:71], v[168:171], v[32:35]
	ds_read_b128 v[196:199], v211 offset:26624
	s_waitcnt lgkmcnt(8)
	v_mfma_f32_16x16x32_bf16 v[12:15], v[64:67], v[172:175], v[12:15]
	v_mfma_f32_16x16x32_bf16 v[4:7], v[68:71], v[172:175], v[4:7]
	ds_read_b128 v[200:203], v211 offset:28672
	s_waitcnt lgkmcnt(6)
	v_mfma_f32_16x16x32_bf16 v[40:43], v[72:75], v[176:179], v[40:43]
	v_mfma_f32_16x16x32_bf16 v[52:55], v[76:79], v[176:179], v[52:55]
	ds_read_b128 v[204:207], v211 offset:30720
	s_waitcnt vmcnt(0) lgkmcnt(0)
	s_barrier
	s_add_u32 m0, s38, 0
	s_nop 0
	global_load_lds_dwordx4 v212, s[98:99]
	s_waitcnt lgkmcnt(6)
	v_mfma_f32_16x16x32_bf16 v[28:31], v[72:75], v[180:183], v[28:31]
	v_mfma_f32_16x16x32_bf16 v[16:19], v[76:79], v[180:183], v[16:19]
	ds_read_b128 v[64:67], v208 offset:32768
	ds_read_b128 v[68:71], v208 offset:34816
	ds_read_b128 v[160:163], v210 offset:49152
	s_add_u32 m0, s38, 4096
	s_nop 0
	global_load_lds_dwordx4 v213, s[98:99]
	s_waitcnt lgkmcnt(8)
	v_mfma_f32_16x16x32_bf16 v[60:63], v[72:75], v[184:187], v[60:63]
	v_mfma_f32_16x16x32_bf16 v[48:51], v[76:79], v[184:187], v[48:51]
	ds_read_b128 v[164:167], v210 offset:51200
	s_add_u32 m0, s38, 8192
	s_nop 0
	global_load_lds_dwordx4 v214, s[98:99]
	s_waitcnt lgkmcnt(8)
	v_mfma_f32_16x16x32_bf16 v[20:23], v[72:75], v[188:191], v[20:23]
	v_mfma_f32_16x16x32_bf16 v[0:3], v[76:79], v[188:191], v[0:3]
	ds_read_b128 v[168:171], v210 offset:53248
	s_add_u32 m0, s38, 12288
	s_nop 0
	global_load_lds_dwordx4 v215, s[98:99]
	s_add_u32 s98, s98, 128
	s_addc_u32 s99, s99, 0
	s_waitcnt lgkmcnt(8)
	v_mfma_f32_16x16x32_bf16 v[44:47], v[72:75], v[192:195], v[44:47]
	v_mfma_f32_16x16x32_bf16 v[36:39], v[76:79], v[192:195], v[36:39]
	ds_read_b128 v[172:175], v210 offset:55296
	s_add_u32 m0, s38, 16384
	s_nop 0
	global_load_lds_dwordx4 v212, s[100:101]
	s_waitcnt lgkmcnt(8)
	v_mfma_f32_16x16x32_bf16 v[24:27], v[72:75], v[196:199], v[24:27]
	v_mfma_f32_16x16x32_bf16 v[8:11], v[76:79], v[196:199], v[8:11]
	ds_read_b128 v[176:179], v210 offset:57344
	s_add_u32 m0, s38, 20480
	s_nop 0
	global_load_lds_dwordx4 v213, s[100:101]
	s_waitcnt lgkmcnt(8)
	v_mfma_f32_16x16x32_bf16 v[56:59], v[72:75], v[200:203], v[56:59]
	v_mfma_f32_16x16x32_bf16 v[32:35], v[76:79], v[200:203], v[32:35]
	ds_read_b128 v[180:183], v210 offset:59392
	s_add_u32 m0, s38, 24576
	s_nop 0
	global_load_lds_dwordx4 v214, s[100:101]
	s_waitcnt lgkmcnt(8)
	v_mfma_f32_16x16x32_bf16 v[12:15], v[72:75], v[204:207], v[12:15]
	v_mfma_f32_16x16x32_bf16 v[4:7], v[76:79], v[204:207], v[4:7]
	ds_read_b128 v[184:187], v210 offset:61440
	s_add_u32 m0, s38, 28672
	s_nop 0
	global_load_lds_dwordx4 v215, s[100:101]
	s_add_u32 s100, s100, 128
	s_addc_u32 s101, s101, 0
	s_waitcnt lgkmcnt(6)
	v_mfma_f32_16x16x32_bf16 v[40:43], v[64:67], v[160:163], v[40:43]
	v_mfma_f32_16x16x32_bf16 v[52:55], v[68:71], v[160:163], v[52:55]
	ds_read_b128 v[188:191], v210 offset:63488
	s_waitcnt lgkmcnt(6)
	v_mfma_f32_16x16x32_bf16 v[28:31], v[64:67], v[164:167], v[28:31]
	v_mfma_f32_16x16x32_bf16 v[16:19], v[68:71], v[164:167], v[16:19]
	ds_read_b128 v[72:75], v209 offset:32768
	ds_read_b128 v[76:79], v209 offset:34816
	ds_read_b128 v[192:195], v211 offset:49152
	s_waitcnt lgkmcnt(8)
	v_mfma_f32_16x16x32_bf16 v[60:63], v[64:67], v[168:171], v[60:63]
	v_mfma_f32_16x16x32_bf16 v[48:51], v[68:71], v[168:171], v[48:51]
	ds_read_b128 v[196:199], v211 offset:51200
	s_waitcnt lgkmcnt(8)
	v_mfma_f32_16x16x32_bf16 v[20:23], v[64:67], v[172:175], v[20:23]
	v_mfma_f32_16x16x32_bf16 v[0:3], v[68:71], v[172:175], v[0:3]
	ds_read_b128 v[200:203], v211 offset:53248
	s_waitcnt lgkmcnt(8)
	v_mfma_f32_16x16x32_bf16 v[44:47], v[64:67], v[176:179], v[44:47]
	v_mfma_f32_16x16x32_bf16 v[36:39], v[68:71], v[176:179], v[36:39]
	ds_read_b128 v[204:207], v211 offset:55296
	s_waitcnt lgkmcnt(8)
	v_mfma_f32_16x16x32_bf16 v[24:27], v[64:67], v[180:183], v[24:27]
	v_mfma_f32_16x16x32_bf16 v[8:11], v[68:71], v[180:183], v[8:11]
	ds_read_b128 v[160:163], v211 offset:57344
	s_waitcnt lgkmcnt(8)
	v_mfma_f32_16x16x32_bf16 v[56:59], v[64:67], v[184:187], v[56:59]
	v_mfma_f32_16x16x32_bf16 v[32:35], v[68:71], v[184:187], v[32:35]
	ds_read_b128 v[164:167], v211 offset:59392
	s_waitcnt lgkmcnt(8)
	v_mfma_f32_16x16x32_bf16 v[12:15], v[64:67], v[188:191], v[12:15]
	v_mfma_f32_16x16x32_bf16 v[4:7], v[68:71], v[188:191], v[4:7]
	ds_read_b128 v[168:171], v211 offset:61440
	s_waitcnt lgkmcnt(6)
	v_mfma_f32_16x16x32_bf16 v[40:43], v[72:75], v[192:195], v[40:43]
	v_mfma_f32_16x16x32_bf16 v[52:55], v[76:79], v[192:195], v[52:55]
	ds_read_b128 v[172:175], v211 offset:63488
	s_waitcnt vmcnt(0) lgkmcnt(0)
	s_barrier
	s_add_u32 m0, s38, 32768
	s_nop 0
	global_load_lds_dwordx4 v212, s[98:99]
	s_waitcnt lgkmcnt(6)
	v_mfma_f32_16x16x32_bf16 v[28:31], v[72:75], v[196:199], v[28:31]
	v_mfma_f32_16x16x32_bf16 v[16:19], v[76:79], v[196:199], v[16:19]
	ds_read_b128 v[64:67], v208 offset:0
	ds_read_b128 v[68:71], v208 offset:2048
	ds_read_b128 v[176:179], v210 offset:16384
	s_add_u32 m0, s38, 36864
	s_nop 0
	global_load_lds_dwordx4 v213, s[98:99]
	s_waitcnt lgkmcnt(8)
	v_mfma_f32_16x16x32_bf16 v[60:63], v[72:75], v[200:203], v[60:63]
	v_mfma_f32_16x16x32_bf16 v[48:51], v[76:79], v[200:203], v[48:51]
	ds_read_b128 v[180:183], v210 offset:18432
	s_add_u32 m0, s38, 40960
	s_nop 0
	global_load_lds_dwordx4 v214, s[98:99]
	s_waitcnt lgkmcnt(8)
	v_mfma_f32_16x16x32_bf16 v[20:23], v[72:75], v[204:207], v[20:23]
	v_mfma_f32_16x16x32_bf16 v[0:3], v[76:79], v[204:207], v[0:3]
	ds_read_b128 v[184:187], v210 offset:20480
	s_add_u32 m0, s38, 45056
	s_nop 0
	global_load_lds_dwordx4 v215, s[98:99]
	s_add_u32 s98, s98, 128
	s_addc_u32 s99, s99, 0
	s_waitcnt lgkmcnt(8)
	v_mfma_f32_16x16x32_bf16 v[44:47], v[72:75], v[160:163], v[44:47]
	v_mfma_f32_16x16x32_bf16 v[36:39], v[76:79], v[160:163], v[36:39]
	ds_read_b128 v[188:191], v210 offset:22528
	s_add_u32 m0, s38, 49152
	s_nop 0
	global_load_lds_dwordx4 v212, s[100:101]
	s_waitcnt lgkmcnt(8)
	v_mfma_f32_16x16x32_bf16 v[24:27], v[72:75], v[164:167], v[24:27]
	v_mfma_f32_16x16x32_bf16 v[8:11], v[76:79], v[164:167], v[8:11]
	ds_read_b128 v[192:195], v210 offset:24576
	s_add_u32 m0, s38, 53248
	s_nop 0
	global_load_lds_dwordx4 v213, s[100:101]
	s_waitcnt lgkmcnt(8)
	v_mfma_f32_16x16x32_bf16 v[56:59], v[72:75], v[168:171], v[56:59]
	v_mfma_f32_16x16x32_bf16 v[32:35], v[76:79], v[168:171], v[32:35]
	ds_read_b128 v[196:199], v210 offset:26624
	s_add_u32 m0, s38, 57344
	s_nop 0
	global_load_lds_dwordx4 v214, s[100:101]
	s_waitcnt lgkmcnt(8)
	v_mfma_f32_16x16x32_bf16 v[12:15], v[72:75], v[172:175], v[12:15]
	v_mfma_f32_16x16x32_bf16 v[4:7], v[76:79], v[172:175], v[4:7]
	ds_read_b128 v[200:203], v210 offset:28672
	s_add_u32 m0, s38, 61440
	s_nop 0
	global_load_lds_dwordx4 v215, s[100:101]
	s_add_u32 s100, s100, 128
	s_addc_u32 s101, s101, 0
	s_waitcnt lgkmcnt(6)
	v_mfma_f32_16x16x32_bf16 v[40:43], v[64:67], v[176:179], v[40:43]
	v_mfma_f32_16x16x32_bf16 v[52:55], v[68:71], v[176:179], v[52:55]
	ds_read_b128 v[204:207], v210 offset:30720
	s_waitcnt lgkmcnt(6)
	v_mfma_f32_16x16x32_bf16 v[28:31], v[64:67], v[180:183], v[28:31]
	v_mfma_f32_16x16x32_bf16 v[16:19], v[68:71], v[180:183], v[16:19]
	ds_read_b128 v[72:75], v209 offset:0
	ds_read_b128 v[76:79], v209 offset:2048
	ds_read_b128 v[160:163], v211 offset:16384
	s_waitcnt lgkmcnt(8)
	v_mfma_f32_16x16x32_bf16 v[60:63], v[64:67], v[184:187], v[60:63]
	v_mfma_f32_16x16x32_bf16 v[48:51], v[68:71], v[184:187], v[48:51]
	ds_read_b128 v[164:167], v211 offset:18432
	s_waitcnt lgkmcnt(8)
	v_mfma_f32_16x16x32_bf16 v[20:23], v[64:67], v[188:191], v[20:23]
	v_mfma_f32_16x16x32_bf16 v[0:3], v[68:71], v[188:191], v[0:3]
	ds_read_b128 v[168:171], v211 offset:20480
	s_waitcnt lgkmcnt(8)
	v_mfma_f32_16x16x32_bf16 v[44:47], v[64:67], v[192:195], v[44:47]
	v_mfma_f32_16x16x32_bf16 v[36:39], v[68:71], v[192:195], v[36:39]
	ds_read_b128 v[172:175], v211 offset:22528
	s_waitcnt lgkmcnt(8)
	v_mfma_f32_16x16x32_bf16 v[24:27], v[64:67], v[196:199], v[24:27]
	v_mfma_f32_16x16x32_bf16 v[8:11], v[68:71], v[196:199], v[8:11]
	ds_read_b128 v[176:179], v211 offset:24576
	s_waitcnt lgkmcnt(8)
	v_mfma_f32_16x16x32_bf16 v[56:59], v[64:67], v[200:203], v[56:59]
	v_mfma_f32_16x16x32_bf16 v[32:35], v[68:71], v[200:203], v[32:35]
	ds_read_b128 v[180:183], v211 offset:26624
	s_waitcnt lgkmcnt(8)
	v_mfma_f32_16x16x32_bf16 v[12:15], v[64:67], v[204:207], v[12:15]
	v_mfma_f32_16x16x32_bf16 v[4:7], v[68:71], v[204:207], v[4:7]
	ds_read_b128 v[184:187], v211 offset:28672
	s_waitcnt lgkmcnt(6)
	v_mfma_f32_16x16x32_bf16 v[40:43], v[72:75], v[160:163], v[40:43]
	v_mfma_f32_16x16x32_bf16 v[52:55], v[76:79], v[160:163], v[52:55]
	ds_read_b128 v[188:191], v211 offset:30720
	s_waitcnt vmcnt(0) lgkmcnt(0)
	s_barrier
	s_add_u32 m0, s38, 0
	s_nop 0
	global_load_lds_dwordx4 v212, s[98:99]
	s_waitcnt lgkmcnt(6)
	v_mfma_f32_16x16x32_bf16 v[28:31], v[72:75], v[164:167], v[28:31]
	v_mfma_f32_16x16x32_bf16 v[16:19], v[76:79], v[164:167], v[16:19]
	ds_read_b128 v[64:67], v208 offset:32768
	ds_read_b128 v[68:71], v208 offset:34816
	ds_read_b128 v[192:195], v210 offset:49152
	s_add_u32 m0, s38, 4096
	s_nop 0
	global_load_lds_dwordx4 v213, s[98:99]
	s_waitcnt lgkmcnt(8)
	v_mfma_f32_16x16x32_bf16 v[60:63], v[72:75], v[168:171], v[60:63]
	v_mfma_f32_16x16x32_bf16 v[48:51], v[76:79], v[168:171], v[48:51]
	ds_read_b128 v[196:199], v210 offset:51200
	s_add_u32 m0, s38, 8192
	s_nop 0
	global_load_lds_dwordx4 v214, s[98:99]
	s_waitcnt lgkmcnt(8)
	v_mfma_f32_16x16x32_bf16 v[20:23], v[72:75], v[172:175], v[20:23]
	v_mfma_f32_16x16x32_bf16 v[0:3], v[76:79], v[172:175], v[0:3]
	ds_read_b128 v[200:203], v210 offset:53248
	s_add_u32 m0, s38, 12288
	s_nop 0
	global_load_lds_dwordx4 v215, s[98:99]
	s_add_u32 s98, s98, 128
	s_addc_u32 s99, s99, 0
	s_waitcnt lgkmcnt(8)
	v_mfma_f32_16x16x32_bf16 v[44:47], v[72:75], v[176:179], v[44:47]
	v_mfma_f32_16x16x32_bf16 v[36:39], v[76:79], v[176:179], v[36:39]
	ds_read_b128 v[204:207], v210 offset:55296
	s_add_u32 m0, s38, 16384
	s_nop 0
	global_load_lds_dwordx4 v212, s[100:101]
	s_waitcnt lgkmcnt(8)
	v_mfma_f32_16x16x32_bf16 v[24:27], v[72:75], v[180:183], v[24:27]
	v_mfma_f32_16x16x32_bf16 v[8:11], v[76:79], v[180:183], v[8:11]
	ds_read_b128 v[160:163], v210 offset:57344
	s_add_u32 m0, s38, 20480
	s_nop 0
	global_load_lds_dwordx4 v213, s[100:101]
	s_waitcnt lgkmcnt(8)
	v_mfma_f32_16x16x32_bf16 v[56:59], v[72:75], v[184:187], v[56:59]
	v_mfma_f32_16x16x32_bf16 v[32:35], v[76:79], v[184:187], v[32:35]
	ds_read_b128 v[164:167], v210 offset:59392
	s_add_u32 m0, s38, 24576
	s_nop 0
	global_load_lds_dwordx4 v214, s[100:101]
	s_waitcnt lgkmcnt(8)
	v_mfma_f32_16x16x32_bf16 v[12:15], v[72:75], v[188:191], v[12:15]
	v_mfma_f32_16x16x32_bf16 v[4:7], v[76:79], v[188:191], v[4:7]
	ds_read_b128 v[168:171], v210 offset:61440
	s_add_u32 m0, s38, 28672
	s_nop 0
	global_load_lds_dwordx4 v215, s[100:101]
	s_add_u32 s100, s100, 128
	s_addc_u32 s101, s101, 0
	s_waitcnt lgkmcnt(6)
	v_mfma_f32_16x16x32_bf16 v[40:43], v[64:67], v[192:195], v[40:43]
	v_mfma_f32_16x16x32_bf16 v[52:55], v[68:71], v[192:195], v[52:55]
	ds_read_b128 v[172:175], v210 offset:63488
	s_waitcnt lgkmcnt(6)
	v_mfma_f32_16x16x32_bf16 v[28:31], v[64:67], v[196:199], v[28:31]
	v_mfma_f32_16x16x32_bf16 v[16:19], v[68:71], v[196:199], v[16:19]
	ds_read_b128 v[72:75], v209 offset:32768
	ds_read_b128 v[76:79], v209 offset:34816
	ds_read_b128 v[176:179], v211 offset:49152
	s_waitcnt lgkmcnt(8)
	v_mfma_f32_16x16x32_bf16 v[60:63], v[64:67], v[200:203], v[60:63]
	v_mfma_f32_16x16x32_bf16 v[48:51], v[68:71], v[200:203], v[48:51]
	ds_read_b128 v[180:183], v211 offset:51200
	s_waitcnt lgkmcnt(8)
	v_mfma_f32_16x16x32_bf16 v[20:23], v[64:67], v[204:207], v[20:23]
	v_mfma_f32_16x16x32_bf16 v[0:3], v[68:71], v[204:207], v[0:3]
	ds_read_b128 v[184:187], v211 offset:53248
	s_waitcnt lgkmcnt(8)
	v_mfma_f32_16x16x32_bf16 v[44:47], v[64:67], v[160:163], v[44:47]
	v_mfma_f32_16x16x32_bf16 v[36:39], v[68:71], v[160:163], v[36:39]
	ds_read_b128 v[188:191], v211 offset:55296
	s_waitcnt lgkmcnt(8)
	v_mfma_f32_16x16x32_bf16 v[24:27], v[64:67], v[164:167], v[24:27]
	v_mfma_f32_16x16x32_bf16 v[8:11], v[68:71], v[164:167], v[8:11]
	ds_read_b128 v[192:195], v211 offset:57344
	s_waitcnt lgkmcnt(8)
	v_mfma_f32_16x16x32_bf16 v[56:59], v[64:67], v[168:171], v[56:59]
	v_mfma_f32_16x16x32_bf16 v[32:35], v[68:71], v[168:171], v[32:35]
	ds_read_b128 v[196:199], v211 offset:59392
	s_waitcnt lgkmcnt(8)
	v_mfma_f32_16x16x32_bf16 v[12:15], v[64:67], v[172:175], v[12:15]
	v_mfma_f32_16x16x32_bf16 v[4:7], v[68:71], v[172:175], v[4:7]
	ds_read_b128 v[200:203], v211 offset:61440
	s_waitcnt lgkmcnt(6)
	v_mfma_f32_16x16x32_bf16 v[40:43], v[72:75], v[176:179], v[40:43]
	v_mfma_f32_16x16x32_bf16 v[52:55], v[76:79], v[176:179], v[52:55]
	ds_read_b128 v[204:207], v211 offset:63488
	s_waitcnt vmcnt(0) lgkmcnt(0)
	s_barrier
	s_add_u32 m0, s38, 32768
	s_nop 0
	global_load_lds_dwordx4 v212, s[98:99]
	s_waitcnt lgkmcnt(6)
	v_mfma_f32_16x16x32_bf16 v[28:31], v[72:75], v[180:183], v[28:31]
	v_mfma_f32_16x16x32_bf16 v[16:19], v[76:79], v[180:183], v[16:19]
	ds_read_b128 v[64:67], v208 offset:0
	ds_read_b128 v[68:71], v208 offset:2048
	ds_read_b128 v[160:163], v210 offset:16384
	s_add_u32 m0, s38, 36864
	s_nop 0
	global_load_lds_dwordx4 v213, s[98:99]
	s_waitcnt lgkmcnt(8)
	v_mfma_f32_16x16x32_bf16 v[60:63], v[72:75], v[184:187], v[60:63]
	v_mfma_f32_16x16x32_bf16 v[48:51], v[76:79], v[184:187], v[48:51]
	ds_read_b128 v[164:167], v210 offset:18432
	s_add_u32 m0, s38, 40960
	s_nop 0
	global_load_lds_dwordx4 v214, s[98:99]
	s_waitcnt lgkmcnt(8)
	v_mfma_f32_16x16x32_bf16 v[20:23], v[72:75], v[188:191], v[20:23]
	v_mfma_f32_16x16x32_bf16 v[0:3], v[76:79], v[188:191], v[0:3]
	ds_read_b128 v[168:171], v210 offset:20480
	s_add_u32 m0, s38, 45056
	s_nop 0
	global_load_lds_dwordx4 v215, s[98:99]
	s_add_u32 s98, s98, 128
	s_addc_u32 s99, s99, 0
	s_waitcnt lgkmcnt(8)
	v_mfma_f32_16x16x32_bf16 v[44:47], v[72:75], v[192:195], v[44:47]
	v_mfma_f32_16x16x32_bf16 v[36:39], v[76:79], v[192:195], v[36:39]
	ds_read_b128 v[172:175], v210 offset:22528
	s_add_u32 m0, s38, 49152
	s_nop 0
	global_load_lds_dwordx4 v212, s[100:101]
	s_waitcnt lgkmcnt(8)
	v_mfma_f32_16x16x32_bf16 v[24:27], v[72:75], v[196:199], v[24:27]
	v_mfma_f32_16x16x32_bf16 v[8:11], v[76:79], v[196:199], v[8:11]
	ds_read_b128 v[176:179], v210 offset:24576
	s_add_u32 m0, s38, 53248
	s_nop 0
	global_load_lds_dwordx4 v213, s[100:101]
	s_waitcnt lgkmcnt(8)
	v_mfma_f32_16x16x32_bf16 v[56:59], v[72:75], v[200:203], v[56:59]
	v_mfma_f32_16x16x32_bf16 v[32:35], v[76:79], v[200:203], v[32:35]
	ds_read_b128 v[180:183], v210 offset:26624
	s_add_u32 m0, s38, 57344
	s_nop 0
	global_load_lds_dwordx4 v214, s[100:101]
	s_waitcnt lgkmcnt(8)
	v_mfma_f32_16x16x32_bf16 v[12:15], v[72:75], v[204:207], v[12:15]
	v_mfma_f32_16x16x32_bf16 v[4:7], v[76:79], v[204:207], v[4:7]
	ds_read_b128 v[184:187], v210 offset:28672
	s_add_u32 m0, s38, 61440
	s_nop 0
	global_load_lds_dwordx4 v215, s[100:101]
	s_add_u32 s100, s100, 128
	s_addc_u32 s101, s101, 0
	s_waitcnt lgkmcnt(6)
	v_mfma_f32_16x16x32_bf16 v[40:43], v[64:67], v[160:163], v[40:43]
	v_mfma_f32_16x16x32_bf16 v[52:55], v[68:71], v[160:163], v[52:55]
	ds_read_b128 v[188:191], v210 offset:30720
	s_waitcnt lgkmcnt(6)
	v_mfma_f32_16x16x32_bf16 v[28:31], v[64:67], v[164:167], v[28:31]
	v_mfma_f32_16x16x32_bf16 v[16:19], v[68:71], v[164:167], v[16:19]
	ds_read_b128 v[72:75], v209 offset:0
	ds_read_b128 v[76:79], v209 offset:2048
	ds_read_b128 v[192:195], v211 offset:16384
	s_waitcnt lgkmcnt(8)
	v_mfma_f32_16x16x32_bf16 v[60:63], v[64:67], v[168:171], v[60:63]
	v_mfma_f32_16x16x32_bf16 v[48:51], v[68:71], v[168:171], v[48:51]
	ds_read_b128 v[196:199], v211 offset:18432
	s_waitcnt lgkmcnt(8)
	v_mfma_f32_16x16x32_bf16 v[20:23], v[64:67], v[172:175], v[20:23]
	v_mfma_f32_16x16x32_bf16 v[0:3], v[68:71], v[172:175], v[0:3]
	ds_read_b128 v[200:203], v211 offset:20480
	s_waitcnt lgkmcnt(8)
	v_mfma_f32_16x16x32_bf16 v[44:47], v[64:67], v[176:179], v[44:47]
	v_mfma_f32_16x16x32_bf16 v[36:39], v[68:71], v[176:179], v[36:39]
	ds_read_b128 v[204:207], v211 offset:22528
	s_waitcnt lgkmcnt(8)
	v_mfma_f32_16x16x32_bf16 v[24:27], v[64:67], v[180:183], v[24:27]
	v_mfma_f32_16x16x32_bf16 v[8:11], v[68:71], v[180:183], v[8:11]
	ds_read_b128 v[160:163], v211 offset:24576
	s_waitcnt lgkmcnt(8)
	v_mfma_f32_16x16x32_bf16 v[56:59], v[64:67], v[184:187], v[56:59]
	v_mfma_f32_16x16x32_bf16 v[32:35], v[68:71], v[184:187], v[32:35]
	ds_read_b128 v[164:167], v211 offset:26624
	s_waitcnt lgkmcnt(8)
	v_mfma_f32_16x16x32_bf16 v[12:15], v[64:67], v[188:191], v[12:15]
	v_mfma_f32_16x16x32_bf16 v[4:7], v[68:71], v[188:191], v[4:7]
	ds_read_b128 v[168:171], v211 offset:28672
	s_waitcnt lgkmcnt(6)
	v_mfma_f32_16x16x32_bf16 v[40:43], v[72:75], v[192:195], v[40:43]
	v_mfma_f32_16x16x32_bf16 v[52:55], v[76:79], v[192:195], v[52:55]
	ds_read_b128 v[172:175], v211 offset:30720
	s_waitcnt vmcnt(0) lgkmcnt(0)
	s_barrier
	s_add_u32 m0, s38, 0
	s_nop 0
	global_load_lds_dwordx4 v212, s[98:99]
	s_waitcnt lgkmcnt(6)
	v_mfma_f32_16x16x32_bf16 v[28:31], v[72:75], v[196:199], v[28:31]
	v_mfma_f32_16x16x32_bf16 v[16:19], v[76:79], v[196:199], v[16:19]
	ds_read_b128 v[64:67], v208 offset:32768
	ds_read_b128 v[68:71], v208 offset:34816
	ds_read_b128 v[176:179], v210 offset:49152
	s_add_u32 m0, s38, 4096
	s_nop 0
	global_load_lds_dwordx4 v213, s[98:99]
	s_waitcnt lgkmcnt(8)
	v_mfma_f32_16x16x32_bf16 v[60:63], v[72:75], v[200:203], v[60:63]
	v_mfma_f32_16x16x32_bf16 v[48:51], v[76:79], v[200:203], v[48:51]
	ds_read_b128 v[180:183], v210 offset:51200
	s_add_u32 m0, s38, 8192
	s_nop 0
	global_load_lds_dwordx4 v214, s[98:99]
	s_waitcnt lgkmcnt(8)
	v_mfma_f32_16x16x32_bf16 v[20:23], v[72:75], v[204:207], v[20:23]
	v_mfma_f32_16x16x32_bf16 v[0:3], v[76:79], v[204:207], v[0:3]
	ds_read_b128 v[184:187], v210 offset:53248
	s_add_u32 m0, s38, 12288
	s_nop 0
	global_load_lds_dwordx4 v215, s[98:99]
	s_add_u32 s98, s98, 128
	s_addc_u32 s99, s99, 0
	s_waitcnt lgkmcnt(8)
	v_mfma_f32_16x16x32_bf16 v[44:47], v[72:75], v[160:163], v[44:47]
	v_mfma_f32_16x16x32_bf16 v[36:39], v[76:79], v[160:163], v[36:39]
	ds_read_b128 v[188:191], v210 offset:55296
	s_add_u32 m0, s38, 16384
	s_nop 0
	global_load_lds_dwordx4 v212, s[100:101]
	s_waitcnt lgkmcnt(8)
	v_mfma_f32_16x16x32_bf16 v[24:27], v[72:75], v[164:167], v[24:27]
	v_mfma_f32_16x16x32_bf16 v[8:11], v[76:79], v[164:167], v[8:11]
	ds_read_b128 v[192:195], v210 offset:57344
	s_add_u32 m0, s38, 20480
	s_nop 0
	global_load_lds_dwordx4 v213, s[100:101]
	s_waitcnt lgkmcnt(8)
	v_mfma_f32_16x16x32_bf16 v[56:59], v[72:75], v[168:171], v[56:59]
	v_mfma_f32_16x16x32_bf16 v[32:35], v[76:79], v[168:171], v[32:35]
	ds_read_b128 v[196:199], v210 offset:59392
	s_add_u32 m0, s38, 24576
	s_nop 0
	global_load_lds_dwordx4 v214, s[100:101]
	s_waitcnt lgkmcnt(8)
	v_mfma_f32_16x16x32_bf16 v[12:15], v[72:75], v[172:175], v[12:15]
	v_mfma_f32_16x16x32_bf16 v[4:7], v[76:79], v[172:175], v[4:7]
	ds_read_b128 v[200:203], v210 offset:61440
	s_add_u32 m0, s38, 28672
	s_nop 0
	global_load_lds_dwordx4 v215, s[100:101]
	s_add_u32 s100, s100, 128
	s_addc_u32 s101, s101, 0
	s_waitcnt lgkmcnt(6)
	v_mfma_f32_16x16x32_bf16 v[40:43], v[64:67], v[176:179], v[40:43]
	v_mfma_f32_16x16x32_bf16 v[52:55], v[68:71], v[176:179], v[52:55]
	ds_read_b128 v[204:207], v210 offset:63488
	s_waitcnt lgkmcnt(6)
	v_mfma_f32_16x16x32_bf16 v[28:31], v[64:67], v[180:183], v[28:31]
	v_mfma_f32_16x16x32_bf16 v[16:19], v[68:71], v[180:183], v[16:19]
	ds_read_b128 v[72:75], v209 offset:32768
	ds_read_b128 v[76:79], v209 offset:34816
	ds_read_b128 v[160:163], v211 offset:49152
	s_waitcnt lgkmcnt(8)
	v_mfma_f32_16x16x32_bf16 v[60:63], v[64:67], v[184:187], v[60:63]
	v_mfma_f32_16x16x32_bf16 v[48:51], v[68:71], v[184:187], v[48:51]
	ds_read_b128 v[164:167], v211 offset:51200
	s_waitcnt lgkmcnt(8)
	v_mfma_f32_16x16x32_bf16 v[20:23], v[64:67], v[188:191], v[20:23]
	v_mfma_f32_16x16x32_bf16 v[0:3], v[68:71], v[188:191], v[0:3]
	ds_read_b128 v[168:171], v211 offset:53248
	s_waitcnt lgkmcnt(8)
	v_mfma_f32_16x16x32_bf16 v[44:47], v[64:67], v[192:195], v[44:47]
	v_mfma_f32_16x16x32_bf16 v[36:39], v[68:71], v[192:195], v[36:39]
	ds_read_b128 v[172:175], v211 offset:55296
	s_waitcnt lgkmcnt(8)
	v_mfma_f32_16x16x32_bf16 v[24:27], v[64:67], v[196:199], v[24:27]
	v_mfma_f32_16x16x32_bf16 v[8:11], v[68:71], v[196:199], v[8:11]
	ds_read_b128 v[176:179], v211 offset:57344
	s_waitcnt lgkmcnt(8)
	v_mfma_f32_16x16x32_bf16 v[56:59], v[64:67], v[200:203], v[56:59]
	v_mfma_f32_16x16x32_bf16 v[32:35], v[68:71], v[200:203], v[32:35]
	ds_read_b128 v[180:183], v211 offset:59392
	s_waitcnt lgkmcnt(8)
	v_mfma_f32_16x16x32_bf16 v[12:15], v[64:67], v[204:207], v[12:15]
	v_mfma_f32_16x16x32_bf16 v[4:7], v[68:71], v[204:207], v[4:7]
	ds_read_b128 v[184:187], v211 offset:61440
	s_waitcnt lgkmcnt(6)
	v_mfma_f32_16x16x32_bf16 v[40:43], v[72:75], v[160:163], v[40:43]
	v_mfma_f32_16x16x32_bf16 v[52:55], v[76:79], v[160:163], v[52:55]
	ds_read_b128 v[188:191], v211 offset:63488
	s_waitcnt vmcnt(0) lgkmcnt(0)
	s_barrier
	s_add_u32 m0, s38, 32768
	s_nop 0
	global_load_lds_dwordx4 v212, s[98:99]
	s_waitcnt lgkmcnt(6)
	v_mfma_f32_16x16x32_bf16 v[28:31], v[72:75], v[164:167], v[28:31]
	v_mfma_f32_16x16x32_bf16 v[16:19], v[76:79], v[164:167], v[16:19]
	ds_read_b128 v[64:67], v208 offset:0
	ds_read_b128 v[68:71], v208 offset:2048
	ds_read_b128 v[192:195], v210 offset:16384
	s_add_u32 m0, s38, 36864
	s_nop 0
	global_load_lds_dwordx4 v213, s[98:99]
	s_waitcnt lgkmcnt(8)
	v_mfma_f32_16x16x32_bf16 v[60:63], v[72:75], v[168:171], v[60:63]
	v_mfma_f32_16x16x32_bf16 v[48:51], v[76:79], v[168:171], v[48:51]
	ds_read_b128 v[196:199], v210 offset:18432
	s_add_u32 m0, s38, 40960
	s_nop 0
	global_load_lds_dwordx4 v214, s[98:99]
	s_waitcnt lgkmcnt(8)
	v_mfma_f32_16x16x32_bf16 v[20:23], v[72:75], v[172:175], v[20:23]
	v_mfma_f32_16x16x32_bf16 v[0:3], v[76:79], v[172:175], v[0:3]
	ds_read_b128 v[200:203], v210 offset:20480
	s_add_u32 m0, s38, 45056
	s_nop 0
	global_load_lds_dwordx4 v215, s[98:99]
	s_add_u32 s98, s98, 128
	s_addc_u32 s99, s99, 0
	s_waitcnt lgkmcnt(8)
	v_mfma_f32_16x16x32_bf16 v[44:47], v[72:75], v[176:179], v[44:47]
	v_mfma_f32_16x16x32_bf16 v[36:39], v[76:79], v[176:179], v[36:39]
	ds_read_b128 v[204:207], v210 offset:22528
	s_add_u32 m0, s38, 49152
	s_nop 0
	global_load_lds_dwordx4 v212, s[100:101]
	s_waitcnt lgkmcnt(8)
	v_mfma_f32_16x16x32_bf16 v[24:27], v[72:75], v[180:183], v[24:27]
	v_mfma_f32_16x16x32_bf16 v[8:11], v[76:79], v[180:183], v[8:11]
	ds_read_b128 v[160:163], v210 offset:24576
	s_add_u32 m0, s38, 53248
	s_nop 0
	global_load_lds_dwordx4 v213, s[100:101]
	s_waitcnt lgkmcnt(8)
	v_mfma_f32_16x16x32_bf16 v[56:59], v[72:75], v[184:187], v[56:59]
	v_mfma_f32_16x16x32_bf16 v[32:35], v[76:79], v[184:187], v[32:35]
	ds_read_b128 v[164:167], v210 offset:26624
	s_add_u32 m0, s38, 57344
	s_nop 0
	global_load_lds_dwordx4 v214, s[100:101]
	s_waitcnt lgkmcnt(8)
	v_mfma_f32_16x16x32_bf16 v[12:15], v[72:75], v[188:191], v[12:15]
	v_mfma_f32_16x16x32_bf16 v[4:7], v[76:79], v[188:191], v[4:7]
	ds_read_b128 v[168:171], v210 offset:28672
	s_add_u32 m0, s38, 61440
	s_nop 0
	global_load_lds_dwordx4 v215, s[100:101]
	s_add_u32 s100, s100, 128
	s_addc_u32 s101, s101, 0
	s_waitcnt lgkmcnt(6)
	v_mfma_f32_16x16x32_bf16 v[40:43], v[64:67], v[192:195], v[40:43]
	v_mfma_f32_16x16x32_bf16 v[52:55], v[68:71], v[192:195], v[52:55]
	ds_read_b128 v[172:175], v210 offset:30720
	s_waitcnt lgkmcnt(6)
	v_mfma_f32_16x16x32_bf16 v[28:31], v[64:67], v[196:199], v[28:31]
	v_mfma_f32_16x16x32_bf16 v[16:19], v[68:71], v[196:199], v[16:19]
	ds_read_b128 v[72:75], v209 offset:0
	ds_read_b128 v[76:79], v209 offset:2048
	ds_read_b128 v[176:179], v211 offset:16384
	s_waitcnt lgkmcnt(8)
	v_mfma_f32_16x16x32_bf16 v[60:63], v[64:67], v[200:203], v[60:63]
	v_mfma_f32_16x16x32_bf16 v[48:51], v[68:71], v[200:203], v[48:51]
	ds_read_b128 v[180:183], v211 offset:18432
	s_waitcnt lgkmcnt(8)
	v_mfma_f32_16x16x32_bf16 v[20:23], v[64:67], v[204:207], v[20:23]
	v_mfma_f32_16x16x32_bf16 v[0:3], v[68:71], v[204:207], v[0:3]
	ds_read_b128 v[184:187], v211 offset:20480
	s_waitcnt lgkmcnt(8)
	v_mfma_f32_16x16x32_bf16 v[44:47], v[64:67], v[160:163], v[44:47]
	v_mfma_f32_16x16x32_bf16 v[36:39], v[68:71], v[160:163], v[36:39]
	ds_read_b128 v[188:191], v211 offset:22528
	s_waitcnt lgkmcnt(8)
	v_mfma_f32_16x16x32_bf16 v[24:27], v[64:67], v[164:167], v[24:27]
	v_mfma_f32_16x16x32_bf16 v[8:11], v[68:71], v[164:167], v[8:11]
	ds_read_b128 v[192:195], v211 offset:24576
	s_waitcnt lgkmcnt(8)
	v_mfma_f32_16x16x32_bf16 v[56:59], v[64:67], v[168:171], v[56:59]
	v_mfma_f32_16x16x32_bf16 v[32:35], v[68:71], v[168:171], v[32:35]
	ds_read_b128 v[196:199], v211 offset:26624
	s_waitcnt lgkmcnt(8)
	v_mfma_f32_16x16x32_bf16 v[12:15], v[64:67], v[172:175], v[12:15]
	v_mfma_f32_16x16x32_bf16 v[4:7], v[68:71], v[172:175], v[4:7]
	ds_read_b128 v[200:203], v211 offset:28672
	s_waitcnt lgkmcnt(6)
	v_mfma_f32_16x16x32_bf16 v[40:43], v[72:75], v[176:179], v[40:43]
	v_mfma_f32_16x16x32_bf16 v[52:55], v[76:79], v[176:179], v[52:55]
	ds_read_b128 v[204:207], v211 offset:30720
	s_waitcnt vmcnt(0) lgkmcnt(0)
	s_barrier
	s_add_u32 m0, s38, 0
	s_nop 0
	global_load_lds_dwordx4 v212, s[98:99]
	s_waitcnt lgkmcnt(6)
	v_mfma_f32_16x16x32_bf16 v[28:31], v[72:75], v[180:183], v[28:31]
	v_mfma_f32_16x16x32_bf16 v[16:19], v[76:79], v[180:183], v[16:19]
	ds_read_b128 v[64:67], v208 offset:32768
	ds_read_b128 v[68:71], v208 offset:34816
	ds_read_b128 v[160:163], v210 offset:49152
	s_add_u32 m0, s38, 4096
	s_nop 0
	global_load_lds_dwordx4 v213, s[98:99]
	s_waitcnt lgkmcnt(8)
	v_mfma_f32_16x16x32_bf16 v[60:63], v[72:75], v[184:187], v[60:63]
	v_mfma_f32_16x16x32_bf16 v[48:51], v[76:79], v[184:187], v[48:51]
	ds_read_b128 v[164:167], v210 offset:51200
	s_add_u32 m0, s38, 8192
	s_nop 0
	global_load_lds_dwordx4 v214, s[98:99]
	s_waitcnt lgkmcnt(8)
	v_mfma_f32_16x16x32_bf16 v[20:23], v[72:75], v[188:191], v[20:23]
	v_mfma_f32_16x16x32_bf16 v[0:3], v[76:79], v[188:191], v[0:3]
	ds_read_b128 v[168:171], v210 offset:53248
	s_add_u32 m0, s38, 12288
	s_nop 0
	global_load_lds_dwordx4 v215, s[98:99]
	s_add_u32 s98, s98, 128
	s_addc_u32 s99, s99, 0
	s_waitcnt lgkmcnt(8)
	v_mfma_f32_16x16x32_bf16 v[44:47], v[72:75], v[192:195], v[44:47]
	v_mfma_f32_16x16x32_bf16 v[36:39], v[76:79], v[192:195], v[36:39]
	ds_read_b128 v[172:175], v210 offset:55296
	s_add_u32 m0, s38, 16384
	s_nop 0
	global_load_lds_dwordx4 v212, s[100:101]
	s_waitcnt lgkmcnt(8)
	v_mfma_f32_16x16x32_bf16 v[24:27], v[72:75], v[196:199], v[24:27]
	v_mfma_f32_16x16x32_bf16 v[8:11], v[76:79], v[196:199], v[8:11]
	ds_read_b128 v[176:179], v210 offset:57344
	s_add_u32 m0, s38, 20480
	s_nop 0
	global_load_lds_dwordx4 v213, s[100:101]
	s_waitcnt lgkmcnt(8)
	v_mfma_f32_16x16x32_bf16 v[56:59], v[72:75], v[200:203], v[56:59]
	v_mfma_f32_16x16x32_bf16 v[32:35], v[76:79], v[200:203], v[32:35]
	ds_read_b128 v[180:183], v210 offset:59392
	s_add_u32 m0, s38, 24576
	s_nop 0
	global_load_lds_dwordx4 v214, s[100:101]
	s_waitcnt lgkmcnt(8)
	v_mfma_f32_16x16x32_bf16 v[12:15], v[72:75], v[204:207], v[12:15]
	v_mfma_f32_16x16x32_bf16 v[4:7], v[76:79], v[204:207], v[4:7]
	ds_read_b128 v[184:187], v210 offset:61440
	s_add_u32 m0, s38, 28672
	s_nop 0
	global_load_lds_dwordx4 v215, s[100:101]
	s_add_u32 s100, s100, 128
	s_addc_u32 s101, s101, 0
	s_waitcnt lgkmcnt(6)
	v_mfma_f32_16x16x32_bf16 v[40:43], v[64:67], v[160:163], v[40:43]
	v_mfma_f32_16x16x32_bf16 v[52:55], v[68:71], v[160:163], v[52:55]
	ds_read_b128 v[188:191], v210 offset:63488
	s_waitcnt lgkmcnt(6)
	v_mfma_f32_16x16x32_bf16 v[28:31], v[64:67], v[164:167], v[28:31]
	v_mfma_f32_16x16x32_bf16 v[16:19], v[68:71], v[164:167], v[16:19]
	ds_read_b128 v[72:75], v209 offset:32768
	ds_read_b128 v[76:79], v209 offset:34816
	ds_read_b128 v[192:195], v211 offset:49152
	s_waitcnt lgkmcnt(8)
	v_mfma_f32_16x16x32_bf16 v[60:63], v[64:67], v[168:171], v[60:63]
	v_mfma_f32_16x16x32_bf16 v[48:51], v[68:71], v[168:171], v[48:51]
	ds_read_b128 v[196:199], v211 offset:51200
	s_waitcnt lgkmcnt(8)
	v_mfma_f32_16x16x32_bf16 v[20:23], v[64:67], v[172:175], v[20:23]
	v_mfma_f32_16x16x32_bf16 v[0:3], v[68:71], v[172:175], v[0:3]
	ds_read_b128 v[200:203], v211 offset:53248
	s_waitcnt lgkmcnt(8)
	v_mfma_f32_16x16x32_bf16 v[44:47], v[64:67], v[176:179], v[44:47]
	v_mfma_f32_16x16x32_bf16 v[36:39], v[68:71], v[176:179], v[36:39]
	ds_read_b128 v[204:207], v211 offset:55296
	s_waitcnt lgkmcnt(8)
	v_mfma_f32_16x16x32_bf16 v[24:27], v[64:67], v[180:183], v[24:27]
	v_mfma_f32_16x16x32_bf16 v[8:11], v[68:71], v[180:183], v[8:11]
	ds_read_b128 v[160:163], v211 offset:57344
	s_waitcnt lgkmcnt(8)
	v_mfma_f32_16x16x32_bf16 v[56:59], v[64:67], v[184:187], v[56:59]
	v_mfma_f32_16x16x32_bf16 v[32:35], v[68:71], v[184:187], v[32:35]
	ds_read_b128 v[164:167], v211 offset:59392
	s_waitcnt lgkmcnt(8)
	v_mfma_f32_16x16x32_bf16 v[12:15], v[64:67], v[188:191], v[12:15]
	v_mfma_f32_16x16x32_bf16 v[4:7], v[68:71], v[188:191], v[4:7]
	ds_read_b128 v[168:171], v211 offset:61440
	s_waitcnt lgkmcnt(6)
	v_mfma_f32_16x16x32_bf16 v[40:43], v[72:75], v[192:195], v[40:43]
	v_mfma_f32_16x16x32_bf16 v[52:55], v[76:79], v[192:195], v[52:55]
	ds_read_b128 v[172:175], v211 offset:63488
	s_waitcnt vmcnt(0) lgkmcnt(0)
	s_barrier
	s_add_u32 m0, s38, 32768
	s_nop 0
	global_load_lds_dwordx4 v212, s[98:99]
	s_waitcnt lgkmcnt(6)
	v_mfma_f32_16x16x32_bf16 v[28:31], v[72:75], v[196:199], v[28:31]
	v_mfma_f32_16x16x32_bf16 v[16:19], v[76:79], v[196:199], v[16:19]
	ds_read_b128 v[64:67], v208 offset:0
	ds_read_b128 v[68:71], v208 offset:2048
	ds_read_b128 v[176:179], v210 offset:16384
	s_add_u32 m0, s38, 36864
	s_nop 0
	global_load_lds_dwordx4 v213, s[98:99]
	s_waitcnt lgkmcnt(8)
	v_mfma_f32_16x16x32_bf16 v[60:63], v[72:75], v[200:203], v[60:63]
	v_mfma_f32_16x16x32_bf16 v[48:51], v[76:79], v[200:203], v[48:51]
	ds_read_b128 v[180:183], v210 offset:18432
	s_add_u32 m0, s38, 40960
	s_nop 0
	global_load_lds_dwordx4 v214, s[98:99]
	s_waitcnt lgkmcnt(8)
	v_mfma_f32_16x16x32_bf16 v[20:23], v[72:75], v[204:207], v[20:23]
	v_mfma_f32_16x16x32_bf16 v[0:3], v[76:79], v[204:207], v[0:3]
	ds_read_b128 v[184:187], v210 offset:20480
	s_add_u32 m0, s38, 45056
	s_nop 0
	global_load_lds_dwordx4 v215, s[98:99]
	s_add_u32 s98, s98, 128
	s_addc_u32 s99, s99, 0
	s_waitcnt lgkmcnt(8)
	v_mfma_f32_16x16x32_bf16 v[44:47], v[72:75], v[160:163], v[44:47]
	v_mfma_f32_16x16x32_bf16 v[36:39], v[76:79], v[160:163], v[36:39]
	ds_read_b128 v[188:191], v210 offset:22528
	s_add_u32 m0, s38, 49152
	s_nop 0
	global_load_lds_dwordx4 v212, s[100:101]
	s_waitcnt lgkmcnt(8)
	v_mfma_f32_16x16x32_bf16 v[24:27], v[72:75], v[164:167], v[24:27]
	v_mfma_f32_16x16x32_bf16 v[8:11], v[76:79], v[164:167], v[8:11]
	ds_read_b128 v[192:195], v210 offset:24576
	s_add_u32 m0, s38, 53248
	s_nop 0
	global_load_lds_dwordx4 v213, s[100:101]
	s_waitcnt lgkmcnt(8)
	v_mfma_f32_16x16x32_bf16 v[56:59], v[72:75], v[168:171], v[56:59]
	v_mfma_f32_16x16x32_bf16 v[32:35], v[76:79], v[168:171], v[32:35]
	ds_read_b128 v[196:199], v210 offset:26624
	s_add_u32 m0, s38, 57344
	s_nop 0
	global_load_lds_dwordx4 v214, s[100:101]
	s_waitcnt lgkmcnt(8)
	v_mfma_f32_16x16x32_bf16 v[12:15], v[72:75], v[172:175], v[12:15]
	v_mfma_f32_16x16x32_bf16 v[4:7], v[76:79], v[172:175], v[4:7]
	ds_read_b128 v[200:203], v210 offset:28672
	s_add_u32 m0, s38, 61440
	s_nop 0
	global_load_lds_dwordx4 v215, s[100:101]
	s_add_u32 s100, s100, 128
	s_addc_u32 s101, s101, 0
	s_waitcnt lgkmcnt(6)
	v_mfma_f32_16x16x32_bf16 v[40:43], v[64:67], v[176:179], v[40:43]
	v_mfma_f32_16x16x32_bf16 v[52:55], v[68:71], v[176:179], v[52:55]
	ds_read_b128 v[204:207], v210 offset:30720
	s_waitcnt lgkmcnt(6)
	v_mfma_f32_16x16x32_bf16 v[28:31], v[64:67], v[180:183], v[28:31]
	v_mfma_f32_16x16x32_bf16 v[16:19], v[68:71], v[180:183], v[16:19]
	ds_read_b128 v[72:75], v209 offset:0
	ds_read_b128 v[76:79], v209 offset:2048
	ds_read_b128 v[160:163], v211 offset:16384
	s_waitcnt lgkmcnt(8)
	v_mfma_f32_16x16x32_bf16 v[60:63], v[64:67], v[184:187], v[60:63]
	v_mfma_f32_16x16x32_bf16 v[48:51], v[68:71], v[184:187], v[48:51]
	ds_read_b128 v[164:167], v211 offset:18432
	s_waitcnt lgkmcnt(8)
	v_mfma_f32_16x16x32_bf16 v[20:23], v[64:67], v[188:191], v[20:23]
	v_mfma_f32_16x16x32_bf16 v[0:3], v[68:71], v[188:191], v[0:3]
	ds_read_b128 v[168:171], v211 offset:20480
	s_waitcnt lgkmcnt(8)
	v_mfma_f32_16x16x32_bf16 v[44:47], v[64:67], v[192:195], v[44:47]
	v_mfma_f32_16x16x32_bf16 v[36:39], v[68:71], v[192:195], v[36:39]
	ds_read_b128 v[172:175], v211 offset:22528
	s_waitcnt lgkmcnt(8)
	v_mfma_f32_16x16x32_bf16 v[24:27], v[64:67], v[196:199], v[24:27]
	v_mfma_f32_16x16x32_bf16 v[8:11], v[68:71], v[196:199], v[8:11]
	ds_read_b128 v[176:179], v211 offset:24576
	s_waitcnt lgkmcnt(8)
	v_mfma_f32_16x16x32_bf16 v[56:59], v[64:67], v[200:203], v[56:59]
	v_mfma_f32_16x16x32_bf16 v[32:35], v[68:71], v[200:203], v[32:35]
	ds_read_b128 v[180:183], v211 offset:26624
	s_waitcnt lgkmcnt(8)
	v_mfma_f32_16x16x32_bf16 v[12:15], v[64:67], v[204:207], v[12:15]
	v_mfma_f32_16x16x32_bf16 v[4:7], v[68:71], v[204:207], v[4:7]
	ds_read_b128 v[184:187], v211 offset:28672
	s_waitcnt lgkmcnt(6)
	v_mfma_f32_16x16x32_bf16 v[40:43], v[72:75], v[160:163], v[40:43]
	v_mfma_f32_16x16x32_bf16 v[52:55], v[76:79], v[160:163], v[52:55]
	ds_read_b128 v[188:191], v211 offset:30720
	s_waitcnt vmcnt(0) lgkmcnt(0)
	s_barrier
	s_add_u32 m0, s38, 0
	s_nop 0
	global_load_lds_dwordx4 v212, s[98:99]
	s_waitcnt lgkmcnt(6)
	v_mfma_f32_16x16x32_bf16 v[28:31], v[72:75], v[164:167], v[28:31]
	v_mfma_f32_16x16x32_bf16 v[16:19], v[76:79], v[164:167], v[16:19]
	ds_read_b128 v[64:67], v208 offset:32768
	ds_read_b128 v[68:71], v208 offset:34816
	ds_read_b128 v[192:195], v210 offset:49152
	s_add_u32 m0, s38, 4096
	s_nop 0
	global_load_lds_dwordx4 v213, s[98:99]
	s_waitcnt lgkmcnt(8)
	v_mfma_f32_16x16x32_bf16 v[60:63], v[72:75], v[168:171], v[60:63]
	v_mfma_f32_16x16x32_bf16 v[48:51], v[76:79], v[168:171], v[48:51]
	ds_read_b128 v[196:199], v210 offset:51200
	s_add_u32 m0, s38, 8192
	s_nop 0
	global_load_lds_dwordx4 v214, s[98:99]
	s_waitcnt lgkmcnt(8)
	v_mfma_f32_16x16x32_bf16 v[20:23], v[72:75], v[172:175], v[20:23]
	v_mfma_f32_16x16x32_bf16 v[0:3], v[76:79], v[172:175], v[0:3]
	ds_read_b128 v[200:203], v210 offset:53248
	s_add_u32 m0, s38, 12288
	s_nop 0
	global_load_lds_dwordx4 v215, s[98:99]
	s_add_u32 s98, s98, 128
	s_addc_u32 s99, s99, 0
	s_waitcnt lgkmcnt(8)
	v_mfma_f32_16x16x32_bf16 v[44:47], v[72:75], v[176:179], v[44:47]
	v_mfma_f32_16x16x32_bf16 v[36:39], v[76:79], v[176:179], v[36:39]
	ds_read_b128 v[204:207], v210 offset:55296
	s_add_u32 m0, s38, 16384
	s_nop 0
	global_load_lds_dwordx4 v212, s[100:101]
	s_waitcnt lgkmcnt(8)
	v_mfma_f32_16x16x32_bf16 v[24:27], v[72:75], v[180:183], v[24:27]
	v_mfma_f32_16x16x32_bf16 v[8:11], v[76:79], v[180:183], v[8:11]
	ds_read_b128 v[160:163], v210 offset:57344
	s_add_u32 m0, s38, 20480
	s_nop 0
	global_load_lds_dwordx4 v213, s[100:101]
	s_waitcnt lgkmcnt(8)
	v_mfma_f32_16x16x32_bf16 v[56:59], v[72:75], v[184:187], v[56:59]
	v_mfma_f32_16x16x32_bf16 v[32:35], v[76:79], v[184:187], v[32:35]
	ds_read_b128 v[164:167], v210 offset:59392
	s_add_u32 m0, s38, 24576
	s_nop 0
	global_load_lds_dwordx4 v214, s[100:101]
	s_waitcnt lgkmcnt(8)
	v_mfma_f32_16x16x32_bf16 v[12:15], v[72:75], v[188:191], v[12:15]
	v_mfma_f32_16x16x32_bf16 v[4:7], v[76:79], v[188:191], v[4:7]
	ds_read_b128 v[168:171], v210 offset:61440
	s_add_u32 m0, s38, 28672
	s_nop 0
	global_load_lds_dwordx4 v215, s[100:101]
	s_add_u32 s100, s100, 128
	s_addc_u32 s101, s101, 0
	s_waitcnt lgkmcnt(6)
	v_mfma_f32_16x16x32_bf16 v[40:43], v[64:67], v[192:195], v[40:43]
	v_mfma_f32_16x16x32_bf16 v[52:55], v[68:71], v[192:195], v[52:55]
	ds_read_b128 v[172:175], v210 offset:63488
	s_waitcnt lgkmcnt(6)
	v_mfma_f32_16x16x32_bf16 v[28:31], v[64:67], v[196:199], v[28:31]
	v_mfma_f32_16x16x32_bf16 v[16:19], v[68:71], v[196:199], v[16:19]
	ds_read_b128 v[72:75], v209 offset:32768
	ds_read_b128 v[76:79], v209 offset:34816
	ds_read_b128 v[176:179], v211 offset:49152
	s_waitcnt lgkmcnt(8)
	v_mfma_f32_16x16x32_bf16 v[60:63], v[64:67], v[200:203], v[60:63]
	v_mfma_f32_16x16x32_bf16 v[48:51], v[68:71], v[200:203], v[48:51]
	ds_read_b128 v[180:183], v211 offset:51200
	s_waitcnt lgkmcnt(8)
	v_mfma_f32_16x16x32_bf16 v[20:23], v[64:67], v[204:207], v[20:23]
	v_mfma_f32_16x16x32_bf16 v[0:3], v[68:71], v[204:207], v[0:3]
	ds_read_b128 v[184:187], v211 offset:53248
	s_waitcnt lgkmcnt(8)
	v_mfma_f32_16x16x32_bf16 v[44:47], v[64:67], v[160:163], v[44:47]
	v_mfma_f32_16x16x32_bf16 v[36:39], v[68:71], v[160:163], v[36:39]
	ds_read_b128 v[188:191], v211 offset:55296
	s_waitcnt lgkmcnt(8)
	v_mfma_f32_16x16x32_bf16 v[24:27], v[64:67], v[164:167], v[24:27]
	v_mfma_f32_16x16x32_bf16 v[8:11], v[68:71], v[164:167], v[8:11]
	ds_read_b128 v[192:195], v211 offset:57344
	s_waitcnt lgkmcnt(8)
	v_mfma_f32_16x16x32_bf16 v[56:59], v[64:67], v[168:171], v[56:59]
	v_mfma_f32_16x16x32_bf16 v[32:35], v[68:71], v[168:171], v[32:35]
	ds_read_b128 v[196:199], v211 offset:59392
	s_waitcnt lgkmcnt(8)
	v_mfma_f32_16x16x32_bf16 v[12:15], v[64:67], v[172:175], v[12:15]
	v_mfma_f32_16x16x32_bf16 v[4:7], v[68:71], v[172:175], v[4:7]
	ds_read_b128 v[200:203], v211 offset:61440
	s_waitcnt lgkmcnt(6)
	v_mfma_f32_16x16x32_bf16 v[40:43], v[72:75], v[176:179], v[40:43]
	v_mfma_f32_16x16x32_bf16 v[52:55], v[76:79], v[176:179], v[52:55]
	ds_read_b128 v[204:207], v211 offset:63488
	s_waitcnt vmcnt(0) lgkmcnt(0)
	s_barrier
	s_add_u32 m0, s38, 32768
	s_nop 0
	global_load_lds_dwordx4 v212, s[98:99]
	s_waitcnt lgkmcnt(6)
	v_mfma_f32_16x16x32_bf16 v[28:31], v[72:75], v[180:183], v[28:31]
	v_mfma_f32_16x16x32_bf16 v[16:19], v[76:79], v[180:183], v[16:19]
	ds_read_b128 v[64:67], v208 offset:0
	ds_read_b128 v[68:71], v208 offset:2048
	ds_read_b128 v[160:163], v210 offset:16384
	s_add_u32 m0, s38, 36864
	s_nop 0
	global_load_lds_dwordx4 v213, s[98:99]
	s_waitcnt lgkmcnt(8)
	v_mfma_f32_16x16x32_bf16 v[60:63], v[72:75], v[184:187], v[60:63]
	v_mfma_f32_16x16x32_bf16 v[48:51], v[76:79], v[184:187], v[48:51]
	ds_read_b128 v[164:167], v210 offset:18432
	s_add_u32 m0, s38, 40960
	s_nop 0
	global_load_lds_dwordx4 v214, s[98:99]
	s_waitcnt lgkmcnt(8)
	v_mfma_f32_16x16x32_bf16 v[20:23], v[72:75], v[188:191], v[20:23]
	v_mfma_f32_16x16x32_bf16 v[0:3], v[76:79], v[188:191], v[0:3]
	ds_read_b128 v[168:171], v210 offset:20480
	s_add_u32 m0, s38, 45056
	s_nop 0
	global_load_lds_dwordx4 v215, s[98:99]
	s_add_u32 s98, s98, 128
	s_addc_u32 s99, s99, 0
	s_waitcnt lgkmcnt(8)
	v_mfma_f32_16x16x32_bf16 v[44:47], v[72:75], v[192:195], v[44:47]
	v_mfma_f32_16x16x32_bf16 v[36:39], v[76:79], v[192:195], v[36:39]
	ds_read_b128 v[172:175], v210 offset:22528
	s_add_u32 m0, s38, 49152
	s_nop 0
	global_load_lds_dwordx4 v212, s[100:101]
	s_waitcnt lgkmcnt(8)
	v_mfma_f32_16x16x32_bf16 v[24:27], v[72:75], v[196:199], v[24:27]
	v_mfma_f32_16x16x32_bf16 v[8:11], v[76:79], v[196:199], v[8:11]
	ds_read_b128 v[176:179], v210 offset:24576
	s_add_u32 m0, s38, 53248
	s_nop 0
	global_load_lds_dwordx4 v213, s[100:101]
	s_waitcnt lgkmcnt(8)
	v_mfma_f32_16x16x32_bf16 v[56:59], v[72:75], v[200:203], v[56:59]
	v_mfma_f32_16x16x32_bf16 v[32:35], v[76:79], v[200:203], v[32:35]
	ds_read_b128 v[180:183], v210 offset:26624
	s_add_u32 m0, s38, 57344
	s_nop 0
	global_load_lds_dwordx4 v214, s[100:101]
	s_waitcnt lgkmcnt(8)
	v_mfma_f32_16x16x32_bf16 v[12:15], v[72:75], v[204:207], v[12:15]
	v_mfma_f32_16x16x32_bf16 v[4:7], v[76:79], v[204:207], v[4:7]
	ds_read_b128 v[184:187], v210 offset:28672
	s_add_u32 m0, s38, 61440
	s_nop 0
	global_load_lds_dwordx4 v215, s[100:101]
	s_add_u32 s100, s100, 128
	s_addc_u32 s101, s101, 0
	s_waitcnt lgkmcnt(6)
	v_mfma_f32_16x16x32_bf16 v[40:43], v[64:67], v[160:163], v[40:43]
	v_mfma_f32_16x16x32_bf16 v[52:55], v[68:71], v[160:163], v[52:55]
	ds_read_b128 v[188:191], v210 offset:30720
	s_waitcnt lgkmcnt(6)
	v_mfma_f32_16x16x32_bf16 v[28:31], v[64:67], v[164:167], v[28:31]
	v_mfma_f32_16x16x32_bf16 v[16:19], v[68:71], v[164:167], v[16:19]
	ds_read_b128 v[72:75], v209 offset:0
	ds_read_b128 v[76:79], v209 offset:2048
	ds_read_b128 v[192:195], v211 offset:16384
	s_waitcnt lgkmcnt(8)
	v_mfma_f32_16x16x32_bf16 v[60:63], v[64:67], v[168:171], v[60:63]
	v_mfma_f32_16x16x32_bf16 v[48:51], v[68:71], v[168:171], v[48:51]
	ds_read_b128 v[196:199], v211 offset:18432
	s_waitcnt lgkmcnt(8)
	v_mfma_f32_16x16x32_bf16 v[20:23], v[64:67], v[172:175], v[20:23]
	v_mfma_f32_16x16x32_bf16 v[0:3], v[68:71], v[172:175], v[0:3]
	ds_read_b128 v[200:203], v211 offset:20480
	s_waitcnt lgkmcnt(8)
	v_mfma_f32_16x16x32_bf16 v[44:47], v[64:67], v[176:179], v[44:47]
	v_mfma_f32_16x16x32_bf16 v[36:39], v[68:71], v[176:179], v[36:39]
	ds_read_b128 v[204:207], v211 offset:22528
	s_waitcnt lgkmcnt(8)
	v_mfma_f32_16x16x32_bf16 v[24:27], v[64:67], v[180:183], v[24:27]
	v_mfma_f32_16x16x32_bf16 v[8:11], v[68:71], v[180:183], v[8:11]
	ds_read_b128 v[160:163], v211 offset:24576
	s_waitcnt lgkmcnt(8)
	v_mfma_f32_16x16x32_bf16 v[56:59], v[64:67], v[184:187], v[56:59]
	v_mfma_f32_16x16x32_bf16 v[32:35], v[68:71], v[184:187], v[32:35]
	ds_read_b128 v[164:167], v211 offset:26624
	s_waitcnt lgkmcnt(8)
	v_mfma_f32_16x16x32_bf16 v[12:15], v[64:67], v[188:191], v[12:15]
	v_mfma_f32_16x16x32_bf16 v[4:7], v[68:71], v[188:191], v[4:7]
	ds_read_b128 v[168:171], v211 offset:28672
	s_waitcnt lgkmcnt(6)
	v_mfma_f32_16x16x32_bf16 v[40:43], v[72:75], v[192:195], v[40:43]
	v_mfma_f32_16x16x32_bf16 v[52:55], v[76:79], v[192:195], v[52:55]
	ds_read_b128 v[172:175], v211 offset:30720
	s_waitcnt vmcnt(0) lgkmcnt(0)
	s_barrier
	s_add_u32 m0, s38, 0
	s_nop 0
	global_load_lds_dwordx4 v212, s[98:99]
	s_waitcnt lgkmcnt(6)
	v_mfma_f32_16x16x32_bf16 v[28:31], v[72:75], v[196:199], v[28:31]
	v_mfma_f32_16x16x32_bf16 v[16:19], v[76:79], v[196:199], v[16:19]
	ds_read_b128 v[64:67], v208 offset:32768
	ds_read_b128 v[68:71], v208 offset:34816
	ds_read_b128 v[176:179], v210 offset:49152
	s_add_u32 m0, s38, 4096
	s_nop 0
	global_load_lds_dwordx4 v213, s[98:99]
	s_waitcnt lgkmcnt(8)
	v_mfma_f32_16x16x32_bf16 v[60:63], v[72:75], v[200:203], v[60:63]
	v_mfma_f32_16x16x32_bf16 v[48:51], v[76:79], v[200:203], v[48:51]
	ds_read_b128 v[180:183], v210 offset:51200
	s_add_u32 m0, s38, 8192
	s_nop 0
	global_load_lds_dwordx4 v214, s[98:99]
	s_waitcnt lgkmcnt(8)
	v_mfma_f32_16x16x32_bf16 v[20:23], v[72:75], v[204:207], v[20:23]
	v_mfma_f32_16x16x32_bf16 v[0:3], v[76:79], v[204:207], v[0:3]
	ds_read_b128 v[184:187], v210 offset:53248
	s_add_u32 m0, s38, 12288
	s_nop 0
	global_load_lds_dwordx4 v215, s[98:99]
	s_add_u32 s98, s98, 128
	s_addc_u32 s99, s99, 0
	s_waitcnt lgkmcnt(8)
	v_mfma_f32_16x16x32_bf16 v[44:47], v[72:75], v[160:163], v[44:47]
	v_mfma_f32_16x16x32_bf16 v[36:39], v[76:79], v[160:163], v[36:39]
	ds_read_b128 v[188:191], v210 offset:55296
	s_add_u32 m0, s38, 16384
	s_nop 0
	global_load_lds_dwordx4 v212, s[100:101]
	s_waitcnt lgkmcnt(8)
	v_mfma_f32_16x16x32_bf16 v[24:27], v[72:75], v[164:167], v[24:27]
	v_mfma_f32_16x16x32_bf16 v[8:11], v[76:79], v[164:167], v[8:11]
	ds_read_b128 v[192:195], v210 offset:57344
	s_add_u32 m0, s38, 20480
	s_nop 0
	global_load_lds_dwordx4 v213, s[100:101]
	s_waitcnt lgkmcnt(8)
	v_mfma_f32_16x16x32_bf16 v[56:59], v[72:75], v[168:171], v[56:59]
	v_mfma_f32_16x16x32_bf16 v[32:35], v[76:79], v[168:171], v[32:35]
	ds_read_b128 v[196:199], v210 offset:59392
	s_add_u32 m0, s38, 24576
	s_nop 0
	global_load_lds_dwordx4 v214, s[100:101]
	s_waitcnt lgkmcnt(8)
	v_mfma_f32_16x16x32_bf16 v[12:15], v[72:75], v[172:175], v[12:15]
	v_mfma_f32_16x16x32_bf16 v[4:7], v[76:79], v[172:175], v[4:7]
	ds_read_b128 v[200:203], v210 offset:61440
	s_add_u32 m0, s38, 28672
	s_nop 0
	global_load_lds_dwordx4 v215, s[100:101]
	s_add_u32 s100, s100, 128
	s_addc_u32 s101, s101, 0
	s_waitcnt lgkmcnt(6)
	v_mfma_f32_16x16x32_bf16 v[40:43], v[64:67], v[176:179], v[40:43]
	v_mfma_f32_16x16x32_bf16 v[52:55], v[68:71], v[176:179], v[52:55]
	ds_read_b128 v[204:207], v210 offset:63488
	s_waitcnt lgkmcnt(6)
	v_mfma_f32_16x16x32_bf16 v[28:31], v[64:67], v[180:183], v[28:31]
	v_mfma_f32_16x16x32_bf16 v[16:19], v[68:71], v[180:183], v[16:19]
	ds_read_b128 v[72:75], v209 offset:32768
	ds_read_b128 v[76:79], v209 offset:34816
	ds_read_b128 v[160:163], v211 offset:49152
	s_waitcnt lgkmcnt(8)
	v_mfma_f32_16x16x32_bf16 v[60:63], v[64:67], v[184:187], v[60:63]
	v_mfma_f32_16x16x32_bf16 v[48:51], v[68:71], v[184:187], v[48:51]
	ds_read_b128 v[164:167], v211 offset:51200
	s_waitcnt lgkmcnt(8)
	v_mfma_f32_16x16x32_bf16 v[20:23], v[64:67], v[188:191], v[20:23]
	v_mfma_f32_16x16x32_bf16 v[0:3], v[68:71], v[188:191], v[0:3]
	ds_read_b128 v[168:171], v211 offset:53248
	s_waitcnt lgkmcnt(8)
	v_mfma_f32_16x16x32_bf16 v[44:47], v[64:67], v[192:195], v[44:47]
	v_mfma_f32_16x16x32_bf16 v[36:39], v[68:71], v[192:195], v[36:39]
	ds_read_b128 v[172:175], v211 offset:55296
	s_waitcnt lgkmcnt(8)
	v_mfma_f32_16x16x32_bf16 v[24:27], v[64:67], v[196:199], v[24:27]
	v_mfma_f32_16x16x32_bf16 v[8:11], v[68:71], v[196:199], v[8:11]
	ds_read_b128 v[176:179], v211 offset:57344
	s_waitcnt lgkmcnt(8)
	v_mfma_f32_16x16x32_bf16 v[56:59], v[64:67], v[200:203], v[56:59]
	v_mfma_f32_16x16x32_bf16 v[32:35], v[68:71], v[200:203], v[32:35]
	ds_read_b128 v[180:183], v211 offset:59392
	s_waitcnt lgkmcnt(8)
	v_mfma_f32_16x16x32_bf16 v[12:15], v[64:67], v[204:207], v[12:15]
	v_mfma_f32_16x16x32_bf16 v[4:7], v[68:71], v[204:207], v[4:7]
	ds_read_b128 v[184:187], v211 offset:61440
	s_waitcnt lgkmcnt(6)
	v_mfma_f32_16x16x32_bf16 v[40:43], v[72:75], v[160:163], v[40:43]
	v_mfma_f32_16x16x32_bf16 v[52:55], v[76:79], v[160:163], v[52:55]
	ds_read_b128 v[188:191], v211 offset:63488
	s_waitcnt vmcnt(0) lgkmcnt(0)
	s_barrier
	s_add_u32 m0, s38, 32768
	s_nop 0
	global_load_lds_dwordx4 v212, s[98:99]
	s_waitcnt lgkmcnt(6)
	v_mfma_f32_16x16x32_bf16 v[28:31], v[72:75], v[164:167], v[28:31]
	v_mfma_f32_16x16x32_bf16 v[16:19], v[76:79], v[164:167], v[16:19]
	ds_read_b128 v[64:67], v208 offset:0
	ds_read_b128 v[68:71], v208 offset:2048
	ds_read_b128 v[192:195], v210 offset:16384
	s_add_u32 m0, s38, 36864
	s_nop 0
	global_load_lds_dwordx4 v213, s[98:99]
	s_waitcnt lgkmcnt(8)
	v_mfma_f32_16x16x32_bf16 v[60:63], v[72:75], v[168:171], v[60:63]
	v_mfma_f32_16x16x32_bf16 v[48:51], v[76:79], v[168:171], v[48:51]
	ds_read_b128 v[196:199], v210 offset:18432
	s_add_u32 m0, s38, 40960
	s_nop 0
	global_load_lds_dwordx4 v214, s[98:99]
	s_waitcnt lgkmcnt(8)
	v_mfma_f32_16x16x32_bf16 v[20:23], v[72:75], v[172:175], v[20:23]
	v_mfma_f32_16x16x32_bf16 v[0:3], v[76:79], v[172:175], v[0:3]
	ds_read_b128 v[200:203], v210 offset:20480
	s_add_u32 m0, s38, 45056
	s_nop 0
	global_load_lds_dwordx4 v215, s[98:99]
	s_add_u32 s98, s98, 128
	s_addc_u32 s99, s99, 0
	s_waitcnt lgkmcnt(8)
	v_mfma_f32_16x16x32_bf16 v[44:47], v[72:75], v[176:179], v[44:47]
	v_mfma_f32_16x16x32_bf16 v[36:39], v[76:79], v[176:179], v[36:39]
	ds_read_b128 v[204:207], v210 offset:22528
	s_add_u32 m0, s38, 49152
	s_nop 0
	global_load_lds_dwordx4 v212, s[100:101]
	s_waitcnt lgkmcnt(8)
	v_mfma_f32_16x16x32_bf16 v[24:27], v[72:75], v[180:183], v[24:27]
	v_mfma_f32_16x16x32_bf16 v[8:11], v[76:79], v[180:183], v[8:11]
	ds_read_b128 v[160:163], v210 offset:24576
	s_add_u32 m0, s38, 53248
	s_nop 0
	global_load_lds_dwordx4 v213, s[100:101]
	s_waitcnt lgkmcnt(8)
	v_mfma_f32_16x16x32_bf16 v[56:59], v[72:75], v[184:187], v[56:59]
	v_mfma_f32_16x16x32_bf16 v[32:35], v[76:79], v[184:187], v[32:35]
	ds_read_b128 v[164:167], v210 offset:26624
	s_add_u32 m0, s38, 57344
	s_nop 0
	global_load_lds_dwordx4 v214, s[100:101]
	s_waitcnt lgkmcnt(8)
	v_mfma_f32_16x16x32_bf16 v[12:15], v[72:75], v[188:191], v[12:15]
	v_mfma_f32_16x16x32_bf16 v[4:7], v[76:79], v[188:191], v[4:7]
	ds_read_b128 v[168:171], v210 offset:28672
	s_add_u32 m0, s38, 61440
	s_nop 0
	global_load_lds_dwordx4 v215, s[100:101]
	s_add_u32 s100, s100, 128
	s_addc_u32 s101, s101, 0
	s_waitcnt lgkmcnt(6)
	v_mfma_f32_16x16x32_bf16 v[40:43], v[64:67], v[192:195], v[40:43]
	v_mfma_f32_16x16x32_bf16 v[52:55], v[68:71], v[192:195], v[52:55]
	ds_read_b128 v[172:175], v210 offset:30720
	s_waitcnt lgkmcnt(6)
	v_mfma_f32_16x16x32_bf16 v[28:31], v[64:67], v[196:199], v[28:31]
	v_mfma_f32_16x16x32_bf16 v[16:19], v[68:71], v[196:199], v[16:19]
	ds_read_b128 v[72:75], v209 offset:0
	ds_read_b128 v[76:79], v209 offset:2048
	ds_read_b128 v[176:179], v211 offset:16384
	s_waitcnt lgkmcnt(8)
	v_mfma_f32_16x16x32_bf16 v[60:63], v[64:67], v[200:203], v[60:63]
	v_mfma_f32_16x16x32_bf16 v[48:51], v[68:71], v[200:203], v[48:51]
	ds_read_b128 v[180:183], v211 offset:18432
	s_waitcnt lgkmcnt(8)
	v_mfma_f32_16x16x32_bf16 v[20:23], v[64:67], v[204:207], v[20:23]
	v_mfma_f32_16x16x32_bf16 v[0:3], v[68:71], v[204:207], v[0:3]
	ds_read_b128 v[184:187], v211 offset:20480
	s_waitcnt lgkmcnt(8)
	v_mfma_f32_16x16x32_bf16 v[44:47], v[64:67], v[160:163], v[44:47]
	v_mfma_f32_16x16x32_bf16 v[36:39], v[68:71], v[160:163], v[36:39]
	ds_read_b128 v[188:191], v211 offset:22528
	s_waitcnt lgkmcnt(8)
	v_mfma_f32_16x16x32_bf16 v[24:27], v[64:67], v[164:167], v[24:27]
	v_mfma_f32_16x16x32_bf16 v[8:11], v[68:71], v[164:167], v[8:11]
	ds_read_b128 v[192:195], v211 offset:24576
	s_waitcnt lgkmcnt(8)
	v_mfma_f32_16x16x32_bf16 v[56:59], v[64:67], v[168:171], v[56:59]
	v_mfma_f32_16x16x32_bf16 v[32:35], v[68:71], v[168:171], v[32:35]
	ds_read_b128 v[196:199], v211 offset:26624
	s_waitcnt lgkmcnt(8)
	v_mfma_f32_16x16x32_bf16 v[12:15], v[64:67], v[172:175], v[12:15]
	v_mfma_f32_16x16x32_bf16 v[4:7], v[68:71], v[172:175], v[4:7]
	ds_read_b128 v[200:203], v211 offset:28672
	s_waitcnt lgkmcnt(6)
	v_mfma_f32_16x16x32_bf16 v[40:43], v[72:75], v[176:179], v[40:43]
	v_mfma_f32_16x16x32_bf16 v[52:55], v[76:79], v[176:179], v[52:55]
	ds_read_b128 v[204:207], v211 offset:30720
	s_waitcnt vmcnt(0) lgkmcnt(0)
	s_barrier
	s_add_u32 m0, s38, 0
	s_nop 0
	global_load_lds_dwordx4 v212, s[98:99]
	s_waitcnt lgkmcnt(6)
	v_mfma_f32_16x16x32_bf16 v[28:31], v[72:75], v[180:183], v[28:31]
	v_mfma_f32_16x16x32_bf16 v[16:19], v[76:79], v[180:183], v[16:19]
	ds_read_b128 v[64:67], v208 offset:32768
	ds_read_b128 v[68:71], v208 offset:34816
	ds_read_b128 v[160:163], v210 offset:49152
	s_add_u32 m0, s38, 4096
	s_nop 0
	global_load_lds_dwordx4 v213, s[98:99]
	s_waitcnt lgkmcnt(8)
	v_mfma_f32_16x16x32_bf16 v[60:63], v[72:75], v[184:187], v[60:63]
	v_mfma_f32_16x16x32_bf16 v[48:51], v[76:79], v[184:187], v[48:51]
	ds_read_b128 v[164:167], v210 offset:51200
	s_add_u32 m0, s38, 8192
	s_nop 0
	global_load_lds_dwordx4 v214, s[98:99]
	s_waitcnt lgkmcnt(8)
	v_mfma_f32_16x16x32_bf16 v[20:23], v[72:75], v[188:191], v[20:23]
	v_mfma_f32_16x16x32_bf16 v[0:3], v[76:79], v[188:191], v[0:3]
	ds_read_b128 v[168:171], v210 offset:53248
	s_add_u32 m0, s38, 12288
	s_nop 0
	global_load_lds_dwordx4 v215, s[98:99]
	s_add_u32 s98, s98, 128
	s_addc_u32 s99, s99, 0
	s_waitcnt lgkmcnt(8)
	v_mfma_f32_16x16x32_bf16 v[44:47], v[72:75], v[192:195], v[44:47]
	v_mfma_f32_16x16x32_bf16 v[36:39], v[76:79], v[192:195], v[36:39]
	ds_read_b128 v[172:175], v210 offset:55296
	s_add_u32 m0, s38, 16384
	s_nop 0
	global_load_lds_dwordx4 v212, s[100:101]
	s_waitcnt lgkmcnt(8)
	v_mfma_f32_16x16x32_bf16 v[24:27], v[72:75], v[196:199], v[24:27]
	v_mfma_f32_16x16x32_bf16 v[8:11], v[76:79], v[196:199], v[8:11]
	ds_read_b128 v[176:179], v210 offset:57344
	s_add_u32 m0, s38, 20480
	s_nop 0
	global_load_lds_dwordx4 v213, s[100:101]
	s_waitcnt lgkmcnt(8)
	v_mfma_f32_16x16x32_bf16 v[56:59], v[72:75], v[200:203], v[56:59]
	v_mfma_f32_16x16x32_bf16 v[32:35], v[76:79], v[200:203], v[32:35]
	ds_read_b128 v[180:183], v210 offset:59392
	s_add_u32 m0, s38, 24576
	s_nop 0
	global_load_lds_dwordx4 v214, s[100:101]
	s_waitcnt lgkmcnt(8)
	v_mfma_f32_16x16x32_bf16 v[12:15], v[72:75], v[204:207], v[12:15]
	v_mfma_f32_16x16x32_bf16 v[4:7], v[76:79], v[204:207], v[4:7]
	ds_read_b128 v[184:187], v210 offset:61440
	s_add_u32 m0, s38, 28672
	s_nop 0
	global_load_lds_dwordx4 v215, s[100:101]
	s_add_u32 s100, s100, 128
	s_addc_u32 s101, s101, 0
	s_waitcnt lgkmcnt(6)
	v_mfma_f32_16x16x32_bf16 v[40:43], v[64:67], v[160:163], v[40:43]
	v_mfma_f32_16x16x32_bf16 v[52:55], v[68:71], v[160:163], v[52:55]
	ds_read_b128 v[188:191], v210 offset:63488
	s_waitcnt lgkmcnt(6)
	v_mfma_f32_16x16x32_bf16 v[28:31], v[64:67], v[164:167], v[28:31]
	v_mfma_f32_16x16x32_bf16 v[16:19], v[68:71], v[164:167], v[16:19]
	ds_read_b128 v[72:75], v209 offset:32768
	ds_read_b128 v[76:79], v209 offset:34816
	ds_read_b128 v[192:195], v211 offset:49152
	s_waitcnt lgkmcnt(8)
	v_mfma_f32_16x16x32_bf16 v[60:63], v[64:67], v[168:171], v[60:63]
	v_mfma_f32_16x16x32_bf16 v[48:51], v[68:71], v[168:171], v[48:51]
	ds_read_b128 v[196:199], v211 offset:51200
	s_waitcnt lgkmcnt(8)
	v_mfma_f32_16x16x32_bf16 v[20:23], v[64:67], v[172:175], v[20:23]
	v_mfma_f32_16x16x32_bf16 v[0:3], v[68:71], v[172:175], v[0:3]
	ds_read_b128 v[200:203], v211 offset:53248
	s_waitcnt lgkmcnt(8)
	v_mfma_f32_16x16x32_bf16 v[44:47], v[64:67], v[176:179], v[44:47]
	v_mfma_f32_16x16x32_bf16 v[36:39], v[68:71], v[176:179], v[36:39]
	ds_read_b128 v[204:207], v211 offset:55296
	s_waitcnt lgkmcnt(8)
	v_mfma_f32_16x16x32_bf16 v[24:27], v[64:67], v[180:183], v[24:27]
	v_mfma_f32_16x16x32_bf16 v[8:11], v[68:71], v[180:183], v[8:11]
	ds_read_b128 v[160:163], v211 offset:57344
	s_waitcnt lgkmcnt(8)
	v_mfma_f32_16x16x32_bf16 v[56:59], v[64:67], v[184:187], v[56:59]
	v_mfma_f32_16x16x32_bf16 v[32:35], v[68:71], v[184:187], v[32:35]
	ds_read_b128 v[164:167], v211 offset:59392
	s_waitcnt lgkmcnt(8)
	v_mfma_f32_16x16x32_bf16 v[12:15], v[64:67], v[188:191], v[12:15]
	v_mfma_f32_16x16x32_bf16 v[4:7], v[68:71], v[188:191], v[4:7]
	ds_read_b128 v[168:171], v211 offset:61440
	s_waitcnt lgkmcnt(6)
	v_mfma_f32_16x16x32_bf16 v[40:43], v[72:75], v[192:195], v[40:43]
	v_mfma_f32_16x16x32_bf16 v[52:55], v[76:79], v[192:195], v[52:55]
	ds_read_b128 v[172:175], v211 offset:63488
	s_waitcnt vmcnt(0) lgkmcnt(0)
	s_barrier
	s_add_u32 m0, s38, 32768
	s_nop 0
	global_load_lds_dwordx4 v212, s[98:99]
	s_waitcnt lgkmcnt(6)
	v_mfma_f32_16x16x32_bf16 v[28:31], v[72:75], v[196:199], v[28:31]
	v_mfma_f32_16x16x32_bf16 v[16:19], v[76:79], v[196:199], v[16:19]
	ds_read_b128 v[64:67], v208 offset:0
	ds_read_b128 v[68:71], v208 offset:2048
	ds_read_b128 v[176:179], v210 offset:16384
	s_add_u32 m0, s38, 36864
	s_nop 0
	global_load_lds_dwordx4 v213, s[98:99]
	s_waitcnt lgkmcnt(8)
	v_mfma_f32_16x16x32_bf16 v[60:63], v[72:75], v[200:203], v[60:63]
	v_mfma_f32_16x16x32_bf16 v[48:51], v[76:79], v[200:203], v[48:51]
	ds_read_b128 v[180:183], v210 offset:18432
	s_add_u32 m0, s38, 40960
	s_nop 0
	global_load_lds_dwordx4 v214, s[98:99]
	s_waitcnt lgkmcnt(8)
	v_mfma_f32_16x16x32_bf16 v[20:23], v[72:75], v[204:207], v[20:23]
	v_mfma_f32_16x16x32_bf16 v[0:3], v[76:79], v[204:207], v[0:3]
	ds_read_b128 v[184:187], v210 offset:20480
	s_add_u32 m0, s38, 45056
	s_nop 0
	global_load_lds_dwordx4 v215, s[98:99]
	s_add_u32 s98, s98, 128
	s_addc_u32 s99, s99, 0
	s_waitcnt lgkmcnt(8)
	v_mfma_f32_16x16x32_bf16 v[44:47], v[72:75], v[160:163], v[44:47]
	v_mfma_f32_16x16x32_bf16 v[36:39], v[76:79], v[160:163], v[36:39]
	ds_read_b128 v[188:191], v210 offset:22528
	s_add_u32 m0, s38, 49152
	s_nop 0
	global_load_lds_dwordx4 v212, s[100:101]
	s_waitcnt lgkmcnt(8)
	v_mfma_f32_16x16x32_bf16 v[24:27], v[72:75], v[164:167], v[24:27]
	v_mfma_f32_16x16x32_bf16 v[8:11], v[76:79], v[164:167], v[8:11]
	ds_read_b128 v[192:195], v210 offset:24576
	s_add_u32 m0, s38, 53248
	s_nop 0
	global_load_lds_dwordx4 v213, s[100:101]
	s_waitcnt lgkmcnt(8)
	v_mfma_f32_16x16x32_bf16 v[56:59], v[72:75], v[168:171], v[56:59]
	v_mfma_f32_16x16x32_bf16 v[32:35], v[76:79], v[168:171], v[32:35]
	ds_read_b128 v[196:199], v210 offset:26624
	s_add_u32 m0, s38, 57344
	s_nop 0
	global_load_lds_dwordx4 v214, s[100:101]
	s_waitcnt lgkmcnt(8)
	v_mfma_f32_16x16x32_bf16 v[12:15], v[72:75], v[172:175], v[12:15]
	v_mfma_f32_16x16x32_bf16 v[4:7], v[76:79], v[172:175], v[4:7]
	ds_read_b128 v[200:203], v210 offset:28672
	s_add_u32 m0, s38, 61440
	s_nop 0
	global_load_lds_dwordx4 v215, s[100:101]
	s_add_u32 s100, s100, 128
	s_addc_u32 s101, s101, 0
	s_waitcnt lgkmcnt(6)
	v_mfma_f32_16x16x32_bf16 v[40:43], v[64:67], v[176:179], v[40:43]
	v_mfma_f32_16x16x32_bf16 v[52:55], v[68:71], v[176:179], v[52:55]
	ds_read_b128 v[204:207], v210 offset:30720
	s_waitcnt lgkmcnt(6)
	v_mfma_f32_16x16x32_bf16 v[28:31], v[64:67], v[180:183], v[28:31]
	v_mfma_f32_16x16x32_bf16 v[16:19], v[68:71], v[180:183], v[16:19]
	ds_read_b128 v[72:75], v209 offset:0
	ds_read_b128 v[76:79], v209 offset:2048
	ds_read_b128 v[160:163], v211 offset:16384
	s_waitcnt lgkmcnt(8)
	v_mfma_f32_16x16x32_bf16 v[60:63], v[64:67], v[184:187], v[60:63]
	v_mfma_f32_16x16x32_bf16 v[48:51], v[68:71], v[184:187], v[48:51]
	ds_read_b128 v[164:167], v211 offset:18432
	s_waitcnt lgkmcnt(8)
	v_mfma_f32_16x16x32_bf16 v[20:23], v[64:67], v[188:191], v[20:23]
	v_mfma_f32_16x16x32_bf16 v[0:3], v[68:71], v[188:191], v[0:3]
	ds_read_b128 v[168:171], v211 offset:20480
	s_waitcnt lgkmcnt(8)
	v_mfma_f32_16x16x32_bf16 v[44:47], v[64:67], v[192:195], v[44:47]
	v_mfma_f32_16x16x32_bf16 v[36:39], v[68:71], v[192:195], v[36:39]
	ds_read_b128 v[172:175], v211 offset:22528
	s_waitcnt lgkmcnt(8)
	v_mfma_f32_16x16x32_bf16 v[24:27], v[64:67], v[196:199], v[24:27]
	v_mfma_f32_16x16x32_bf16 v[8:11], v[68:71], v[196:199], v[8:11]
	ds_read_b128 v[176:179], v211 offset:24576
	s_waitcnt lgkmcnt(8)
	v_mfma_f32_16x16x32_bf16 v[56:59], v[64:67], v[200:203], v[56:59]
	v_mfma_f32_16x16x32_bf16 v[32:35], v[68:71], v[200:203], v[32:35]
	ds_read_b128 v[180:183], v211 offset:26624
	s_waitcnt lgkmcnt(8)
	v_mfma_f32_16x16x32_bf16 v[12:15], v[64:67], v[204:207], v[12:15]
	v_mfma_f32_16x16x32_bf16 v[4:7], v[68:71], v[204:207], v[4:7]
	ds_read_b128 v[184:187], v211 offset:28672
	s_waitcnt lgkmcnt(6)
	v_mfma_f32_16x16x32_bf16 v[40:43], v[72:75], v[160:163], v[40:43]
	v_mfma_f32_16x16x32_bf16 v[52:55], v[76:79], v[160:163], v[52:55]
	ds_read_b128 v[188:191], v211 offset:30720
	s_waitcnt vmcnt(0) lgkmcnt(0)
	s_barrier
	s_add_u32 m0, s38, 0
	s_nop 0
	global_load_lds_dwordx4 v212, s[98:99]
	s_waitcnt lgkmcnt(6)
	v_mfma_f32_16x16x32_bf16 v[28:31], v[72:75], v[164:167], v[28:31]
	v_mfma_f32_16x16x32_bf16 v[16:19], v[76:79], v[164:167], v[16:19]
	ds_read_b128 v[64:67], v208 offset:32768
	ds_read_b128 v[68:71], v208 offset:34816
	ds_read_b128 v[192:195], v210 offset:49152
	s_add_u32 m0, s38, 4096
	s_nop 0
	global_load_lds_dwordx4 v213, s[98:99]
	s_waitcnt lgkmcnt(8)
	v_mfma_f32_16x16x32_bf16 v[60:63], v[72:75], v[168:171], v[60:63]
	v_mfma_f32_16x16x32_bf16 v[48:51], v[76:79], v[168:171], v[48:51]
	ds_read_b128 v[196:199], v210 offset:51200
	s_add_u32 m0, s38, 8192
	s_nop 0
	global_load_lds_dwordx4 v214, s[98:99]
	s_waitcnt lgkmcnt(8)
	v_mfma_f32_16x16x32_bf16 v[20:23], v[72:75], v[172:175], v[20:23]
	v_mfma_f32_16x16x32_bf16 v[0:3], v[76:79], v[172:175], v[0:3]
	ds_read_b128 v[200:203], v210 offset:53248
	s_add_u32 m0, s38, 12288
	s_nop 0
	global_load_lds_dwordx4 v215, s[98:99]
	s_add_u32 s98, s98, 128
	s_addc_u32 s99, s99, 0
	s_waitcnt lgkmcnt(8)
	v_mfma_f32_16x16x32_bf16 v[44:47], v[72:75], v[176:179], v[44:47]
	v_mfma_f32_16x16x32_bf16 v[36:39], v[76:79], v[176:179], v[36:39]
	ds_read_b128 v[204:207], v210 offset:55296
	s_add_u32 m0, s38, 16384
	s_nop 0
	global_load_lds_dwordx4 v212, s[100:101]
	s_waitcnt lgkmcnt(8)
	v_mfma_f32_16x16x32_bf16 v[24:27], v[72:75], v[180:183], v[24:27]
	v_mfma_f32_16x16x32_bf16 v[8:11], v[76:79], v[180:183], v[8:11]
	ds_read_b128 v[160:163], v210 offset:57344
	s_add_u32 m0, s38, 20480
	s_nop 0
	global_load_lds_dwordx4 v213, s[100:101]
	s_waitcnt lgkmcnt(8)
	v_mfma_f32_16x16x32_bf16 v[56:59], v[72:75], v[184:187], v[56:59]
	v_mfma_f32_16x16x32_bf16 v[32:35], v[76:79], v[184:187], v[32:35]
	ds_read_b128 v[164:167], v210 offset:59392
	s_add_u32 m0, s38, 24576
	s_nop 0
	global_load_lds_dwordx4 v214, s[100:101]
	s_waitcnt lgkmcnt(8)
	v_mfma_f32_16x16x32_bf16 v[12:15], v[72:75], v[188:191], v[12:15]
	v_mfma_f32_16x16x32_bf16 v[4:7], v[76:79], v[188:191], v[4:7]
	ds_read_b128 v[168:171], v210 offset:61440
	s_add_u32 m0, s38, 28672
	s_nop 0
	global_load_lds_dwordx4 v215, s[100:101]
	s_add_u32 s100, s100, 128
	s_addc_u32 s101, s101, 0
	s_waitcnt lgkmcnt(6)
	v_mfma_f32_16x16x32_bf16 v[40:43], v[64:67], v[192:195], v[40:43]
	v_mfma_f32_16x16x32_bf16 v[52:55], v[68:71], v[192:195], v[52:55]
	ds_read_b128 v[172:175], v210 offset:63488
	s_waitcnt lgkmcnt(6)
	v_mfma_f32_16x16x32_bf16 v[28:31], v[64:67], v[196:199], v[28:31]
	v_mfma_f32_16x16x32_bf16 v[16:19], v[68:71], v[196:199], v[16:19]
	ds_read_b128 v[72:75], v209 offset:32768
	ds_read_b128 v[76:79], v209 offset:34816
	ds_read_b128 v[176:179], v211 offset:49152
	s_waitcnt lgkmcnt(8)
	v_mfma_f32_16x16x32_bf16 v[60:63], v[64:67], v[200:203], v[60:63]
	v_mfma_f32_16x16x32_bf16 v[48:51], v[68:71], v[200:203], v[48:51]
	ds_read_b128 v[180:183], v211 offset:51200
	s_waitcnt lgkmcnt(8)
	v_mfma_f32_16x16x32_bf16 v[20:23], v[64:67], v[204:207], v[20:23]
	v_mfma_f32_16x16x32_bf16 v[0:3], v[68:71], v[204:207], v[0:3]
	ds_read_b128 v[184:187], v211 offset:53248
	s_waitcnt lgkmcnt(8)
	v_mfma_f32_16x16x32_bf16 v[44:47], v[64:67], v[160:163], v[44:47]
	v_mfma_f32_16x16x32_bf16 v[36:39], v[68:71], v[160:163], v[36:39]
	ds_read_b128 v[188:191], v211 offset:55296
	s_waitcnt lgkmcnt(8)
	v_mfma_f32_16x16x32_bf16 v[24:27], v[64:67], v[164:167], v[24:27]
	v_mfma_f32_16x16x32_bf16 v[8:11], v[68:71], v[164:167], v[8:11]
	ds_read_b128 v[192:195], v211 offset:57344
	s_waitcnt lgkmcnt(8)
	v_mfma_f32_16x16x32_bf16 v[56:59], v[64:67], v[168:171], v[56:59]
	v_mfma_f32_16x16x32_bf16 v[32:35], v[68:71], v[168:171], v[32:35]
	ds_read_b128 v[196:199], v211 offset:59392
	s_waitcnt lgkmcnt(8)
	v_mfma_f32_16x16x32_bf16 v[12:15], v[64:67], v[172:175], v[12:15]
	v_mfma_f32_16x16x32_bf16 v[4:7], v[68:71], v[172:175], v[4:7]
	ds_read_b128 v[200:203], v211 offset:61440
	s_waitcnt lgkmcnt(6)
	v_mfma_f32_16x16x32_bf16 v[40:43], v[72:75], v[176:179], v[40:43]
	v_mfma_f32_16x16x32_bf16 v[52:55], v[76:79], v[176:179], v[52:55]
	ds_read_b128 v[204:207], v211 offset:63488
	s_waitcnt vmcnt(0) lgkmcnt(0)
	s_barrier
	s_add_u32 m0, s38, 32768
	s_nop 0
	global_load_lds_dwordx4 v212, s[98:99]
	s_waitcnt lgkmcnt(6)
	v_mfma_f32_16x16x32_bf16 v[28:31], v[72:75], v[180:183], v[28:31]
	v_mfma_f32_16x16x32_bf16 v[16:19], v[76:79], v[180:183], v[16:19]
	ds_read_b128 v[64:67], v208 offset:0
	ds_read_b128 v[68:71], v208 offset:2048
	ds_read_b128 v[160:163], v210 offset:16384
	s_add_u32 m0, s38, 36864
	s_nop 0
	global_load_lds_dwordx4 v213, s[98:99]
	s_waitcnt lgkmcnt(8)
	v_mfma_f32_16x16x32_bf16 v[60:63], v[72:75], v[184:187], v[60:63]
	v_mfma_f32_16x16x32_bf16 v[48:51], v[76:79], v[184:187], v[48:51]
	ds_read_b128 v[164:167], v210 offset:18432
	s_add_u32 m0, s38, 40960
	s_nop 0
	global_load_lds_dwordx4 v214, s[98:99]
	s_waitcnt lgkmcnt(8)
	v_mfma_f32_16x16x32_bf16 v[20:23], v[72:75], v[188:191], v[20:23]
	v_mfma_f32_16x16x32_bf16 v[0:3], v[76:79], v[188:191], v[0:3]
	ds_read_b128 v[168:171], v210 offset:20480
	s_add_u32 m0, s38, 45056
	s_nop 0
	global_load_lds_dwordx4 v215, s[98:99]
	s_add_u32 s98, s98, 128
	s_addc_u32 s99, s99, 0
	s_waitcnt lgkmcnt(8)
	v_mfma_f32_16x16x32_bf16 v[44:47], v[72:75], v[192:195], v[44:47]
	v_mfma_f32_16x16x32_bf16 v[36:39], v[76:79], v[192:195], v[36:39]
	ds_read_b128 v[172:175], v210 offset:22528
	s_add_u32 m0, s38, 49152
	s_nop 0
	global_load_lds_dwordx4 v212, s[100:101]
	s_waitcnt lgkmcnt(8)
	v_mfma_f32_16x16x32_bf16 v[24:27], v[72:75], v[196:199], v[24:27]
	v_mfma_f32_16x16x32_bf16 v[8:11], v[76:79], v[196:199], v[8:11]
	ds_read_b128 v[176:179], v210 offset:24576
	s_add_u32 m0, s38, 53248
	s_nop 0
	global_load_lds_dwordx4 v213, s[100:101]
	s_waitcnt lgkmcnt(8)
	v_mfma_f32_16x16x32_bf16 v[56:59], v[72:75], v[200:203], v[56:59]
	v_mfma_f32_16x16x32_bf16 v[32:35], v[76:79], v[200:203], v[32:35]
	ds_read_b128 v[180:183], v210 offset:26624
	s_add_u32 m0, s38, 57344
	s_nop 0
	global_load_lds_dwordx4 v214, s[100:101]
	s_waitcnt lgkmcnt(8)
	v_mfma_f32_16x16x32_bf16 v[12:15], v[72:75], v[204:207], v[12:15]
	v_mfma_f32_16x16x32_bf16 v[4:7], v[76:79], v[204:207], v[4:7]
	ds_read_b128 v[184:187], v210 offset:28672
	s_add_u32 m0, s38, 61440
	s_nop 0
	global_load_lds_dwordx4 v215, s[100:101]
	s_add_u32 s100, s100, 128
	s_addc_u32 s101, s101, 0
	s_waitcnt lgkmcnt(6)
	v_mfma_f32_16x16x32_bf16 v[40:43], v[64:67], v[160:163], v[40:43]
	v_mfma_f32_16x16x32_bf16 v[52:55], v[68:71], v[160:163], v[52:55]
	ds_read_b128 v[188:191], v210 offset:30720
	s_waitcnt lgkmcnt(6)
	v_mfma_f32_16x16x32_bf16 v[28:31], v[64:67], v[164:167], v[28:31]
	v_mfma_f32_16x16x32_bf16 v[16:19], v[68:71], v[164:167], v[16:19]
	ds_read_b128 v[72:75], v209 offset:0
	ds_read_b128 v[76:79], v209 offset:2048
	ds_read_b128 v[192:195], v211 offset:16384
	s_waitcnt lgkmcnt(8)
	v_mfma_f32_16x16x32_bf16 v[60:63], v[64:67], v[168:171], v[60:63]
	v_mfma_f32_16x16x32_bf16 v[48:51], v[68:71], v[168:171], v[48:51]
	ds_read_b128 v[196:199], v211 offset:18432
	s_waitcnt lgkmcnt(8)
	v_mfma_f32_16x16x32_bf16 v[20:23], v[64:67], v[172:175], v[20:23]
	v_mfma_f32_16x16x32_bf16 v[0:3], v[68:71], v[172:175], v[0:3]
	ds_read_b128 v[200:203], v211 offset:20480
	s_waitcnt lgkmcnt(8)
	v_mfma_f32_16x16x32_bf16 v[44:47], v[64:67], v[176:179], v[44:47]
	v_mfma_f32_16x16x32_bf16 v[36:39], v[68:71], v[176:179], v[36:39]
	ds_read_b128 v[204:207], v211 offset:22528
	s_waitcnt lgkmcnt(8)
	v_mfma_f32_16x16x32_bf16 v[24:27], v[64:67], v[180:183], v[24:27]
	v_mfma_f32_16x16x32_bf16 v[8:11], v[68:71], v[180:183], v[8:11]
	ds_read_b128 v[160:163], v211 offset:24576
	s_waitcnt lgkmcnt(8)
	v_mfma_f32_16x16x32_bf16 v[56:59], v[64:67], v[184:187], v[56:59]
	v_mfma_f32_16x16x32_bf16 v[32:35], v[68:71], v[184:187], v[32:35]
	ds_read_b128 v[164:167], v211 offset:26624
	s_waitcnt lgkmcnt(8)
	v_mfma_f32_16x16x32_bf16 v[12:15], v[64:67], v[188:191], v[12:15]
	v_mfma_f32_16x16x32_bf16 v[4:7], v[68:71], v[188:191], v[4:7]
	ds_read_b128 v[168:171], v211 offset:28672
	s_waitcnt lgkmcnt(6)
	v_mfma_f32_16x16x32_bf16 v[40:43], v[72:75], v[192:195], v[40:43]
	v_mfma_f32_16x16x32_bf16 v[52:55], v[76:79], v[192:195], v[52:55]
	ds_read_b128 v[172:175], v211 offset:30720
	s_waitcnt vmcnt(0) lgkmcnt(0)
	s_barrier
	s_add_u32 m0, s38, 0
	s_nop 0
	global_load_lds_dwordx4 v212, s[98:99]
	s_waitcnt lgkmcnt(6)
	v_mfma_f32_16x16x32_bf16 v[28:31], v[72:75], v[196:199], v[28:31]
	v_mfma_f32_16x16x32_bf16 v[16:19], v[76:79], v[196:199], v[16:19]
	ds_read_b128 v[64:67], v208 offset:32768
	ds_read_b128 v[68:71], v208 offset:34816
	ds_read_b128 v[176:179], v210 offset:49152
	s_add_u32 m0, s38, 4096
	s_nop 0
	global_load_lds_dwordx4 v213, s[98:99]
	s_waitcnt lgkmcnt(8)
	v_mfma_f32_16x16x32_bf16 v[60:63], v[72:75], v[200:203], v[60:63]
	v_mfma_f32_16x16x32_bf16 v[48:51], v[76:79], v[200:203], v[48:51]
	ds_read_b128 v[180:183], v210 offset:51200
	s_add_u32 m0, s38, 8192
	s_nop 0
	global_load_lds_dwordx4 v214, s[98:99]
	s_waitcnt lgkmcnt(8)
	v_mfma_f32_16x16x32_bf16 v[20:23], v[72:75], v[204:207], v[20:23]
	v_mfma_f32_16x16x32_bf16 v[0:3], v[76:79], v[204:207], v[0:3]
	ds_read_b128 v[184:187], v210 offset:53248
	s_add_u32 m0, s38, 12288
	s_nop 0
	global_load_lds_dwordx4 v215, s[98:99]
	s_add_u32 s98, s98, 128
	s_addc_u32 s99, s99, 0
	s_waitcnt lgkmcnt(8)
	v_mfma_f32_16x16x32_bf16 v[44:47], v[72:75], v[160:163], v[44:47]
	v_mfma_f32_16x16x32_bf16 v[36:39], v[76:79], v[160:163], v[36:39]
	ds_read_b128 v[188:191], v210 offset:55296
	s_add_u32 m0, s38, 16384
	s_nop 0
	global_load_lds_dwordx4 v212, s[100:101]
	s_waitcnt lgkmcnt(8)
	v_mfma_f32_16x16x32_bf16 v[24:27], v[72:75], v[164:167], v[24:27]
	v_mfma_f32_16x16x32_bf16 v[8:11], v[76:79], v[164:167], v[8:11]
	ds_read_b128 v[192:195], v210 offset:57344
	s_add_u32 m0, s38, 20480
	s_nop 0
	global_load_lds_dwordx4 v213, s[100:101]
	s_waitcnt lgkmcnt(8)
	v_mfma_f32_16x16x32_bf16 v[56:59], v[72:75], v[168:171], v[56:59]
	v_mfma_f32_16x16x32_bf16 v[32:35], v[76:79], v[168:171], v[32:35]
	ds_read_b128 v[196:199], v210 offset:59392
	s_add_u32 m0, s38, 24576
	s_nop 0
	global_load_lds_dwordx4 v214, s[100:101]
	s_waitcnt lgkmcnt(8)
	v_mfma_f32_16x16x32_bf16 v[12:15], v[72:75], v[172:175], v[12:15]
	v_mfma_f32_16x16x32_bf16 v[4:7], v[76:79], v[172:175], v[4:7]
	ds_read_b128 v[200:203], v210 offset:61440
	s_add_u32 m0, s38, 28672
	s_nop 0
	global_load_lds_dwordx4 v215, s[100:101]
	s_add_u32 s100, s100, 128
	s_addc_u32 s101, s101, 0
	s_waitcnt lgkmcnt(6)
	v_mfma_f32_16x16x32_bf16 v[40:43], v[64:67], v[176:179], v[40:43]
	v_mfma_f32_16x16x32_bf16 v[52:55], v[68:71], v[176:179], v[52:55]
	ds_read_b128 v[204:207], v210 offset:63488
	s_waitcnt lgkmcnt(6)
	v_mfma_f32_16x16x32_bf16 v[28:31], v[64:67], v[180:183], v[28:31]
	v_mfma_f32_16x16x32_bf16 v[16:19], v[68:71], v[180:183], v[16:19]
	ds_read_b128 v[72:75], v209 offset:32768
	ds_read_b128 v[76:79], v209 offset:34816
	ds_read_b128 v[160:163], v211 offset:49152
	s_waitcnt lgkmcnt(8)
	v_mfma_f32_16x16x32_bf16 v[60:63], v[64:67], v[184:187], v[60:63]
	v_mfma_f32_16x16x32_bf16 v[48:51], v[68:71], v[184:187], v[48:51]
	ds_read_b128 v[164:167], v211 offset:51200
	s_waitcnt lgkmcnt(8)
	v_mfma_f32_16x16x32_bf16 v[20:23], v[64:67], v[188:191], v[20:23]
	v_mfma_f32_16x16x32_bf16 v[0:3], v[68:71], v[188:191], v[0:3]
	ds_read_b128 v[168:171], v211 offset:53248
	s_waitcnt lgkmcnt(8)
	v_mfma_f32_16x16x32_bf16 v[44:47], v[64:67], v[192:195], v[44:47]
	v_mfma_f32_16x16x32_bf16 v[36:39], v[68:71], v[192:195], v[36:39]
	ds_read_b128 v[172:175], v211 offset:55296
	s_waitcnt lgkmcnt(8)
	v_mfma_f32_16x16x32_bf16 v[24:27], v[64:67], v[196:199], v[24:27]
	v_mfma_f32_16x16x32_bf16 v[8:11], v[68:71], v[196:199], v[8:11]
	ds_read_b128 v[176:179], v211 offset:57344
	s_waitcnt lgkmcnt(8)
	v_mfma_f32_16x16x32_bf16 v[56:59], v[64:67], v[200:203], v[56:59]
	v_mfma_f32_16x16x32_bf16 v[32:35], v[68:71], v[200:203], v[32:35]
	ds_read_b128 v[180:183], v211 offset:59392
	s_waitcnt lgkmcnt(8)
	v_mfma_f32_16x16x32_bf16 v[12:15], v[64:67], v[204:207], v[12:15]
	v_mfma_f32_16x16x32_bf16 v[4:7], v[68:71], v[204:207], v[4:7]
	ds_read_b128 v[184:187], v211 offset:61440
	s_waitcnt lgkmcnt(6)
	v_mfma_f32_16x16x32_bf16 v[40:43], v[72:75], v[160:163], v[40:43]
	v_mfma_f32_16x16x32_bf16 v[52:55], v[76:79], v[160:163], v[52:55]
	ds_read_b128 v[188:191], v211 offset:63488
	s_waitcnt vmcnt(0) lgkmcnt(0)
	s_barrier
	s_add_u32 m0, s38, 32768
	s_nop 0
	global_load_lds_dwordx4 v212, s[98:99]
	s_waitcnt lgkmcnt(6)
	v_mfma_f32_16x16x32_bf16 v[28:31], v[72:75], v[164:167], v[28:31]
	v_mfma_f32_16x16x32_bf16 v[16:19], v[76:79], v[164:167], v[16:19]
	ds_read_b128 v[64:67], v208 offset:0
	ds_read_b128 v[68:71], v208 offset:2048
	ds_read_b128 v[192:195], v210 offset:16384
	s_add_u32 m0, s38, 36864
	s_nop 0
	global_load_lds_dwordx4 v213, s[98:99]
	s_waitcnt lgkmcnt(8)
	v_mfma_f32_16x16x32_bf16 v[60:63], v[72:75], v[168:171], v[60:63]
	v_mfma_f32_16x16x32_bf16 v[48:51], v[76:79], v[168:171], v[48:51]
	ds_read_b128 v[196:199], v210 offset:18432
	s_add_u32 m0, s38, 40960
	s_nop 0
	global_load_lds_dwordx4 v214, s[98:99]
	s_waitcnt lgkmcnt(8)
	v_mfma_f32_16x16x32_bf16 v[20:23], v[72:75], v[172:175], v[20:23]
	v_mfma_f32_16x16x32_bf16 v[0:3], v[76:79], v[172:175], v[0:3]
	ds_read_b128 v[200:203], v210 offset:20480
	s_add_u32 m0, s38, 45056
	s_nop 0
	global_load_lds_dwordx4 v215, s[98:99]
	s_add_u32 s98, s98, 128
	s_addc_u32 s99, s99, 0
	s_waitcnt lgkmcnt(8)
	v_mfma_f32_16x16x32_bf16 v[44:47], v[72:75], v[176:179], v[44:47]
	v_mfma_f32_16x16x32_bf16 v[36:39], v[76:79], v[176:179], v[36:39]
	ds_read_b128 v[204:207], v210 offset:22528
	s_add_u32 m0, s38, 49152
	s_nop 0
	global_load_lds_dwordx4 v212, s[100:101]
	s_waitcnt lgkmcnt(8)
	v_mfma_f32_16x16x32_bf16 v[24:27], v[72:75], v[180:183], v[24:27]
	v_mfma_f32_16x16x32_bf16 v[8:11], v[76:79], v[180:183], v[8:11]
	ds_read_b128 v[160:163], v210 offset:24576
	s_add_u32 m0, s38, 53248
	s_nop 0
	global_load_lds_dwordx4 v213, s[100:101]
	s_waitcnt lgkmcnt(8)
	v_mfma_f32_16x16x32_bf16 v[56:59], v[72:75], v[184:187], v[56:59]
	v_mfma_f32_16x16x32_bf16 v[32:35], v[76:79], v[184:187], v[32:35]
	ds_read_b128 v[164:167], v210 offset:26624
	s_add_u32 m0, s38, 57344
	s_nop 0
	global_load_lds_dwordx4 v214, s[100:101]
	s_waitcnt lgkmcnt(8)
	v_mfma_f32_16x16x32_bf16 v[12:15], v[72:75], v[188:191], v[12:15]
	v_mfma_f32_16x16x32_bf16 v[4:7], v[76:79], v[188:191], v[4:7]
	ds_read_b128 v[168:171], v210 offset:28672
	s_add_u32 m0, s38, 61440
	s_nop 0
	global_load_lds_dwordx4 v215, s[100:101]
	s_add_u32 s100, s100, 128
	s_addc_u32 s101, s101, 0
	s_waitcnt lgkmcnt(6)
	v_mfma_f32_16x16x32_bf16 v[40:43], v[64:67], v[192:195], v[40:43]
	v_mfma_f32_16x16x32_bf16 v[52:55], v[68:71], v[192:195], v[52:55]
	ds_read_b128 v[172:175], v210 offset:30720
	s_waitcnt lgkmcnt(6)
	v_mfma_f32_16x16x32_bf16 v[28:31], v[64:67], v[196:199], v[28:31]
	v_mfma_f32_16x16x32_bf16 v[16:19], v[68:71], v[196:199], v[16:19]
	ds_read_b128 v[72:75], v209 offset:0
	ds_read_b128 v[76:79], v209 offset:2048
	ds_read_b128 v[176:179], v211 offset:16384
	s_waitcnt lgkmcnt(8)
	v_mfma_f32_16x16x32_bf16 v[60:63], v[64:67], v[200:203], v[60:63]
	v_mfma_f32_16x16x32_bf16 v[48:51], v[68:71], v[200:203], v[48:51]
	ds_read_b128 v[180:183], v211 offset:18432
	s_waitcnt lgkmcnt(8)
	v_mfma_f32_16x16x32_bf16 v[20:23], v[64:67], v[204:207], v[20:23]
	v_mfma_f32_16x16x32_bf16 v[0:3], v[68:71], v[204:207], v[0:3]
	ds_read_b128 v[184:187], v211 offset:20480
	s_waitcnt lgkmcnt(8)
	v_mfma_f32_16x16x32_bf16 v[44:47], v[64:67], v[160:163], v[44:47]
	v_mfma_f32_16x16x32_bf16 v[36:39], v[68:71], v[160:163], v[36:39]
	ds_read_b128 v[188:191], v211 offset:22528
	s_waitcnt lgkmcnt(8)
	v_mfma_f32_16x16x32_bf16 v[24:27], v[64:67], v[164:167], v[24:27]
	v_mfma_f32_16x16x32_bf16 v[8:11], v[68:71], v[164:167], v[8:11]
	ds_read_b128 v[192:195], v211 offset:24576
	s_waitcnt lgkmcnt(8)
	v_mfma_f32_16x16x32_bf16 v[56:59], v[64:67], v[168:171], v[56:59]
	v_mfma_f32_16x16x32_bf16 v[32:35], v[68:71], v[168:171], v[32:35]
	ds_read_b128 v[196:199], v211 offset:26624
	s_waitcnt lgkmcnt(8)
	v_mfma_f32_16x16x32_bf16 v[12:15], v[64:67], v[172:175], v[12:15]
	v_mfma_f32_16x16x32_bf16 v[4:7], v[68:71], v[172:175], v[4:7]
	ds_read_b128 v[200:203], v211 offset:28672
	s_waitcnt lgkmcnt(6)
	v_mfma_f32_16x16x32_bf16 v[40:43], v[72:75], v[176:179], v[40:43]
	v_mfma_f32_16x16x32_bf16 v[52:55], v[76:79], v[176:179], v[52:55]
	ds_read_b128 v[204:207], v211 offset:30720
	s_waitcnt vmcnt(0) lgkmcnt(0)
	s_barrier
	s_add_u32 m0, s38, 0
	s_nop 0
	global_load_lds_dwordx4 v212, s[98:99]
	s_waitcnt lgkmcnt(6)
	v_mfma_f32_16x16x32_bf16 v[28:31], v[72:75], v[180:183], v[28:31]
	v_mfma_f32_16x16x32_bf16 v[16:19], v[76:79], v[180:183], v[16:19]
	ds_read_b128 v[64:67], v208 offset:32768
	ds_read_b128 v[68:71], v208 offset:34816
	ds_read_b128 v[160:163], v210 offset:49152
	s_add_u32 m0, s38, 4096
	s_nop 0
	global_load_lds_dwordx4 v213, s[98:99]
	s_waitcnt lgkmcnt(8)
	v_mfma_f32_16x16x32_bf16 v[60:63], v[72:75], v[184:187], v[60:63]
	v_mfma_f32_16x16x32_bf16 v[48:51], v[76:79], v[184:187], v[48:51]
	ds_read_b128 v[164:167], v210 offset:51200
	s_add_u32 m0, s38, 8192
	s_nop 0
	global_load_lds_dwordx4 v214, s[98:99]
	s_waitcnt lgkmcnt(8)
	v_mfma_f32_16x16x32_bf16 v[20:23], v[72:75], v[188:191], v[20:23]
	v_mfma_f32_16x16x32_bf16 v[0:3], v[76:79], v[188:191], v[0:3]
	ds_read_b128 v[168:171], v210 offset:53248
	s_add_u32 m0, s38, 12288
	s_nop 0
	global_load_lds_dwordx4 v215, s[98:99]
	s_add_u32 s98, s98, 128
	s_addc_u32 s99, s99, 0
	s_waitcnt lgkmcnt(8)
	v_mfma_f32_16x16x32_bf16 v[44:47], v[72:75], v[192:195], v[44:47]
	v_mfma_f32_16x16x32_bf16 v[36:39], v[76:79], v[192:195], v[36:39]
	ds_read_b128 v[172:175], v210 offset:55296
	s_add_u32 m0, s38, 16384
	s_nop 0
	global_load_lds_dwordx4 v212, s[100:101]
	s_waitcnt lgkmcnt(8)
	v_mfma_f32_16x16x32_bf16 v[24:27], v[72:75], v[196:199], v[24:27]
	v_mfma_f32_16x16x32_bf16 v[8:11], v[76:79], v[196:199], v[8:11]
	ds_read_b128 v[176:179], v210 offset:57344
	s_add_u32 m0, s38, 20480
	s_nop 0
	global_load_lds_dwordx4 v213, s[100:101]
	s_waitcnt lgkmcnt(8)
	v_mfma_f32_16x16x32_bf16 v[56:59], v[72:75], v[200:203], v[56:59]
	v_mfma_f32_16x16x32_bf16 v[32:35], v[76:79], v[200:203], v[32:35]
	ds_read_b128 v[180:183], v210 offset:59392
	s_add_u32 m0, s38, 24576
	s_nop 0
	global_load_lds_dwordx4 v214, s[100:101]
	s_waitcnt lgkmcnt(8)
	v_mfma_f32_16x16x32_bf16 v[12:15], v[72:75], v[204:207], v[12:15]
	v_mfma_f32_16x16x32_bf16 v[4:7], v[76:79], v[204:207], v[4:7]
	ds_read_b128 v[184:187], v210 offset:61440
	s_add_u32 m0, s38, 28672
	s_nop 0
	global_load_lds_dwordx4 v215, s[100:101]
	s_add_u32 s100, s100, 128
	s_addc_u32 s101, s101, 0
	s_waitcnt lgkmcnt(6)
	v_mfma_f32_16x16x32_bf16 v[40:43], v[64:67], v[160:163], v[40:43]
	v_mfma_f32_16x16x32_bf16 v[52:55], v[68:71], v[160:163], v[52:55]
	ds_read_b128 v[188:191], v210 offset:63488
	s_waitcnt lgkmcnt(6)
	v_mfma_f32_16x16x32_bf16 v[28:31], v[64:67], v[164:167], v[28:31]
	v_mfma_f32_16x16x32_bf16 v[16:19], v[68:71], v[164:167], v[16:19]
	ds_read_b128 v[72:75], v209 offset:32768
	ds_read_b128 v[76:79], v209 offset:34816
	ds_read_b128 v[192:195], v211 offset:49152
	s_waitcnt lgkmcnt(8)
	v_mfma_f32_16x16x32_bf16 v[60:63], v[64:67], v[168:171], v[60:63]
	v_mfma_f32_16x16x32_bf16 v[48:51], v[68:71], v[168:171], v[48:51]
	ds_read_b128 v[196:199], v211 offset:51200
	s_waitcnt lgkmcnt(8)
	v_mfma_f32_16x16x32_bf16 v[20:23], v[64:67], v[172:175], v[20:23]
	v_mfma_f32_16x16x32_bf16 v[0:3], v[68:71], v[172:175], v[0:3]
	ds_read_b128 v[200:203], v211 offset:53248
	s_waitcnt lgkmcnt(8)
	v_mfma_f32_16x16x32_bf16 v[44:47], v[64:67], v[176:179], v[44:47]
	v_mfma_f32_16x16x32_bf16 v[36:39], v[68:71], v[176:179], v[36:39]
	ds_read_b128 v[204:207], v211 offset:55296
	s_waitcnt lgkmcnt(8)
	v_mfma_f32_16x16x32_bf16 v[24:27], v[64:67], v[180:183], v[24:27]
	v_mfma_f32_16x16x32_bf16 v[8:11], v[68:71], v[180:183], v[8:11]
	ds_read_b128 v[160:163], v211 offset:57344
	s_waitcnt lgkmcnt(8)
	v_mfma_f32_16x16x32_bf16 v[56:59], v[64:67], v[184:187], v[56:59]
	v_mfma_f32_16x16x32_bf16 v[32:35], v[68:71], v[184:187], v[32:35]
	ds_read_b128 v[164:167], v211 offset:59392
	s_waitcnt lgkmcnt(8)
	v_mfma_f32_16x16x32_bf16 v[12:15], v[64:67], v[188:191], v[12:15]
	v_mfma_f32_16x16x32_bf16 v[4:7], v[68:71], v[188:191], v[4:7]
	ds_read_b128 v[168:171], v211 offset:61440
	s_waitcnt lgkmcnt(6)
	v_mfma_f32_16x16x32_bf16 v[40:43], v[72:75], v[192:195], v[40:43]
	v_mfma_f32_16x16x32_bf16 v[52:55], v[76:79], v[192:195], v[52:55]
	ds_read_b128 v[172:175], v211 offset:63488
	s_waitcnt vmcnt(0) lgkmcnt(0)
	s_barrier
	s_add_u32 m0, s38, 32768
	s_nop 0
	global_load_lds_dwordx4 v212, s[98:99]
	s_waitcnt lgkmcnt(6)
	v_mfma_f32_16x16x32_bf16 v[28:31], v[72:75], v[196:199], v[28:31]
	v_mfma_f32_16x16x32_bf16 v[16:19], v[76:79], v[196:199], v[16:19]
	ds_read_b128 v[64:67], v208 offset:0
	ds_read_b128 v[68:71], v208 offset:2048
	ds_read_b128 v[176:179], v210 offset:16384
	s_add_u32 m0, s38, 36864
	s_nop 0
	global_load_lds_dwordx4 v213, s[98:99]
	s_waitcnt lgkmcnt(8)
	v_mfma_f32_16x16x32_bf16 v[60:63], v[72:75], v[200:203], v[60:63]
	v_mfma_f32_16x16x32_bf16 v[48:51], v[76:79], v[200:203], v[48:51]
	ds_read_b128 v[180:183], v210 offset:18432
	s_add_u32 m0, s38, 40960
	s_nop 0
	global_load_lds_dwordx4 v214, s[98:99]
	s_waitcnt lgkmcnt(8)
	v_mfma_f32_16x16x32_bf16 v[20:23], v[72:75], v[204:207], v[20:23]
	v_mfma_f32_16x16x32_bf16 v[0:3], v[76:79], v[204:207], v[0:3]
	ds_read_b128 v[184:187], v210 offset:20480
	s_add_u32 m0, s38, 45056
	s_nop 0
	global_load_lds_dwordx4 v215, s[98:99]
	s_add_u32 s98, s98, 128
	s_addc_u32 s99, s99, 0
	s_waitcnt lgkmcnt(8)
	v_mfma_f32_16x16x32_bf16 v[44:47], v[72:75], v[160:163], v[44:47]
	v_mfma_f32_16x16x32_bf16 v[36:39], v[76:79], v[160:163], v[36:39]
	ds_read_b128 v[188:191], v210 offset:22528
	s_add_u32 m0, s38, 49152
	s_nop 0
	global_load_lds_dwordx4 v212, s[100:101]
	s_waitcnt lgkmcnt(8)
	v_mfma_f32_16x16x32_bf16 v[24:27], v[72:75], v[164:167], v[24:27]
	v_mfma_f32_16x16x32_bf16 v[8:11], v[76:79], v[164:167], v[8:11]
	ds_read_b128 v[192:195], v210 offset:24576
	s_add_u32 m0, s38, 53248
	s_nop 0
	global_load_lds_dwordx4 v213, s[100:101]
	s_waitcnt lgkmcnt(8)
	v_mfma_f32_16x16x32_bf16 v[56:59], v[72:75], v[168:171], v[56:59]
	v_mfma_f32_16x16x32_bf16 v[32:35], v[76:79], v[168:171], v[32:35]
	ds_read_b128 v[196:199], v210 offset:26624
	s_add_u32 m0, s38, 57344
	s_nop 0
	global_load_lds_dwordx4 v214, s[100:101]
	s_waitcnt lgkmcnt(8)
	v_mfma_f32_16x16x32_bf16 v[12:15], v[72:75], v[172:175], v[12:15]
	v_mfma_f32_16x16x32_bf16 v[4:7], v[76:79], v[172:175], v[4:7]
	ds_read_b128 v[200:203], v210 offset:28672
	s_add_u32 m0, s38, 61440
	s_nop 0
	global_load_lds_dwordx4 v215, s[100:101]
	s_add_u32 s100, s100, 128
	s_addc_u32 s101, s101, 0
	s_waitcnt lgkmcnt(6)
	v_mfma_f32_16x16x32_bf16 v[40:43], v[64:67], v[176:179], v[40:43]
	v_mfma_f32_16x16x32_bf16 v[52:55], v[68:71], v[176:179], v[52:55]
	ds_read_b128 v[204:207], v210 offset:30720
	s_waitcnt lgkmcnt(6)
	v_mfma_f32_16x16x32_bf16 v[28:31], v[64:67], v[180:183], v[28:31]
	v_mfma_f32_16x16x32_bf16 v[16:19], v[68:71], v[180:183], v[16:19]
	ds_read_b128 v[72:75], v209 offset:0
	ds_read_b128 v[76:79], v209 offset:2048
	ds_read_b128 v[160:163], v211 offset:16384
	s_waitcnt lgkmcnt(8)
	v_mfma_f32_16x16x32_bf16 v[60:63], v[64:67], v[184:187], v[60:63]
	v_mfma_f32_16x16x32_bf16 v[48:51], v[68:71], v[184:187], v[48:51]
	ds_read_b128 v[164:167], v211 offset:18432
	s_waitcnt lgkmcnt(8)
	v_mfma_f32_16x16x32_bf16 v[20:23], v[64:67], v[188:191], v[20:23]
	v_mfma_f32_16x16x32_bf16 v[0:3], v[68:71], v[188:191], v[0:3]
	ds_read_b128 v[168:171], v211 offset:20480
	s_waitcnt lgkmcnt(8)
	v_mfma_f32_16x16x32_bf16 v[44:47], v[64:67], v[192:195], v[44:47]
	v_mfma_f32_16x16x32_bf16 v[36:39], v[68:71], v[192:195], v[36:39]
	ds_read_b128 v[172:175], v211 offset:22528
	s_waitcnt lgkmcnt(8)
	v_mfma_f32_16x16x32_bf16 v[24:27], v[64:67], v[196:199], v[24:27]
	v_mfma_f32_16x16x32_bf16 v[8:11], v[68:71], v[196:199], v[8:11]
	ds_read_b128 v[176:179], v211 offset:24576
	s_waitcnt lgkmcnt(8)
	v_mfma_f32_16x16x32_bf16 v[56:59], v[64:67], v[200:203], v[56:59]
	v_mfma_f32_16x16x32_bf16 v[32:35], v[68:71], v[200:203], v[32:35]
	ds_read_b128 v[180:183], v211 offset:26624
	s_waitcnt lgkmcnt(8)
	v_mfma_f32_16x16x32_bf16 v[12:15], v[64:67], v[204:207], v[12:15]
	v_mfma_f32_16x16x32_bf16 v[4:7], v[68:71], v[204:207], v[4:7]
	ds_read_b128 v[184:187], v211 offset:28672
	s_waitcnt lgkmcnt(6)
	v_mfma_f32_16x16x32_bf16 v[40:43], v[72:75], v[160:163], v[40:43]
	v_mfma_f32_16x16x32_bf16 v[52:55], v[76:79], v[160:163], v[52:55]
	ds_read_b128 v[188:191], v211 offset:30720
	s_waitcnt vmcnt(0) lgkmcnt(0)
	s_barrier
	s_add_u32 m0, s38, 0
	s_nop 0
	global_load_lds_dwordx4 v212, s[98:99]
	s_waitcnt lgkmcnt(6)
	v_mfma_f32_16x16x32_bf16 v[28:31], v[72:75], v[164:167], v[28:31]
	v_mfma_f32_16x16x32_bf16 v[16:19], v[76:79], v[164:167], v[16:19]
	ds_read_b128 v[64:67], v208 offset:32768
	ds_read_b128 v[68:71], v208 offset:34816
	ds_read_b128 v[192:195], v210 offset:49152
	s_add_u32 m0, s38, 4096
	s_nop 0
	global_load_lds_dwordx4 v213, s[98:99]
	s_waitcnt lgkmcnt(8)
	v_mfma_f32_16x16x32_bf16 v[60:63], v[72:75], v[168:171], v[60:63]
	v_mfma_f32_16x16x32_bf16 v[48:51], v[76:79], v[168:171], v[48:51]
	ds_read_b128 v[196:199], v210 offset:51200
	s_add_u32 m0, s38, 8192
	s_nop 0
	global_load_lds_dwordx4 v214, s[98:99]
	s_waitcnt lgkmcnt(8)
	v_mfma_f32_16x16x32_bf16 v[20:23], v[72:75], v[172:175], v[20:23]
	v_mfma_f32_16x16x32_bf16 v[0:3], v[76:79], v[172:175], v[0:3]
	ds_read_b128 v[200:203], v210 offset:53248
	s_add_u32 m0, s38, 12288
	s_nop 0
	global_load_lds_dwordx4 v215, s[98:99]
	s_add_u32 s98, s98, 128
	s_addc_u32 s99, s99, 0
	s_waitcnt lgkmcnt(8)
	v_mfma_f32_16x16x32_bf16 v[44:47], v[72:75], v[176:179], v[44:47]
	v_mfma_f32_16x16x32_bf16 v[36:39], v[76:79], v[176:179], v[36:39]
	ds_read_b128 v[204:207], v210 offset:55296
	s_add_u32 m0, s38, 16384
	s_nop 0
	global_load_lds_dwordx4 v212, s[100:101]
	s_waitcnt lgkmcnt(8)
	v_mfma_f32_16x16x32_bf16 v[24:27], v[72:75], v[180:183], v[24:27]
	v_mfma_f32_16x16x32_bf16 v[8:11], v[76:79], v[180:183], v[8:11]
	ds_read_b128 v[160:163], v210 offset:57344
	s_add_u32 m0, s38, 20480
	s_nop 0
	global_load_lds_dwordx4 v213, s[100:101]
	s_waitcnt lgkmcnt(8)
	v_mfma_f32_16x16x32_bf16 v[56:59], v[72:75], v[184:187], v[56:59]
	v_mfma_f32_16x16x32_bf16 v[32:35], v[76:79], v[184:187], v[32:35]
	ds_read_b128 v[164:167], v210 offset:59392
	s_add_u32 m0, s38, 24576
	s_nop 0
	global_load_lds_dwordx4 v214, s[100:101]
	s_waitcnt lgkmcnt(8)
	v_mfma_f32_16x16x32_bf16 v[12:15], v[72:75], v[188:191], v[12:15]
	v_mfma_f32_16x16x32_bf16 v[4:7], v[76:79], v[188:191], v[4:7]
	ds_read_b128 v[168:171], v210 offset:61440
	s_add_u32 m0, s38, 28672
	s_nop 0
	global_load_lds_dwordx4 v215, s[100:101]
	s_add_u32 s100, s100, 128
	s_addc_u32 s101, s101, 0
	s_waitcnt lgkmcnt(6)
	v_mfma_f32_16x16x32_bf16 v[40:43], v[64:67], v[192:195], v[40:43]
	v_mfma_f32_16x16x32_bf16 v[52:55], v[68:71], v[192:195], v[52:55]
	ds_read_b128 v[172:175], v210 offset:63488
	s_waitcnt lgkmcnt(6)
	v_mfma_f32_16x16x32_bf16 v[28:31], v[64:67], v[196:199], v[28:31]
	v_mfma_f32_16x16x32_bf16 v[16:19], v[68:71], v[196:199], v[16:19]
	ds_read_b128 v[72:75], v209 offset:32768
	ds_read_b128 v[76:79], v209 offset:34816
	ds_read_b128 v[176:179], v211 offset:49152
	s_waitcnt lgkmcnt(8)
	v_mfma_f32_16x16x32_bf16 v[60:63], v[64:67], v[200:203], v[60:63]
	v_mfma_f32_16x16x32_bf16 v[48:51], v[68:71], v[200:203], v[48:51]
	ds_read_b128 v[180:183], v211 offset:51200
	s_waitcnt lgkmcnt(8)
	v_mfma_f32_16x16x32_bf16 v[20:23], v[64:67], v[204:207], v[20:23]
	v_mfma_f32_16x16x32_bf16 v[0:3], v[68:71], v[204:207], v[0:3]
	ds_read_b128 v[184:187], v211 offset:53248
	s_waitcnt lgkmcnt(8)
	v_mfma_f32_16x16x32_bf16 v[44:47], v[64:67], v[160:163], v[44:47]
	v_mfma_f32_16x16x32_bf16 v[36:39], v[68:71], v[160:163], v[36:39]
	ds_read_b128 v[188:191], v211 offset:55296
	s_waitcnt lgkmcnt(8)
	v_mfma_f32_16x16x32_bf16 v[24:27], v[64:67], v[164:167], v[24:27]
	v_mfma_f32_16x16x32_bf16 v[8:11], v[68:71], v[164:167], v[8:11]
	ds_read_b128 v[192:195], v211 offset:57344
	s_waitcnt lgkmcnt(8)
	v_mfma_f32_16x16x32_bf16 v[56:59], v[64:67], v[168:171], v[56:59]
	v_mfma_f32_16x16x32_bf16 v[32:35], v[68:71], v[168:171], v[32:35]
	ds_read_b128 v[196:199], v211 offset:59392
	s_waitcnt lgkmcnt(8)
	v_mfma_f32_16x16x32_bf16 v[12:15], v[64:67], v[172:175], v[12:15]
	v_mfma_f32_16x16x32_bf16 v[4:7], v[68:71], v[172:175], v[4:7]
	ds_read_b128 v[200:203], v211 offset:61440
	s_waitcnt lgkmcnt(6)
	v_mfma_f32_16x16x32_bf16 v[40:43], v[72:75], v[176:179], v[40:43]
	v_mfma_f32_16x16x32_bf16 v[52:55], v[76:79], v[176:179], v[52:55]
	ds_read_b128 v[204:207], v211 offset:63488
	s_waitcnt vmcnt(0) lgkmcnt(0)
	s_barrier
	s_add_u32 m0, s38, 32768
	s_nop 0
	global_load_lds_dwordx4 v212, s[98:99]
	s_waitcnt lgkmcnt(6)
	v_mfma_f32_16x16x32_bf16 v[28:31], v[72:75], v[180:183], v[28:31]
	v_mfma_f32_16x16x32_bf16 v[16:19], v[76:79], v[180:183], v[16:19]
	ds_read_b128 v[64:67], v208 offset:0
	ds_read_b128 v[68:71], v208 offset:2048
	ds_read_b128 v[160:163], v210 offset:16384
	s_add_u32 m0, s38, 36864
	s_nop 0
	global_load_lds_dwordx4 v213, s[98:99]
	s_waitcnt lgkmcnt(8)
	v_mfma_f32_16x16x32_bf16 v[60:63], v[72:75], v[184:187], v[60:63]
	v_mfma_f32_16x16x32_bf16 v[48:51], v[76:79], v[184:187], v[48:51]
	ds_read_b128 v[164:167], v210 offset:18432
	s_add_u32 m0, s38, 40960
	s_nop 0
	global_load_lds_dwordx4 v214, s[98:99]
	s_waitcnt lgkmcnt(8)
	v_mfma_f32_16x16x32_bf16 v[20:23], v[72:75], v[188:191], v[20:23]
	v_mfma_f32_16x16x32_bf16 v[0:3], v[76:79], v[188:191], v[0:3]
	ds_read_b128 v[168:171], v210 offset:20480
	s_add_u32 m0, s38, 45056
	s_nop 0
	global_load_lds_dwordx4 v215, s[98:99]
	s_add_u32 s98, s98, 128
	s_addc_u32 s99, s99, 0
	s_waitcnt lgkmcnt(8)
	v_mfma_f32_16x16x32_bf16 v[44:47], v[72:75], v[192:195], v[44:47]
	v_mfma_f32_16x16x32_bf16 v[36:39], v[76:79], v[192:195], v[36:39]
	ds_read_b128 v[172:175], v210 offset:22528
	s_add_u32 m0, s38, 49152
	s_nop 0
	global_load_lds_dwordx4 v212, s[100:101]
	s_waitcnt lgkmcnt(8)
	v_mfma_f32_16x16x32_bf16 v[24:27], v[72:75], v[196:199], v[24:27]
	v_mfma_f32_16x16x32_bf16 v[8:11], v[76:79], v[196:199], v[8:11]
	ds_read_b128 v[176:179], v210 offset:24576
	s_add_u32 m0, s38, 53248
	s_nop 0
	global_load_lds_dwordx4 v213, s[100:101]
	s_waitcnt lgkmcnt(8)
	v_mfma_f32_16x16x32_bf16 v[56:59], v[72:75], v[200:203], v[56:59]
	v_mfma_f32_16x16x32_bf16 v[32:35], v[76:79], v[200:203], v[32:35]
	ds_read_b128 v[180:183], v210 offset:26624
	s_add_u32 m0, s38, 57344
	s_nop 0
	global_load_lds_dwordx4 v214, s[100:101]
	s_waitcnt lgkmcnt(8)
	v_mfma_f32_16x16x32_bf16 v[12:15], v[72:75], v[204:207], v[12:15]
	v_mfma_f32_16x16x32_bf16 v[4:7], v[76:79], v[204:207], v[4:7]
	ds_read_b128 v[184:187], v210 offset:28672
	s_add_u32 m0, s38, 61440
	s_nop 0
	global_load_lds_dwordx4 v215, s[100:101]
	s_add_u32 s100, s100, 128
	s_addc_u32 s101, s101, 0
	s_waitcnt lgkmcnt(6)
	v_mfma_f32_16x16x32_bf16 v[40:43], v[64:67], v[160:163], v[40:43]
	v_mfma_f32_16x16x32_bf16 v[52:55], v[68:71], v[160:163], v[52:55]
	ds_read_b128 v[188:191], v210 offset:30720
	s_waitcnt lgkmcnt(6)
	v_mfma_f32_16x16x32_bf16 v[28:31], v[64:67], v[164:167], v[28:31]
	v_mfma_f32_16x16x32_bf16 v[16:19], v[68:71], v[164:167], v[16:19]
	ds_read_b128 v[72:75], v209 offset:0
	ds_read_b128 v[76:79], v209 offset:2048
	ds_read_b128 v[192:195], v211 offset:16384
	s_waitcnt lgkmcnt(8)
	v_mfma_f32_16x16x32_bf16 v[60:63], v[64:67], v[168:171], v[60:63]
	v_mfma_f32_16x16x32_bf16 v[48:51], v[68:71], v[168:171], v[48:51]
	ds_read_b128 v[196:199], v211 offset:18432
	s_waitcnt lgkmcnt(8)
	v_mfma_f32_16x16x32_bf16 v[20:23], v[64:67], v[172:175], v[20:23]
	v_mfma_f32_16x16x32_bf16 v[0:3], v[68:71], v[172:175], v[0:3]
	ds_read_b128 v[200:203], v211 offset:20480
	s_waitcnt lgkmcnt(8)
	v_mfma_f32_16x16x32_bf16 v[44:47], v[64:67], v[176:179], v[44:47]
	v_mfma_f32_16x16x32_bf16 v[36:39], v[68:71], v[176:179], v[36:39]
	ds_read_b128 v[204:207], v211 offset:22528
	s_waitcnt lgkmcnt(8)
	v_mfma_f32_16x16x32_bf16 v[24:27], v[64:67], v[180:183], v[24:27]
	v_mfma_f32_16x16x32_bf16 v[8:11], v[68:71], v[180:183], v[8:11]
	ds_read_b128 v[160:163], v211 offset:24576
	s_waitcnt lgkmcnt(8)
	v_mfma_f32_16x16x32_bf16 v[56:59], v[64:67], v[184:187], v[56:59]
	v_mfma_f32_16x16x32_bf16 v[32:35], v[68:71], v[184:187], v[32:35]
	ds_read_b128 v[164:167], v211 offset:26624
	s_waitcnt lgkmcnt(8)
	v_mfma_f32_16x16x32_bf16 v[12:15], v[64:67], v[188:191], v[12:15]
	v_mfma_f32_16x16x32_bf16 v[4:7], v[68:71], v[188:191], v[4:7]
	ds_read_b128 v[168:171], v211 offset:28672
	s_waitcnt lgkmcnt(6)
	v_mfma_f32_16x16x32_bf16 v[40:43], v[72:75], v[192:195], v[40:43]
	v_mfma_f32_16x16x32_bf16 v[52:55], v[76:79], v[192:195], v[52:55]
	ds_read_b128 v[172:175], v211 offset:30720
	s_waitcnt lgkmcnt(6)
	v_mfma_f32_16x16x32_bf16 v[28:31], v[72:75], v[196:199], v[28:31]
	v_mfma_f32_16x16x32_bf16 v[16:19], v[76:79], v[196:199], v[16:19]
	s_waitcnt lgkmcnt(5)
	v_mfma_f32_16x16x32_bf16 v[60:63], v[72:75], v[200:203], v[60:63]
	v_mfma_f32_16x16x32_bf16 v[48:51], v[76:79], v[200:203], v[48:51]
	s_waitcnt lgkmcnt(4)
	v_mfma_f32_16x16x32_bf16 v[20:23], v[72:75], v[204:207], v[20:23]
	v_mfma_f32_16x16x32_bf16 v[0:3], v[76:79], v[204:207], v[0:3]
	s_waitcnt lgkmcnt(3)
	v_mfma_f32_16x16x32_bf16 v[44:47], v[72:75], v[160:163], v[44:47]
	v_mfma_f32_16x16x32_bf16 v[36:39], v[76:79], v[160:163], v[36:39]
	s_waitcnt lgkmcnt(2)
	v_mfma_f32_16x16x32_bf16 v[24:27], v[72:75], v[164:167], v[24:27]
	v_mfma_f32_16x16x32_bf16 v[8:11], v[76:79], v[164:167], v[8:11]
	s_waitcnt lgkmcnt(1)
	v_mfma_f32_16x16x32_bf16 v[56:59], v[72:75], v[168:171], v[56:59]
	v_mfma_f32_16x16x32_bf16 v[32:35], v[76:79], v[168:171], v[32:35]
	s_waitcnt lgkmcnt(0)
	v_mfma_f32_16x16x32_bf16 v[12:15], v[72:75], v[172:175], v[12:15]
	v_mfma_f32_16x16x32_bf16 v[4:7], v[76:79], v[172:175], v[4:7]
	s_setprio 0
	s_mov_b32 s55, 0x8000
	v_add_u32_e32 v68, s55, v109
	v_add_u32_e32 v72, v68, v110
	s_waitcnt vmcnt(0)
	s_barrier
	ds_read_b128 v[64:67], v72
	v_add_u32_e32 v126, v68, v108
	ds_read_b128 v[68:71], v126 offset:16384
	ds_read_b128 v[80:83], v126 offset:20480
	ds_read_b128 v[142:145], v126 offset:24576
	s_ashr_i32 s54, s54, 5
	s_lshl_b32 s0, s53, 7
	s_waitcnt lgkmcnt(0)
	v_mfma_f32_16x16x32_bf16 v[160:163], v[64:67], v[68:71], v[40:43]
	s_mul_hi_i32 s38, s54, 0x3000
	s_nop 1
	ds_read_b128 v[40:43], v72 offset:2048
	v_add_u32_e32 v141, 0x400, v113
	v_mfma_f32_16x16x32_bf16 v[164:167], v[64:67], v[80:83], v[60:63]
	ds_read_b128 v[72:75], v126 offset:18432
	v_mfma_f32_16x16x32_bf16 v[168:171], v[64:67], v[142:145], v[44:47]
	s_nop 2
	ds_read_b128 v[44:47], v126 offset:22528
	s_waitcnt lgkmcnt(0)
	v_mfma_f32_16x16x32_bf16 v[52:55], v[40:43], v[68:71], v[52:55]
	ds_read_b128 v[76:79], v126 offset:26624
	v_mfma_f32_16x16x32_bf16 v[80:83], v[40:43], v[80:83], v[48:51]
	ds_read_b128 v[68:71], v126 offset:28672
	s_waitcnt lgkmcnt(0)
	v_mfma_f32_16x16x32_bf16 v[56:59], v[64:67], v[68:71], v[56:59]
	ds_read_b128 v[48:51], v126 offset:30720
	v_mfma_f32_16x16x32_bf16 v[142:145], v[40:43], v[142:145], v[36:39]
	s_nop 2
	v_add_u32_e32 v36, s55, v111
	v_add_u32_e32 v37, v36, v110
	ds_read_b128 v[60:63], v37
	v_mfma_f32_16x16x32_bf16 v[172:175], v[40:43], v[68:71], v[32:35]
	v_add_u32_e32 v126, v36, v108
	s_mul_i32 s55, s54, 0x3000
	s_add_u32 s39, s50, s55
	ds_read_b128 v[32:35], v37 offset:2048
	v_mfma_f32_16x16x32_bf16 v[176:179], v[64:67], v[72:75], v[28:31]
	s_addc_u32 s56, s51, s38
	s_lshl_b32 s53, s53, 9
	s_add_u32 s38, s39, s53
	ds_read_b128 v[28:31], v126 offset:16384
	s_waitcnt lgkmcnt(0)
	v_mfma_f32_16x16x32_bf16 v[160:163], v[60:63], v[28:31], v[160:163]
	ds_read_b128 v[180:183], v126 offset:18432
	s_addc_u32 s39, s56, 0
	v_mfma_f32_16x16x32_bf16 v[28:31], v[32:35], v[28:31], v[52:55]
	ds_read_b128 v[36:39], v126 offset:20480
	s_waitcnt lgkmcnt(0)
	v_mfma_f32_16x16x32_bf16 v[164:167], v[60:63], v[36:39], v[164:167]
	ds_read_b128 v[68:71], v126 offset:22528
	v_mfma_f32_16x16x32_bf16 v[36:39], v[32:35], v[36:39], v[80:83]
	ds_read_b128 v[52:55], v126 offset:24576
	s_waitcnt lgkmcnt(0)
	v_mfma_f32_16x16x32_bf16 v[168:171], v[60:63], v[52:55], v[168:171]
	ds_read_b128 v[184:187], v126 offset:26624
	v_mfma_f32_16x16x32_bf16 v[52:55], v[32:35], v[52:55], v[142:145]
	s_nop 2
	ds_read_b128 v[142:145], v126 offset:28672
	s_waitcnt lgkmcnt(0)
	v_mfma_f32_16x16x32_bf16 v[188:191], v[60:63], v[142:145], v[56:59]
	ds_read_b128 v[80:83], v126 offset:30720
	s_barrier
	v_mfma_f32_16x16x32_bf16 v[56:59], v[32:35], v[142:145], v[172:175]
	v_mfma_f32_16x16x32_bf16 v[24:27], v[64:67], v[76:79], v[24:27]
	v_mfma_f32_16x16x32_bf16 v[16:19], v[40:43], v[72:75], v[16:19]
	v_mfma_f32_16x16x32_bf16 v[8:11], v[40:43], v[76:79], v[8:11]
	v_mfma_f32_16x16x32_bf16 v[72:75], v[60:63], v[180:183], v[176:179]
	v_mfma_f32_16x16x32_bf16 v[24:27], v[60:63], v[184:187], v[24:27]
	v_mfma_f32_16x16x32_bf16 v[16:19], v[32:35], v[180:183], v[16:19]
	v_mfma_f32_16x16x32_bf16 v[8:11], v[32:35], v[184:187], v[8:11]
	v_mfma_f32_16x16x32_bf16 v[20:23], v[64:67], v[44:47], v[20:23]
	v_mfma_f32_16x16x32_bf16 v[12:15], v[64:67], v[48:51], v[12:15]
	v_lshl_add_u64 v[64:65], s[38:39], 0, v[84:85]
	s_add_i32 s38, s54, 4
	s_add_i32 s39, s55, 0xc000
	s_mul_hi_i32 s38, s38, 0x3000
	s_add_u32 s39, s50, s39
	s_addc_u32 s56, s51, s38
	v_lshl_add_u64 v[66:67], v[64:65], 0, s[30:31]
	v_add_co_u32_e32 v64, vcc, s47, v64
	s_add_u32 s38, s39, s53
	s_nop 0
	v_addc_co_u32_e32 v65, vcc, 0, v65, vcc
	s_addc_u32 s39, s56, 0
	v_mfma_f32_16x16x32_bf16 v[20:23], v[60:63], v[68:71], v[20:23]
	s_waitcnt lgkmcnt(0)
	v_mfma_f32_16x16x32_bf16 v[12:15], v[60:63], v[80:83], v[12:15]
	ds_write2_b32 v113, v160, v72 offset1:16
	global_load_dwordx4 v[60:63], v[64:65], off
	ds_write2_b32 v113, v161, v73 offset0:128 offset1:144
	v_lshl_add_u64 v[72:73], s[38:39], 0, v[84:85]
	s_add_i32 s38, s54, 8
	s_add_i32 s39, s55, 0x18000
	s_mul_hi_i32 s38, s38, 0x3000
	s_add_u32 s39, s50, s39
	s_addc_u32 s56, s51, s38
	v_lshl_add_u64 v[126:127], v[72:73], 0, s[30:31]
	v_add_co_u32_e32 v72, vcc, s47, v72
	s_add_u32 s38, s39, s53
	s_nop 0
	v_addc_co_u32_e32 v73, vcc, 0, v73, vcc
	s_addc_u32 s39, s56, 0
	global_load_dwordx4 v[64:67], v[66:67], off offset:16
	ds_write2_b32 v141, v162, v74 offset1:16
	global_load_dwordx4 v[76:79], v[72:73], off
	ds_write2_b32 v141, v163, v75 offset0:128 offset1:144
	global_load_dwordx4 v[72:75], v[126:127], off offset:16
	v_lshl_add_u64 v[126:127], s[38:39], 0, v[84:85]
	s_add_i32 s38, s54, 12
	s_add_i32 s39, s55, 0x24000
	s_mul_hi_i32 s38, s38, 0x3000
	s_add_u32 s39, s50, s39
	s_addc_u32 s56, s51, s38
	v_lshl_add_u64 v[146:147], v[126:127], 0, s[30:31]
	v_add_co_u32_e32 v126, vcc, s47, v126
	s_add_u32 s38, s39, s53
	s_nop 0
	v_addc_co_u32_e32 v127, vcc, 0, v127, vcc
	s_addc_u32 s39, s56, 0
	ds_write2_b32 v113, v164, v20 offset0:32 offset1:48
	global_load_dwordx4 v[142:145], v[126:127], off
	ds_write2_b32 v113, v165, v21 offset0:160 offset1:176
	v_lshl_add_u64 v[20:21], s[38:39], 0, v[84:85]
	s_add_i32 s38, s54, 16
	s_add_i32 s39, s55, 0x30000
	s_mul_hi_i32 s38, s38, 0x3000
	s_add_u32 s39, s50, s39
	s_addc_u32 s56, s51, s38
	v_lshl_add_u64 v[126:127], v[20:21], 0, s[30:31]
	v_add_co_u32_e32 v20, vcc, s47, v20
	s_add_u32 s38, s39, s53
	s_nop 0
	v_addc_co_u32_e32 v21, vcc, 0, v21, vcc
	s_addc_u32 s39, s56, 0
	global_load_dwordx4 v[160:163], v[146:147], off offset:16
	ds_write2_b32 v141, v166, v22 offset0:32 offset1:48
	global_load_dwordx4 v[172:175], v[20:21], off
	ds_write2_b32 v141, v167, v23 offset0:160 offset1:176
	global_load_dwordx4 v[20:23], v[126:127], off offset:16
	v_lshl_add_u64 v[126:127], s[38:39], 0, v[84:85]
	s_add_i32 s38, s54, 20
	s_add_i32 s39, s55, 0x3c000
	s_mul_hi_i32 s38, s38, 0x3000
	s_add_u32 s39, s50, s39
	s_addc_u32 s56, s51, s38
	v_lshl_add_u64 v[146:147], v[126:127], 0, s[30:31]
	v_add_co_u32_e32 v126, vcc, s47, v126
	s_add_u32 s38, s39, s53
	s_nop 0
	v_addc_co_u32_e32 v127, vcc, 0, v127, vcc
	s_addc_u32 s39, s56, 0
	ds_write2_b32 v113, v168, v24 offset0:64 offset1:80
	global_load_dwordx4 v[164:167], v[126:127], off
	ds_write2_b32 v113, v169, v25 offset0:192 offset1:208
	v_lshl_add_u64 v[24:25], s[38:39], 0, v[84:85]
	s_add_i32 s38, s54, 24
	s_add_i32 s39, s55, 0x48000
	s_mul_hi_i32 s38, s38, 0x3000
	s_add_u32 s39, s50, s39
	s_addc_u32 s56, s51, s38
	v_lshl_add_u64 v[126:127], v[24:25], 0, s[30:31]
	v_add_co_u32_e32 v24, vcc, s47, v24
	s_add_u32 s38, s39, s53
	s_nop 0
	v_addc_co_u32_e32 v25, vcc, 0, v25, vcc
	s_addc_u32 s39, s56, 0
	s_add_i32 s54, s54, 28
	s_add_i32 s55, s55, 0x54000
	global_load_dwordx4 v[176:179], v[146:147], off offset:16
	ds_write2_b32 v141, v170, v26 offset0:64 offset1:80
	global_load_dwordx4 v[180:183], v[24:25], off
	ds_write2_b32 v141, v171, v27 offset0:192 offset1:208
	global_load_dwordx4 v[24:27], v[126:127], off offset:16
	v_lshl_add_u64 v[126:127], s[38:39], 0, v[84:85]
	s_mul_hi_i32 s38, s54, 0x3000
	s_add_u32 s39, s50, s55
	s_addc_u32 s54, s51, s38
	v_lshl_add_u64 v[146:147], v[126:127], 0, s[30:31]
	v_add_co_u32_e32 v126, vcc, s47, v126
	s_add_u32 s38, s39, s53
	s_nop 0
	v_addc_co_u32_e32 v127, vcc, 0, v127, vcc
	s_addc_u32 s39, s54, 0
	ds_write2st64_b32 v114, v188, v189 offset1:2
	global_load_dwordx4 v[168:171], v[126:127], off
	v_lshl_add_u64 v[126:127], s[38:39], 0, v[84:85]
	ds_write2st64_b32 v114, v190, v191 offset0:4 offset1:6
	global_load_dwordx4 v[184:187], v[146:147], off offset:16
	v_lshl_add_u64 v[146:147], v[126:127], 0, s[30:31]
	v_add_co_u32_e32 v126, vcc, s47, v126
	ds_write2st64_b32 v115, v12, v13 offset1:2
	s_nop 0
	v_addc_co_u32_e32 v127, vcc, 0, v127, vcc
	global_load_dwordx4 v[188:191], v[126:127], off
	ds_write2st64_b32 v115, v14, v15 offset0:4 offset1:6
	global_load_dwordx4 v[12:15], v[146:147], off offset:16
	v_mfma_f32_16x16x32_bf16 v[0:3], v[40:43], v[44:47], v[0:3]
	s_lshl_b64 s[34:35], s[34:35], 17
	s_add_i32 s52, s52, s3
	v_mfma_f32_16x16x32_bf16 v[4:7], v[40:43], v[48:51], v[4:7]
	s_add_i32 s33, s33, s46
	s_cmpk_gt_i32 s52, 0x3ff
	v_mfma_f32_16x16x32_bf16 v[68:71], v[32:35], v[68:71], v[0:3]
	s_nop 2
	v_lshl_add_u64 v[0:1], s[34:35], 0, v[90:91]
	v_or_b32_e32 v0, s0, v0
	v_lshlrev_b64 v[126:127], 2, v[0:1]
	v_lshl_add_u64 v[0:1], s[68:69], 0, v[126:127]
	v_mfma_f32_16x16x32_bf16 v[32:35], v[32:35], v[80:83], v[4:7]
	ds_read_b128 v[80:83], v112
	ds_read_b128 v[204:207], v112 offset:16
	ds_read_b128 v[200:203], v116
	ds_read_b128 v[192:195], v118 offset:16
	ds_read_b128 v[196:199], v118
	ds_read_b128 v[44:47], v117 offset:16
	ds_read_b128 v[40:43], v117
	ds_read_b128 v[48:51], v116 offset:16
	global_load_dwordx4 v[208:211], v[0:1], off offset:16 nt
	global_load_dwordx4 v[212:215], v[0:1], off nt
	s_waitcnt vmcnt(0)
	v_pk_add_f32 v[0:1], v[62:63], 0 op_sel_hi:[1,0]
	v_pk_add_f32 v[2:3], v[60:61], 0 op_sel_hi:[1,0]
	v_pk_add_f32 v[4:5], v[66:67], 0 op_sel_hi:[1,0]
	v_pk_add_f32 v[6:7], v[64:65], 0 op_sel_hi:[1,0]
	v_pk_add_f32 v[0:1], v[0:1], v[78:79]
	v_pk_add_f32 v[2:3], v[2:3], v[76:77]
	v_pk_add_f32 v[4:5], v[4:5], v[74:75]
	v_pk_add_f32 v[6:7], v[6:7], v[72:73]
	v_pk_add_f32 v[0:1], v[0:1], v[144:145]
	v_pk_add_f32 v[2:3], v[2:3], v[142:143]
	v_pk_add_f32 v[4:5], v[4:5], v[162:163]
	v_pk_add_f32 v[6:7], v[6:7], v[160:161]
	v_pk_add_f32 v[0:1], v[0:1], v[174:175]
	v_pk_add_f32 v[2:3], v[2:3], v[172:173]
	v_pk_add_f32 v[4:5], v[4:5], v[22:23]
	v_pk_add_f32 v[6:7], v[6:7], v[20:21]
	v_pk_add_f32 v[0:1], v[0:1], v[166:167]
	v_pk_add_f32 v[2:3], v[2:3], v[164:165]
	v_pk_add_f32 v[4:5], v[4:5], v[178:179]
	v_pk_add_f32 v[6:7], v[6:7], v[176:177]
	v_pk_add_f32 v[0:1], v[0:1], v[182:183]
	v_pk_add_f32 v[2:3], v[2:3], v[180:181]
	v_pk_add_f32 v[4:5], v[4:5], v[26:27]
	v_pk_add_f32 v[6:7], v[6:7], v[24:25]
	v_lshl_add_u64 v[24:25], s[48:49], 0, v[126:127]
	v_lshl_add_u64 v[26:27], s[34:35], 0, v[96:97]
	v_or_b32_e32 v26, s0, v26
	v_lshlrev_b64 v[26:27], 2, v[26:27]
	v_pk_add_f32 v[0:1], v[0:1], v[170:171]
	v_pk_add_f32 v[2:3], v[2:3], v[168:169]
	v_pk_add_f32 v[4:5], v[4:5], v[186:187]
	v_pk_add_f32 v[6:7], v[6:7], v[184:185]
	v_pk_add_f32 v[0:1], v[0:1], v[190:191]
	v_pk_add_f32 v[2:3], v[2:3], v[188:189]
	v_pk_add_f32 v[4:5], v[4:5], v[14:15]
	v_pk_add_f32 v[6:7], v[6:7], v[12:13]
	s_waitcnt lgkmcnt(6)
	v_pk_fma_f32 v[22:23], v[4:5], v[206:207], v[210:211]
	v_pk_fma_f32 v[14:15], v[0:1], v[82:83], v[214:215]
	v_pk_fma_f32 v[12:13], v[2:3], v[80:81], v[212:213]
	global_store_dwordx4 v[24:25], v[12:15], off
	v_pk_fma_f32 v[20:21], v[6:7], v[204:205], v[208:209]
	global_store_dwordx4 v[24:25], v[20:23], off offset:16
	v_lshl_add_u64 v[12:13], s[34:35], 0, v[92:93]
	v_or_b32_e32 v12, s0, v12
	v_lshlrev_b64 v[24:25], 2, v[12:13]
	v_lshl_add_u64 v[20:21], s[68:69], 0, v[24:25]
	global_load_dwordx4 v[12:15], v[20:21], off offset:16 nt
	v_lshl_add_u64 v[24:25], s[48:49], 0, v[24:25]
	global_load_dwordx4 v[20:23], v[20:21], off nt
	s_waitcnt vmcnt(1) lgkmcnt(0)
	v_pk_fma_f32 v[14:15], v[4:5], v[50:51], v[14:15]
	v_pk_fma_f32 v[12:13], v[6:7], v[48:49], v[12:13]
	global_store_dwordx4 v[24:25], v[12:15], off offset:16
	s_waitcnt vmcnt(1)
	v_pk_fma_f32 v[22:23], v[0:1], v[202:203], v[22:23]
	v_pk_fma_f32 v[20:21], v[2:3], v[200:201], v[20:21]
	v_lshl_add_u64 v[12:13], s[34:35], 0, v[94:95]
	v_or_b32_e32 v12, s0, v12
	global_store_dwordx4 v[24:25], v[20:23], off
	v_lshlrev_b64 v[24:25], 2, v[12:13]
	v_lshl_add_u64 v[48:49], s[68:69], 0, v[26:27]
	v_lshl_add_u64 v[20:21], s[68:69], 0, v[24:25]
	global_load_dwordx4 v[12:15], v[20:21], off offset:16 nt
	v_lshl_add_u64 v[24:25], s[48:49], 0, v[24:25]
	global_load_dwordx4 v[20:23], v[20:21], off nt
	v_lshl_add_u64 v[50:51], s[34:35], 0, v[100:101]
	v_or_b32_e32 v50, s0, v50
	v_lshlrev_b64 v[50:51], 2, v[50:51]
	s_waitcnt vmcnt(1)
	v_pk_fma_f32 v[14:15], v[4:5], v[46:47], v[14:15]
	v_pk_fma_f32 v[12:13], v[6:7], v[44:45], v[12:13]
	s_waitcnt vmcnt(0)
	v_pk_fma_f32 v[22:23], v[0:1], v[42:43], v[22:23]
	v_pk_fma_f32 v[20:21], v[2:3], v[40:41], v[20:21]
	global_store_dwordx4 v[24:25], v[20:23], off
	global_store_dwordx4 v[24:25], v[12:15], off offset:16
	global_load_dwordx4 v[12:15], v[48:49], off offset:16 nt
	v_lshl_add_u64 v[24:25], s[34:35], 0, v[98:99]
	global_load_dwordx4 v[20:23], v[48:49], off nt
	v_or_b32_e32 v24, s0, v24
	v_lshlrev_b64 v[48:49], 2, v[24:25]
	v_lshl_add_u64 v[24:25], s[48:49], 0, v[26:27]
	v_lshl_add_u64 v[44:45], s[68:69], 0, v[48:49]
	v_lshl_add_u64 v[48:49], s[48:49], 0, v[48:49]
	s_waitcnt vmcnt(1)
	v_pk_fma_f32 v[14:15], v[4:5], v[194:195], v[14:15]
	v_pk_fma_f32 v[12:13], v[6:7], v[192:193], v[12:13]
	s_waitcnt vmcnt(0)
	v_pk_fma_f32 v[22:23], v[0:1], v[198:199], v[22:23]
	v_pk_fma_f32 v[20:21], v[2:3], v[196:197], v[20:21]
	global_store_dwordx4 v[24:25], v[20:23], off
	global_store_dwordx4 v[24:25], v[12:15], off offset:16
	ds_write2_b32 v113, v28, v16 offset1:16
	ds_write2_b32 v113, v29, v17 offset0:128 offset1:144
	ds_write2_b32 v141, v30, v18 offset1:16
	ds_write2_b32 v141, v31, v19 offset0:128 offset1:144
	ds_write2_b32 v113, v36, v68 offset0:32 offset1:48
	ds_write2_b32 v113, v37, v69 offset0:160 offset1:176
	ds_write2_b32 v141, v38, v70 offset0:32 offset1:48
	ds_write2_b32 v141, v39, v71 offset0:160 offset1:176
	ds_write2_b32 v113, v52, v8 offset0:64 offset1:80
	ds_write2_b32 v113, v53, v9 offset0:192 offset1:208
	ds_write2_b32 v141, v54, v10 offset0:64 offset1:80
	ds_write2_b32 v141, v55, v11 offset0:192 offset1:208
	ds_write2st64_b32 v114, v56, v57 offset1:2
	ds_write2st64_b32 v114, v58, v59 offset0:4 offset1:6
	ds_write2st64_b32 v115, v32, v33 offset1:2
	ds_write2st64_b32 v115, v34, v35 offset0:4 offset1:6
	ds_read_b128 v[36:39], v112
	ds_read_b128 v[32:35], v112 offset:16
	ds_read_b128 v[28:31], v116
	ds_read_b128 v[24:27], v116 offset:16
	ds_read_b128 v[20:23], v117
	ds_read_b128 v[16:19], v117 offset:16
	ds_read_b128 v[12:15], v118
	ds_read_b128 v[8:11], v118 offset:16
	global_load_dwordx4 v[40:43], v[44:45], off offset:16 nt
	v_lshl_add_u64 v[52:53], s[68:69], 0, v[50:51]
	global_load_dwordx4 v[44:47], v[44:45], off nt
	s_waitcnt vmcnt(1) lgkmcnt(6)
	v_pk_fma_f32 v[34:35], v[4:5], v[34:35], v[42:43]
	v_pk_fma_f32 v[32:33], v[6:7], v[32:33], v[40:41]
	s_waitcnt vmcnt(0)
	v_pk_fma_f32 v[38:39], v[0:1], v[38:39], v[46:47]
	v_pk_fma_f32 v[36:37], v[2:3], v[36:37], v[44:45]
	global_store_dwordx4 v[48:49], v[36:39], off
	global_store_dwordx4 v[48:49], v[32:35], off offset:16
	global_load_dwordx4 v[32:35], v[52:53], off offset:16 nt
	v_lshl_add_u64 v[40:41], s[34:35], 0, v[102:103]
	global_load_dwordx4 v[36:39], v[52:53], off nt
	v_or_b32_e32 v40, s0, v40
	v_lshlrev_b64 v[40:41], 2, v[40:41]
	v_lshl_add_u64 v[42:43], s[48:49], 0, v[50:51]
	v_lshl_add_u64 v[44:45], s[68:69], 0, v[40:41]
	s_waitcnt vmcnt(1) lgkmcnt(4)
	v_pk_fma_f32 v[26:27], v[4:5], v[26:27], v[34:35]
	v_pk_fma_f32 v[24:25], v[6:7], v[24:25], v[32:33]
	s_waitcnt vmcnt(0)
	v_pk_fma_f32 v[30:31], v[0:1], v[30:31], v[38:39]
	v_pk_fma_f32 v[28:29], v[2:3], v[28:29], v[36:37]
	global_store_dwordx4 v[42:43], v[28:31], off
	global_store_dwordx4 v[42:43], v[24:27], off offset:16
	global_load_dwordx4 v[24:27], v[44:45], off offset:16 nt
	v_lshl_add_u64 v[32:33], s[34:35], 0, v[104:105]
	global_load_dwordx4 v[28:31], v[44:45], off nt
	v_or_b32_e32 v32, s0, v32
	v_lshlrev_b64 v[32:33], 2, v[32:33]
	v_lshl_add_u64 v[34:35], s[48:49], 0, v[40:41]
	v_lshl_add_u64 v[36:37], s[68:69], 0, v[32:33]
	s_waitcnt vmcnt(1) lgkmcnt(2)
	v_pk_fma_f32 v[18:19], v[4:5], v[18:19], v[26:27]
	v_pk_fma_f32 v[16:17], v[6:7], v[16:17], v[24:25]
	s_waitcnt vmcnt(0)
	v_pk_fma_f32 v[22:23], v[0:1], v[22:23], v[30:31]
	v_pk_fma_f32 v[20:21], v[2:3], v[20:21], v[28:29]
	global_store_dwordx4 v[34:35], v[20:23], off
	global_store_dwordx4 v[34:35], v[16:19], off offset:16
	global_load_dwordx4 v[16:19], v[36:37], off offset:16 nt
	v_lshl_add_u64 v[24:25], s[48:49], 0, v[32:33]
	global_load_dwordx4 v[20:23], v[36:37], off nt
	s_waitcnt vmcnt(0) lgkmcnt(1)
	v_pk_fma_f32 v[14:15], v[0:1], v[14:15], v[22:23]
	v_pk_fma_f32 v[12:13], v[2:3], v[12:13], v[20:21]
	s_waitcnt lgkmcnt(0)
	v_pk_fma_f32 v[2:3], v[4:5], v[10:11], v[18:19]
	v_pk_fma_f32 v[0:1], v[6:7], v[8:9], v[16:17]
	global_store_dwordx4 v[24:25], v[12:15], off
	global_store_dwordx4 v[24:25], v[0:3], off offset:16
	s_cbranch_scc0 .LBB0_315

.LBB0_686:
	s_ashr_i32 s28, s2, 31
	s_lshr_b32 s28, s28, 23
	s_add_i32 s28, s2, s28
	s_ashr_i32 s28, s28, 9
	s_lshl_b32 s30, s28, 6
	s_lshl_b32 s28, s2, 3
	s_and_b32 s28, s28, 56
	s_or_b32 s39, s30, s28
	s_bfe_u32 s31, s2, 0x30003
	s_or_b32 s28, s39, s31
	s_ashr_i32 s29, s28, 31
	s_lshl_b64 s[28:29], s[28:29], 19
	v_readfirstlane_b32 s40, v129
	v_lshl_add_u64 v[0:1], v[78:79], 0, s[28:29]
	s_mov_b32 m0, s40
	v_readfirstlane_b32 s40, v111
	s_barrier
	s_setprio 2
	s_bfe_u32 s38, s2, 0x30006
	s_add_u32 s98, s28, s50
	s_addc_u32 s99, s29, s51
	s_add_u32 s98, s98, 0x5a00000
	s_addc_u32 s99, s99, 0
	s_lshl_b32 s100, s38, 19
	s_add_u32 s100, s100, s50
	s_addc_u32 s101, s51, 0
	s_add_u32 s100, s100, 0xc00000
	s_addc_u32 s101, s101, 0
	v_readfirstlane_b32 s41, v129
	v_lshrrev_b32_e32 v124, 4, v129
	v_and_b32_e32 v120, 15, v124
	v_bfe_u32 v121, v124, 4, 2
	v_bfe_u32 v122, v124, 1, 3
	v_xor_b32_e32 v122, v121, v122
	v_lshlrev_b32_e32 v122, 4, v122
	v_lshl_or_b32 v210, v120, 7, v122
	v_xor_b32_e32 v211, 64, v210
	v_lshrrev_b32_e32 v122, 6, v124
	v_lshl_add_u32 v208, v122, 12, v210
	v_lshl_add_u32 v209, v122, 12, v211
	v_bfe_u32 v120, v124, 4, 3
	v_and_b32_e32 v121, 7, v124
	v_xor_b32_e32 v120, v120, v121
	v_lshlrev_b32_e32 v120, 4, v120
	v_lshrrev_b32_e32 v121, 3, v124
	v_lshl_or_b32 v212, v121, 12, v120
	v_add_u32_e32 v213, 131072, v212
	v_add_u32_e32 v214, 262144, v212
	v_add_u32_e32 v215, 393216, v212
	s_add_u32 m0, s41, 0
	v_mov_b32_e32 v44, 0
	v_mov_b32_e32 v45, 0
	global_load_lds_dwordx4 v212, s[98:99]
	s_add_u32 m0, s41, 4096
	v_mov_b32_e32 v46, 0
	v_mov_b32_e32 v47, 0
	global_load_lds_dwordx4 v213, s[98:99]
	s_add_u32 m0, s41, 8192
	v_mov_b32_e32 v28, 0
	v_mov_b32_e32 v29, 0
	global_load_lds_dwordx4 v214, s[98:99]
	s_add_u32 m0, s41, 12288
	v_mov_b32_e32 v30, 0
	v_mov_b32_e32 v31, 0
	global_load_lds_dwordx4 v215, s[98:99]
	s_add_u32 s98, s98, 128
	s_addc_u32 s99, s99, 0
	s_add_u32 m0, s41, 16384
	v_mov_b32_e32 v60, 0
	v_mov_b32_e32 v61, 0
	global_load_lds_dwordx4 v212, s[100:101]
	s_add_u32 m0, s41, 20480
	v_mov_b32_e32 v62, 0
	v_mov_b32_e32 v63, 0
	global_load_lds_dwordx4 v213, s[100:101]
	s_add_u32 m0, s41, 24576
	v_mov_b32_e32 v20, 0
	v_mov_b32_e32 v21, 0
	global_load_lds_dwordx4 v214, s[100:101]
	s_add_u32 m0, s41, 28672
	v_mov_b32_e32 v22, 0
	v_mov_b32_e32 v23, 0
	global_load_lds_dwordx4 v215, s[100:101]
	s_add_u32 s100, s100, 128
	s_addc_u32 s101, s101, 0
	s_add_u32 m0, s41, 32768
	v_mov_b32_e32 v52, 0
	v_mov_b32_e32 v53, 0
	global_load_lds_dwordx4 v212, s[98:99]
	s_add_u32 m0, s41, 36864
	v_mov_b32_e32 v54, 0
	v_mov_b32_e32 v55, 0
	global_load_lds_dwordx4 v213, s[98:99]
	s_add_u32 m0, s41, 40960
	v_mov_b32_e32 v24, 0
	v_mov_b32_e32 v25, 0
	global_load_lds_dwordx4 v214, s[98:99]
	s_add_u32 m0, s41, 45056
	v_mov_b32_e32 v26, 0
	v_mov_b32_e32 v27, 0
	global_load_lds_dwordx4 v215, s[98:99]
	s_add_u32 s98, s98, 128
	s_addc_u32 s99, s99, 0
	s_add_u32 m0, s41, 49152
	v_mov_b32_e32 v56, 0
	v_mov_b32_e32 v57, 0
	global_load_lds_dwordx4 v212, s[100:101]
	s_add_u32 m0, s41, 53248
	v_mov_b32_e32 v58, 0
	v_mov_b32_e32 v59, 0
	global_load_lds_dwordx4 v213, s[100:101]
	s_add_u32 m0, s41, 57344
	v_mov_b32_e32 v12, 0
	v_mov_b32_e32 v13, 0
	global_load_lds_dwordx4 v214, s[100:101]
	s_add_u32 m0, s41, 61440
	v_mov_b32_e32 v14, 0
	v_mov_b32_e32 v15, 0
	global_load_lds_dwordx4 v215, s[100:101]
	s_add_u32 s100, s100, 128
	s_addc_u32 s101, s101, 0
	v_mov_b32_e32 v48, 0
	v_mov_b32_e32 v49, 0
	v_mov_b32_e32 v50, 0
	v_mov_b32_e32 v51, 0
	v_mov_b32_e32 v16, 0
	v_mov_b32_e32 v17, 0
	v_mov_b32_e32 v18, 0
	v_mov_b32_e32 v19, 0
	v_mov_b32_e32 v40, 0
	v_mov_b32_e32 v41, 0
	v_mov_b32_e32 v42, 0
	v_mov_b32_e32 v43, 0
	v_mov_b32_e32 v0, 0
	v_mov_b32_e32 v1, 0
	v_mov_b32_e32 v2, 0
	v_mov_b32_e32 v3, 0
	v_mov_b32_e32 v36, 0
	v_mov_b32_e32 v37, 0
	v_mov_b32_e32 v38, 0
	v_mov_b32_e32 v39, 0
	v_mov_b32_e32 v8, 0
	v_mov_b32_e32 v9, 0
	v_mov_b32_e32 v10, 0
	v_mov_b32_e32 v11, 0
	v_mov_b32_e32 v32, 0
	v_mov_b32_e32 v33, 0
	v_mov_b32_e32 v34, 0
	v_mov_b32_e32 v35, 0
	v_mov_b32_e32 v4, 0
	v_mov_b32_e32 v5, 0
	v_mov_b32_e32 v6, 0
	v_mov_b32_e32 v7, 0
	s_waitcnt vmcnt(8)
	s_barrier
	ds_read_b128 v[64:67], v208 offset:0
	ds_read_b128 v[68:71], v208 offset:2048
	ds_read_b128 v[160:163], v210 offset:16384
	ds_read_b128 v[164:167], v210 offset:18432
	ds_read_b128 v[168:171], v210 offset:20480
	ds_read_b128 v[172:175], v210 offset:22528
	ds_read_b128 v[176:179], v210 offset:24576
	ds_read_b128 v[180:183], v210 offset:26624
	ds_read_b128 v[184:187], v210 offset:28672
	s_waitcnt lgkmcnt(6)
	v_mfma_f32_16x16x32_bf16 v[44:47], v[64:67], v[160:163], v[44:47]
	v_mfma_f32_16x16x32_bf16 v[48:51], v[68:71], v[160:163], v[48:51]
	ds_read_b128 v[188:191], v210 offset:30720
	s_waitcnt lgkmcnt(6)
	v_mfma_f32_16x16x32_bf16 v[28:31], v[64:67], v[164:167], v[28:31]
	v_mfma_f32_16x16x32_bf16 v[16:19], v[68:71], v[164:167], v[16:19]
	ds_read_b128 v[72:75], v209 offset:0
	ds_read_b128 v[216:219], v209 offset:2048
	ds_read_b128 v[192:195], v211 offset:16384
	s_waitcnt lgkmcnt(8)
	v_mfma_f32_16x16x32_bf16 v[60:63], v[64:67], v[168:171], v[60:63]
	v_mfma_f32_16x16x32_bf16 v[40:43], v[68:71], v[168:171], v[40:43]
	ds_read_b128 v[196:199], v211 offset:18432
	s_waitcnt lgkmcnt(8)
	v_mfma_f32_16x16x32_bf16 v[20:23], v[64:67], v[172:175], v[20:23]
	v_mfma_f32_16x16x32_bf16 v[0:3], v[68:71], v[172:175], v[0:3]
	ds_read_b128 v[200:203], v211 offset:20480
	s_waitcnt lgkmcnt(8)
	v_mfma_f32_16x16x32_bf16 v[52:55], v[64:67], v[176:179], v[52:55]
	v_mfma_f32_16x16x32_bf16 v[36:39], v[68:71], v[176:179], v[36:39]
	ds_read_b128 v[204:207], v211 offset:22528
	s_waitcnt lgkmcnt(8)
	v_mfma_f32_16x16x32_bf16 v[24:27], v[64:67], v[180:183], v[24:27]
	v_mfma_f32_16x16x32_bf16 v[8:11], v[68:71], v[180:183], v[8:11]
	ds_read_b128 v[160:163], v211 offset:24576
	s_waitcnt lgkmcnt(8)
	v_mfma_f32_16x16x32_bf16 v[56:59], v[64:67], v[184:187], v[56:59]
	v_mfma_f32_16x16x32_bf16 v[32:35], v[68:71], v[184:187], v[32:35]
	ds_read_b128 v[164:167], v211 offset:26624
	s_waitcnt lgkmcnt(8)
	v_mfma_f32_16x16x32_bf16 v[12:15], v[64:67], v[188:191], v[12:15]
	v_mfma_f32_16x16x32_bf16 v[4:7], v[68:71], v[188:191], v[4:7]
	ds_read_b128 v[168:171], v211 offset:28672
	s_waitcnt lgkmcnt(6)
	v_mfma_f32_16x16x32_bf16 v[44:47], v[72:75], v[192:195], v[44:47]
	v_mfma_f32_16x16x32_bf16 v[48:51], v[216:219], v[192:195], v[48:51]
	ds_read_b128 v[172:175], v211 offset:30720
	s_waitcnt vmcnt(0) lgkmcnt(0)
	s_barrier
	s_add_u32 m0, s41, 0
	s_nop 0
	global_load_lds_dwordx4 v212, s[98:99]
	s_waitcnt lgkmcnt(6)
	v_mfma_f32_16x16x32_bf16 v[28:31], v[72:75], v[196:199], v[28:31]
	v_mfma_f32_16x16x32_bf16 v[16:19], v[216:219], v[196:199], v[16:19]
	ds_read_b128 v[64:67], v208 offset:32768
	ds_read_b128 v[68:71], v208 offset:34816
	ds_read_b128 v[176:179], v210 offset:49152
	s_add_u32 m0, s41, 4096
	s_nop 0
	global_load_lds_dwordx4 v213, s[98:99]
	s_waitcnt lgkmcnt(8)
	v_mfma_f32_16x16x32_bf16 v[60:63], v[72:75], v[200:203], v[60:63]
	v_mfma_f32_16x16x32_bf16 v[40:43], v[216:219], v[200:203], v[40:43]
	ds_read_b128 v[180:183], v210 offset:51200
	s_add_u32 m0, s41, 8192
	s_nop 0
	global_load_lds_dwordx4 v214, s[98:99]
	s_waitcnt lgkmcnt(8)
	v_mfma_f32_16x16x32_bf16 v[20:23], v[72:75], v[204:207], v[20:23]
	v_mfma_f32_16x16x32_bf16 v[0:3], v[216:219], v[204:207], v[0:3]
	ds_read_b128 v[184:187], v210 offset:53248
	s_add_u32 m0, s41, 12288
	s_nop 0
	global_load_lds_dwordx4 v215, s[98:99]
	s_add_u32 s98, s98, 128
	s_addc_u32 s99, s99, 0
	s_waitcnt lgkmcnt(8)
	v_mfma_f32_16x16x32_bf16 v[52:55], v[72:75], v[160:163], v[52:55]
	v_mfma_f32_16x16x32_bf16 v[36:39], v[216:219], v[160:163], v[36:39]
	ds_read_b128 v[188:191], v210 offset:55296
	s_add_u32 m0, s41, 16384
	s_nop 0
	global_load_lds_dwordx4 v212, s[100:101]
	s_waitcnt lgkmcnt(8)
	v_mfma_f32_16x16x32_bf16 v[24:27], v[72:75], v[164:167], v[24:27]
	v_mfma_f32_16x16x32_bf16 v[8:11], v[216:219], v[164:167], v[8:11]
	ds_read_b128 v[192:195], v210 offset:57344
	s_add_u32 m0, s41, 20480
	s_nop 0
	global_load_lds_dwordx4 v213, s[100:101]
	s_waitcnt lgkmcnt(8)
	v_mfma_f32_16x16x32_bf16 v[56:59], v[72:75], v[168:171], v[56:59]
	v_mfma_f32_16x16x32_bf16 v[32:35], v[216:219], v[168:171], v[32:35]
	ds_read_b128 v[196:199], v210 offset:59392
	s_add_u32 m0, s41, 24576
	s_nop 0
	global_load_lds_dwordx4 v214, s[100:101]
	s_waitcnt lgkmcnt(8)
	v_mfma_f32_16x16x32_bf16 v[12:15], v[72:75], v[172:175], v[12:15]
	v_mfma_f32_16x16x32_bf16 v[4:7], v[216:219], v[172:175], v[4:7]
	ds_read_b128 v[200:203], v210 offset:61440
	s_add_u32 m0, s41, 28672
	s_nop 0
	global_load_lds_dwordx4 v215, s[100:101]
	s_add_u32 s100, s100, 128
	s_addc_u32 s101, s101, 0
	s_waitcnt lgkmcnt(6)
	v_mfma_f32_16x16x32_bf16 v[44:47], v[64:67], v[176:179], v[44:47]
	v_mfma_f32_16x16x32_bf16 v[48:51], v[68:71], v[176:179], v[48:51]
	ds_read_b128 v[204:207], v210 offset:63488
	s_waitcnt lgkmcnt(6)
	v_mfma_f32_16x16x32_bf16 v[28:31], v[64:67], v[180:183], v[28:31]
	v_mfma_f32_16x16x32_bf16 v[16:19], v[68:71], v[180:183], v[16:19]
	ds_read_b128 v[72:75], v209 offset:32768
	ds_read_b128 v[216:219], v209 offset:34816
	ds_read_b128 v[160:163], v211 offset:49152
	s_waitcnt lgkmcnt(8)
	v_mfma_f32_16x16x32_bf16 v[60:63], v[64:67], v[184:187], v[60:63]
	v_mfma_f32_16x16x32_bf16 v[40:43], v[68:71], v[184:187], v[40:43]
	ds_read_b128 v[164:167], v211 offset:51200
	s_waitcnt lgkmcnt(8)
	v_mfma_f32_16x16x32_bf16 v[20:23], v[64:67], v[188:191], v[20:23]
	v_mfma_f32_16x16x32_bf16 v[0:3], v[68:71], v[188:191], v[0:3]
	ds_read_b128 v[168:171], v211 offset:53248
	s_waitcnt lgkmcnt(8)
	v_mfma_f32_16x16x32_bf16 v[52:55], v[64:67], v[192:195], v[52:55]
	v_mfma_f32_16x16x32_bf16 v[36:39], v[68:71], v[192:195], v[36:39]
	ds_read_b128 v[172:175], v211 offset:55296
	s_waitcnt lgkmcnt(8)
	v_mfma_f32_16x16x32_bf16 v[24:27], v[64:67], v[196:199], v[24:27]
	v_mfma_f32_16x16x32_bf16 v[8:11], v[68:71], v[196:199], v[8:11]
	ds_read_b128 v[176:179], v211 offset:57344
	s_waitcnt lgkmcnt(8)
	v_mfma_f32_16x16x32_bf16 v[56:59], v[64:67], v[200:203], v[56:59]
	v_mfma_f32_16x16x32_bf16 v[32:35], v[68:71], v[200:203], v[32:35]
	ds_read_b128 v[180:183], v211 offset:59392
	s_waitcnt lgkmcnt(8)
	v_mfma_f32_16x16x32_bf16 v[12:15], v[64:67], v[204:207], v[12:15]
	v_mfma_f32_16x16x32_bf16 v[4:7], v[68:71], v[204:207], v[4:7]
	ds_read_b128 v[184:187], v211 offset:61440
	s_waitcnt lgkmcnt(6)
	v_mfma_f32_16x16x32_bf16 v[44:47], v[72:75], v[160:163], v[44:47]
	v_mfma_f32_16x16x32_bf16 v[48:51], v[216:219], v[160:163], v[48:51]
	ds_read_b128 v[188:191], v211 offset:63488
	s_waitcnt vmcnt(0) lgkmcnt(0)
	s_barrier
	s_add_u32 m0, s41, 32768
	s_nop 0
	global_load_lds_dwordx4 v212, s[98:99]
	s_waitcnt lgkmcnt(6)
	v_mfma_f32_16x16x32_bf16 v[28:31], v[72:75], v[164:167], v[28:31]
	v_mfma_f32_16x16x32_bf16 v[16:19], v[216:219], v[164:167], v[16:19]
	ds_read_b128 v[64:67], v208 offset:0
	ds_read_b128 v[68:71], v208 offset:2048
	ds_read_b128 v[192:195], v210 offset:16384
	s_add_u32 m0, s41, 36864
	s_nop 0
	global_load_lds_dwordx4 v213, s[98:99]
	s_waitcnt lgkmcnt(8)
	v_mfma_f32_16x16x32_bf16 v[60:63], v[72:75], v[168:171], v[60:63]
	v_mfma_f32_16x16x32_bf16 v[40:43], v[216:219], v[168:171], v[40:43]
	ds_read_b128 v[196:199], v210 offset:18432
	s_add_u32 m0, s41, 40960
	s_nop 0
	global_load_lds_dwordx4 v214, s[98:99]
	s_waitcnt lgkmcnt(8)
	v_mfma_f32_16x16x32_bf16 v[20:23], v[72:75], v[172:175], v[20:23]
	v_mfma_f32_16x16x32_bf16 v[0:3], v[216:219], v[172:175], v[0:3]
	ds_read_b128 v[200:203], v210 offset:20480
	s_add_u32 m0, s41, 45056
	s_nop 0
	global_load_lds_dwordx4 v215, s[98:99]
	s_add_u32 s98, s98, 128
	s_addc_u32 s99, s99, 0
	s_waitcnt lgkmcnt(8)
	v_mfma_f32_16x16x32_bf16 v[52:55], v[72:75], v[176:179], v[52:55]
	v_mfma_f32_16x16x32_bf16 v[36:39], v[216:219], v[176:179], v[36:39]
	ds_read_b128 v[204:207], v210 offset:22528
	s_add_u32 m0, s41, 49152
	s_nop 0
	global_load_lds_dwordx4 v212, s[100:101]
	s_waitcnt lgkmcnt(8)
	v_mfma_f32_16x16x32_bf16 v[24:27], v[72:75], v[180:183], v[24:27]
	v_mfma_f32_16x16x32_bf16 v[8:11], v[216:219], v[180:183], v[8:11]
	ds_read_b128 v[160:163], v210 offset:24576
	s_add_u32 m0, s41, 53248
	s_nop 0
	global_load_lds_dwordx4 v213, s[100:101]
	s_waitcnt lgkmcnt(8)
	v_mfma_f32_16x16x32_bf16 v[56:59], v[72:75], v[184:187], v[56:59]
	v_mfma_f32_16x16x32_bf16 v[32:35], v[216:219], v[184:187], v[32:35]
	ds_read_b128 v[164:167], v210 offset:26624
	s_add_u32 m0, s41, 57344
	s_nop 0
	global_load_lds_dwordx4 v214, s[100:101]
	s_waitcnt lgkmcnt(8)
	v_mfma_f32_16x16x32_bf16 v[12:15], v[72:75], v[188:191], v[12:15]
	v_mfma_f32_16x16x32_bf16 v[4:7], v[216:219], v[188:191], v[4:7]
	ds_read_b128 v[168:171], v210 offset:28672
	s_add_u32 m0, s41, 61440
	s_nop 0
	global_load_lds_dwordx4 v215, s[100:101]
	s_add_u32 s100, s100, 128
	s_addc_u32 s101, s101, 0
	s_waitcnt lgkmcnt(6)
	v_mfma_f32_16x16x32_bf16 v[44:47], v[64:67], v[192:195], v[44:47]
	v_mfma_f32_16x16x32_bf16 v[48:51], v[68:71], v[192:195], v[48:51]
	ds_read_b128 v[172:175], v210 offset:30720
	s_waitcnt lgkmcnt(6)
	v_mfma_f32_16x16x32_bf16 v[28:31], v[64:67], v[196:199], v[28:31]
	v_mfma_f32_16x16x32_bf16 v[16:19], v[68:71], v[196:199], v[16:19]
	ds_read_b128 v[72:75], v209 offset:0
	ds_read_b128 v[216:219], v209 offset:2048
	ds_read_b128 v[176:179], v211 offset:16384
	s_waitcnt lgkmcnt(8)
	v_mfma_f32_16x16x32_bf16 v[60:63], v[64:67], v[200:203], v[60:63]
	v_mfma_f32_16x16x32_bf16 v[40:43], v[68:71], v[200:203], v[40:43]
	ds_read_b128 v[180:183], v211 offset:18432
	s_waitcnt lgkmcnt(8)
	v_mfma_f32_16x16x32_bf16 v[20:23], v[64:67], v[204:207], v[20:23]
	v_mfma_f32_16x16x32_bf16 v[0:3], v[68:71], v[204:207], v[0:3]
	ds_read_b128 v[184:187], v211 offset:20480
	s_waitcnt lgkmcnt(8)
	v_mfma_f32_16x16x32_bf16 v[52:55], v[64:67], v[160:163], v[52:55]
	v_mfma_f32_16x16x32_bf16 v[36:39], v[68:71], v[160:163], v[36:39]
	ds_read_b128 v[188:191], v211 offset:22528
	s_waitcnt lgkmcnt(8)
	v_mfma_f32_16x16x32_bf16 v[24:27], v[64:67], v[164:167], v[24:27]
	v_mfma_f32_16x16x32_bf16 v[8:11], v[68:71], v[164:167], v[8:11]
	ds_read_b128 v[192:195], v211 offset:24576
	s_waitcnt lgkmcnt(8)
	v_mfma_f32_16x16x32_bf16 v[56:59], v[64:67], v[168:171], v[56:59]
	v_mfma_f32_16x16x32_bf16 v[32:35], v[68:71], v[168:171], v[32:35]
	ds_read_b128 v[196:199], v211 offset:26624
	s_waitcnt lgkmcnt(8)
	v_mfma_f32_16x16x32_bf16 v[12:15], v[64:67], v[172:175], v[12:15]
	v_mfma_f32_16x16x32_bf16 v[4:7], v[68:71], v[172:175], v[4:7]
	ds_read_b128 v[200:203], v211 offset:28672
	s_waitcnt lgkmcnt(6)
	v_mfma_f32_16x16x32_bf16 v[44:47], v[72:75], v[176:179], v[44:47]
	v_mfma_f32_16x16x32_bf16 v[48:51], v[216:219], v[176:179], v[48:51]
	ds_read_b128 v[204:207], v211 offset:30720
	s_waitcnt vmcnt(0) lgkmcnt(0)
	s_barrier
	s_add_u32 m0, s41, 0
	s_nop 0
	global_load_lds_dwordx4 v212, s[98:99]
	s_waitcnt lgkmcnt(6)
	v_mfma_f32_16x16x32_bf16 v[28:31], v[72:75], v[180:183], v[28:31]
	v_mfma_f32_16x16x32_bf16 v[16:19], v[216:219], v[180:183], v[16:19]
	ds_read_b128 v[64:67], v208 offset:32768
	ds_read_b128 v[68:71], v208 offset:34816
	ds_read_b128 v[160:163], v210 offset:49152
	s_add_u32 m0, s41, 4096
	s_nop 0
	global_load_lds_dwordx4 v213, s[98:99]
	s_waitcnt lgkmcnt(8)
	v_mfma_f32_16x16x32_bf16 v[60:63], v[72:75], v[184:187], v[60:63]
	v_mfma_f32_16x16x32_bf16 v[40:43], v[216:219], v[184:187], v[40:43]
	ds_read_b128 v[164:167], v210 offset:51200
	s_add_u32 m0, s41, 8192
	s_nop 0
	global_load_lds_dwordx4 v214, s[98:99]
	s_waitcnt lgkmcnt(8)
	v_mfma_f32_16x16x32_bf16 v[20:23], v[72:75], v[188:191], v[20:23]
	v_mfma_f32_16x16x32_bf16 v[0:3], v[216:219], v[188:191], v[0:3]
	ds_read_b128 v[168:171], v210 offset:53248
	s_add_u32 m0, s41, 12288
	s_nop 0
	global_load_lds_dwordx4 v215, s[98:99]
	s_add_u32 s98, s98, 128
	s_addc_u32 s99, s99, 0
	s_waitcnt lgkmcnt(8)
	v_mfma_f32_16x16x32_bf16 v[52:55], v[72:75], v[192:195], v[52:55]
	v_mfma_f32_16x16x32_bf16 v[36:39], v[216:219], v[192:195], v[36:39]
	ds_read_b128 v[172:175], v210 offset:55296
	s_add_u32 m0, s41, 16384
	s_nop 0
	global_load_lds_dwordx4 v212, s[100:101]
	s_waitcnt lgkmcnt(8)
	v_mfma_f32_16x16x32_bf16 v[24:27], v[72:75], v[196:199], v[24:27]
	v_mfma_f32_16x16x32_bf16 v[8:11], v[216:219], v[196:199], v[8:11]
	ds_read_b128 v[176:179], v210 offset:57344
	s_add_u32 m0, s41, 20480
	s_nop 0
	global_load_lds_dwordx4 v213, s[100:101]
	s_waitcnt lgkmcnt(8)
	v_mfma_f32_16x16x32_bf16 v[56:59], v[72:75], v[200:203], v[56:59]
	v_mfma_f32_16x16x32_bf16 v[32:35], v[216:219], v[200:203], v[32:35]
	ds_read_b128 v[180:183], v210 offset:59392
	s_add_u32 m0, s41, 24576
	s_nop 0
	global_load_lds_dwordx4 v214, s[100:101]
	s_waitcnt lgkmcnt(8)
	v_mfma_f32_16x16x32_bf16 v[12:15], v[72:75], v[204:207], v[12:15]
	v_mfma_f32_16x16x32_bf16 v[4:7], v[216:219], v[204:207], v[4:7]
	ds_read_b128 v[184:187], v210 offset:61440
	s_add_u32 m0, s41, 28672
	s_nop 0
	global_load_lds_dwordx4 v215, s[100:101]
	s_add_u32 s100, s100, 128
	s_addc_u32 s101, s101, 0
	s_waitcnt lgkmcnt(6)
	v_mfma_f32_16x16x32_bf16 v[44:47], v[64:67], v[160:163], v[44:47]
	v_mfma_f32_16x16x32_bf16 v[48:51], v[68:71], v[160:163], v[48:51]
	ds_read_b128 v[188:191], v210 offset:63488
	s_waitcnt lgkmcnt(6)
	v_mfma_f32_16x16x32_bf16 v[28:31], v[64:67], v[164:167], v[28:31]
	v_mfma_f32_16x16x32_bf16 v[16:19], v[68:71], v[164:167], v[16:19]
	ds_read_b128 v[72:75], v209 offset:32768
	ds_read_b128 v[216:219], v209 offset:34816
	ds_read_b128 v[192:195], v211 offset:49152
	s_waitcnt lgkmcnt(8)
	v_mfma_f32_16x16x32_bf16 v[60:63], v[64:67], v[168:171], v[60:63]
	v_mfma_f32_16x16x32_bf16 v[40:43], v[68:71], v[168:171], v[40:43]
	ds_read_b128 v[196:199], v211 offset:51200
	s_waitcnt lgkmcnt(8)
	v_mfma_f32_16x16x32_bf16 v[20:23], v[64:67], v[172:175], v[20:23]
	v_mfma_f32_16x16x32_bf16 v[0:3], v[68:71], v[172:175], v[0:3]
	ds_read_b128 v[200:203], v211 offset:53248
	s_waitcnt lgkmcnt(8)
	v_mfma_f32_16x16x32_bf16 v[52:55], v[64:67], v[176:179], v[52:55]
	v_mfma_f32_16x16x32_bf16 v[36:39], v[68:71], v[176:179], v[36:39]
	ds_read_b128 v[204:207], v211 offset:55296
	s_waitcnt lgkmcnt(8)
	v_mfma_f32_16x16x32_bf16 v[24:27], v[64:67], v[180:183], v[24:27]
	v_mfma_f32_16x16x32_bf16 v[8:11], v[68:71], v[180:183], v[8:11]
	ds_read_b128 v[160:163], v211 offset:57344
	s_waitcnt lgkmcnt(8)
	v_mfma_f32_16x16x32_bf16 v[56:59], v[64:67], v[184:187], v[56:59]
	v_mfma_f32_16x16x32_bf16 v[32:35], v[68:71], v[184:187], v[32:35]
	ds_read_b128 v[164:167], v211 offset:59392
	s_waitcnt lgkmcnt(8)
	v_mfma_f32_16x16x32_bf16 v[12:15], v[64:67], v[188:191], v[12:15]
	v_mfma_f32_16x16x32_bf16 v[4:7], v[68:71], v[188:191], v[4:7]
	ds_read_b128 v[168:171], v211 offset:61440
	s_waitcnt lgkmcnt(6)
	v_mfma_f32_16x16x32_bf16 v[44:47], v[72:75], v[192:195], v[44:47]
	v_mfma_f32_16x16x32_bf16 v[48:51], v[216:219], v[192:195], v[48:51]
	ds_read_b128 v[172:175], v211 offset:63488
	s_waitcnt vmcnt(0) lgkmcnt(0)
	s_barrier
	s_add_u32 m0, s41, 32768
	s_nop 0
	global_load_lds_dwordx4 v212, s[98:99]
	s_waitcnt lgkmcnt(6)
	v_mfma_f32_16x16x32_bf16 v[28:31], v[72:75], v[196:199], v[28:31]
	v_mfma_f32_16x16x32_bf16 v[16:19], v[216:219], v[196:199], v[16:19]
	ds_read_b128 v[64:67], v208 offset:0
	ds_read_b128 v[68:71], v208 offset:2048
	ds_read_b128 v[176:179], v210 offset:16384
	s_add_u32 m0, s41, 36864
	s_nop 0
	global_load_lds_dwordx4 v213, s[98:99]
	s_waitcnt lgkmcnt(8)
	v_mfma_f32_16x16x32_bf16 v[60:63], v[72:75], v[200:203], v[60:63]
	v_mfma_f32_16x16x32_bf16 v[40:43], v[216:219], v[200:203], v[40:43]
	ds_read_b128 v[180:183], v210 offset:18432
	s_add_u32 m0, s41, 40960
	s_nop 0
	global_load_lds_dwordx4 v214, s[98:99]
	s_waitcnt lgkmcnt(8)
	v_mfma_f32_16x16x32_bf16 v[20:23], v[72:75], v[204:207], v[20:23]
	v_mfma_f32_16x16x32_bf16 v[0:3], v[216:219], v[204:207], v[0:3]
	ds_read_b128 v[184:187], v210 offset:20480
	s_add_u32 m0, s41, 45056
	s_nop 0
	global_load_lds_dwordx4 v215, s[98:99]
	s_add_u32 s98, s98, 128
	s_addc_u32 s99, s99, 0
	s_waitcnt lgkmcnt(8)
	v_mfma_f32_16x16x32_bf16 v[52:55], v[72:75], v[160:163], v[52:55]
	v_mfma_f32_16x16x32_bf16 v[36:39], v[216:219], v[160:163], v[36:39]
	ds_read_b128 v[188:191], v210 offset:22528
	s_add_u32 m0, s41, 49152
	s_nop 0
	global_load_lds_dwordx4 v212, s[100:101]
	s_waitcnt lgkmcnt(8)
	v_mfma_f32_16x16x32_bf16 v[24:27], v[72:75], v[164:167], v[24:27]
	v_mfma_f32_16x16x32_bf16 v[8:11], v[216:219], v[164:167], v[8:11]
	ds_read_b128 v[192:195], v210 offset:24576
	s_add_u32 m0, s41, 53248
	s_nop 0
	global_load_lds_dwordx4 v213, s[100:101]
	s_waitcnt lgkmcnt(8)
	v_mfma_f32_16x16x32_bf16 v[56:59], v[72:75], v[168:171], v[56:59]
	v_mfma_f32_16x16x32_bf16 v[32:35], v[216:219], v[168:171], v[32:35]
	ds_read_b128 v[196:199], v210 offset:26624
	s_add_u32 m0, s41, 57344
	s_nop 0
	global_load_lds_dwordx4 v214, s[100:101]
	s_waitcnt lgkmcnt(8)
	v_mfma_f32_16x16x32_bf16 v[12:15], v[72:75], v[172:175], v[12:15]
	v_mfma_f32_16x16x32_bf16 v[4:7], v[216:219], v[172:175], v[4:7]
	ds_read_b128 v[200:203], v210 offset:28672
	s_add_u32 m0, s41, 61440
	s_nop 0
	global_load_lds_dwordx4 v215, s[100:101]
	s_add_u32 s100, s100, 128
	s_addc_u32 s101, s101, 0
	s_waitcnt lgkmcnt(6)
	v_mfma_f32_16x16x32_bf16 v[44:47], v[64:67], v[176:179], v[44:47]
	v_mfma_f32_16x16x32_bf16 v[48:51], v[68:71], v[176:179], v[48:51]
	ds_read_b128 v[204:207], v210 offset:30720
	s_waitcnt lgkmcnt(6)
	v_mfma_f32_16x16x32_bf16 v[28:31], v[64:67], v[180:183], v[28:31]
	v_mfma_f32_16x16x32_bf16 v[16:19], v[68:71], v[180:183], v[16:19]
	ds_read_b128 v[72:75], v209 offset:0
	ds_read_b128 v[216:219], v209 offset:2048
	ds_read_b128 v[160:163], v211 offset:16384
	s_waitcnt lgkmcnt(8)
	v_mfma_f32_16x16x32_bf16 v[60:63], v[64:67], v[184:187], v[60:63]
	v_mfma_f32_16x16x32_bf16 v[40:43], v[68:71], v[184:187], v[40:43]
	ds_read_b128 v[164:167], v211 offset:18432
	s_waitcnt lgkmcnt(8)
	v_mfma_f32_16x16x32_bf16 v[20:23], v[64:67], v[188:191], v[20:23]
	v_mfma_f32_16x16x32_bf16 v[0:3], v[68:71], v[188:191], v[0:3]
	ds_read_b128 v[168:171], v211 offset:20480
	s_waitcnt lgkmcnt(8)
	v_mfma_f32_16x16x32_bf16 v[52:55], v[64:67], v[192:195], v[52:55]
	v_mfma_f32_16x16x32_bf16 v[36:39], v[68:71], v[192:195], v[36:39]
	ds_read_b128 v[172:175], v211 offset:22528
	s_waitcnt lgkmcnt(8)
	v_mfma_f32_16x16x32_bf16 v[24:27], v[64:67], v[196:199], v[24:27]
	v_mfma_f32_16x16x32_bf16 v[8:11], v[68:71], v[196:199], v[8:11]
	ds_read_b128 v[176:179], v211 offset:24576
	s_waitcnt lgkmcnt(8)
	v_mfma_f32_16x16x32_bf16 v[56:59], v[64:67], v[200:203], v[56:59]
	v_mfma_f32_16x16x32_bf16 v[32:35], v[68:71], v[200:203], v[32:35]
	ds_read_b128 v[180:183], v211 offset:26624
	s_waitcnt lgkmcnt(8)
	v_mfma_f32_16x16x32_bf16 v[12:15], v[64:67], v[204:207], v[12:15]
	v_mfma_f32_16x16x32_bf16 v[4:7], v[68:71], v[204:207], v[4:7]
	ds_read_b128 v[184:187], v211 offset:28672
	s_waitcnt lgkmcnt(6)
	v_mfma_f32_16x16x32_bf16 v[44:47], v[72:75], v[160:163], v[44:47]
	v_mfma_f32_16x16x32_bf16 v[48:51], v[216:219], v[160:163], v[48:51]
	ds_read_b128 v[188:191], v211 offset:30720
	s_waitcnt vmcnt(0) lgkmcnt(0)
	s_barrier
	s_add_u32 m0, s41, 0
	s_nop 0
	global_load_lds_dwordx4 v212, s[98:99]
	s_waitcnt lgkmcnt(6)
	v_mfma_f32_16x16x32_bf16 v[28:31], v[72:75], v[164:167], v[28:31]
	v_mfma_f32_16x16x32_bf16 v[16:19], v[216:219], v[164:167], v[16:19]
	ds_read_b128 v[64:67], v208 offset:32768
	ds_read_b128 v[68:71], v208 offset:34816
	ds_read_b128 v[192:195], v210 offset:49152
	s_add_u32 m0, s41, 4096
	s_nop 0
	global_load_lds_dwordx4 v213, s[98:99]
	s_waitcnt lgkmcnt(8)
	v_mfma_f32_16x16x32_bf16 v[60:63], v[72:75], v[168:171], v[60:63]
	v_mfma_f32_16x16x32_bf16 v[40:43], v[216:219], v[168:171], v[40:43]
	ds_read_b128 v[196:199], v210 offset:51200
	s_add_u32 m0, s41, 8192
	s_nop 0
	global_load_lds_dwordx4 v214, s[98:99]
	s_waitcnt lgkmcnt(8)
	v_mfma_f32_16x16x32_bf16 v[20:23], v[72:75], v[172:175], v[20:23]
	v_mfma_f32_16x16x32_bf16 v[0:3], v[216:219], v[172:175], v[0:3]
	ds_read_b128 v[200:203], v210 offset:53248
	s_add_u32 m0, s41, 12288
	s_nop 0
	global_load_lds_dwordx4 v215, s[98:99]
	s_add_u32 s98, s98, 128
	s_addc_u32 s99, s99, 0
	s_waitcnt lgkmcnt(8)
	v_mfma_f32_16x16x32_bf16 v[52:55], v[72:75], v[176:179], v[52:55]
	v_mfma_f32_16x16x32_bf16 v[36:39], v[216:219], v[176:179], v[36:39]
	ds_read_b128 v[204:207], v210 offset:55296
	s_add_u32 m0, s41, 16384
	s_nop 0
	global_load_lds_dwordx4 v212, s[100:101]
	s_waitcnt lgkmcnt(8)
	v_mfma_f32_16x16x32_bf16 v[24:27], v[72:75], v[180:183], v[24:27]
	v_mfma_f32_16x16x32_bf16 v[8:11], v[216:219], v[180:183], v[8:11]
	ds_read_b128 v[160:163], v210 offset:57344
	s_add_u32 m0, s41, 20480
	s_nop 0
	global_load_lds_dwordx4 v213, s[100:101]
	s_waitcnt lgkmcnt(8)
	v_mfma_f32_16x16x32_bf16 v[56:59], v[72:75], v[184:187], v[56:59]
	v_mfma_f32_16x16x32_bf16 v[32:35], v[216:219], v[184:187], v[32:35]
	ds_read_b128 v[164:167], v210 offset:59392
	s_add_u32 m0, s41, 24576
	s_nop 0
	global_load_lds_dwordx4 v214, s[100:101]
	s_waitcnt lgkmcnt(8)
	v_mfma_f32_16x16x32_bf16 v[12:15], v[72:75], v[188:191], v[12:15]
	v_mfma_f32_16x16x32_bf16 v[4:7], v[216:219], v[188:191], v[4:7]
	ds_read_b128 v[168:171], v210 offset:61440
	s_add_u32 m0, s41, 28672
	s_nop 0
	global_load_lds_dwordx4 v215, s[100:101]
	s_add_u32 s100, s100, 128
	s_addc_u32 s101, s101, 0
	s_waitcnt lgkmcnt(6)
	v_mfma_f32_16x16x32_bf16 v[44:47], v[64:67], v[192:195], v[44:47]
	v_mfma_f32_16x16x32_bf16 v[48:51], v[68:71], v[192:195], v[48:51]
	ds_read_b128 v[172:175], v210 offset:63488
	s_waitcnt lgkmcnt(6)
	v_mfma_f32_16x16x32_bf16 v[28:31], v[64:67], v[196:199], v[28:31]
	v_mfma_f32_16x16x32_bf16 v[16:19], v[68:71], v[196:199], v[16:19]
	ds_read_b128 v[72:75], v209 offset:32768
	ds_read_b128 v[216:219], v209 offset:34816
	ds_read_b128 v[176:179], v211 offset:49152
	s_waitcnt lgkmcnt(8)
	v_mfma_f32_16x16x32_bf16 v[60:63], v[64:67], v[200:203], v[60:63]
	v_mfma_f32_16x16x32_bf16 v[40:43], v[68:71], v[200:203], v[40:43]
	ds_read_b128 v[180:183], v211 offset:51200
	s_waitcnt lgkmcnt(8)
	v_mfma_f32_16x16x32_bf16 v[20:23], v[64:67], v[204:207], v[20:23]
	v_mfma_f32_16x16x32_bf16 v[0:3], v[68:71], v[204:207], v[0:3]
	ds_read_b128 v[184:187], v211 offset:53248
	s_waitcnt lgkmcnt(8)
	v_mfma_f32_16x16x32_bf16 v[52:55], v[64:67], v[160:163], v[52:55]
	v_mfma_f32_16x16x32_bf16 v[36:39], v[68:71], v[160:163], v[36:39]
	ds_read_b128 v[188:191], v211 offset:55296
	s_waitcnt lgkmcnt(8)
	v_mfma_f32_16x16x32_bf16 v[24:27], v[64:67], v[164:167], v[24:27]
	v_mfma_f32_16x16x32_bf16 v[8:11], v[68:71], v[164:167], v[8:11]
	ds_read_b128 v[192:195], v211 offset:57344
	s_waitcnt lgkmcnt(8)
	v_mfma_f32_16x16x32_bf16 v[56:59], v[64:67], v[168:171], v[56:59]
	v_mfma_f32_16x16x32_bf16 v[32:35], v[68:71], v[168:171], v[32:35]
	ds_read_b128 v[196:199], v211 offset:59392
	s_waitcnt lgkmcnt(8)
	v_mfma_f32_16x16x32_bf16 v[12:15], v[64:67], v[172:175], v[12:15]
	v_mfma_f32_16x16x32_bf16 v[4:7], v[68:71], v[172:175], v[4:7]
	ds_read_b128 v[200:203], v211 offset:61440
	s_waitcnt lgkmcnt(6)
	v_mfma_f32_16x16x32_bf16 v[44:47], v[72:75], v[176:179], v[44:47]
	v_mfma_f32_16x16x32_bf16 v[48:51], v[216:219], v[176:179], v[48:51]
	ds_read_b128 v[204:207], v211 offset:63488
	s_waitcnt vmcnt(0) lgkmcnt(0)
	s_barrier
	s_add_u32 m0, s41, 32768
	s_nop 0
	global_load_lds_dwordx4 v212, s[98:99]
	s_waitcnt lgkmcnt(6)
	v_mfma_f32_16x16x32_bf16 v[28:31], v[72:75], v[180:183], v[28:31]
	v_mfma_f32_16x16x32_bf16 v[16:19], v[216:219], v[180:183], v[16:19]
	ds_read_b128 v[64:67], v208 offset:0
	ds_read_b128 v[68:71], v208 offset:2048
	ds_read_b128 v[160:163], v210 offset:16384
	s_add_u32 m0, s41, 36864
	s_nop 0
	global_load_lds_dwordx4 v213, s[98:99]
	s_waitcnt lgkmcnt(8)
	v_mfma_f32_16x16x32_bf16 v[60:63], v[72:75], v[184:187], v[60:63]
	v_mfma_f32_16x16x32_bf16 v[40:43], v[216:219], v[184:187], v[40:43]
	ds_read_b128 v[164:167], v210 offset:18432
	s_add_u32 m0, s41, 40960
	s_nop 0
	global_load_lds_dwordx4 v214, s[98:99]
	s_waitcnt lgkmcnt(8)
	v_mfma_f32_16x16x32_bf16 v[20:23], v[72:75], v[188:191], v[20:23]
	v_mfma_f32_16x16x32_bf16 v[0:3], v[216:219], v[188:191], v[0:3]
	ds_read_b128 v[168:171], v210 offset:20480
	s_add_u32 m0, s41, 45056
	s_nop 0
	global_load_lds_dwordx4 v215, s[98:99]
	s_add_u32 s98, s98, 128
	s_addc_u32 s99, s99, 0
	s_waitcnt lgkmcnt(8)
	v_mfma_f32_16x16x32_bf16 v[52:55], v[72:75], v[192:195], v[52:55]
	v_mfma_f32_16x16x32_bf16 v[36:39], v[216:219], v[192:195], v[36:39]
	ds_read_b128 v[172:175], v210 offset:22528
	s_add_u32 m0, s41, 49152
	s_nop 0
	global_load_lds_dwordx4 v212, s[100:101]
	s_waitcnt lgkmcnt(8)
	v_mfma_f32_16x16x32_bf16 v[24:27], v[72:75], v[196:199], v[24:27]
	v_mfma_f32_16x16x32_bf16 v[8:11], v[216:219], v[196:199], v[8:11]
	ds_read_b128 v[176:179], v210 offset:24576
	s_add_u32 m0, s41, 53248
	s_nop 0
	global_load_lds_dwordx4 v213, s[100:101]
	s_waitcnt lgkmcnt(8)
	v_mfma_f32_16x16x32_bf16 v[56:59], v[72:75], v[200:203], v[56:59]
	v_mfma_f32_16x16x32_bf16 v[32:35], v[216:219], v[200:203], v[32:35]
	ds_read_b128 v[180:183], v210 offset:26624
	s_add_u32 m0, s41, 57344
	s_nop 0
	global_load_lds_dwordx4 v214, s[100:101]
	s_waitcnt lgkmcnt(8)
	v_mfma_f32_16x16x32_bf16 v[12:15], v[72:75], v[204:207], v[12:15]
	v_mfma_f32_16x16x32_bf16 v[4:7], v[216:219], v[204:207], v[4:7]
	ds_read_b128 v[184:187], v210 offset:28672
	s_add_u32 m0, s41, 61440
	s_nop 0
	global_load_lds_dwordx4 v215, s[100:101]
	s_add_u32 s100, s100, 128
	s_addc_u32 s101, s101, 0
	s_waitcnt lgkmcnt(6)
	v_mfma_f32_16x16x32_bf16 v[44:47], v[64:67], v[160:163], v[44:47]
	v_mfma_f32_16x16x32_bf16 v[48:51], v[68:71], v[160:163], v[48:51]
	ds_read_b128 v[188:191], v210 offset:30720
	s_waitcnt lgkmcnt(6)
	v_mfma_f32_16x16x32_bf16 v[28:31], v[64:67], v[164:167], v[28:31]
	v_mfma_f32_16x16x32_bf16 v[16:19], v[68:71], v[164:167], v[16:19]
	ds_read_b128 v[72:75], v209 offset:0
	ds_read_b128 v[216:219], v209 offset:2048
	ds_read_b128 v[192:195], v211 offset:16384
	s_waitcnt lgkmcnt(8)
	v_mfma_f32_16x16x32_bf16 v[60:63], v[64:67], v[168:171], v[60:63]
	v_mfma_f32_16x16x32_bf16 v[40:43], v[68:71], v[168:171], v[40:43]
	ds_read_b128 v[196:199], v211 offset:18432
	s_waitcnt lgkmcnt(8)
	v_mfma_f32_16x16x32_bf16 v[20:23], v[64:67], v[172:175], v[20:23]
	v_mfma_f32_16x16x32_bf16 v[0:3], v[68:71], v[172:175], v[0:3]
	ds_read_b128 v[200:203], v211 offset:20480
	s_waitcnt lgkmcnt(8)
	v_mfma_f32_16x16x32_bf16 v[52:55], v[64:67], v[176:179], v[52:55]
	v_mfma_f32_16x16x32_bf16 v[36:39], v[68:71], v[176:179], v[36:39]
	ds_read_b128 v[204:207], v211 offset:22528
	s_waitcnt lgkmcnt(8)
	v_mfma_f32_16x16x32_bf16 v[24:27], v[64:67], v[180:183], v[24:27]
	v_mfma_f32_16x16x32_bf16 v[8:11], v[68:71], v[180:183], v[8:11]
	ds_read_b128 v[160:163], v211 offset:24576
	s_waitcnt lgkmcnt(8)
	v_mfma_f32_16x16x32_bf16 v[56:59], v[64:67], v[184:187], v[56:59]
	v_mfma_f32_16x16x32_bf16 v[32:35], v[68:71], v[184:187], v[32:35]
	ds_read_b128 v[164:167], v211 offset:26624
	s_waitcnt lgkmcnt(8)
	v_mfma_f32_16x16x32_bf16 v[12:15], v[64:67], v[188:191], v[12:15]
	v_mfma_f32_16x16x32_bf16 v[4:7], v[68:71], v[188:191], v[4:7]
	ds_read_b128 v[168:171], v211 offset:28672
	s_waitcnt lgkmcnt(6)
	v_mfma_f32_16x16x32_bf16 v[44:47], v[72:75], v[192:195], v[44:47]
	v_mfma_f32_16x16x32_bf16 v[48:51], v[216:219], v[192:195], v[48:51]
	ds_read_b128 v[172:175], v211 offset:30720
	s_waitcnt vmcnt(0) lgkmcnt(0)
	s_barrier
	s_add_u32 m0, s41, 0
	s_nop 0
	global_load_lds_dwordx4 v212, s[98:99]
	s_waitcnt lgkmcnt(6)
	v_mfma_f32_16x16x32_bf16 v[28:31], v[72:75], v[196:199], v[28:31]
	v_mfma_f32_16x16x32_bf16 v[16:19], v[216:219], v[196:199], v[16:19]
	ds_read_b128 v[64:67], v208 offset:32768
	ds_read_b128 v[68:71], v208 offset:34816
	ds_read_b128 v[176:179], v210 offset:49152
	s_add_u32 m0, s41, 4096
	s_nop 0
	global_load_lds_dwordx4 v213, s[98:99]
	s_waitcnt lgkmcnt(8)
	v_mfma_f32_16x16x32_bf16 v[60:63], v[72:75], v[200:203], v[60:63]
	v_mfma_f32_16x16x32_bf16 v[40:43], v[216:219], v[200:203], v[40:43]
	ds_read_b128 v[180:183], v210 offset:51200
	s_add_u32 m0, s41, 8192
	s_nop 0
	global_load_lds_dwordx4 v214, s[98:99]
	s_waitcnt lgkmcnt(8)
	v_mfma_f32_16x16x32_bf16 v[20:23], v[72:75], v[204:207], v[20:23]
	v_mfma_f32_16x16x32_bf16 v[0:3], v[216:219], v[204:207], v[0:3]
	ds_read_b128 v[184:187], v210 offset:53248
	s_add_u32 m0, s41, 12288
	s_nop 0
	global_load_lds_dwordx4 v215, s[98:99]
	s_add_u32 s98, s98, 128
	s_addc_u32 s99, s99, 0
	s_waitcnt lgkmcnt(8)
	v_mfma_f32_16x16x32_bf16 v[52:55], v[72:75], v[160:163], v[52:55]
	v_mfma_f32_16x16x32_bf16 v[36:39], v[216:219], v[160:163], v[36:39]
	ds_read_b128 v[188:191], v210 offset:55296
	s_add_u32 m0, s41, 16384
	s_nop 0
	global_load_lds_dwordx4 v212, s[100:101]
	s_waitcnt lgkmcnt(8)
	v_mfma_f32_16x16x32_bf16 v[24:27], v[72:75], v[164:167], v[24:27]
	v_mfma_f32_16x16x32_bf16 v[8:11], v[216:219], v[164:167], v[8:11]
	ds_read_b128 v[192:195], v210 offset:57344
	s_add_u32 m0, s41, 20480
	s_nop 0
	global_load_lds_dwordx4 v213, s[100:101]
	s_waitcnt lgkmcnt(8)
	v_mfma_f32_16x16x32_bf16 v[56:59], v[72:75], v[168:171], v[56:59]
	v_mfma_f32_16x16x32_bf16 v[32:35], v[216:219], v[168:171], v[32:35]
	ds_read_b128 v[196:199], v210 offset:59392
	s_add_u32 m0, s41, 24576
	s_nop 0
	global_load_lds_dwordx4 v214, s[100:101]
	s_waitcnt lgkmcnt(8)
	v_mfma_f32_16x16x32_bf16 v[12:15], v[72:75], v[172:175], v[12:15]
	v_mfma_f32_16x16x32_bf16 v[4:7], v[216:219], v[172:175], v[4:7]
	ds_read_b128 v[200:203], v210 offset:61440
	s_add_u32 m0, s41, 28672
	s_nop 0
	global_load_lds_dwordx4 v215, s[100:101]
	s_add_u32 s100, s100, 128
	s_addc_u32 s101, s101, 0
	s_waitcnt lgkmcnt(6)
	v_mfma_f32_16x16x32_bf16 v[44:47], v[64:67], v[176:179], v[44:47]
	v_mfma_f32_16x16x32_bf16 v[48:51], v[68:71], v[176:179], v[48:51]
	ds_read_b128 v[204:207], v210 offset:63488
	s_waitcnt lgkmcnt(6)
	v_mfma_f32_16x16x32_bf16 v[28:31], v[64:67], v[180:183], v[28:31]
	v_mfma_f32_16x16x32_bf16 v[16:19], v[68:71], v[180:183], v[16:19]
	ds_read_b128 v[72:75], v209 offset:32768
	ds_read_b128 v[216:219], v209 offset:34816
	ds_read_b128 v[160:163], v211 offset:49152
	s_waitcnt lgkmcnt(8)
	v_mfma_f32_16x16x32_bf16 v[60:63], v[64:67], v[184:187], v[60:63]
	v_mfma_f32_16x16x32_bf16 v[40:43], v[68:71], v[184:187], v[40:43]
	ds_read_b128 v[164:167], v211 offset:51200
	s_waitcnt lgkmcnt(8)
	v_mfma_f32_16x16x32_bf16 v[20:23], v[64:67], v[188:191], v[20:23]
	v_mfma_f32_16x16x32_bf16 v[0:3], v[68:71], v[188:191], v[0:3]
	ds_read_b128 v[168:171], v211 offset:53248
	s_waitcnt lgkmcnt(8)
	v_mfma_f32_16x16x32_bf16 v[52:55], v[64:67], v[192:195], v[52:55]
	v_mfma_f32_16x16x32_bf16 v[36:39], v[68:71], v[192:195], v[36:39]
	ds_read_b128 v[172:175], v211 offset:55296
	s_waitcnt lgkmcnt(8)
	v_mfma_f32_16x16x32_bf16 v[24:27], v[64:67], v[196:199], v[24:27]
	v_mfma_f32_16x16x32_bf16 v[8:11], v[68:71], v[196:199], v[8:11]
	ds_read_b128 v[176:179], v211 offset:57344
	s_waitcnt lgkmcnt(8)
	v_mfma_f32_16x16x32_bf16 v[56:59], v[64:67], v[200:203], v[56:59]
	v_mfma_f32_16x16x32_bf16 v[32:35], v[68:71], v[200:203], v[32:35]
	ds_read_b128 v[180:183], v211 offset:59392
	s_waitcnt lgkmcnt(8)
	v_mfma_f32_16x16x32_bf16 v[12:15], v[64:67], v[204:207], v[12:15]
	v_mfma_f32_16x16x32_bf16 v[4:7], v[68:71], v[204:207], v[4:7]
	ds_read_b128 v[184:187], v211 offset:61440
	s_waitcnt lgkmcnt(6)
	v_mfma_f32_16x16x32_bf16 v[44:47], v[72:75], v[160:163], v[44:47]
	v_mfma_f32_16x16x32_bf16 v[48:51], v[216:219], v[160:163], v[48:51]
	ds_read_b128 v[188:191], v211 offset:63488
	s_waitcnt vmcnt(0) lgkmcnt(0)
	s_barrier
	s_add_u32 m0, s41, 32768
	s_nop 0
	global_load_lds_dwordx4 v212, s[98:99]
	s_waitcnt lgkmcnt(6)
	v_mfma_f32_16x16x32_bf16 v[28:31], v[72:75], v[164:167], v[28:31]
	v_mfma_f32_16x16x32_bf16 v[16:19], v[216:219], v[164:167], v[16:19]
	ds_read_b128 v[64:67], v208 offset:0
	ds_read_b128 v[68:71], v208 offset:2048
	ds_read_b128 v[192:195], v210 offset:16384
	s_add_u32 m0, s41, 36864
	s_nop 0
	global_load_lds_dwordx4 v213, s[98:99]
	s_waitcnt lgkmcnt(8)
	v_mfma_f32_16x16x32_bf16 v[60:63], v[72:75], v[168:171], v[60:63]
	v_mfma_f32_16x16x32_bf16 v[40:43], v[216:219], v[168:171], v[40:43]
	ds_read_b128 v[196:199], v210 offset:18432
	s_add_u32 m0, s41, 40960
	s_nop 0
	global_load_lds_dwordx4 v214, s[98:99]
	s_waitcnt lgkmcnt(8)
	v_mfma_f32_16x16x32_bf16 v[20:23], v[72:75], v[172:175], v[20:23]
	v_mfma_f32_16x16x32_bf16 v[0:3], v[216:219], v[172:175], v[0:3]
	ds_read_b128 v[200:203], v210 offset:20480
	s_add_u32 m0, s41, 45056
	s_nop 0
	global_load_lds_dwordx4 v215, s[98:99]
	s_add_u32 s98, s98, 128
	s_addc_u32 s99, s99, 0
	s_waitcnt lgkmcnt(8)
	v_mfma_f32_16x16x32_bf16 v[52:55], v[72:75], v[176:179], v[52:55]
	v_mfma_f32_16x16x32_bf16 v[36:39], v[216:219], v[176:179], v[36:39]
	ds_read_b128 v[204:207], v210 offset:22528
	s_add_u32 m0, s41, 49152
	s_nop 0
	global_load_lds_dwordx4 v212, s[100:101]
	s_waitcnt lgkmcnt(8)
	v_mfma_f32_16x16x32_bf16 v[24:27], v[72:75], v[180:183], v[24:27]
	v_mfma_f32_16x16x32_bf16 v[8:11], v[216:219], v[180:183], v[8:11]
	ds_read_b128 v[160:163], v210 offset:24576
	s_add_u32 m0, s41, 53248
	s_nop 0
	global_load_lds_dwordx4 v213, s[100:101]
	s_waitcnt lgkmcnt(8)
	v_mfma_f32_16x16x32_bf16 v[56:59], v[72:75], v[184:187], v[56:59]
	v_mfma_f32_16x16x32_bf16 v[32:35], v[216:219], v[184:187], v[32:35]
	ds_read_b128 v[164:167], v210 offset:26624
	s_add_u32 m0, s41, 57344
	s_nop 0
	global_load_lds_dwordx4 v214, s[100:101]
	s_waitcnt lgkmcnt(8)
	v_mfma_f32_16x16x32_bf16 v[12:15], v[72:75], v[188:191], v[12:15]
	v_mfma_f32_16x16x32_bf16 v[4:7], v[216:219], v[188:191], v[4:7]
	ds_read_b128 v[168:171], v210 offset:28672
	s_add_u32 m0, s41, 61440
	s_nop 0
	global_load_lds_dwordx4 v215, s[100:101]
	s_add_u32 s100, s100, 128
	s_addc_u32 s101, s101, 0
	s_waitcnt lgkmcnt(6)
	v_mfma_f32_16x16x32_bf16 v[44:47], v[64:67], v[192:195], v[44:47]
	v_mfma_f32_16x16x32_bf16 v[48:51], v[68:71], v[192:195], v[48:51]
	ds_read_b128 v[172:175], v210 offset:30720
	s_waitcnt lgkmcnt(6)
	v_mfma_f32_16x16x32_bf16 v[28:31], v[64:67], v[196:199], v[28:31]
	v_mfma_f32_16x16x32_bf16 v[16:19], v[68:71], v[196:199], v[16:19]
	ds_read_b128 v[72:75], v209 offset:0
	ds_read_b128 v[216:219], v209 offset:2048
	ds_read_b128 v[176:179], v211 offset:16384
	s_waitcnt lgkmcnt(8)
	v_mfma_f32_16x16x32_bf16 v[60:63], v[64:67], v[200:203], v[60:63]
	v_mfma_f32_16x16x32_bf16 v[40:43], v[68:71], v[200:203], v[40:43]
	ds_read_b128 v[180:183], v211 offset:18432
	s_waitcnt lgkmcnt(8)
	v_mfma_f32_16x16x32_bf16 v[20:23], v[64:67], v[204:207], v[20:23]
	v_mfma_f32_16x16x32_bf16 v[0:3], v[68:71], v[204:207], v[0:3]
	ds_read_b128 v[184:187], v211 offset:20480
	s_waitcnt lgkmcnt(8)
	v_mfma_f32_16x16x32_bf16 v[52:55], v[64:67], v[160:163], v[52:55]
	v_mfma_f32_16x16x32_bf16 v[36:39], v[68:71], v[160:163], v[36:39]
	ds_read_b128 v[188:191], v211 offset:22528
	s_waitcnt lgkmcnt(8)
	v_mfma_f32_16x16x32_bf16 v[24:27], v[64:67], v[164:167], v[24:27]
	v_mfma_f32_16x16x32_bf16 v[8:11], v[68:71], v[164:167], v[8:11]
	ds_read_b128 v[192:195], v211 offset:24576
	s_waitcnt lgkmcnt(8)
	v_mfma_f32_16x16x32_bf16 v[56:59], v[64:67], v[168:171], v[56:59]
	v_mfma_f32_16x16x32_bf16 v[32:35], v[68:71], v[168:171], v[32:35]
	ds_read_b128 v[196:199], v211 offset:26624
	s_waitcnt lgkmcnt(8)
	v_mfma_f32_16x16x32_bf16 v[12:15], v[64:67], v[172:175], v[12:15]
	v_mfma_f32_16x16x32_bf16 v[4:7], v[68:71], v[172:175], v[4:7]
	ds_read_b128 v[200:203], v211 offset:28672
	s_waitcnt lgkmcnt(6)
	v_mfma_f32_16x16x32_bf16 v[44:47], v[72:75], v[176:179], v[44:47]
	v_mfma_f32_16x16x32_bf16 v[48:51], v[216:219], v[176:179], v[48:51]
	ds_read_b128 v[204:207], v211 offset:30720
	s_waitcnt vmcnt(0) lgkmcnt(0)
	s_barrier
	s_add_u32 m0, s41, 0
	s_nop 0
	global_load_lds_dwordx4 v212, s[98:99]
	s_waitcnt lgkmcnt(6)
	v_mfma_f32_16x16x32_bf16 v[28:31], v[72:75], v[180:183], v[28:31]
	v_mfma_f32_16x16x32_bf16 v[16:19], v[216:219], v[180:183], v[16:19]
	ds_read_b128 v[64:67], v208 offset:32768
	ds_read_b128 v[68:71], v208 offset:34816
	ds_read_b128 v[160:163], v210 offset:49152
	s_add_u32 m0, s41, 4096
	s_nop 0
	global_load_lds_dwordx4 v213, s[98:99]
	s_waitcnt lgkmcnt(8)
	v_mfma_f32_16x16x32_bf16 v[60:63], v[72:75], v[184:187], v[60:63]
	v_mfma_f32_16x16x32_bf16 v[40:43], v[216:219], v[184:187], v[40:43]
	ds_read_b128 v[164:167], v210 offset:51200
	s_add_u32 m0, s41, 8192
	s_nop 0
	global_load_lds_dwordx4 v214, s[98:99]
	s_waitcnt lgkmcnt(8)
	v_mfma_f32_16x16x32_bf16 v[20:23], v[72:75], v[188:191], v[20:23]
	v_mfma_f32_16x16x32_bf16 v[0:3], v[216:219], v[188:191], v[0:3]
	ds_read_b128 v[168:171], v210 offset:53248
	s_add_u32 m0, s41, 12288
	s_nop 0
	global_load_lds_dwordx4 v215, s[98:99]
	s_add_u32 s98, s98, 128
	s_addc_u32 s99, s99, 0
	s_waitcnt lgkmcnt(8)
	v_mfma_f32_16x16x32_bf16 v[52:55], v[72:75], v[192:195], v[52:55]
	v_mfma_f32_16x16x32_bf16 v[36:39], v[216:219], v[192:195], v[36:39]
	ds_read_b128 v[172:175], v210 offset:55296
	s_add_u32 m0, s41, 16384
	s_nop 0
	global_load_lds_dwordx4 v212, s[100:101]
	s_waitcnt lgkmcnt(8)
	v_mfma_f32_16x16x32_bf16 v[24:27], v[72:75], v[196:199], v[24:27]
	v_mfma_f32_16x16x32_bf16 v[8:11], v[216:219], v[196:199], v[8:11]
	ds_read_b128 v[176:179], v210 offset:57344
	s_add_u32 m0, s41, 20480
	s_nop 0
	global_load_lds_dwordx4 v213, s[100:101]
	s_waitcnt lgkmcnt(8)
	v_mfma_f32_16x16x32_bf16 v[56:59], v[72:75], v[200:203], v[56:59]
	v_mfma_f32_16x16x32_bf16 v[32:35], v[216:219], v[200:203], v[32:35]
	ds_read_b128 v[180:183], v210 offset:59392
	s_add_u32 m0, s41, 24576
	s_nop 0
	global_load_lds_dwordx4 v214, s[100:101]
	s_waitcnt lgkmcnt(8)
	v_mfma_f32_16x16x32_bf16 v[12:15], v[72:75], v[204:207], v[12:15]
	v_mfma_f32_16x16x32_bf16 v[4:7], v[216:219], v[204:207], v[4:7]
	ds_read_b128 v[184:187], v210 offset:61440
	s_add_u32 m0, s41, 28672
	s_nop 0
	global_load_lds_dwordx4 v215, s[100:101]
	s_add_u32 s100, s100, 128
	s_addc_u32 s101, s101, 0
	s_waitcnt lgkmcnt(6)
	v_mfma_f32_16x16x32_bf16 v[44:47], v[64:67], v[160:163], v[44:47]
	v_mfma_f32_16x16x32_bf16 v[48:51], v[68:71], v[160:163], v[48:51]
	ds_read_b128 v[188:191], v210 offset:63488
	s_waitcnt lgkmcnt(6)
	v_mfma_f32_16x16x32_bf16 v[28:31], v[64:67], v[164:167], v[28:31]
	v_mfma_f32_16x16x32_bf16 v[16:19], v[68:71], v[164:167], v[16:19]
	ds_read_b128 v[72:75], v209 offset:32768
	ds_read_b128 v[216:219], v209 offset:34816
	ds_read_b128 v[192:195], v211 offset:49152
	s_waitcnt lgkmcnt(8)
	v_mfma_f32_16x16x32_bf16 v[60:63], v[64:67], v[168:171], v[60:63]
	v_mfma_f32_16x16x32_bf16 v[40:43], v[68:71], v[168:171], v[40:43]
	ds_read_b128 v[196:199], v211 offset:51200
	s_waitcnt lgkmcnt(8)
	v_mfma_f32_16x16x32_bf16 v[20:23], v[64:67], v[172:175], v[20:23]
	v_mfma_f32_16x16x32_bf16 v[0:3], v[68:71], v[172:175], v[0:3]
	ds_read_b128 v[200:203], v211 offset:53248
	s_waitcnt lgkmcnt(8)
	v_mfma_f32_16x16x32_bf16 v[52:55], v[64:67], v[176:179], v[52:55]
	v_mfma_f32_16x16x32_bf16 v[36:39], v[68:71], v[176:179], v[36:39]
	ds_read_b128 v[204:207], v211 offset:55296
	s_waitcnt lgkmcnt(8)
	v_mfma_f32_16x16x32_bf16 v[24:27], v[64:67], v[180:183], v[24:27]
	v_mfma_f32_16x16x32_bf16 v[8:11], v[68:71], v[180:183], v[8:11]
	ds_read_b128 v[160:163], v211 offset:57344
	s_waitcnt lgkmcnt(8)
	v_mfma_f32_16x16x32_bf16 v[56:59], v[64:67], v[184:187], v[56:59]
	v_mfma_f32_16x16x32_bf16 v[32:35], v[68:71], v[184:187], v[32:35]
	ds_read_b128 v[164:167], v211 offset:59392
	s_waitcnt lgkmcnt(8)
	v_mfma_f32_16x16x32_bf16 v[12:15], v[64:67], v[188:191], v[12:15]
	v_mfma_f32_16x16x32_bf16 v[4:7], v[68:71], v[188:191], v[4:7]
	ds_read_b128 v[168:171], v211 offset:61440
	s_waitcnt lgkmcnt(6)
	v_mfma_f32_16x16x32_bf16 v[44:47], v[72:75], v[192:195], v[44:47]
	v_mfma_f32_16x16x32_bf16 v[48:51], v[216:219], v[192:195], v[48:51]
	ds_read_b128 v[172:175], v211 offset:63488
	s_waitcnt vmcnt(0) lgkmcnt(0)
	s_barrier
	s_add_u32 m0, s41, 32768
	s_nop 0
	global_load_lds_dwordx4 v212, s[98:99]
	s_waitcnt lgkmcnt(6)
	v_mfma_f32_16x16x32_bf16 v[28:31], v[72:75], v[196:199], v[28:31]
	v_mfma_f32_16x16x32_bf16 v[16:19], v[216:219], v[196:199], v[16:19]
	ds_read_b128 v[64:67], v208 offset:0
	ds_read_b128 v[68:71], v208 offset:2048
	ds_read_b128 v[176:179], v210 offset:16384
	s_add_u32 m0, s41, 36864
	s_nop 0
	global_load_lds_dwordx4 v213, s[98:99]
	s_waitcnt lgkmcnt(8)
	v_mfma_f32_16x16x32_bf16 v[60:63], v[72:75], v[200:203], v[60:63]
	v_mfma_f32_16x16x32_bf16 v[40:43], v[216:219], v[200:203], v[40:43]
	ds_read_b128 v[180:183], v210 offset:18432
	s_add_u32 m0, s41, 40960
	s_nop 0
	global_load_lds_dwordx4 v214, s[98:99]
	s_waitcnt lgkmcnt(8)
	v_mfma_f32_16x16x32_bf16 v[20:23], v[72:75], v[204:207], v[20:23]
	v_mfma_f32_16x16x32_bf16 v[0:3], v[216:219], v[204:207], v[0:3]
	ds_read_b128 v[184:187], v210 offset:20480
	s_add_u32 m0, s41, 45056
	s_nop 0
	global_load_lds_dwordx4 v215, s[98:99]
	s_add_u32 s98, s98, 128
	s_addc_u32 s99, s99, 0
	s_waitcnt lgkmcnt(8)
	v_mfma_f32_16x16x32_bf16 v[52:55], v[72:75], v[160:163], v[52:55]
	v_mfma_f32_16x16x32_bf16 v[36:39], v[216:219], v[160:163], v[36:39]
	ds_read_b128 v[188:191], v210 offset:22528
	s_add_u32 m0, s41, 49152
	s_nop 0
	global_load_lds_dwordx4 v212, s[100:101]
	s_waitcnt lgkmcnt(8)
	v_mfma_f32_16x16x32_bf16 v[24:27], v[72:75], v[164:167], v[24:27]
	v_mfma_f32_16x16x32_bf16 v[8:11], v[216:219], v[164:167], v[8:11]
	ds_read_b128 v[192:195], v210 offset:24576
	s_add_u32 m0, s41, 53248
	s_nop 0
	global_load_lds_dwordx4 v213, s[100:101]
	s_waitcnt lgkmcnt(8)
	v_mfma_f32_16x16x32_bf16 v[56:59], v[72:75], v[168:171], v[56:59]
	v_mfma_f32_16x16x32_bf16 v[32:35], v[216:219], v[168:171], v[32:35]
	ds_read_b128 v[196:199], v210 offset:26624
	s_add_u32 m0, s41, 57344
	s_nop 0
	global_load_lds_dwordx4 v214, s[100:101]
	s_waitcnt lgkmcnt(8)
	v_mfma_f32_16x16x32_bf16 v[12:15], v[72:75], v[172:175], v[12:15]
	v_mfma_f32_16x16x32_bf16 v[4:7], v[216:219], v[172:175], v[4:7]
	ds_read_b128 v[200:203], v210 offset:28672
	s_add_u32 m0, s41, 61440
	s_nop 0
	global_load_lds_dwordx4 v215, s[100:101]
	s_add_u32 s100, s100, 128
	s_addc_u32 s101, s101, 0
	s_waitcnt lgkmcnt(6)
	v_mfma_f32_16x16x32_bf16 v[44:47], v[64:67], v[176:179], v[44:47]
	v_mfma_f32_16x16x32_bf16 v[48:51], v[68:71], v[176:179], v[48:51]
	ds_read_b128 v[204:207], v210 offset:30720
	s_waitcnt lgkmcnt(6)
	v_mfma_f32_16x16x32_bf16 v[28:31], v[64:67], v[180:183], v[28:31]
	v_mfma_f32_16x16x32_bf16 v[16:19], v[68:71], v[180:183], v[16:19]
	ds_read_b128 v[72:75], v209 offset:0
	ds_read_b128 v[216:219], v209 offset:2048
	ds_read_b128 v[160:163], v211 offset:16384
	s_waitcnt lgkmcnt(8)
	v_mfma_f32_16x16x32_bf16 v[60:63], v[64:67], v[184:187], v[60:63]
	v_mfma_f32_16x16x32_bf16 v[40:43], v[68:71], v[184:187], v[40:43]
	ds_read_b128 v[164:167], v211 offset:18432
	s_waitcnt lgkmcnt(8)
	v_mfma_f32_16x16x32_bf16 v[20:23], v[64:67], v[188:191], v[20:23]
	v_mfma_f32_16x16x32_bf16 v[0:3], v[68:71], v[188:191], v[0:3]
	ds_read_b128 v[168:171], v211 offset:20480
	s_waitcnt lgkmcnt(8)
	v_mfma_f32_16x16x32_bf16 v[52:55], v[64:67], v[192:195], v[52:55]
	v_mfma_f32_16x16x32_bf16 v[36:39], v[68:71], v[192:195], v[36:39]
	ds_read_b128 v[172:175], v211 offset:22528
	s_waitcnt lgkmcnt(8)
	v_mfma_f32_16x16x32_bf16 v[24:27], v[64:67], v[196:199], v[24:27]
	v_mfma_f32_16x16x32_bf16 v[8:11], v[68:71], v[196:199], v[8:11]
	ds_read_b128 v[176:179], v211 offset:24576
	s_waitcnt lgkmcnt(8)
	v_mfma_f32_16x16x32_bf16 v[56:59], v[64:67], v[200:203], v[56:59]
	v_mfma_f32_16x16x32_bf16 v[32:35], v[68:71], v[200:203], v[32:35]
	ds_read_b128 v[180:183], v211 offset:26624
	s_waitcnt lgkmcnt(8)
	v_mfma_f32_16x16x32_bf16 v[12:15], v[64:67], v[204:207], v[12:15]
	v_mfma_f32_16x16x32_bf16 v[4:7], v[68:71], v[204:207], v[4:7]
	ds_read_b128 v[184:187], v211 offset:28672
	s_waitcnt lgkmcnt(6)
	v_mfma_f32_16x16x32_bf16 v[44:47], v[72:75], v[160:163], v[44:47]
	v_mfma_f32_16x16x32_bf16 v[48:51], v[216:219], v[160:163], v[48:51]
	ds_read_b128 v[188:191], v211 offset:30720
	s_waitcnt vmcnt(0) lgkmcnt(0)
	s_barrier
	s_add_u32 m0, s41, 0
	s_nop 0
	global_load_lds_dwordx4 v212, s[98:99]
	s_waitcnt lgkmcnt(6)
	v_mfma_f32_16x16x32_bf16 v[28:31], v[72:75], v[164:167], v[28:31]
	v_mfma_f32_16x16x32_bf16 v[16:19], v[216:219], v[164:167], v[16:19]
	ds_read_b128 v[64:67], v208 offset:32768
	ds_read_b128 v[68:71], v208 offset:34816
	ds_read_b128 v[192:195], v210 offset:49152
	s_add_u32 m0, s41, 4096
	s_nop 0
	global_load_lds_dwordx4 v213, s[98:99]
	s_waitcnt lgkmcnt(8)
	v_mfma_f32_16x16x32_bf16 v[60:63], v[72:75], v[168:171], v[60:63]
	v_mfma_f32_16x16x32_bf16 v[40:43], v[216:219], v[168:171], v[40:43]
	ds_read_b128 v[196:199], v210 offset:51200
	s_add_u32 m0, s41, 8192
	s_nop 0
	global_load_lds_dwordx4 v214, s[98:99]
	s_waitcnt lgkmcnt(8)
	v_mfma_f32_16x16x32_bf16 v[20:23], v[72:75], v[172:175], v[20:23]
	v_mfma_f32_16x16x32_bf16 v[0:3], v[216:219], v[172:175], v[0:3]
	ds_read_b128 v[200:203], v210 offset:53248
	s_add_u32 m0, s41, 12288
	s_nop 0
	global_load_lds_dwordx4 v215, s[98:99]
	s_add_u32 s98, s98, 128
	s_addc_u32 s99, s99, 0
	s_waitcnt lgkmcnt(8)
	v_mfma_f32_16x16x32_bf16 v[52:55], v[72:75], v[176:179], v[52:55]
	v_mfma_f32_16x16x32_bf16 v[36:39], v[216:219], v[176:179], v[36:39]
	ds_read_b128 v[204:207], v210 offset:55296
	s_add_u32 m0, s41, 16384
	s_nop 0
	global_load_lds_dwordx4 v212, s[100:101]
	s_waitcnt lgkmcnt(8)
	v_mfma_f32_16x16x32_bf16 v[24:27], v[72:75], v[180:183], v[24:27]
	v_mfma_f32_16x16x32_bf16 v[8:11], v[216:219], v[180:183], v[8:11]
	ds_read_b128 v[160:163], v210 offset:57344
	s_add_u32 m0, s41, 20480
	s_nop 0
	global_load_lds_dwordx4 v213, s[100:101]
	s_waitcnt lgkmcnt(8)
	v_mfma_f32_16x16x32_bf16 v[56:59], v[72:75], v[184:187], v[56:59]
	v_mfma_f32_16x16x32_bf16 v[32:35], v[216:219], v[184:187], v[32:35]
	ds_read_b128 v[164:167], v210 offset:59392
	s_add_u32 m0, s41, 24576
	s_nop 0
	global_load_lds_dwordx4 v214, s[100:101]
	s_waitcnt lgkmcnt(8)
	v_mfma_f32_16x16x32_bf16 v[12:15], v[72:75], v[188:191], v[12:15]
	v_mfma_f32_16x16x32_bf16 v[4:7], v[216:219], v[188:191], v[4:7]
	ds_read_b128 v[168:171], v210 offset:61440
	s_add_u32 m0, s41, 28672
	s_nop 0
	global_load_lds_dwordx4 v215, s[100:101]
	s_add_u32 s100, s100, 128
	s_addc_u32 s101, s101, 0
	s_waitcnt lgkmcnt(6)
	v_mfma_f32_16x16x32_bf16 v[44:47], v[64:67], v[192:195], v[44:47]
	v_mfma_f32_16x16x32_bf16 v[48:51], v[68:71], v[192:195], v[48:51]
	ds_read_b128 v[172:175], v210 offset:63488
	s_waitcnt lgkmcnt(6)
	v_mfma_f32_16x16x32_bf16 v[28:31], v[64:67], v[196:199], v[28:31]
	v_mfma_f32_16x16x32_bf16 v[16:19], v[68:71], v[196:199], v[16:19]
	ds_read_b128 v[72:75], v209 offset:32768
	ds_read_b128 v[216:219], v209 offset:34816
	ds_read_b128 v[176:179], v211 offset:49152
	s_waitcnt lgkmcnt(8)
	v_mfma_f32_16x16x32_bf16 v[60:63], v[64:67], v[200:203], v[60:63]
	v_mfma_f32_16x16x32_bf16 v[40:43], v[68:71], v[200:203], v[40:43]
	ds_read_b128 v[180:183], v211 offset:51200
	s_waitcnt lgkmcnt(8)
	v_mfma_f32_16x16x32_bf16 v[20:23], v[64:67], v[204:207], v[20:23]
	v_mfma_f32_16x16x32_bf16 v[0:3], v[68:71], v[204:207], v[0:3]
	ds_read_b128 v[184:187], v211 offset:53248
	s_waitcnt lgkmcnt(8)
	v_mfma_f32_16x16x32_bf16 v[52:55], v[64:67], v[160:163], v[52:55]
	v_mfma_f32_16x16x32_bf16 v[36:39], v[68:71], v[160:163], v[36:39]
	ds_read_b128 v[188:191], v211 offset:55296
	s_waitcnt lgkmcnt(8)
	v_mfma_f32_16x16x32_bf16 v[24:27], v[64:67], v[164:167], v[24:27]
	v_mfma_f32_16x16x32_bf16 v[8:11], v[68:71], v[164:167], v[8:11]
	ds_read_b128 v[192:195], v211 offset:57344
	s_waitcnt lgkmcnt(8)
	v_mfma_f32_16x16x32_bf16 v[56:59], v[64:67], v[168:171], v[56:59]
	v_mfma_f32_16x16x32_bf16 v[32:35], v[68:71], v[168:171], v[32:35]
	ds_read_b128 v[196:199], v211 offset:59392
	s_waitcnt lgkmcnt(8)
	v_mfma_f32_16x16x32_bf16 v[12:15], v[64:67], v[172:175], v[12:15]
	v_mfma_f32_16x16x32_bf16 v[4:7], v[68:71], v[172:175], v[4:7]
	ds_read_b128 v[200:203], v211 offset:61440
	s_waitcnt lgkmcnt(6)
	v_mfma_f32_16x16x32_bf16 v[44:47], v[72:75], v[176:179], v[44:47]
	v_mfma_f32_16x16x32_bf16 v[48:51], v[216:219], v[176:179], v[48:51]
	ds_read_b128 v[204:207], v211 offset:63488
	s_waitcnt vmcnt(0) lgkmcnt(0)
	s_barrier
	s_add_u32 m0, s41, 32768
	s_nop 0
	global_load_lds_dwordx4 v212, s[98:99]
	s_waitcnt lgkmcnt(6)
	v_mfma_f32_16x16x32_bf16 v[28:31], v[72:75], v[180:183], v[28:31]
	v_mfma_f32_16x16x32_bf16 v[16:19], v[216:219], v[180:183], v[16:19]
	ds_read_b128 v[64:67], v208 offset:0
	ds_read_b128 v[68:71], v208 offset:2048
	ds_read_b128 v[160:163], v210 offset:16384
	s_add_u32 m0, s41, 36864
	s_nop 0
	global_load_lds_dwordx4 v213, s[98:99]
	s_waitcnt lgkmcnt(8)
	v_mfma_f32_16x16x32_bf16 v[60:63], v[72:75], v[184:187], v[60:63]
	v_mfma_f32_16x16x32_bf16 v[40:43], v[216:219], v[184:187], v[40:43]
	ds_read_b128 v[164:167], v210 offset:18432
	s_add_u32 m0, s41, 40960
	s_nop 0
	global_load_lds_dwordx4 v214, s[98:99]
	s_waitcnt lgkmcnt(8)
	v_mfma_f32_16x16x32_bf16 v[20:23], v[72:75], v[188:191], v[20:23]
	v_mfma_f32_16x16x32_bf16 v[0:3], v[216:219], v[188:191], v[0:3]
	ds_read_b128 v[168:171], v210 offset:20480
	s_add_u32 m0, s41, 45056
	s_nop 0
	global_load_lds_dwordx4 v215, s[98:99]
	s_add_u32 s98, s98, 128
	s_addc_u32 s99, s99, 0
	s_waitcnt lgkmcnt(8)
	v_mfma_f32_16x16x32_bf16 v[52:55], v[72:75], v[192:195], v[52:55]
	v_mfma_f32_16x16x32_bf16 v[36:39], v[216:219], v[192:195], v[36:39]
	ds_read_b128 v[172:175], v210 offset:22528
	s_add_u32 m0, s41, 49152
	s_nop 0
	global_load_lds_dwordx4 v212, s[100:101]
	s_waitcnt lgkmcnt(8)
	v_mfma_f32_16x16x32_bf16 v[24:27], v[72:75], v[196:199], v[24:27]
	v_mfma_f32_16x16x32_bf16 v[8:11], v[216:219], v[196:199], v[8:11]
	ds_read_b128 v[176:179], v210 offset:24576
	s_add_u32 m0, s41, 53248
	s_nop 0
	global_load_lds_dwordx4 v213, s[100:101]
	s_waitcnt lgkmcnt(8)
	v_mfma_f32_16x16x32_bf16 v[56:59], v[72:75], v[200:203], v[56:59]
	v_mfma_f32_16x16x32_bf16 v[32:35], v[216:219], v[200:203], v[32:35]
	ds_read_b128 v[180:183], v210 offset:26624
	s_add_u32 m0, s41, 57344
	s_nop 0
	global_load_lds_dwordx4 v214, s[100:101]
	s_waitcnt lgkmcnt(8)
	v_mfma_f32_16x16x32_bf16 v[12:15], v[72:75], v[204:207], v[12:15]
	v_mfma_f32_16x16x32_bf16 v[4:7], v[216:219], v[204:207], v[4:7]
	ds_read_b128 v[184:187], v210 offset:28672
	s_add_u32 m0, s41, 61440
	s_nop 0
	global_load_lds_dwordx4 v215, s[100:101]
	s_add_u32 s100, s100, 128
	s_addc_u32 s101, s101, 0
	s_waitcnt lgkmcnt(6)
	v_mfma_f32_16x16x32_bf16 v[44:47], v[64:67], v[160:163], v[44:47]
	v_mfma_f32_16x16x32_bf16 v[48:51], v[68:71], v[160:163], v[48:51]
	ds_read_b128 v[188:191], v210 offset:30720
	s_waitcnt lgkmcnt(6)
	v_mfma_f32_16x16x32_bf16 v[28:31], v[64:67], v[164:167], v[28:31]
	v_mfma_f32_16x16x32_bf16 v[16:19], v[68:71], v[164:167], v[16:19]
	ds_read_b128 v[72:75], v209 offset:0
	ds_read_b128 v[216:219], v209 offset:2048
	ds_read_b128 v[192:195], v211 offset:16384
	s_waitcnt lgkmcnt(8)
	v_mfma_f32_16x16x32_bf16 v[60:63], v[64:67], v[168:171], v[60:63]
	v_mfma_f32_16x16x32_bf16 v[40:43], v[68:71], v[168:171], v[40:43]
	ds_read_b128 v[196:199], v211 offset:18432
	s_waitcnt lgkmcnt(8)
	v_mfma_f32_16x16x32_bf16 v[20:23], v[64:67], v[172:175], v[20:23]
	v_mfma_f32_16x16x32_bf16 v[0:3], v[68:71], v[172:175], v[0:3]
	ds_read_b128 v[200:203], v211 offset:20480
	s_waitcnt lgkmcnt(8)
	v_mfma_f32_16x16x32_bf16 v[52:55], v[64:67], v[176:179], v[52:55]
	v_mfma_f32_16x16x32_bf16 v[36:39], v[68:71], v[176:179], v[36:39]
	ds_read_b128 v[204:207], v211 offset:22528
	s_waitcnt lgkmcnt(8)
	v_mfma_f32_16x16x32_bf16 v[24:27], v[64:67], v[180:183], v[24:27]
	v_mfma_f32_16x16x32_bf16 v[8:11], v[68:71], v[180:183], v[8:11]
	ds_read_b128 v[160:163], v211 offset:24576
	s_waitcnt lgkmcnt(8)
	v_mfma_f32_16x16x32_bf16 v[56:59], v[64:67], v[184:187], v[56:59]
	v_mfma_f32_16x16x32_bf16 v[32:35], v[68:71], v[184:187], v[32:35]
	ds_read_b128 v[164:167], v211 offset:26624
	s_waitcnt lgkmcnt(8)
	v_mfma_f32_16x16x32_bf16 v[12:15], v[64:67], v[188:191], v[12:15]
	v_mfma_f32_16x16x32_bf16 v[4:7], v[68:71], v[188:191], v[4:7]
	ds_read_b128 v[168:171], v211 offset:28672
	s_waitcnt lgkmcnt(6)
	v_mfma_f32_16x16x32_bf16 v[44:47], v[72:75], v[192:195], v[44:47]
	v_mfma_f32_16x16x32_bf16 v[48:51], v[216:219], v[192:195], v[48:51]
	ds_read_b128 v[172:175], v211 offset:30720
	s_waitcnt vmcnt(0) lgkmcnt(0)
	s_barrier
	s_add_u32 m0, s41, 0
	s_nop 0
	global_load_lds_dwordx4 v212, s[98:99]
	s_waitcnt lgkmcnt(6)
	v_mfma_f32_16x16x32_bf16 v[28:31], v[72:75], v[196:199], v[28:31]
	v_mfma_f32_16x16x32_bf16 v[16:19], v[216:219], v[196:199], v[16:19]
	ds_read_b128 v[64:67], v208 offset:32768
	ds_read_b128 v[68:71], v208 offset:34816
	ds_read_b128 v[176:179], v210 offset:49152
	s_add_u32 m0, s41, 4096
	s_nop 0
	global_load_lds_dwordx4 v213, s[98:99]
	s_waitcnt lgkmcnt(8)
	v_mfma_f32_16x16x32_bf16 v[60:63], v[72:75], v[200:203], v[60:63]
	v_mfma_f32_16x16x32_bf16 v[40:43], v[216:219], v[200:203], v[40:43]
	ds_read_b128 v[180:183], v210 offset:51200
	s_add_u32 m0, s41, 8192
	s_nop 0
	global_load_lds_dwordx4 v214, s[98:99]
	s_waitcnt lgkmcnt(8)
	v_mfma_f32_16x16x32_bf16 v[20:23], v[72:75], v[204:207], v[20:23]
	v_mfma_f32_16x16x32_bf16 v[0:3], v[216:219], v[204:207], v[0:3]
	ds_read_b128 v[184:187], v210 offset:53248
	s_add_u32 m0, s41, 12288
	s_nop 0
	global_load_lds_dwordx4 v215, s[98:99]
	s_add_u32 s98, s98, 128
	s_addc_u32 s99, s99, 0
	s_waitcnt lgkmcnt(8)
	v_mfma_f32_16x16x32_bf16 v[52:55], v[72:75], v[160:163], v[52:55]
	v_mfma_f32_16x16x32_bf16 v[36:39], v[216:219], v[160:163], v[36:39]
	ds_read_b128 v[188:191], v210 offset:55296
	s_add_u32 m0, s41, 16384
	s_nop 0
	global_load_lds_dwordx4 v212, s[100:101]
	s_waitcnt lgkmcnt(8)
	v_mfma_f32_16x16x32_bf16 v[24:27], v[72:75], v[164:167], v[24:27]
	v_mfma_f32_16x16x32_bf16 v[8:11], v[216:219], v[164:167], v[8:11]
	ds_read_b128 v[192:195], v210 offset:57344
	s_add_u32 m0, s41, 20480
	s_nop 0
	global_load_lds_dwordx4 v213, s[100:101]
	s_waitcnt lgkmcnt(8)
	v_mfma_f32_16x16x32_bf16 v[56:59], v[72:75], v[168:171], v[56:59]
	v_mfma_f32_16x16x32_bf16 v[32:35], v[216:219], v[168:171], v[32:35]
	ds_read_b128 v[196:199], v210 offset:59392
	s_add_u32 m0, s41, 24576
	s_nop 0
	global_load_lds_dwordx4 v214, s[100:101]
	s_waitcnt lgkmcnt(8)
	v_mfma_f32_16x16x32_bf16 v[12:15], v[72:75], v[172:175], v[12:15]
	v_mfma_f32_16x16x32_bf16 v[4:7], v[216:219], v[172:175], v[4:7]
	ds_read_b128 v[200:203], v210 offset:61440
	s_add_u32 m0, s41, 28672
	s_nop 0
	global_load_lds_dwordx4 v215, s[100:101]
	s_add_u32 s100, s100, 128
	s_addc_u32 s101, s101, 0
	s_waitcnt lgkmcnt(6)
	v_mfma_f32_16x16x32_bf16 v[44:47], v[64:67], v[176:179], v[44:47]
	v_mfma_f32_16x16x32_bf16 v[48:51], v[68:71], v[176:179], v[48:51]
	ds_read_b128 v[204:207], v210 offset:63488
	s_waitcnt lgkmcnt(6)
	v_mfma_f32_16x16x32_bf16 v[28:31], v[64:67], v[180:183], v[28:31]
	v_mfma_f32_16x16x32_bf16 v[16:19], v[68:71], v[180:183], v[16:19]
	ds_read_b128 v[72:75], v209 offset:32768
	ds_read_b128 v[216:219], v209 offset:34816
	ds_read_b128 v[160:163], v211 offset:49152
	s_waitcnt lgkmcnt(8)
	v_mfma_f32_16x16x32_bf16 v[60:63], v[64:67], v[184:187], v[60:63]
	v_mfma_f32_16x16x32_bf16 v[40:43], v[68:71], v[184:187], v[40:43]
	ds_read_b128 v[164:167], v211 offset:51200
	s_waitcnt lgkmcnt(8)
	v_mfma_f32_16x16x32_bf16 v[20:23], v[64:67], v[188:191], v[20:23]
	v_mfma_f32_16x16x32_bf16 v[0:3], v[68:71], v[188:191], v[0:3]
	ds_read_b128 v[168:171], v211 offset:53248
	s_waitcnt lgkmcnt(8)
	v_mfma_f32_16x16x32_bf16 v[52:55], v[64:67], v[192:195], v[52:55]
	v_mfma_f32_16x16x32_bf16 v[36:39], v[68:71], v[192:195], v[36:39]
	ds_read_b128 v[172:175], v211 offset:55296
	s_waitcnt lgkmcnt(8)
	v_mfma_f32_16x16x32_bf16 v[24:27], v[64:67], v[196:199], v[24:27]
	v_mfma_f32_16x16x32_bf16 v[8:11], v[68:71], v[196:199], v[8:11]
	ds_read_b128 v[176:179], v211 offset:57344
	s_waitcnt lgkmcnt(8)
	v_mfma_f32_16x16x32_bf16 v[56:59], v[64:67], v[200:203], v[56:59]
	v_mfma_f32_16x16x32_bf16 v[32:35], v[68:71], v[200:203], v[32:35]
	ds_read_b128 v[180:183], v211 offset:59392
	s_waitcnt lgkmcnt(8)
	v_mfma_f32_16x16x32_bf16 v[12:15], v[64:67], v[204:207], v[12:15]
	v_mfma_f32_16x16x32_bf16 v[4:7], v[68:71], v[204:207], v[4:7]
	ds_read_b128 v[184:187], v211 offset:61440
	s_waitcnt lgkmcnt(6)
	v_mfma_f32_16x16x32_bf16 v[44:47], v[72:75], v[160:163], v[44:47]
	v_mfma_f32_16x16x32_bf16 v[48:51], v[216:219], v[160:163], v[48:51]
	ds_read_b128 v[188:191], v211 offset:63488
	s_waitcnt vmcnt(0) lgkmcnt(0)
	s_barrier
	s_add_u32 m0, s41, 32768
	s_nop 0
	global_load_lds_dwordx4 v212, s[98:99]
	s_waitcnt lgkmcnt(6)
	v_mfma_f32_16x16x32_bf16 v[28:31], v[72:75], v[164:167], v[28:31]
	v_mfma_f32_16x16x32_bf16 v[16:19], v[216:219], v[164:167], v[16:19]
	ds_read_b128 v[64:67], v208 offset:0
	ds_read_b128 v[68:71], v208 offset:2048
	ds_read_b128 v[192:195], v210 offset:16384
	s_add_u32 m0, s41, 36864
	s_nop 0
	global_load_lds_dwordx4 v213, s[98:99]
	s_waitcnt lgkmcnt(8)
	v_mfma_f32_16x16x32_bf16 v[60:63], v[72:75], v[168:171], v[60:63]
	v_mfma_f32_16x16x32_bf16 v[40:43], v[216:219], v[168:171], v[40:43]
	ds_read_b128 v[196:199], v210 offset:18432
	s_add_u32 m0, s41, 40960
	s_nop 0
	global_load_lds_dwordx4 v214, s[98:99]
	s_waitcnt lgkmcnt(8)
	v_mfma_f32_16x16x32_bf16 v[20:23], v[72:75], v[172:175], v[20:23]
	v_mfma_f32_16x16x32_bf16 v[0:3], v[216:219], v[172:175], v[0:3]
	ds_read_b128 v[200:203], v210 offset:20480
	s_add_u32 m0, s41, 45056
	s_nop 0
	global_load_lds_dwordx4 v215, s[98:99]
	s_add_u32 s98, s98, 128
	s_addc_u32 s99, s99, 0
	s_waitcnt lgkmcnt(8)
	v_mfma_f32_16x16x32_bf16 v[52:55], v[72:75], v[176:179], v[52:55]
	v_mfma_f32_16x16x32_bf16 v[36:39], v[216:219], v[176:179], v[36:39]
	ds_read_b128 v[204:207], v210 offset:22528
	s_add_u32 m0, s41, 49152
	s_nop 0
	global_load_lds_dwordx4 v212, s[100:101]
	s_waitcnt lgkmcnt(8)
	v_mfma_f32_16x16x32_bf16 v[24:27], v[72:75], v[180:183], v[24:27]
	v_mfma_f32_16x16x32_bf16 v[8:11], v[216:219], v[180:183], v[8:11]
	ds_read_b128 v[160:163], v210 offset:24576
	s_add_u32 m0, s41, 53248
	s_nop 0
	global_load_lds_dwordx4 v213, s[100:101]
	s_waitcnt lgkmcnt(8)
	v_mfma_f32_16x16x32_bf16 v[56:59], v[72:75], v[184:187], v[56:59]
	v_mfma_f32_16x16x32_bf16 v[32:35], v[216:219], v[184:187], v[32:35]
	ds_read_b128 v[164:167], v210 offset:26624
	s_add_u32 m0, s41, 57344
	s_nop 0
	global_load_lds_dwordx4 v214, s[100:101]
	s_waitcnt lgkmcnt(8)
	v_mfma_f32_16x16x32_bf16 v[12:15], v[72:75], v[188:191], v[12:15]
	v_mfma_f32_16x16x32_bf16 v[4:7], v[216:219], v[188:191], v[4:7]
	ds_read_b128 v[168:171], v210 offset:28672
	s_add_u32 m0, s41, 61440
	s_nop 0
	global_load_lds_dwordx4 v215, s[100:101]
	s_add_u32 s100, s100, 128
	s_addc_u32 s101, s101, 0
	s_waitcnt lgkmcnt(6)
	v_mfma_f32_16x16x32_bf16 v[44:47], v[64:67], v[192:195], v[44:47]
	v_mfma_f32_16x16x32_bf16 v[48:51], v[68:71], v[192:195], v[48:51]
	ds_read_b128 v[172:175], v210 offset:30720
	s_waitcnt lgkmcnt(6)
	v_mfma_f32_16x16x32_bf16 v[28:31], v[64:67], v[196:199], v[28:31]
	v_mfma_f32_16x16x32_bf16 v[16:19], v[68:71], v[196:199], v[16:19]
	ds_read_b128 v[72:75], v209 offset:0
	ds_read_b128 v[216:219], v209 offset:2048
	ds_read_b128 v[176:179], v211 offset:16384
	s_waitcnt lgkmcnt(8)
	v_mfma_f32_16x16x32_bf16 v[60:63], v[64:67], v[200:203], v[60:63]
	v_mfma_f32_16x16x32_bf16 v[40:43], v[68:71], v[200:203], v[40:43]
	ds_read_b128 v[180:183], v211 offset:18432
	s_waitcnt lgkmcnt(8)
	v_mfma_f32_16x16x32_bf16 v[20:23], v[64:67], v[204:207], v[20:23]
	v_mfma_f32_16x16x32_bf16 v[0:3], v[68:71], v[204:207], v[0:3]
	ds_read_b128 v[184:187], v211 offset:20480
	s_waitcnt lgkmcnt(8)
	v_mfma_f32_16x16x32_bf16 v[52:55], v[64:67], v[160:163], v[52:55]
	v_mfma_f32_16x16x32_bf16 v[36:39], v[68:71], v[160:163], v[36:39]
	ds_read_b128 v[188:191], v211 offset:22528
	s_waitcnt lgkmcnt(8)
	v_mfma_f32_16x16x32_bf16 v[24:27], v[64:67], v[164:167], v[24:27]
	v_mfma_f32_16x16x32_bf16 v[8:11], v[68:71], v[164:167], v[8:11]
	ds_read_b128 v[192:195], v211 offset:24576
	s_waitcnt lgkmcnt(8)
	v_mfma_f32_16x16x32_bf16 v[56:59], v[64:67], v[168:171], v[56:59]
	v_mfma_f32_16x16x32_bf16 v[32:35], v[68:71], v[168:171], v[32:35]
	ds_read_b128 v[196:199], v211 offset:26624
	s_waitcnt lgkmcnt(8)
	v_mfma_f32_16x16x32_bf16 v[12:15], v[64:67], v[172:175], v[12:15]
	v_mfma_f32_16x16x32_bf16 v[4:7], v[68:71], v[172:175], v[4:7]
	ds_read_b128 v[200:203], v211 offset:28672
	s_waitcnt lgkmcnt(6)
	v_mfma_f32_16x16x32_bf16 v[44:47], v[72:75], v[176:179], v[44:47]
	v_mfma_f32_16x16x32_bf16 v[48:51], v[216:219], v[176:179], v[48:51]
	ds_read_b128 v[204:207], v211 offset:30720
	s_waitcnt vmcnt(0) lgkmcnt(0)
	s_barrier
	s_add_u32 m0, s41, 0
	s_nop 0
	global_load_lds_dwordx4 v212, s[98:99]
	s_waitcnt lgkmcnt(6)
	v_mfma_f32_16x16x32_bf16 v[28:31], v[72:75], v[180:183], v[28:31]
	v_mfma_f32_16x16x32_bf16 v[16:19], v[216:219], v[180:183], v[16:19]
	ds_read_b128 v[64:67], v208 offset:32768
	ds_read_b128 v[68:71], v208 offset:34816
	ds_read_b128 v[160:163], v210 offset:49152
	s_add_u32 m0, s41, 4096
	s_nop 0
	global_load_lds_dwordx4 v213, s[98:99]
	s_waitcnt lgkmcnt(8)
	v_mfma_f32_16x16x32_bf16 v[60:63], v[72:75], v[184:187], v[60:63]
	v_mfma_f32_16x16x32_bf16 v[40:43], v[216:219], v[184:187], v[40:43]
	ds_read_b128 v[164:167], v210 offset:51200
	s_add_u32 m0, s41, 8192
	s_nop 0
	global_load_lds_dwordx4 v214, s[98:99]
	s_waitcnt lgkmcnt(8)
	v_mfma_f32_16x16x32_bf16 v[20:23], v[72:75], v[188:191], v[20:23]
	v_mfma_f32_16x16x32_bf16 v[0:3], v[216:219], v[188:191], v[0:3]
	ds_read_b128 v[168:171], v210 offset:53248
	s_add_u32 m0, s41, 12288
	s_nop 0
	global_load_lds_dwordx4 v215, s[98:99]
	s_add_u32 s98, s98, 128
	s_addc_u32 s99, s99, 0
	s_waitcnt lgkmcnt(8)
	v_mfma_f32_16x16x32_bf16 v[52:55], v[72:75], v[192:195], v[52:55]
	v_mfma_f32_16x16x32_bf16 v[36:39], v[216:219], v[192:195], v[36:39]
	ds_read_b128 v[172:175], v210 offset:55296
	s_add_u32 m0, s41, 16384
	s_nop 0
	global_load_lds_dwordx4 v212, s[100:101]
	s_waitcnt lgkmcnt(8)
	v_mfma_f32_16x16x32_bf16 v[24:27], v[72:75], v[196:199], v[24:27]
	v_mfma_f32_16x16x32_bf16 v[8:11], v[216:219], v[196:199], v[8:11]
	ds_read_b128 v[176:179], v210 offset:57344
	s_add_u32 m0, s41, 20480
	s_nop 0
	global_load_lds_dwordx4 v213, s[100:101]
	s_waitcnt lgkmcnt(8)
	v_mfma_f32_16x16x32_bf16 v[56:59], v[72:75], v[200:203], v[56:59]
	v_mfma_f32_16x16x32_bf16 v[32:35], v[216:219], v[200:203], v[32:35]
	ds_read_b128 v[180:183], v210 offset:59392
	s_add_u32 m0, s41, 24576
	s_nop 0
	global_load_lds_dwordx4 v214, s[100:101]
	s_waitcnt lgkmcnt(8)
	v_mfma_f32_16x16x32_bf16 v[12:15], v[72:75], v[204:207], v[12:15]
	v_mfma_f32_16x16x32_bf16 v[4:7], v[216:219], v[204:207], v[4:7]
	ds_read_b128 v[184:187], v210 offset:61440
	s_add_u32 m0, s41, 28672
	s_nop 0
	global_load_lds_dwordx4 v215, s[100:101]
	s_add_u32 s100, s100, 128
	s_addc_u32 s101, s101, 0
	s_waitcnt lgkmcnt(6)
	v_mfma_f32_16x16x32_bf16 v[44:47], v[64:67], v[160:163], v[44:47]
	v_mfma_f32_16x16x32_bf16 v[48:51], v[68:71], v[160:163], v[48:51]
	ds_read_b128 v[188:191], v210 offset:63488
	s_waitcnt lgkmcnt(6)
	v_mfma_f32_16x16x32_bf16 v[28:31], v[64:67], v[164:167], v[28:31]
	v_mfma_f32_16x16x32_bf16 v[16:19], v[68:71], v[164:167], v[16:19]
	ds_read_b128 v[72:75], v209 offset:32768
	ds_read_b128 v[216:219], v209 offset:34816
	ds_read_b128 v[192:195], v211 offset:49152
	s_waitcnt lgkmcnt(8)
	v_mfma_f32_16x16x32_bf16 v[60:63], v[64:67], v[168:171], v[60:63]
	v_mfma_f32_16x16x32_bf16 v[40:43], v[68:71], v[168:171], v[40:43]
	ds_read_b128 v[196:199], v211 offset:51200
	s_waitcnt lgkmcnt(8)
	v_mfma_f32_16x16x32_bf16 v[20:23], v[64:67], v[172:175], v[20:23]
	v_mfma_f32_16x16x32_bf16 v[0:3], v[68:71], v[172:175], v[0:3]
	ds_read_b128 v[200:203], v211 offset:53248
	s_waitcnt lgkmcnt(8)
	v_mfma_f32_16x16x32_bf16 v[52:55], v[64:67], v[176:179], v[52:55]
	v_mfma_f32_16x16x32_bf16 v[36:39], v[68:71], v[176:179], v[36:39]
	ds_read_b128 v[204:207], v211 offset:55296
	s_waitcnt lgkmcnt(8)
	v_mfma_f32_16x16x32_bf16 v[24:27], v[64:67], v[180:183], v[24:27]
	v_mfma_f32_16x16x32_bf16 v[8:11], v[68:71], v[180:183], v[8:11]
	ds_read_b128 v[160:163], v211 offset:57344
	s_waitcnt lgkmcnt(8)
	v_mfma_f32_16x16x32_bf16 v[56:59], v[64:67], v[184:187], v[56:59]
	v_mfma_f32_16x16x32_bf16 v[32:35], v[68:71], v[184:187], v[32:35]
	ds_read_b128 v[164:167], v211 offset:59392
	s_waitcnt lgkmcnt(8)
	v_mfma_f32_16x16x32_bf16 v[12:15], v[64:67], v[188:191], v[12:15]
	v_mfma_f32_16x16x32_bf16 v[4:7], v[68:71], v[188:191], v[4:7]
	ds_read_b128 v[168:171], v211 offset:61440
	s_waitcnt lgkmcnt(6)
	v_mfma_f32_16x16x32_bf16 v[44:47], v[72:75], v[192:195], v[44:47]
	v_mfma_f32_16x16x32_bf16 v[48:51], v[216:219], v[192:195], v[48:51]
	ds_read_b128 v[172:175], v211 offset:63488
	s_waitcnt vmcnt(0) lgkmcnt(0)
	s_barrier
	s_add_u32 m0, s41, 32768
	s_nop 0
	global_load_lds_dwordx4 v212, s[98:99]
	s_waitcnt lgkmcnt(6)
	v_mfma_f32_16x16x32_bf16 v[28:31], v[72:75], v[196:199], v[28:31]
	v_mfma_f32_16x16x32_bf16 v[16:19], v[216:219], v[196:199], v[16:19]
	ds_read_b128 v[64:67], v208 offset:0
	ds_read_b128 v[68:71], v208 offset:2048
	ds_read_b128 v[176:179], v210 offset:16384
	s_add_u32 m0, s41, 36864
	s_nop 0
	global_load_lds_dwordx4 v213, s[98:99]
	s_waitcnt lgkmcnt(8)
	v_mfma_f32_16x16x32_bf16 v[60:63], v[72:75], v[200:203], v[60:63]
	v_mfma_f32_16x16x32_bf16 v[40:43], v[216:219], v[200:203], v[40:43]
	ds_read_b128 v[180:183], v210 offset:18432
	s_add_u32 m0, s41, 40960
	s_nop 0
	global_load_lds_dwordx4 v214, s[98:99]
	s_waitcnt lgkmcnt(8)
	v_mfma_f32_16x16x32_bf16 v[20:23], v[72:75], v[204:207], v[20:23]
	v_mfma_f32_16x16x32_bf16 v[0:3], v[216:219], v[204:207], v[0:3]
	ds_read_b128 v[184:187], v210 offset:20480
	s_add_u32 m0, s41, 45056
	s_nop 0
	global_load_lds_dwordx4 v215, s[98:99]
	s_add_u32 s98, s98, 128
	s_addc_u32 s99, s99, 0
	s_waitcnt lgkmcnt(8)
	v_mfma_f32_16x16x32_bf16 v[52:55], v[72:75], v[160:163], v[52:55]
	v_mfma_f32_16x16x32_bf16 v[36:39], v[216:219], v[160:163], v[36:39]
	ds_read_b128 v[188:191], v210 offset:22528
	s_add_u32 m0, s41, 49152
	s_nop 0
	global_load_lds_dwordx4 v212, s[100:101]
	s_waitcnt lgkmcnt(8)
	v_mfma_f32_16x16x32_bf16 v[24:27], v[72:75], v[164:167], v[24:27]
	v_mfma_f32_16x16x32_bf16 v[8:11], v[216:219], v[164:167], v[8:11]
	ds_read_b128 v[192:195], v210 offset:24576
	s_add_u32 m0, s41, 53248
	s_nop 0
	global_load_lds_dwordx4 v213, s[100:101]
	s_waitcnt lgkmcnt(8)
	v_mfma_f32_16x16x32_bf16 v[56:59], v[72:75], v[168:171], v[56:59]
	v_mfma_f32_16x16x32_bf16 v[32:35], v[216:219], v[168:171], v[32:35]
	ds_read_b128 v[196:199], v210 offset:26624
	s_add_u32 m0, s41, 57344
	s_nop 0
	global_load_lds_dwordx4 v214, s[100:101]
	s_waitcnt lgkmcnt(8)
	v_mfma_f32_16x16x32_bf16 v[12:15], v[72:75], v[172:175], v[12:15]
	v_mfma_f32_16x16x32_bf16 v[4:7], v[216:219], v[172:175], v[4:7]
	ds_read_b128 v[200:203], v210 offset:28672
	s_add_u32 m0, s41, 61440
	s_nop 0
	global_load_lds_dwordx4 v215, s[100:101]
	s_add_u32 s100, s100, 128
	s_addc_u32 s101, s101, 0
	s_waitcnt lgkmcnt(6)
	v_mfma_f32_16x16x32_bf16 v[44:47], v[64:67], v[176:179], v[44:47]
	v_mfma_f32_16x16x32_bf16 v[48:51], v[68:71], v[176:179], v[48:51]
	ds_read_b128 v[204:207], v210 offset:30720
	s_waitcnt lgkmcnt(6)
	v_mfma_f32_16x16x32_bf16 v[28:31], v[64:67], v[180:183], v[28:31]
	v_mfma_f32_16x16x32_bf16 v[16:19], v[68:71], v[180:183], v[16:19]
	ds_read_b128 v[72:75], v209 offset:0
	ds_read_b128 v[216:219], v209 offset:2048
	ds_read_b128 v[160:163], v211 offset:16384
	s_waitcnt lgkmcnt(8)
	v_mfma_f32_16x16x32_bf16 v[60:63], v[64:67], v[184:187], v[60:63]
	v_mfma_f32_16x16x32_bf16 v[40:43], v[68:71], v[184:187], v[40:43]
	ds_read_b128 v[164:167], v211 offset:18432
	s_waitcnt lgkmcnt(8)
	v_mfma_f32_16x16x32_bf16 v[20:23], v[64:67], v[188:191], v[20:23]
	v_mfma_f32_16x16x32_bf16 v[0:3], v[68:71], v[188:191], v[0:3]
	ds_read_b128 v[168:171], v211 offset:20480
	s_waitcnt lgkmcnt(8)
	v_mfma_f32_16x16x32_bf16 v[52:55], v[64:67], v[192:195], v[52:55]
	v_mfma_f32_16x16x32_bf16 v[36:39], v[68:71], v[192:195], v[36:39]
	ds_read_b128 v[172:175], v211 offset:22528
	s_waitcnt lgkmcnt(8)
	v_mfma_f32_16x16x32_bf16 v[24:27], v[64:67], v[196:199], v[24:27]
	v_mfma_f32_16x16x32_bf16 v[8:11], v[68:71], v[196:199], v[8:11]
	ds_read_b128 v[176:179], v211 offset:24576
	s_waitcnt lgkmcnt(8)
	v_mfma_f32_16x16x32_bf16 v[56:59], v[64:67], v[200:203], v[56:59]
	v_mfma_f32_16x16x32_bf16 v[32:35], v[68:71], v[200:203], v[32:35]
	ds_read_b128 v[180:183], v211 offset:26624
	s_waitcnt lgkmcnt(8)
	v_mfma_f32_16x16x32_bf16 v[12:15], v[64:67], v[204:207], v[12:15]
	v_mfma_f32_16x16x32_bf16 v[4:7], v[68:71], v[204:207], v[4:7]
	ds_read_b128 v[184:187], v211 offset:28672
	s_waitcnt lgkmcnt(6)
	v_mfma_f32_16x16x32_bf16 v[44:47], v[72:75], v[160:163], v[44:47]
	v_mfma_f32_16x16x32_bf16 v[48:51], v[216:219], v[160:163], v[48:51]
	ds_read_b128 v[188:191], v211 offset:30720
	s_waitcnt vmcnt(0) lgkmcnt(0)
	s_barrier
	s_add_u32 m0, s41, 0
	s_nop 0
	global_load_lds_dwordx4 v212, s[98:99]
	s_waitcnt lgkmcnt(6)
	v_mfma_f32_16x16x32_bf16 v[28:31], v[72:75], v[164:167], v[28:31]
	v_mfma_f32_16x16x32_bf16 v[16:19], v[216:219], v[164:167], v[16:19]
	ds_read_b128 v[64:67], v208 offset:32768
	ds_read_b128 v[68:71], v208 offset:34816
	ds_read_b128 v[192:195], v210 offset:49152
	s_add_u32 m0, s41, 4096
	s_nop 0
	global_load_lds_dwordx4 v213, s[98:99]
	s_waitcnt lgkmcnt(8)
	v_mfma_f32_16x16x32_bf16 v[60:63], v[72:75], v[168:171], v[60:63]
	v_mfma_f32_16x16x32_bf16 v[40:43], v[216:219], v[168:171], v[40:43]
	ds_read_b128 v[196:199], v210 offset:51200
	s_add_u32 m0, s41, 8192
	s_nop 0
	global_load_lds_dwordx4 v214, s[98:99]
	s_waitcnt lgkmcnt(8)
	v_mfma_f32_16x16x32_bf16 v[20:23], v[72:75], v[172:175], v[20:23]
	v_mfma_f32_16x16x32_bf16 v[0:3], v[216:219], v[172:175], v[0:3]
	ds_read_b128 v[200:203], v210 offset:53248
	s_add_u32 m0, s41, 12288
	s_nop 0
	global_load_lds_dwordx4 v215, s[98:99]
	s_add_u32 s98, s98, 128
	s_addc_u32 s99, s99, 0
	s_waitcnt lgkmcnt(8)
	v_mfma_f32_16x16x32_bf16 v[52:55], v[72:75], v[176:179], v[52:55]
	v_mfma_f32_16x16x32_bf16 v[36:39], v[216:219], v[176:179], v[36:39]
	ds_read_b128 v[204:207], v210 offset:55296
	s_add_u32 m0, s41, 16384
	s_nop 0
	global_load_lds_dwordx4 v212, s[100:101]
	s_waitcnt lgkmcnt(8)
	v_mfma_f32_16x16x32_bf16 v[24:27], v[72:75], v[180:183], v[24:27]
	v_mfma_f32_16x16x32_bf16 v[8:11], v[216:219], v[180:183], v[8:11]
	ds_read_b128 v[160:163], v210 offset:57344
	s_add_u32 m0, s41, 20480
	s_nop 0
	global_load_lds_dwordx4 v213, s[100:101]
	s_waitcnt lgkmcnt(8)
	v_mfma_f32_16x16x32_bf16 v[56:59], v[72:75], v[184:187], v[56:59]
	v_mfma_f32_16x16x32_bf16 v[32:35], v[216:219], v[184:187], v[32:35]
	ds_read_b128 v[164:167], v210 offset:59392
	s_add_u32 m0, s41, 24576
	s_nop 0
	global_load_lds_dwordx4 v214, s[100:101]
	s_waitcnt lgkmcnt(8)
	v_mfma_f32_16x16x32_bf16 v[12:15], v[72:75], v[188:191], v[12:15]
	v_mfma_f32_16x16x32_bf16 v[4:7], v[216:219], v[188:191], v[4:7]
	ds_read_b128 v[168:171], v210 offset:61440
	s_add_u32 m0, s41, 28672
	s_nop 0
	global_load_lds_dwordx4 v215, s[100:101]
	s_add_u32 s100, s100, 128
	s_addc_u32 s101, s101, 0
	s_waitcnt lgkmcnt(6)
	v_mfma_f32_16x16x32_bf16 v[44:47], v[64:67], v[192:195], v[44:47]
	v_mfma_f32_16x16x32_bf16 v[48:51], v[68:71], v[192:195], v[48:51]
	ds_read_b128 v[172:175], v210 offset:63488
	s_waitcnt lgkmcnt(6)
	v_mfma_f32_16x16x32_bf16 v[28:31], v[64:67], v[196:199], v[28:31]
	v_mfma_f32_16x16x32_bf16 v[16:19], v[68:71], v[196:199], v[16:19]
	ds_read_b128 v[72:75], v209 offset:32768
	ds_read_b128 v[216:219], v209 offset:34816
	ds_read_b128 v[176:179], v211 offset:49152
	s_waitcnt lgkmcnt(8)
	v_mfma_f32_16x16x32_bf16 v[60:63], v[64:67], v[200:203], v[60:63]
	v_mfma_f32_16x16x32_bf16 v[40:43], v[68:71], v[200:203], v[40:43]
	ds_read_b128 v[180:183], v211 offset:51200
	s_waitcnt lgkmcnt(8)
	v_mfma_f32_16x16x32_bf16 v[20:23], v[64:67], v[204:207], v[20:23]
	v_mfma_f32_16x16x32_bf16 v[0:3], v[68:71], v[204:207], v[0:3]
	ds_read_b128 v[184:187], v211 offset:53248
	s_waitcnt lgkmcnt(8)
	v_mfma_f32_16x16x32_bf16 v[52:55], v[64:67], v[160:163], v[52:55]
	v_mfma_f32_16x16x32_bf16 v[36:39], v[68:71], v[160:163], v[36:39]
	ds_read_b128 v[188:191], v211 offset:55296
	s_waitcnt lgkmcnt(8)
	v_mfma_f32_16x16x32_bf16 v[24:27], v[64:67], v[164:167], v[24:27]
	v_mfma_f32_16x16x32_bf16 v[8:11], v[68:71], v[164:167], v[8:11]
	ds_read_b128 v[192:195], v211 offset:57344
	s_waitcnt lgkmcnt(8)
	v_mfma_f32_16x16x32_bf16 v[56:59], v[64:67], v[168:171], v[56:59]
	v_mfma_f32_16x16x32_bf16 v[32:35], v[68:71], v[168:171], v[32:35]
	ds_read_b128 v[196:199], v211 offset:59392
	s_waitcnt lgkmcnt(8)
	v_mfma_f32_16x16x32_bf16 v[12:15], v[64:67], v[172:175], v[12:15]
	v_mfma_f32_16x16x32_bf16 v[4:7], v[68:71], v[172:175], v[4:7]
	ds_read_b128 v[200:203], v211 offset:61440
	s_waitcnt lgkmcnt(6)
	v_mfma_f32_16x16x32_bf16 v[44:47], v[72:75], v[176:179], v[44:47]
	v_mfma_f32_16x16x32_bf16 v[48:51], v[216:219], v[176:179], v[48:51]
	ds_read_b128 v[204:207], v211 offset:63488
	s_waitcnt vmcnt(0) lgkmcnt(0)
	s_barrier
	s_add_u32 m0, s41, 32768
	s_nop 0
	global_load_lds_dwordx4 v212, s[98:99]
	s_waitcnt lgkmcnt(6)
	v_mfma_f32_16x16x32_bf16 v[28:31], v[72:75], v[180:183], v[28:31]
	v_mfma_f32_16x16x32_bf16 v[16:19], v[216:219], v[180:183], v[16:19]
	ds_read_b128 v[64:67], v208 offset:0
	ds_read_b128 v[68:71], v208 offset:2048
	ds_read_b128 v[160:163], v210 offset:16384
	s_add_u32 m0, s41, 36864
	s_nop 0
	global_load_lds_dwordx4 v213, s[98:99]
	s_waitcnt lgkmcnt(8)
	v_mfma_f32_16x16x32_bf16 v[60:63], v[72:75], v[184:187], v[60:63]
	v_mfma_f32_16x16x32_bf16 v[40:43], v[216:219], v[184:187], v[40:43]
	ds_read_b128 v[164:167], v210 offset:18432
	s_add_u32 m0, s41, 40960
	s_nop 0
	global_load_lds_dwordx4 v214, s[98:99]
	s_waitcnt lgkmcnt(8)
	v_mfma_f32_16x16x32_bf16 v[20:23], v[72:75], v[188:191], v[20:23]
	v_mfma_f32_16x16x32_bf16 v[0:3], v[216:219], v[188:191], v[0:3]
	ds_read_b128 v[168:171], v210 offset:20480
	s_add_u32 m0, s41, 45056
	s_nop 0
	global_load_lds_dwordx4 v215, s[98:99]
	s_add_u32 s98, s98, 128
	s_addc_u32 s99, s99, 0
	s_waitcnt lgkmcnt(8)
	v_mfma_f32_16x16x32_bf16 v[52:55], v[72:75], v[192:195], v[52:55]
	v_mfma_f32_16x16x32_bf16 v[36:39], v[216:219], v[192:195], v[36:39]
	ds_read_b128 v[172:175], v210 offset:22528
	s_add_u32 m0, s41, 49152
	s_nop 0
	global_load_lds_dwordx4 v212, s[100:101]
	s_waitcnt lgkmcnt(8)
	v_mfma_f32_16x16x32_bf16 v[24:27], v[72:75], v[196:199], v[24:27]
	v_mfma_f32_16x16x32_bf16 v[8:11], v[216:219], v[196:199], v[8:11]
	ds_read_b128 v[176:179], v210 offset:24576
	s_add_u32 m0, s41, 53248
	s_nop 0
	global_load_lds_dwordx4 v213, s[100:101]
	s_waitcnt lgkmcnt(8)
	v_mfma_f32_16x16x32_bf16 v[56:59], v[72:75], v[200:203], v[56:59]
	v_mfma_f32_16x16x32_bf16 v[32:35], v[216:219], v[200:203], v[32:35]
	ds_read_b128 v[180:183], v210 offset:26624
	s_add_u32 m0, s41, 57344
	s_nop 0
	global_load_lds_dwordx4 v214, s[100:101]
	s_waitcnt lgkmcnt(8)
	v_mfma_f32_16x16x32_bf16 v[12:15], v[72:75], v[204:207], v[12:15]
	v_mfma_f32_16x16x32_bf16 v[4:7], v[216:219], v[204:207], v[4:7]
	ds_read_b128 v[184:187], v210 offset:28672
	s_add_u32 m0, s41, 61440
	s_nop 0
	global_load_lds_dwordx4 v215, s[100:101]
	s_add_u32 s100, s100, 128
	s_addc_u32 s101, s101, 0
	s_waitcnt lgkmcnt(6)
	v_mfma_f32_16x16x32_bf16 v[44:47], v[64:67], v[160:163], v[44:47]
	v_mfma_f32_16x16x32_bf16 v[48:51], v[68:71], v[160:163], v[48:51]
	ds_read_b128 v[188:191], v210 offset:30720
	s_waitcnt lgkmcnt(6)
	v_mfma_f32_16x16x32_bf16 v[28:31], v[64:67], v[164:167], v[28:31]
	v_mfma_f32_16x16x32_bf16 v[16:19], v[68:71], v[164:167], v[16:19]
	ds_read_b128 v[72:75], v209 offset:0
	ds_read_b128 v[216:219], v209 offset:2048
	ds_read_b128 v[192:195], v211 offset:16384
	s_waitcnt lgkmcnt(8)
	v_mfma_f32_16x16x32_bf16 v[60:63], v[64:67], v[168:171], v[60:63]
	v_mfma_f32_16x16x32_bf16 v[40:43], v[68:71], v[168:171], v[40:43]
	ds_read_b128 v[196:199], v211 offset:18432
	s_waitcnt lgkmcnt(8)
	v_mfma_f32_16x16x32_bf16 v[20:23], v[64:67], v[172:175], v[20:23]
	v_mfma_f32_16x16x32_bf16 v[0:3], v[68:71], v[172:175], v[0:3]
	ds_read_b128 v[200:203], v211 offset:20480
	s_waitcnt lgkmcnt(8)
	v_mfma_f32_16x16x32_bf16 v[52:55], v[64:67], v[176:179], v[52:55]
	v_mfma_f32_16x16x32_bf16 v[36:39], v[68:71], v[176:179], v[36:39]
	ds_read_b128 v[204:207], v211 offset:22528
	s_waitcnt lgkmcnt(8)
	v_mfma_f32_16x16x32_bf16 v[24:27], v[64:67], v[180:183], v[24:27]
	v_mfma_f32_16x16x32_bf16 v[8:11], v[68:71], v[180:183], v[8:11]
	ds_read_b128 v[160:163], v211 offset:24576
	s_waitcnt lgkmcnt(8)
	v_mfma_f32_16x16x32_bf16 v[56:59], v[64:67], v[184:187], v[56:59]
	v_mfma_f32_16x16x32_bf16 v[32:35], v[68:71], v[184:187], v[32:35]
	ds_read_b128 v[164:167], v211 offset:26624
	s_waitcnt lgkmcnt(8)
	v_mfma_f32_16x16x32_bf16 v[12:15], v[64:67], v[188:191], v[12:15]
	v_mfma_f32_16x16x32_bf16 v[4:7], v[68:71], v[188:191], v[4:7]
	ds_read_b128 v[168:171], v211 offset:28672
	s_waitcnt lgkmcnt(6)
	v_mfma_f32_16x16x32_bf16 v[44:47], v[72:75], v[192:195], v[44:47]
	v_mfma_f32_16x16x32_bf16 v[48:51], v[216:219], v[192:195], v[48:51]
	ds_read_b128 v[172:175], v211 offset:30720
	s_waitcnt vmcnt(0) lgkmcnt(0)
	s_barrier
	s_add_u32 m0, s41, 0
	s_nop 0
	global_load_lds_dwordx4 v212, s[98:99]
	s_waitcnt lgkmcnt(6)
	v_mfma_f32_16x16x32_bf16 v[28:31], v[72:75], v[196:199], v[28:31]
	v_mfma_f32_16x16x32_bf16 v[16:19], v[216:219], v[196:199], v[16:19]
	ds_read_b128 v[64:67], v208 offset:32768
	ds_read_b128 v[68:71], v208 offset:34816
	ds_read_b128 v[176:179], v210 offset:49152
	s_add_u32 m0, s41, 4096
	s_nop 0
	global_load_lds_dwordx4 v213, s[98:99]
	s_waitcnt lgkmcnt(8)
	v_mfma_f32_16x16x32_bf16 v[60:63], v[72:75], v[200:203], v[60:63]
	v_mfma_f32_16x16x32_bf16 v[40:43], v[216:219], v[200:203], v[40:43]
	ds_read_b128 v[180:183], v210 offset:51200
	s_add_u32 m0, s41, 8192
	s_nop 0
	global_load_lds_dwordx4 v214, s[98:99]
	s_waitcnt lgkmcnt(8)
	v_mfma_f32_16x16x32_bf16 v[20:23], v[72:75], v[204:207], v[20:23]
	v_mfma_f32_16x16x32_bf16 v[0:3], v[216:219], v[204:207], v[0:3]
	ds_read_b128 v[184:187], v210 offset:53248
	s_add_u32 m0, s41, 12288
	s_nop 0
	global_load_lds_dwordx4 v215, s[98:99]
	s_add_u32 s98, s98, 128
	s_addc_u32 s99, s99, 0
	s_waitcnt lgkmcnt(8)
	v_mfma_f32_16x16x32_bf16 v[52:55], v[72:75], v[160:163], v[52:55]
	v_mfma_f32_16x16x32_bf16 v[36:39], v[216:219], v[160:163], v[36:39]
	ds_read_b128 v[188:191], v210 offset:55296
	s_add_u32 m0, s41, 16384
	s_nop 0
	global_load_lds_dwordx4 v212, s[100:101]
	s_waitcnt lgkmcnt(8)
	v_mfma_f32_16x16x32_bf16 v[24:27], v[72:75], v[164:167], v[24:27]
	v_mfma_f32_16x16x32_bf16 v[8:11], v[216:219], v[164:167], v[8:11]
	ds_read_b128 v[192:195], v210 offset:57344
	s_add_u32 m0, s41, 20480
	s_nop 0
	global_load_lds_dwordx4 v213, s[100:101]
	s_waitcnt lgkmcnt(8)
	v_mfma_f32_16x16x32_bf16 v[56:59], v[72:75], v[168:171], v[56:59]
	v_mfma_f32_16x16x32_bf16 v[32:35], v[216:219], v[168:171], v[32:35]
	ds_read_b128 v[196:199], v210 offset:59392
	s_add_u32 m0, s41, 24576
	s_nop 0
	global_load_lds_dwordx4 v214, s[100:101]
	s_waitcnt lgkmcnt(8)
	v_mfma_f32_16x16x32_bf16 v[12:15], v[72:75], v[172:175], v[12:15]
	v_mfma_f32_16x16x32_bf16 v[4:7], v[216:219], v[172:175], v[4:7]
	ds_read_b128 v[200:203], v210 offset:61440
	s_add_u32 m0, s41, 28672
	s_nop 0
	global_load_lds_dwordx4 v215, s[100:101]
	s_add_u32 s100, s100, 128
	s_addc_u32 s101, s101, 0
	s_waitcnt lgkmcnt(6)
	v_mfma_f32_16x16x32_bf16 v[44:47], v[64:67], v[176:179], v[44:47]
	v_mfma_f32_16x16x32_bf16 v[48:51], v[68:71], v[176:179], v[48:51]
	ds_read_b128 v[204:207], v210 offset:63488
	s_waitcnt lgkmcnt(6)
	v_mfma_f32_16x16x32_bf16 v[28:31], v[64:67], v[180:183], v[28:31]
	v_mfma_f32_16x16x32_bf16 v[16:19], v[68:71], v[180:183], v[16:19]
	ds_read_b128 v[72:75], v209 offset:32768
	ds_read_b128 v[216:219], v209 offset:34816
	ds_read_b128 v[160:163], v211 offset:49152
	s_waitcnt lgkmcnt(8)
	v_mfma_f32_16x16x32_bf16 v[60:63], v[64:67], v[184:187], v[60:63]
	v_mfma_f32_16x16x32_bf16 v[40:43], v[68:71], v[184:187], v[40:43]
	ds_read_b128 v[164:167], v211 offset:51200
	s_waitcnt lgkmcnt(8)
	v_mfma_f32_16x16x32_bf16 v[20:23], v[64:67], v[188:191], v[20:23]
	v_mfma_f32_16x16x32_bf16 v[0:3], v[68:71], v[188:191], v[0:3]
	ds_read_b128 v[168:171], v211 offset:53248
	s_waitcnt lgkmcnt(8)
	v_mfma_f32_16x16x32_bf16 v[52:55], v[64:67], v[192:195], v[52:55]
	v_mfma_f32_16x16x32_bf16 v[36:39], v[68:71], v[192:195], v[36:39]
	ds_read_b128 v[172:175], v211 offset:55296
	s_waitcnt lgkmcnt(8)
	v_mfma_f32_16x16x32_bf16 v[24:27], v[64:67], v[196:199], v[24:27]
	v_mfma_f32_16x16x32_bf16 v[8:11], v[68:71], v[196:199], v[8:11]
	ds_read_b128 v[176:179], v211 offset:57344
	s_waitcnt lgkmcnt(8)
	v_mfma_f32_16x16x32_bf16 v[56:59], v[64:67], v[200:203], v[56:59]
	v_mfma_f32_16x16x32_bf16 v[32:35], v[68:71], v[200:203], v[32:35]
	ds_read_b128 v[180:183], v211 offset:59392
	s_waitcnt lgkmcnt(8)
	v_mfma_f32_16x16x32_bf16 v[12:15], v[64:67], v[204:207], v[12:15]
	v_mfma_f32_16x16x32_bf16 v[4:7], v[68:71], v[204:207], v[4:7]
	ds_read_b128 v[184:187], v211 offset:61440
	s_waitcnt lgkmcnt(6)
	v_mfma_f32_16x16x32_bf16 v[44:47], v[72:75], v[160:163], v[44:47]
	v_mfma_f32_16x16x32_bf16 v[48:51], v[216:219], v[160:163], v[48:51]
	ds_read_b128 v[188:191], v211 offset:63488
	s_waitcnt vmcnt(0) lgkmcnt(0)
	s_barrier
	s_add_u32 m0, s41, 32768
	s_nop 0
	global_load_lds_dwordx4 v212, s[98:99]
	s_waitcnt lgkmcnt(6)
	v_mfma_f32_16x16x32_bf16 v[28:31], v[72:75], v[164:167], v[28:31]
	v_mfma_f32_16x16x32_bf16 v[16:19], v[216:219], v[164:167], v[16:19]
	ds_read_b128 v[64:67], v208 offset:0
	ds_read_b128 v[68:71], v208 offset:2048
	ds_read_b128 v[192:195], v210 offset:16384
	s_add_u32 m0, s41, 36864
	s_nop 0
	global_load_lds_dwordx4 v213, s[98:99]
	s_waitcnt lgkmcnt(8)
	v_mfma_f32_16x16x32_bf16 v[60:63], v[72:75], v[168:171], v[60:63]
	v_mfma_f32_16x16x32_bf16 v[40:43], v[216:219], v[168:171], v[40:43]
	ds_read_b128 v[196:199], v210 offset:18432
	s_add_u32 m0, s41, 40960
	s_nop 0
	global_load_lds_dwordx4 v214, s[98:99]
	s_waitcnt lgkmcnt(8)
	v_mfma_f32_16x16x32_bf16 v[20:23], v[72:75], v[172:175], v[20:23]
	v_mfma_f32_16x16x32_bf16 v[0:3], v[216:219], v[172:175], v[0:3]
	ds_read_b128 v[200:203], v210 offset:20480
	s_add_u32 m0, s41, 45056
	s_nop 0
	global_load_lds_dwordx4 v215, s[98:99]
	s_add_u32 s98, s98, 128
	s_addc_u32 s99, s99, 0
	s_waitcnt lgkmcnt(8)
	v_mfma_f32_16x16x32_bf16 v[52:55], v[72:75], v[176:179], v[52:55]
	v_mfma_f32_16x16x32_bf16 v[36:39], v[216:219], v[176:179], v[36:39]
	ds_read_b128 v[204:207], v210 offset:22528
	s_add_u32 m0, s41, 49152
	s_nop 0
	global_load_lds_dwordx4 v212, s[100:101]
	s_waitcnt lgkmcnt(8)
	v_mfma_f32_16x16x32_bf16 v[24:27], v[72:75], v[180:183], v[24:27]
	v_mfma_f32_16x16x32_bf16 v[8:11], v[216:219], v[180:183], v[8:11]
	ds_read_b128 v[160:163], v210 offset:24576
	s_add_u32 m0, s41, 53248
	s_nop 0
	global_load_lds_dwordx4 v213, s[100:101]
	s_waitcnt lgkmcnt(8)
	v_mfma_f32_16x16x32_bf16 v[56:59], v[72:75], v[184:187], v[56:59]
	v_mfma_f32_16x16x32_bf16 v[32:35], v[216:219], v[184:187], v[32:35]
	ds_read_b128 v[164:167], v210 offset:26624
	s_add_u32 m0, s41, 57344
	s_nop 0
	global_load_lds_dwordx4 v214, s[100:101]
	s_waitcnt lgkmcnt(8)
	v_mfma_f32_16x16x32_bf16 v[12:15], v[72:75], v[188:191], v[12:15]
	v_mfma_f32_16x16x32_bf16 v[4:7], v[216:219], v[188:191], v[4:7]
	ds_read_b128 v[168:171], v210 offset:28672
	s_add_u32 m0, s41, 61440
	s_nop 0
	global_load_lds_dwordx4 v215, s[100:101]
	s_add_u32 s100, s100, 128
	s_addc_u32 s101, s101, 0
	s_waitcnt lgkmcnt(6)
	v_mfma_f32_16x16x32_bf16 v[44:47], v[64:67], v[192:195], v[44:47]
	v_mfma_f32_16x16x32_bf16 v[48:51], v[68:71], v[192:195], v[48:51]
	ds_read_b128 v[172:175], v210 offset:30720
	s_waitcnt lgkmcnt(6)
	v_mfma_f32_16x16x32_bf16 v[28:31], v[64:67], v[196:199], v[28:31]
	v_mfma_f32_16x16x32_bf16 v[16:19], v[68:71], v[196:199], v[16:19]
	ds_read_b128 v[72:75], v209 offset:0
	ds_read_b128 v[216:219], v209 offset:2048
	ds_read_b128 v[176:179], v211 offset:16384
	s_waitcnt lgkmcnt(8)
	v_mfma_f32_16x16x32_bf16 v[60:63], v[64:67], v[200:203], v[60:63]
	v_mfma_f32_16x16x32_bf16 v[40:43], v[68:71], v[200:203], v[40:43]
	ds_read_b128 v[180:183], v211 offset:18432
	s_waitcnt lgkmcnt(8)
	v_mfma_f32_16x16x32_bf16 v[20:23], v[64:67], v[204:207], v[20:23]
	v_mfma_f32_16x16x32_bf16 v[0:3], v[68:71], v[204:207], v[0:3]
	ds_read_b128 v[184:187], v211 offset:20480
	s_waitcnt lgkmcnt(8)
	v_mfma_f32_16x16x32_bf16 v[52:55], v[64:67], v[160:163], v[52:55]
	v_mfma_f32_16x16x32_bf16 v[36:39], v[68:71], v[160:163], v[36:39]
	ds_read_b128 v[188:191], v211 offset:22528
	s_waitcnt lgkmcnt(8)
	v_mfma_f32_16x16x32_bf16 v[24:27], v[64:67], v[164:167], v[24:27]
	v_mfma_f32_16x16x32_bf16 v[8:11], v[68:71], v[164:167], v[8:11]
	ds_read_b128 v[192:195], v211 offset:24576
	s_waitcnt lgkmcnt(8)
	v_mfma_f32_16x16x32_bf16 v[56:59], v[64:67], v[168:171], v[56:59]
	v_mfma_f32_16x16x32_bf16 v[32:35], v[68:71], v[168:171], v[32:35]
	ds_read_b128 v[196:199], v211 offset:26624
	s_waitcnt lgkmcnt(8)
	v_mfma_f32_16x16x32_bf16 v[12:15], v[64:67], v[172:175], v[12:15]
	v_mfma_f32_16x16x32_bf16 v[4:7], v[68:71], v[172:175], v[4:7]
	ds_read_b128 v[200:203], v211 offset:28672
	s_waitcnt lgkmcnt(6)
	v_mfma_f32_16x16x32_bf16 v[44:47], v[72:75], v[176:179], v[44:47]
	v_mfma_f32_16x16x32_bf16 v[48:51], v[216:219], v[176:179], v[48:51]
	ds_read_b128 v[204:207], v211 offset:30720
	s_waitcnt vmcnt(0) lgkmcnt(0)
	s_barrier
	s_add_u32 m0, s41, 0
	s_nop 0
	global_load_lds_dwordx4 v212, s[98:99]
	s_waitcnt lgkmcnt(6)
	v_mfma_f32_16x16x32_bf16 v[28:31], v[72:75], v[180:183], v[28:31]
	v_mfma_f32_16x16x32_bf16 v[16:19], v[216:219], v[180:183], v[16:19]
	ds_read_b128 v[64:67], v208 offset:32768
	ds_read_b128 v[68:71], v208 offset:34816
	ds_read_b128 v[160:163], v210 offset:49152
	s_add_u32 m0, s41, 4096
	s_nop 0
	global_load_lds_dwordx4 v213, s[98:99]
	s_waitcnt lgkmcnt(8)
	v_mfma_f32_16x16x32_bf16 v[60:63], v[72:75], v[184:187], v[60:63]
	v_mfma_f32_16x16x32_bf16 v[40:43], v[216:219], v[184:187], v[40:43]
	ds_read_b128 v[164:167], v210 offset:51200
	s_add_u32 m0, s41, 8192
	s_nop 0
	global_load_lds_dwordx4 v214, s[98:99]
	s_waitcnt lgkmcnt(8)
	v_mfma_f32_16x16x32_bf16 v[20:23], v[72:75], v[188:191], v[20:23]
	v_mfma_f32_16x16x32_bf16 v[0:3], v[216:219], v[188:191], v[0:3]
	ds_read_b128 v[168:171], v210 offset:53248
	s_add_u32 m0, s41, 12288
	s_nop 0
	global_load_lds_dwordx4 v215, s[98:99]
	s_add_u32 s98, s98, 128
	s_addc_u32 s99, s99, 0
	s_waitcnt lgkmcnt(8)
	v_mfma_f32_16x16x32_bf16 v[52:55], v[72:75], v[192:195], v[52:55]
	v_mfma_f32_16x16x32_bf16 v[36:39], v[216:219], v[192:195], v[36:39]
	ds_read_b128 v[172:175], v210 offset:55296
	s_add_u32 m0, s41, 16384
	s_nop 0
	global_load_lds_dwordx4 v212, s[100:101]
	s_waitcnt lgkmcnt(8)
	v_mfma_f32_16x16x32_bf16 v[24:27], v[72:75], v[196:199], v[24:27]
	v_mfma_f32_16x16x32_bf16 v[8:11], v[216:219], v[196:199], v[8:11]
	ds_read_b128 v[176:179], v210 offset:57344
	s_add_u32 m0, s41, 20480
	s_nop 0
	global_load_lds_dwordx4 v213, s[100:101]
	s_waitcnt lgkmcnt(8)
	v_mfma_f32_16x16x32_bf16 v[56:59], v[72:75], v[200:203], v[56:59]
	v_mfma_f32_16x16x32_bf16 v[32:35], v[216:219], v[200:203], v[32:35]
	ds_read_b128 v[180:183], v210 offset:59392
	s_add_u32 m0, s41, 24576
	s_nop 0
	global_load_lds_dwordx4 v214, s[100:101]
	s_waitcnt lgkmcnt(8)
	v_mfma_f32_16x16x32_bf16 v[12:15], v[72:75], v[204:207], v[12:15]
	v_mfma_f32_16x16x32_bf16 v[4:7], v[216:219], v[204:207], v[4:7]
	ds_read_b128 v[184:187], v210 offset:61440
	s_add_u32 m0, s41, 28672
	s_nop 0
	global_load_lds_dwordx4 v215, s[100:101]
	s_add_u32 s100, s100, 128
	s_addc_u32 s101, s101, 0
	s_waitcnt lgkmcnt(6)
	v_mfma_f32_16x16x32_bf16 v[44:47], v[64:67], v[160:163], v[44:47]
	v_mfma_f32_16x16x32_bf16 v[48:51], v[68:71], v[160:163], v[48:51]
	ds_read_b128 v[188:191], v210 offset:63488
	s_waitcnt lgkmcnt(6)
	v_mfma_f32_16x16x32_bf16 v[28:31], v[64:67], v[164:167], v[28:31]
	v_mfma_f32_16x16x32_bf16 v[16:19], v[68:71], v[164:167], v[16:19]
	ds_read_b128 v[72:75], v209 offset:32768
	ds_read_b128 v[216:219], v209 offset:34816
	ds_read_b128 v[192:195], v211 offset:49152
	s_waitcnt lgkmcnt(8)
	v_mfma_f32_16x16x32_bf16 v[60:63], v[64:67], v[168:171], v[60:63]
	v_mfma_f32_16x16x32_bf16 v[40:43], v[68:71], v[168:171], v[40:43]
	ds_read_b128 v[196:199], v211 offset:51200
	s_waitcnt lgkmcnt(8)
	v_mfma_f32_16x16x32_bf16 v[20:23], v[64:67], v[172:175], v[20:23]
	v_mfma_f32_16x16x32_bf16 v[0:3], v[68:71], v[172:175], v[0:3]
	ds_read_b128 v[200:203], v211 offset:53248
	s_waitcnt lgkmcnt(8)
	v_mfma_f32_16x16x32_bf16 v[52:55], v[64:67], v[176:179], v[52:55]
	v_mfma_f32_16x16x32_bf16 v[36:39], v[68:71], v[176:179], v[36:39]
	ds_read_b128 v[204:207], v211 offset:55296
	s_waitcnt lgkmcnt(8)
	v_mfma_f32_16x16x32_bf16 v[24:27], v[64:67], v[180:183], v[24:27]
	v_mfma_f32_16x16x32_bf16 v[8:11], v[68:71], v[180:183], v[8:11]
	ds_read_b128 v[160:163], v211 offset:57344
	s_waitcnt lgkmcnt(8)
	v_mfma_f32_16x16x32_bf16 v[56:59], v[64:67], v[184:187], v[56:59]
	v_mfma_f32_16x16x32_bf16 v[32:35], v[68:71], v[184:187], v[32:35]
	ds_read_b128 v[164:167], v211 offset:59392
	s_waitcnt lgkmcnt(8)
	v_mfma_f32_16x16x32_bf16 v[12:15], v[64:67], v[188:191], v[12:15]
	v_mfma_f32_16x16x32_bf16 v[4:7], v[68:71], v[188:191], v[4:7]
	ds_read_b128 v[168:171], v211 offset:61440
	s_waitcnt lgkmcnt(6)
	v_mfma_f32_16x16x32_bf16 v[44:47], v[72:75], v[192:195], v[44:47]
	v_mfma_f32_16x16x32_bf16 v[48:51], v[216:219], v[192:195], v[48:51]
	ds_read_b128 v[172:175], v211 offset:63488
	s_waitcnt vmcnt(0) lgkmcnt(0)
	s_barrier
	s_add_u32 m0, s41, 32768
	s_nop 0
	global_load_lds_dwordx4 v212, s[98:99]
	s_waitcnt lgkmcnt(6)
	v_mfma_f32_16x16x32_bf16 v[28:31], v[72:75], v[196:199], v[28:31]
	v_mfma_f32_16x16x32_bf16 v[16:19], v[216:219], v[196:199], v[16:19]
	ds_read_b128 v[64:67], v208 offset:0
	ds_read_b128 v[68:71], v208 offset:2048
	ds_read_b128 v[176:179], v210 offset:16384
	s_add_u32 m0, s41, 36864
	s_nop 0
	global_load_lds_dwordx4 v213, s[98:99]
	s_waitcnt lgkmcnt(8)
	v_mfma_f32_16x16x32_bf16 v[60:63], v[72:75], v[200:203], v[60:63]
	v_mfma_f32_16x16x32_bf16 v[40:43], v[216:219], v[200:203], v[40:43]
	ds_read_b128 v[180:183], v210 offset:18432
	s_add_u32 m0, s41, 40960
	s_nop 0
	global_load_lds_dwordx4 v214, s[98:99]
	s_waitcnt lgkmcnt(8)
	v_mfma_f32_16x16x32_bf16 v[20:23], v[72:75], v[204:207], v[20:23]
	v_mfma_f32_16x16x32_bf16 v[0:3], v[216:219], v[204:207], v[0:3]
	ds_read_b128 v[184:187], v210 offset:20480
	s_add_u32 m0, s41, 45056
	s_nop 0
	global_load_lds_dwordx4 v215, s[98:99]
	s_add_u32 s98, s98, 128
	s_addc_u32 s99, s99, 0
	s_waitcnt lgkmcnt(8)
	v_mfma_f32_16x16x32_bf16 v[52:55], v[72:75], v[160:163], v[52:55]
	v_mfma_f32_16x16x32_bf16 v[36:39], v[216:219], v[160:163], v[36:39]
	ds_read_b128 v[188:191], v210 offset:22528
	s_add_u32 m0, s41, 49152
	s_nop 0
	global_load_lds_dwordx4 v212, s[100:101]
	s_waitcnt lgkmcnt(8)
	v_mfma_f32_16x16x32_bf16 v[24:27], v[72:75], v[164:167], v[24:27]
	v_mfma_f32_16x16x32_bf16 v[8:11], v[216:219], v[164:167], v[8:11]
	ds_read_b128 v[192:195], v210 offset:24576
	s_add_u32 m0, s41, 53248
	s_nop 0
	global_load_lds_dwordx4 v213, s[100:101]
	s_waitcnt lgkmcnt(8)
	v_mfma_f32_16x16x32_bf16 v[56:59], v[72:75], v[168:171], v[56:59]
	v_mfma_f32_16x16x32_bf16 v[32:35], v[216:219], v[168:171], v[32:35]
	ds_read_b128 v[196:199], v210 offset:26624
	s_add_u32 m0, s41, 57344
	s_nop 0
	global_load_lds_dwordx4 v214, s[100:101]
	s_waitcnt lgkmcnt(8)
	v_mfma_f32_16x16x32_bf16 v[12:15], v[72:75], v[172:175], v[12:15]
	v_mfma_f32_16x16x32_bf16 v[4:7], v[216:219], v[172:175], v[4:7]
	ds_read_b128 v[200:203], v210 offset:28672
	s_add_u32 m0, s41, 61440
	s_nop 0
	global_load_lds_dwordx4 v215, s[100:101]
	s_add_u32 s100, s100, 128
	s_addc_u32 s101, s101, 0
	s_waitcnt lgkmcnt(6)
	v_mfma_f32_16x16x32_bf16 v[44:47], v[64:67], v[176:179], v[44:47]
	v_mfma_f32_16x16x32_bf16 v[48:51], v[68:71], v[176:179], v[48:51]
	ds_read_b128 v[204:207], v210 offset:30720
	s_waitcnt lgkmcnt(6)
	v_mfma_f32_16x16x32_bf16 v[28:31], v[64:67], v[180:183], v[28:31]
	v_mfma_f32_16x16x32_bf16 v[16:19], v[68:71], v[180:183], v[16:19]
	ds_read_b128 v[72:75], v209 offset:0
	ds_read_b128 v[216:219], v209 offset:2048
	ds_read_b128 v[160:163], v211 offset:16384
	s_waitcnt lgkmcnt(8)
	v_mfma_f32_16x16x32_bf16 v[60:63], v[64:67], v[184:187], v[60:63]
	v_mfma_f32_16x16x32_bf16 v[40:43], v[68:71], v[184:187], v[40:43]
	ds_read_b128 v[164:167], v211 offset:18432
	s_waitcnt lgkmcnt(8)
	v_mfma_f32_16x16x32_bf16 v[20:23], v[64:67], v[188:191], v[20:23]
	v_mfma_f32_16x16x32_bf16 v[0:3], v[68:71], v[188:191], v[0:3]
	ds_read_b128 v[168:171], v211 offset:20480
	s_waitcnt lgkmcnt(8)
	v_mfma_f32_16x16x32_bf16 v[52:55], v[64:67], v[192:195], v[52:55]
	v_mfma_f32_16x16x32_bf16 v[36:39], v[68:71], v[192:195], v[36:39]
	ds_read_b128 v[172:175], v211 offset:22528
	s_waitcnt lgkmcnt(8)
	v_mfma_f32_16x16x32_bf16 v[24:27], v[64:67], v[196:199], v[24:27]
	v_mfma_f32_16x16x32_bf16 v[8:11], v[68:71], v[196:199], v[8:11]
	ds_read_b128 v[176:179], v211 offset:24576
	s_waitcnt lgkmcnt(8)
	v_mfma_f32_16x16x32_bf16 v[56:59], v[64:67], v[200:203], v[56:59]
	v_mfma_f32_16x16x32_bf16 v[32:35], v[68:71], v[200:203], v[32:35]
	ds_read_b128 v[180:183], v211 offset:26624
	s_waitcnt lgkmcnt(8)
	v_mfma_f32_16x16x32_bf16 v[12:15], v[64:67], v[204:207], v[12:15]
	v_mfma_f32_16x16x32_bf16 v[4:7], v[68:71], v[204:207], v[4:7]
	ds_read_b128 v[184:187], v211 offset:28672
	s_waitcnt lgkmcnt(6)
	v_mfma_f32_16x16x32_bf16 v[44:47], v[72:75], v[160:163], v[44:47]
	v_mfma_f32_16x16x32_bf16 v[48:51], v[216:219], v[160:163], v[48:51]
	ds_read_b128 v[188:191], v211 offset:30720
	s_waitcnt vmcnt(0) lgkmcnt(0)
	s_barrier
	s_add_u32 m0, s41, 0
	s_nop 0
	global_load_lds_dwordx4 v212, s[98:99]
	s_waitcnt lgkmcnt(6)
	v_mfma_f32_16x16x32_bf16 v[28:31], v[72:75], v[164:167], v[28:31]
	v_mfma_f32_16x16x32_bf16 v[16:19], v[216:219], v[164:167], v[16:19]
	ds_read_b128 v[64:67], v208 offset:32768
	ds_read_b128 v[68:71], v208 offset:34816
	ds_read_b128 v[192:195], v210 offset:49152
	s_add_u32 m0, s41, 4096
	s_nop 0
	global_load_lds_dwordx4 v213, s[98:99]
	s_waitcnt lgkmcnt(8)
	v_mfma_f32_16x16x32_bf16 v[60:63], v[72:75], v[168:171], v[60:63]
	v_mfma_f32_16x16x32_bf16 v[40:43], v[216:219], v[168:171], v[40:43]
	ds_read_b128 v[196:199], v210 offset:51200
	s_add_u32 m0, s41, 8192
	s_nop 0
	global_load_lds_dwordx4 v214, s[98:99]
	s_waitcnt lgkmcnt(8)
	v_mfma_f32_16x16x32_bf16 v[20:23], v[72:75], v[172:175], v[20:23]
	v_mfma_f32_16x16x32_bf16 v[0:3], v[216:219], v[172:175], v[0:3]
	ds_read_b128 v[200:203], v210 offset:53248
	s_add_u32 m0, s41, 12288
	s_nop 0
	global_load_lds_dwordx4 v215, s[98:99]
	s_add_u32 s98, s98, 128
	s_addc_u32 s99, s99, 0
	s_waitcnt lgkmcnt(8)
	v_mfma_f32_16x16x32_bf16 v[52:55], v[72:75], v[176:179], v[52:55]
	v_mfma_f32_16x16x32_bf16 v[36:39], v[216:219], v[176:179], v[36:39]
	ds_read_b128 v[204:207], v210 offset:55296
	s_add_u32 m0, s41, 16384
	s_nop 0
	global_load_lds_dwordx4 v212, s[100:101]
	s_waitcnt lgkmcnt(8)
	v_mfma_f32_16x16x32_bf16 v[24:27], v[72:75], v[180:183], v[24:27]
	v_mfma_f32_16x16x32_bf16 v[8:11], v[216:219], v[180:183], v[8:11]
	ds_read_b128 v[160:163], v210 offset:57344
	s_add_u32 m0, s41, 20480
	s_nop 0
	global_load_lds_dwordx4 v213, s[100:101]
	s_waitcnt lgkmcnt(8)
	v_mfma_f32_16x16x32_bf16 v[56:59], v[72:75], v[184:187], v[56:59]
	v_mfma_f32_16x16x32_bf16 v[32:35], v[216:219], v[184:187], v[32:35]
	ds_read_b128 v[164:167], v210 offset:59392
	s_add_u32 m0, s41, 24576
	s_nop 0
	global_load_lds_dwordx4 v214, s[100:101]
	s_waitcnt lgkmcnt(8)
	v_mfma_f32_16x16x32_bf16 v[12:15], v[72:75], v[188:191], v[12:15]
	v_mfma_f32_16x16x32_bf16 v[4:7], v[216:219], v[188:191], v[4:7]
	ds_read_b128 v[168:171], v210 offset:61440
	s_add_u32 m0, s41, 28672
	s_nop 0
	global_load_lds_dwordx4 v215, s[100:101]
	s_add_u32 s100, s100, 128
	s_addc_u32 s101, s101, 0
	s_waitcnt lgkmcnt(6)
	v_mfma_f32_16x16x32_bf16 v[44:47], v[64:67], v[192:195], v[44:47]
	v_mfma_f32_16x16x32_bf16 v[48:51], v[68:71], v[192:195], v[48:51]
	ds_read_b128 v[172:175], v210 offset:63488
	s_waitcnt lgkmcnt(6)
	v_mfma_f32_16x16x32_bf16 v[28:31], v[64:67], v[196:199], v[28:31]
	v_mfma_f32_16x16x32_bf16 v[16:19], v[68:71], v[196:199], v[16:19]
	ds_read_b128 v[72:75], v209 offset:32768
	ds_read_b128 v[216:219], v209 offset:34816
	ds_read_b128 v[176:179], v211 offset:49152
	s_waitcnt lgkmcnt(8)
	v_mfma_f32_16x16x32_bf16 v[60:63], v[64:67], v[200:203], v[60:63]
	v_mfma_f32_16x16x32_bf16 v[40:43], v[68:71], v[200:203], v[40:43]
	ds_read_b128 v[180:183], v211 offset:51200
	s_waitcnt lgkmcnt(8)
	v_mfma_f32_16x16x32_bf16 v[20:23], v[64:67], v[204:207], v[20:23]
	v_mfma_f32_16x16x32_bf16 v[0:3], v[68:71], v[204:207], v[0:3]
	ds_read_b128 v[184:187], v211 offset:53248
	s_waitcnt lgkmcnt(8)
	v_mfma_f32_16x16x32_bf16 v[52:55], v[64:67], v[160:163], v[52:55]
	v_mfma_f32_16x16x32_bf16 v[36:39], v[68:71], v[160:163], v[36:39]
	ds_read_b128 v[188:191], v211 offset:55296
	s_waitcnt lgkmcnt(8)
	v_mfma_f32_16x16x32_bf16 v[24:27], v[64:67], v[164:167], v[24:27]
	v_mfma_f32_16x16x32_bf16 v[8:11], v[68:71], v[164:167], v[8:11]
	ds_read_b128 v[192:195], v211 offset:57344
	s_waitcnt lgkmcnt(8)
	v_mfma_f32_16x16x32_bf16 v[56:59], v[64:67], v[168:171], v[56:59]
	v_mfma_f32_16x16x32_bf16 v[32:35], v[68:71], v[168:171], v[32:35]
	ds_read_b128 v[196:199], v211 offset:59392
	s_waitcnt lgkmcnt(8)
	v_mfma_f32_16x16x32_bf16 v[12:15], v[64:67], v[172:175], v[12:15]
	v_mfma_f32_16x16x32_bf16 v[4:7], v[68:71], v[172:175], v[4:7]
	ds_read_b128 v[200:203], v211 offset:61440
	s_waitcnt lgkmcnt(6)
	v_mfma_f32_16x16x32_bf16 v[44:47], v[72:75], v[176:179], v[44:47]
	v_mfma_f32_16x16x32_bf16 v[48:51], v[216:219], v[176:179], v[48:51]
	ds_read_b128 v[204:207], v211 offset:63488
	s_waitcnt vmcnt(0) lgkmcnt(0)
	s_barrier
	s_add_u32 m0, s41, 32768
	s_nop 0
	global_load_lds_dwordx4 v212, s[98:99]
	s_waitcnt lgkmcnt(6)
	v_mfma_f32_16x16x32_bf16 v[28:31], v[72:75], v[180:183], v[28:31]
	v_mfma_f32_16x16x32_bf16 v[16:19], v[216:219], v[180:183], v[16:19]
	ds_read_b128 v[64:67], v208 offset:0
	ds_read_b128 v[68:71], v208 offset:2048
	ds_read_b128 v[160:163], v210 offset:16384
	s_add_u32 m0, s41, 36864
	s_nop 0
	global_load_lds_dwordx4 v213, s[98:99]
	s_waitcnt lgkmcnt(8)
	v_mfma_f32_16x16x32_bf16 v[60:63], v[72:75], v[184:187], v[60:63]
	v_mfma_f32_16x16x32_bf16 v[40:43], v[216:219], v[184:187], v[40:43]
	ds_read_b128 v[164:167], v210 offset:18432
	s_add_u32 m0, s41, 40960
	s_nop 0
	global_load_lds_dwordx4 v214, s[98:99]
	s_waitcnt lgkmcnt(8)
	v_mfma_f32_16x16x32_bf16 v[20:23], v[72:75], v[188:191], v[20:23]
	v_mfma_f32_16x16x32_bf16 v[0:3], v[216:219], v[188:191], v[0:3]
	ds_read_b128 v[168:171], v210 offset:20480
	s_add_u32 m0, s41, 45056
	s_nop 0
	global_load_lds_dwordx4 v215, s[98:99]
	s_add_u32 s98, s98, 128
	s_addc_u32 s99, s99, 0
	s_waitcnt lgkmcnt(8)
	v_mfma_f32_16x16x32_bf16 v[52:55], v[72:75], v[192:195], v[52:55]
	v_mfma_f32_16x16x32_bf16 v[36:39], v[216:219], v[192:195], v[36:39]
	ds_read_b128 v[172:175], v210 offset:22528
	s_add_u32 m0, s41, 49152
	s_nop 0
	global_load_lds_dwordx4 v212, s[100:101]
	s_waitcnt lgkmcnt(8)
	v_mfma_f32_16x16x32_bf16 v[24:27], v[72:75], v[196:199], v[24:27]
	v_mfma_f32_16x16x32_bf16 v[8:11], v[216:219], v[196:199], v[8:11]
	ds_read_b128 v[176:179], v210 offset:24576
	s_add_u32 m0, s41, 53248
	s_nop 0
	global_load_lds_dwordx4 v213, s[100:101]
	s_waitcnt lgkmcnt(8)
	v_mfma_f32_16x16x32_bf16 v[56:59], v[72:75], v[200:203], v[56:59]
	v_mfma_f32_16x16x32_bf16 v[32:35], v[216:219], v[200:203], v[32:35]
	ds_read_b128 v[180:183], v210 offset:26624
	s_add_u32 m0, s41, 57344
	s_nop 0
	global_load_lds_dwordx4 v214, s[100:101]
	s_waitcnt lgkmcnt(8)
	v_mfma_f32_16x16x32_bf16 v[12:15], v[72:75], v[204:207], v[12:15]
	v_mfma_f32_16x16x32_bf16 v[4:7], v[216:219], v[204:207], v[4:7]
	ds_read_b128 v[184:187], v210 offset:28672
	s_add_u32 m0, s41, 61440
	s_nop 0
	global_load_lds_dwordx4 v215, s[100:101]
	s_add_u32 s100, s100, 128
	s_addc_u32 s101, s101, 0
	s_waitcnt lgkmcnt(6)
	v_mfma_f32_16x16x32_bf16 v[44:47], v[64:67], v[160:163], v[44:47]
	v_mfma_f32_16x16x32_bf16 v[48:51], v[68:71], v[160:163], v[48:51]
	ds_read_b128 v[188:191], v210 offset:30720
	s_waitcnt lgkmcnt(6)
	v_mfma_f32_16x16x32_bf16 v[28:31], v[64:67], v[164:167], v[28:31]
	v_mfma_f32_16x16x32_bf16 v[16:19], v[68:71], v[164:167], v[16:19]
	ds_read_b128 v[72:75], v209 offset:0
	ds_read_b128 v[216:219], v209 offset:2048
	ds_read_b128 v[192:195], v211 offset:16384
	s_waitcnt lgkmcnt(8)
	v_mfma_f32_16x16x32_bf16 v[60:63], v[64:67], v[168:171], v[60:63]
	v_mfma_f32_16x16x32_bf16 v[40:43], v[68:71], v[168:171], v[40:43]
	ds_read_b128 v[196:199], v211 offset:18432
	s_waitcnt lgkmcnt(8)
	v_mfma_f32_16x16x32_bf16 v[20:23], v[64:67], v[172:175], v[20:23]
	v_mfma_f32_16x16x32_bf16 v[0:3], v[68:71], v[172:175], v[0:3]
	ds_read_b128 v[200:203], v211 offset:20480
	s_waitcnt lgkmcnt(8)
	v_mfma_f32_16x16x32_bf16 v[52:55], v[64:67], v[176:179], v[52:55]
	v_mfma_f32_16x16x32_bf16 v[36:39], v[68:71], v[176:179], v[36:39]
	ds_read_b128 v[204:207], v211 offset:22528
	s_waitcnt lgkmcnt(8)
	v_mfma_f32_16x16x32_bf16 v[24:27], v[64:67], v[180:183], v[24:27]
	v_mfma_f32_16x16x32_bf16 v[8:11], v[68:71], v[180:183], v[8:11]
	ds_read_b128 v[160:163], v211 offset:24576
	s_waitcnt lgkmcnt(8)
	v_mfma_f32_16x16x32_bf16 v[56:59], v[64:67], v[184:187], v[56:59]
	v_mfma_f32_16x16x32_bf16 v[32:35], v[68:71], v[184:187], v[32:35]
	ds_read_b128 v[164:167], v211 offset:26624
	s_waitcnt lgkmcnt(8)
	v_mfma_f32_16x16x32_bf16 v[12:15], v[64:67], v[188:191], v[12:15]
	v_mfma_f32_16x16x32_bf16 v[4:7], v[68:71], v[188:191], v[4:7]
	ds_read_b128 v[168:171], v211 offset:28672
	s_waitcnt lgkmcnt(6)
	v_mfma_f32_16x16x32_bf16 v[44:47], v[72:75], v[192:195], v[44:47]
	v_mfma_f32_16x16x32_bf16 v[48:51], v[216:219], v[192:195], v[48:51]
	ds_read_b128 v[172:175], v211 offset:30720
	s_waitcnt vmcnt(0) lgkmcnt(0)
	s_barrier
	s_add_u32 m0, s41, 0
	s_nop 0
	global_load_lds_dwordx4 v212, s[98:99]
	s_waitcnt lgkmcnt(6)
	v_mfma_f32_16x16x32_bf16 v[28:31], v[72:75], v[196:199], v[28:31]
	v_mfma_f32_16x16x32_bf16 v[16:19], v[216:219], v[196:199], v[16:19]
	ds_read_b128 v[64:67], v208 offset:32768
	ds_read_b128 v[68:71], v208 offset:34816
	ds_read_b128 v[176:179], v210 offset:49152
	s_add_u32 m0, s41, 4096
	s_nop 0
	global_load_lds_dwordx4 v213, s[98:99]
	s_waitcnt lgkmcnt(8)
	v_mfma_f32_16x16x32_bf16 v[60:63], v[72:75], v[200:203], v[60:63]
	v_mfma_f32_16x16x32_bf16 v[40:43], v[216:219], v[200:203], v[40:43]
	ds_read_b128 v[180:183], v210 offset:51200
	s_add_u32 m0, s41, 8192
	s_nop 0
	global_load_lds_dwordx4 v214, s[98:99]
	s_waitcnt lgkmcnt(8)
	v_mfma_f32_16x16x32_bf16 v[20:23], v[72:75], v[204:207], v[20:23]
	v_mfma_f32_16x16x32_bf16 v[0:3], v[216:219], v[204:207], v[0:3]
	ds_read_b128 v[184:187], v210 offset:53248
	s_add_u32 m0, s41, 12288
	s_nop 0
	global_load_lds_dwordx4 v215, s[98:99]
	s_add_u32 s98, s98, 128
	s_addc_u32 s99, s99, 0
	s_waitcnt lgkmcnt(8)
	v_mfma_f32_16x16x32_bf16 v[52:55], v[72:75], v[160:163], v[52:55]
	v_mfma_f32_16x16x32_bf16 v[36:39], v[216:219], v[160:163], v[36:39]
	ds_read_b128 v[188:191], v210 offset:55296
	s_add_u32 m0, s41, 16384
	s_nop 0
	global_load_lds_dwordx4 v212, s[100:101]
	s_waitcnt lgkmcnt(8)
	v_mfma_f32_16x16x32_bf16 v[24:27], v[72:75], v[164:167], v[24:27]
	v_mfma_f32_16x16x32_bf16 v[8:11], v[216:219], v[164:167], v[8:11]
	ds_read_b128 v[192:195], v210 offset:57344
	s_add_u32 m0, s41, 20480
	s_nop 0
	global_load_lds_dwordx4 v213, s[100:101]
	s_waitcnt lgkmcnt(8)
	v_mfma_f32_16x16x32_bf16 v[56:59], v[72:75], v[168:171], v[56:59]
	v_mfma_f32_16x16x32_bf16 v[32:35], v[216:219], v[168:171], v[32:35]
	ds_read_b128 v[196:199], v210 offset:59392
	s_add_u32 m0, s41, 24576
	s_nop 0
	global_load_lds_dwordx4 v214, s[100:101]
	s_waitcnt lgkmcnt(8)
	v_mfma_f32_16x16x32_bf16 v[12:15], v[72:75], v[172:175], v[12:15]
	v_mfma_f32_16x16x32_bf16 v[4:7], v[216:219], v[172:175], v[4:7]
	ds_read_b128 v[200:203], v210 offset:61440
	s_add_u32 m0, s41, 28672
	s_nop 0
	global_load_lds_dwordx4 v215, s[100:101]
	s_add_u32 s100, s100, 128
	s_addc_u32 s101, s101, 0
	s_waitcnt lgkmcnt(6)
	v_mfma_f32_16x16x32_bf16 v[44:47], v[64:67], v[176:179], v[44:47]
	v_mfma_f32_16x16x32_bf16 v[48:51], v[68:71], v[176:179], v[48:51]
	ds_read_b128 v[204:207], v210 offset:63488
	s_waitcnt lgkmcnt(6)
	v_mfma_f32_16x16x32_bf16 v[28:31], v[64:67], v[180:183], v[28:31]
	v_mfma_f32_16x16x32_bf16 v[16:19], v[68:71], v[180:183], v[16:19]
	ds_read_b128 v[72:75], v209 offset:32768
	ds_read_b128 v[216:219], v209 offset:34816
	ds_read_b128 v[160:163], v211 offset:49152
	s_waitcnt lgkmcnt(8)
	v_mfma_f32_16x16x32_bf16 v[60:63], v[64:67], v[184:187], v[60:63]
	v_mfma_f32_16x16x32_bf16 v[40:43], v[68:71], v[184:187], v[40:43]
	ds_read_b128 v[164:167], v211 offset:51200
	s_waitcnt lgkmcnt(8)
	v_mfma_f32_16x16x32_bf16 v[20:23], v[64:67], v[188:191], v[20:23]
	v_mfma_f32_16x16x32_bf16 v[0:3], v[68:71], v[188:191], v[0:3]
	ds_read_b128 v[168:171], v211 offset:53248
	s_waitcnt lgkmcnt(8)
	v_mfma_f32_16x16x32_bf16 v[52:55], v[64:67], v[192:195], v[52:55]
	v_mfma_f32_16x16x32_bf16 v[36:39], v[68:71], v[192:195], v[36:39]
	ds_read_b128 v[172:175], v211 offset:55296
	s_waitcnt lgkmcnt(8)
	v_mfma_f32_16x16x32_bf16 v[24:27], v[64:67], v[196:199], v[24:27]
	v_mfma_f32_16x16x32_bf16 v[8:11], v[68:71], v[196:199], v[8:11]
	ds_read_b128 v[176:179], v211 offset:57344
	s_waitcnt lgkmcnt(8)
	v_mfma_f32_16x16x32_bf16 v[56:59], v[64:67], v[200:203], v[56:59]
	v_mfma_f32_16x16x32_bf16 v[32:35], v[68:71], v[200:203], v[32:35]
	ds_read_b128 v[180:183], v211 offset:59392
	s_waitcnt lgkmcnt(8)
	v_mfma_f32_16x16x32_bf16 v[12:15], v[64:67], v[204:207], v[12:15]
	v_mfma_f32_16x16x32_bf16 v[4:7], v[68:71], v[204:207], v[4:7]
	ds_read_b128 v[184:187], v211 offset:61440
	s_waitcnt lgkmcnt(6)
	v_mfma_f32_16x16x32_bf16 v[44:47], v[72:75], v[160:163], v[44:47]
	v_mfma_f32_16x16x32_bf16 v[48:51], v[216:219], v[160:163], v[48:51]
	ds_read_b128 v[188:191], v211 offset:63488
	s_waitcnt vmcnt(0) lgkmcnt(0)
	s_barrier
	s_add_u32 m0, s41, 32768
	s_nop 0
	global_load_lds_dwordx4 v212, s[98:99]
	s_waitcnt lgkmcnt(6)
	v_mfma_f32_16x16x32_bf16 v[28:31], v[72:75], v[164:167], v[28:31]
	v_mfma_f32_16x16x32_bf16 v[16:19], v[216:219], v[164:167], v[16:19]
	ds_read_b128 v[64:67], v208 offset:0
	ds_read_b128 v[68:71], v208 offset:2048
	ds_read_b128 v[192:195], v210 offset:16384
	s_add_u32 m0, s41, 36864
	s_nop 0
	global_load_lds_dwordx4 v213, s[98:99]
	s_waitcnt lgkmcnt(8)
	v_mfma_f32_16x16x32_bf16 v[60:63], v[72:75], v[168:171], v[60:63]
	v_mfma_f32_16x16x32_bf16 v[40:43], v[216:219], v[168:171], v[40:43]
	ds_read_b128 v[196:199], v210 offset:18432
	s_add_u32 m0, s41, 40960
	s_nop 0
	global_load_lds_dwordx4 v214, s[98:99]
	s_waitcnt lgkmcnt(8)
	v_mfma_f32_16x16x32_bf16 v[20:23], v[72:75], v[172:175], v[20:23]
	v_mfma_f32_16x16x32_bf16 v[0:3], v[216:219], v[172:175], v[0:3]
	ds_read_b128 v[200:203], v210 offset:20480
	s_add_u32 m0, s41, 45056
	s_nop 0
	global_load_lds_dwordx4 v215, s[98:99]
	s_add_u32 s98, s98, 128
	s_addc_u32 s99, s99, 0
	s_waitcnt lgkmcnt(8)
	v_mfma_f32_16x16x32_bf16 v[52:55], v[72:75], v[176:179], v[52:55]
	v_mfma_f32_16x16x32_bf16 v[36:39], v[216:219], v[176:179], v[36:39]
	ds_read_b128 v[204:207], v210 offset:22528
	s_add_u32 m0, s41, 49152
	s_nop 0
	global_load_lds_dwordx4 v212, s[100:101]
	s_waitcnt lgkmcnt(8)
	v_mfma_f32_16x16x32_bf16 v[24:27], v[72:75], v[180:183], v[24:27]
	v_mfma_f32_16x16x32_bf16 v[8:11], v[216:219], v[180:183], v[8:11]
	ds_read_b128 v[160:163], v210 offset:24576
	s_add_u32 m0, s41, 53248
	s_nop 0
	global_load_lds_dwordx4 v213, s[100:101]
	s_waitcnt lgkmcnt(8)
	v_mfma_f32_16x16x32_bf16 v[56:59], v[72:75], v[184:187], v[56:59]
	v_mfma_f32_16x16x32_bf16 v[32:35], v[216:219], v[184:187], v[32:35]
	ds_read_b128 v[164:167], v210 offset:26624
	s_add_u32 m0, s41, 57344
	s_nop 0
	global_load_lds_dwordx4 v214, s[100:101]
	s_waitcnt lgkmcnt(8)
	v_mfma_f32_16x16x32_bf16 v[12:15], v[72:75], v[188:191], v[12:15]
	v_mfma_f32_16x16x32_bf16 v[4:7], v[216:219], v[188:191], v[4:7]
	ds_read_b128 v[168:171], v210 offset:28672
	s_add_u32 m0, s41, 61440
	s_nop 0
	global_load_lds_dwordx4 v215, s[100:101]
	s_add_u32 s100, s100, 128
	s_addc_u32 s101, s101, 0
	s_waitcnt lgkmcnt(6)
	v_mfma_f32_16x16x32_bf16 v[44:47], v[64:67], v[192:195], v[44:47]
	v_mfma_f32_16x16x32_bf16 v[48:51], v[68:71], v[192:195], v[48:51]
	ds_read_b128 v[172:175], v210 offset:30720
	s_waitcnt lgkmcnt(6)
	v_mfma_f32_16x16x32_bf16 v[28:31], v[64:67], v[196:199], v[28:31]
	v_mfma_f32_16x16x32_bf16 v[16:19], v[68:71], v[196:199], v[16:19]
	ds_read_b128 v[72:75], v209 offset:0
	ds_read_b128 v[216:219], v209 offset:2048
	ds_read_b128 v[176:179], v211 offset:16384
	s_waitcnt lgkmcnt(8)
	v_mfma_f32_16x16x32_bf16 v[60:63], v[64:67], v[200:203], v[60:63]
	v_mfma_f32_16x16x32_bf16 v[40:43], v[68:71], v[200:203], v[40:43]
	ds_read_b128 v[180:183], v211 offset:18432
	s_waitcnt lgkmcnt(8)
	v_mfma_f32_16x16x32_bf16 v[20:23], v[64:67], v[204:207], v[20:23]
	v_mfma_f32_16x16x32_bf16 v[0:3], v[68:71], v[204:207], v[0:3]
	ds_read_b128 v[184:187], v211 offset:20480
	s_waitcnt lgkmcnt(8)
	v_mfma_f32_16x16x32_bf16 v[52:55], v[64:67], v[160:163], v[52:55]
	v_mfma_f32_16x16x32_bf16 v[36:39], v[68:71], v[160:163], v[36:39]
	ds_read_b128 v[188:191], v211 offset:22528
	s_waitcnt lgkmcnt(8)
	v_mfma_f32_16x16x32_bf16 v[24:27], v[64:67], v[164:167], v[24:27]
	v_mfma_f32_16x16x32_bf16 v[8:11], v[68:71], v[164:167], v[8:11]
	ds_read_b128 v[192:195], v211 offset:24576
	s_waitcnt lgkmcnt(8)
	v_mfma_f32_16x16x32_bf16 v[56:59], v[64:67], v[168:171], v[56:59]
	v_mfma_f32_16x16x32_bf16 v[32:35], v[68:71], v[168:171], v[32:35]
	ds_read_b128 v[196:199], v211 offset:26624
	s_waitcnt lgkmcnt(8)
	v_mfma_f32_16x16x32_bf16 v[12:15], v[64:67], v[172:175], v[12:15]
	v_mfma_f32_16x16x32_bf16 v[4:7], v[68:71], v[172:175], v[4:7]
	ds_read_b128 v[200:203], v211 offset:28672
	s_waitcnt lgkmcnt(6)
	v_mfma_f32_16x16x32_bf16 v[44:47], v[72:75], v[176:179], v[44:47]
	v_mfma_f32_16x16x32_bf16 v[48:51], v[216:219], v[176:179], v[48:51]
	ds_read_b128 v[204:207], v211 offset:30720
	s_waitcnt vmcnt(0) lgkmcnt(0)
	s_barrier
	s_add_u32 m0, s41, 0
	s_nop 0
	global_load_lds_dwordx4 v212, s[98:99]
	s_waitcnt lgkmcnt(6)
	v_mfma_f32_16x16x32_bf16 v[28:31], v[72:75], v[180:183], v[28:31]
	v_mfma_f32_16x16x32_bf16 v[16:19], v[216:219], v[180:183], v[16:19]
	ds_read_b128 v[64:67], v208 offset:32768
	ds_read_b128 v[68:71], v208 offset:34816
	ds_read_b128 v[160:163], v210 offset:49152
	s_add_u32 m0, s41, 4096
	s_nop 0
	global_load_lds_dwordx4 v213, s[98:99]
	s_waitcnt lgkmcnt(8)
	v_mfma_f32_16x16x32_bf16 v[60:63], v[72:75], v[184:187], v[60:63]
	v_mfma_f32_16x16x32_bf16 v[40:43], v[216:219], v[184:187], v[40:43]
	ds_read_b128 v[164:167], v210 offset:51200
	s_add_u32 m0, s41, 8192
	s_nop 0
	global_load_lds_dwordx4 v214, s[98:99]
	s_waitcnt lgkmcnt(8)
	v_mfma_f32_16x16x32_bf16 v[20:23], v[72:75], v[188:191], v[20:23]
	v_mfma_f32_16x16x32_bf16 v[0:3], v[216:219], v[188:191], v[0:3]
	ds_read_b128 v[168:171], v210 offset:53248
	s_add_u32 m0, s41, 12288
	s_nop 0
	global_load_lds_dwordx4 v215, s[98:99]
	s_add_u32 s98, s98, 128
	s_addc_u32 s99, s99, 0
	s_waitcnt lgkmcnt(8)
	v_mfma_f32_16x16x32_bf16 v[52:55], v[72:75], v[192:195], v[52:55]
	v_mfma_f32_16x16x32_bf16 v[36:39], v[216:219], v[192:195], v[36:39]
	ds_read_b128 v[172:175], v210 offset:55296
	s_add_u32 m0, s41, 16384
	s_nop 0
	global_load_lds_dwordx4 v212, s[100:101]
	s_waitcnt lgkmcnt(8)
	v_mfma_f32_16x16x32_bf16 v[24:27], v[72:75], v[196:199], v[24:27]
	v_mfma_f32_16x16x32_bf16 v[8:11], v[216:219], v[196:199], v[8:11]
	ds_read_b128 v[176:179], v210 offset:57344
	s_add_u32 m0, s41, 20480
	s_nop 0
	global_load_lds_dwordx4 v213, s[100:101]
	s_waitcnt lgkmcnt(8)
	v_mfma_f32_16x16x32_bf16 v[56:59], v[72:75], v[200:203], v[56:59]
	v_mfma_f32_16x16x32_bf16 v[32:35], v[216:219], v[200:203], v[32:35]
	ds_read_b128 v[180:183], v210 offset:59392
	s_add_u32 m0, s41, 24576
	s_nop 0
	global_load_lds_dwordx4 v214, s[100:101]
	s_waitcnt lgkmcnt(8)
	v_mfma_f32_16x16x32_bf16 v[12:15], v[72:75], v[204:207], v[12:15]
	v_mfma_f32_16x16x32_bf16 v[4:7], v[216:219], v[204:207], v[4:7]
	ds_read_b128 v[184:187], v210 offset:61440
	s_add_u32 m0, s41, 28672
	s_nop 0
	global_load_lds_dwordx4 v215, s[100:101]
	s_add_u32 s100, s100, 128
	s_addc_u32 s101, s101, 0
	s_waitcnt lgkmcnt(6)
	v_mfma_f32_16x16x32_bf16 v[44:47], v[64:67], v[160:163], v[44:47]
	v_mfma_f32_16x16x32_bf16 v[48:51], v[68:71], v[160:163], v[48:51]
	ds_read_b128 v[188:191], v210 offset:63488
	s_waitcnt lgkmcnt(6)
	v_mfma_f32_16x16x32_bf16 v[28:31], v[64:67], v[164:167], v[28:31]
	v_mfma_f32_16x16x32_bf16 v[16:19], v[68:71], v[164:167], v[16:19]
	ds_read_b128 v[72:75], v209 offset:32768
	ds_read_b128 v[216:219], v209 offset:34816
	ds_read_b128 v[192:195], v211 offset:49152
	s_waitcnt lgkmcnt(8)
	v_mfma_f32_16x16x32_bf16 v[60:63], v[64:67], v[168:171], v[60:63]
	v_mfma_f32_16x16x32_bf16 v[40:43], v[68:71], v[168:171], v[40:43]
	ds_read_b128 v[196:199], v211 offset:51200
	s_waitcnt lgkmcnt(8)
	v_mfma_f32_16x16x32_bf16 v[20:23], v[64:67], v[172:175], v[20:23]
	v_mfma_f32_16x16x32_bf16 v[0:3], v[68:71], v[172:175], v[0:3]
	ds_read_b128 v[200:203], v211 offset:53248
	s_waitcnt lgkmcnt(8)
	v_mfma_f32_16x16x32_bf16 v[52:55], v[64:67], v[176:179], v[52:55]
	v_mfma_f32_16x16x32_bf16 v[36:39], v[68:71], v[176:179], v[36:39]
	ds_read_b128 v[204:207], v211 offset:55296
	s_waitcnt lgkmcnt(8)
	v_mfma_f32_16x16x32_bf16 v[24:27], v[64:67], v[180:183], v[24:27]
	v_mfma_f32_16x16x32_bf16 v[8:11], v[68:71], v[180:183], v[8:11]
	ds_read_b128 v[160:163], v211 offset:57344
	s_waitcnt lgkmcnt(8)
	v_mfma_f32_16x16x32_bf16 v[56:59], v[64:67], v[184:187], v[56:59]
	v_mfma_f32_16x16x32_bf16 v[32:35], v[68:71], v[184:187], v[32:35]
	ds_read_b128 v[164:167], v211 offset:59392
	s_waitcnt lgkmcnt(8)
	v_mfma_f32_16x16x32_bf16 v[12:15], v[64:67], v[188:191], v[12:15]
	v_mfma_f32_16x16x32_bf16 v[4:7], v[68:71], v[188:191], v[4:7]
	ds_read_b128 v[168:171], v211 offset:61440
	s_waitcnt lgkmcnt(6)
	v_mfma_f32_16x16x32_bf16 v[44:47], v[72:75], v[192:195], v[44:47]
	v_mfma_f32_16x16x32_bf16 v[48:51], v[216:219], v[192:195], v[48:51]
	ds_read_b128 v[172:175], v211 offset:63488
	s_waitcnt vmcnt(0) lgkmcnt(0)
	s_barrier
	s_add_u32 m0, s41, 32768
	s_nop 0
	global_load_lds_dwordx4 v212, s[98:99]
	s_waitcnt lgkmcnt(6)
	v_mfma_f32_16x16x32_bf16 v[28:31], v[72:75], v[196:199], v[28:31]
	v_mfma_f32_16x16x32_bf16 v[16:19], v[216:219], v[196:199], v[16:19]
	ds_read_b128 v[64:67], v208 offset:0
	ds_read_b128 v[68:71], v208 offset:2048
	ds_read_b128 v[176:179], v210 offset:16384
	s_add_u32 m0, s41, 36864
	s_nop 0
	global_load_lds_dwordx4 v213, s[98:99]
	s_waitcnt lgkmcnt(8)
	v_mfma_f32_16x16x32_bf16 v[60:63], v[72:75], v[200:203], v[60:63]
	v_mfma_f32_16x16x32_bf16 v[40:43], v[216:219], v[200:203], v[40:43]
	ds_read_b128 v[180:183], v210 offset:18432
	s_add_u32 m0, s41, 40960
	s_nop 0
	global_load_lds_dwordx4 v214, s[98:99]
	s_waitcnt lgkmcnt(8)
	v_mfma_f32_16x16x32_bf16 v[20:23], v[72:75], v[204:207], v[20:23]
	v_mfma_f32_16x16x32_bf16 v[0:3], v[216:219], v[204:207], v[0:3]
	ds_read_b128 v[184:187], v210 offset:20480
	s_add_u32 m0, s41, 45056
	s_nop 0
	global_load_lds_dwordx4 v215, s[98:99]
	s_add_u32 s98, s98, 128
	s_addc_u32 s99, s99, 0
	s_waitcnt lgkmcnt(8)
	v_mfma_f32_16x16x32_bf16 v[52:55], v[72:75], v[160:163], v[52:55]
	v_mfma_f32_16x16x32_bf16 v[36:39], v[216:219], v[160:163], v[36:39]
	ds_read_b128 v[188:191], v210 offset:22528
	s_add_u32 m0, s41, 49152
	s_nop 0
	global_load_lds_dwordx4 v212, s[100:101]
	s_waitcnt lgkmcnt(8)
	v_mfma_f32_16x16x32_bf16 v[24:27], v[72:75], v[164:167], v[24:27]
	v_mfma_f32_16x16x32_bf16 v[8:11], v[216:219], v[164:167], v[8:11]
	ds_read_b128 v[192:195], v210 offset:24576
	s_add_u32 m0, s41, 53248
	s_nop 0
	global_load_lds_dwordx4 v213, s[100:101]
	s_waitcnt lgkmcnt(8)
	v_mfma_f32_16x16x32_bf16 v[56:59], v[72:75], v[168:171], v[56:59]
	v_mfma_f32_16x16x32_bf16 v[32:35], v[216:219], v[168:171], v[32:35]
	ds_read_b128 v[196:199], v210 offset:26624
	s_add_u32 m0, s41, 57344
	s_nop 0
	global_load_lds_dwordx4 v214, s[100:101]
	s_waitcnt lgkmcnt(8)
	v_mfma_f32_16x16x32_bf16 v[12:15], v[72:75], v[172:175], v[12:15]
	v_mfma_f32_16x16x32_bf16 v[4:7], v[216:219], v[172:175], v[4:7]
	ds_read_b128 v[200:203], v210 offset:28672
	s_add_u32 m0, s41, 61440
	s_nop 0
	global_load_lds_dwordx4 v215, s[100:101]
	s_add_u32 s100, s100, 128
	s_addc_u32 s101, s101, 0
	s_waitcnt lgkmcnt(6)
	v_mfma_f32_16x16x32_bf16 v[44:47], v[64:67], v[176:179], v[44:47]
	v_mfma_f32_16x16x32_bf16 v[48:51], v[68:71], v[176:179], v[48:51]
	ds_read_b128 v[204:207], v210 offset:30720
	s_waitcnt lgkmcnt(6)
	v_mfma_f32_16x16x32_bf16 v[28:31], v[64:67], v[180:183], v[28:31]
	v_mfma_f32_16x16x32_bf16 v[16:19], v[68:71], v[180:183], v[16:19]
	ds_read_b128 v[72:75], v209 offset:0
	ds_read_b128 v[216:219], v209 offset:2048
	ds_read_b128 v[160:163], v211 offset:16384
	s_waitcnt lgkmcnt(8)
	v_mfma_f32_16x16x32_bf16 v[60:63], v[64:67], v[184:187], v[60:63]
	v_mfma_f32_16x16x32_bf16 v[40:43], v[68:71], v[184:187], v[40:43]
	ds_read_b128 v[164:167], v211 offset:18432
	s_waitcnt lgkmcnt(8)
	v_mfma_f32_16x16x32_bf16 v[20:23], v[64:67], v[188:191], v[20:23]
	v_mfma_f32_16x16x32_bf16 v[0:3], v[68:71], v[188:191], v[0:3]
	ds_read_b128 v[168:171], v211 offset:20480
	s_waitcnt lgkmcnt(8)
	v_mfma_f32_16x16x32_bf16 v[52:55], v[64:67], v[192:195], v[52:55]
	v_mfma_f32_16x16x32_bf16 v[36:39], v[68:71], v[192:195], v[36:39]
	ds_read_b128 v[172:175], v211 offset:22528
	s_waitcnt lgkmcnt(8)
	v_mfma_f32_16x16x32_bf16 v[24:27], v[64:67], v[196:199], v[24:27]
	v_mfma_f32_16x16x32_bf16 v[8:11], v[68:71], v[196:199], v[8:11]
	ds_read_b128 v[176:179], v211 offset:24576
	s_waitcnt lgkmcnt(8)
	v_mfma_f32_16x16x32_bf16 v[56:59], v[64:67], v[200:203], v[56:59]
	v_mfma_f32_16x16x32_bf16 v[32:35], v[68:71], v[200:203], v[32:35]
	ds_read_b128 v[180:183], v211 offset:26624
	s_waitcnt lgkmcnt(8)
	v_mfma_f32_16x16x32_bf16 v[12:15], v[64:67], v[204:207], v[12:15]
	v_mfma_f32_16x16x32_bf16 v[4:7], v[68:71], v[204:207], v[4:7]
	ds_read_b128 v[184:187], v211 offset:28672
	s_waitcnt lgkmcnt(6)
	v_mfma_f32_16x16x32_bf16 v[44:47], v[72:75], v[160:163], v[44:47]
	v_mfma_f32_16x16x32_bf16 v[48:51], v[216:219], v[160:163], v[48:51]
	ds_read_b128 v[188:191], v211 offset:30720
	s_waitcnt vmcnt(0) lgkmcnt(0)
	s_barrier
	s_add_u32 m0, s41, 0
	s_nop 0
	global_load_lds_dwordx4 v212, s[98:99]
	s_waitcnt lgkmcnt(6)
	v_mfma_f32_16x16x32_bf16 v[28:31], v[72:75], v[164:167], v[28:31]
	v_mfma_f32_16x16x32_bf16 v[16:19], v[216:219], v[164:167], v[16:19]
	ds_read_b128 v[64:67], v208 offset:32768
	ds_read_b128 v[68:71], v208 offset:34816
	ds_read_b128 v[192:195], v210 offset:49152
	s_add_u32 m0, s41, 4096
	s_nop 0
	global_load_lds_dwordx4 v213, s[98:99]
	s_waitcnt lgkmcnt(8)
	v_mfma_f32_16x16x32_bf16 v[60:63], v[72:75], v[168:171], v[60:63]
	v_mfma_f32_16x16x32_bf16 v[40:43], v[216:219], v[168:171], v[40:43]
	ds_read_b128 v[196:199], v210 offset:51200
	s_add_u32 m0, s41, 8192
	s_nop 0
	global_load_lds_dwordx4 v214, s[98:99]
	s_waitcnt lgkmcnt(8)
	v_mfma_f32_16x16x32_bf16 v[20:23], v[72:75], v[172:175], v[20:23]
	v_mfma_f32_16x16x32_bf16 v[0:3], v[216:219], v[172:175], v[0:3]
	ds_read_b128 v[200:203], v210 offset:53248
	s_add_u32 m0, s41, 12288
	s_nop 0
	global_load_lds_dwordx4 v215, s[98:99]
	s_add_u32 s98, s98, 128
	s_addc_u32 s99, s99, 0
	s_waitcnt lgkmcnt(8)
	v_mfma_f32_16x16x32_bf16 v[52:55], v[72:75], v[176:179], v[52:55]
	v_mfma_f32_16x16x32_bf16 v[36:39], v[216:219], v[176:179], v[36:39]
	ds_read_b128 v[204:207], v210 offset:55296
	s_add_u32 m0, s41, 16384
	s_nop 0
	global_load_lds_dwordx4 v212, s[100:101]
	s_waitcnt lgkmcnt(8)
	v_mfma_f32_16x16x32_bf16 v[24:27], v[72:75], v[180:183], v[24:27]
	v_mfma_f32_16x16x32_bf16 v[8:11], v[216:219], v[180:183], v[8:11]
	ds_read_b128 v[160:163], v210 offset:57344
	s_add_u32 m0, s41, 20480
	s_nop 0
	global_load_lds_dwordx4 v213, s[100:101]
	s_waitcnt lgkmcnt(8)
	v_mfma_f32_16x16x32_bf16 v[56:59], v[72:75], v[184:187], v[56:59]
	v_mfma_f32_16x16x32_bf16 v[32:35], v[216:219], v[184:187], v[32:35]
	ds_read_b128 v[164:167], v210 offset:59392
	s_add_u32 m0, s41, 24576
	s_nop 0
	global_load_lds_dwordx4 v214, s[100:101]
	s_waitcnt lgkmcnt(8)
	v_mfma_f32_16x16x32_bf16 v[12:15], v[72:75], v[188:191], v[12:15]
	v_mfma_f32_16x16x32_bf16 v[4:7], v[216:219], v[188:191], v[4:7]
	ds_read_b128 v[168:171], v210 offset:61440
	s_add_u32 m0, s41, 28672
	s_nop 0
	global_load_lds_dwordx4 v215, s[100:101]
	s_add_u32 s100, s100, 128
	s_addc_u32 s101, s101, 0
	s_waitcnt lgkmcnt(6)
	v_mfma_f32_16x16x32_bf16 v[44:47], v[64:67], v[192:195], v[44:47]
	v_mfma_f32_16x16x32_bf16 v[48:51], v[68:71], v[192:195], v[48:51]
	ds_read_b128 v[172:175], v210 offset:63488
	s_waitcnt lgkmcnt(6)
	v_mfma_f32_16x16x32_bf16 v[28:31], v[64:67], v[196:199], v[28:31]
	v_mfma_f32_16x16x32_bf16 v[16:19], v[68:71], v[196:199], v[16:19]
	ds_read_b128 v[72:75], v209 offset:32768
	ds_read_b128 v[216:219], v209 offset:34816
	ds_read_b128 v[176:179], v211 offset:49152
	s_waitcnt lgkmcnt(8)
	v_mfma_f32_16x16x32_bf16 v[60:63], v[64:67], v[200:203], v[60:63]
	v_mfma_f32_16x16x32_bf16 v[40:43], v[68:71], v[200:203], v[40:43]
	ds_read_b128 v[180:183], v211 offset:51200
	s_waitcnt lgkmcnt(8)
	v_mfma_f32_16x16x32_bf16 v[20:23], v[64:67], v[204:207], v[20:23]
	v_mfma_f32_16x16x32_bf16 v[0:3], v[68:71], v[204:207], v[0:3]
	ds_read_b128 v[184:187], v211 offset:53248
	s_waitcnt lgkmcnt(8)
	v_mfma_f32_16x16x32_bf16 v[52:55], v[64:67], v[160:163], v[52:55]
	v_mfma_f32_16x16x32_bf16 v[36:39], v[68:71], v[160:163], v[36:39]
	ds_read_b128 v[188:191], v211 offset:55296
	s_waitcnt lgkmcnt(8)
	v_mfma_f32_16x16x32_bf16 v[24:27], v[64:67], v[164:167], v[24:27]
	v_mfma_f32_16x16x32_bf16 v[8:11], v[68:71], v[164:167], v[8:11]
	ds_read_b128 v[192:195], v211 offset:57344
	s_waitcnt lgkmcnt(8)
	v_mfma_f32_16x16x32_bf16 v[56:59], v[64:67], v[168:171], v[56:59]
	v_mfma_f32_16x16x32_bf16 v[32:35], v[68:71], v[168:171], v[32:35]
	ds_read_b128 v[196:199], v211 offset:59392
	s_waitcnt lgkmcnt(8)
	v_mfma_f32_16x16x32_bf16 v[12:15], v[64:67], v[172:175], v[12:15]
	v_mfma_f32_16x16x32_bf16 v[4:7], v[68:71], v[172:175], v[4:7]
	ds_read_b128 v[200:203], v211 offset:61440
	s_waitcnt lgkmcnt(6)
	v_mfma_f32_16x16x32_bf16 v[44:47], v[72:75], v[176:179], v[44:47]
	v_mfma_f32_16x16x32_bf16 v[48:51], v[216:219], v[176:179], v[48:51]
	ds_read_b128 v[204:207], v211 offset:63488
	s_waitcnt vmcnt(0) lgkmcnt(0)
	s_barrier
	s_add_u32 m0, s41, 32768
	s_nop 0
	global_load_lds_dwordx4 v212, s[98:99]
	s_waitcnt lgkmcnt(6)
	v_mfma_f32_16x16x32_bf16 v[28:31], v[72:75], v[180:183], v[28:31]
	v_mfma_f32_16x16x32_bf16 v[16:19], v[216:219], v[180:183], v[16:19]
	ds_read_b128 v[64:67], v208 offset:0
	ds_read_b128 v[68:71], v208 offset:2048
	ds_read_b128 v[160:163], v210 offset:16384
	s_add_u32 m0, s41, 36864
	s_nop 0
	global_load_lds_dwordx4 v213, s[98:99]
	s_waitcnt lgkmcnt(8)
	v_mfma_f32_16x16x32_bf16 v[60:63], v[72:75], v[184:187], v[60:63]
	v_mfma_f32_16x16x32_bf16 v[40:43], v[216:219], v[184:187], v[40:43]
	ds_read_b128 v[164:167], v210 offset:18432
	s_add_u32 m0, s41, 40960
	s_nop 0
	global_load_lds_dwordx4 v214, s[98:99]
	s_waitcnt lgkmcnt(8)
	v_mfma_f32_16x16x32_bf16 v[20:23], v[72:75], v[188:191], v[20:23]
	v_mfma_f32_16x16x32_bf16 v[0:3], v[216:219], v[188:191], v[0:3]
	ds_read_b128 v[168:171], v210 offset:20480
	s_add_u32 m0, s41, 45056
	s_nop 0
	global_load_lds_dwordx4 v215, s[98:99]
	s_add_u32 s98, s98, 128
	s_addc_u32 s99, s99, 0
	s_waitcnt lgkmcnt(8)
	v_mfma_f32_16x16x32_bf16 v[52:55], v[72:75], v[192:195], v[52:55]
	v_mfma_f32_16x16x32_bf16 v[36:39], v[216:219], v[192:195], v[36:39]
	ds_read_b128 v[172:175], v210 offset:22528
	s_add_u32 m0, s41, 49152
	s_nop 0
	global_load_lds_dwordx4 v212, s[100:101]
	s_waitcnt lgkmcnt(8)
	v_mfma_f32_16x16x32_bf16 v[24:27], v[72:75], v[196:199], v[24:27]
	v_mfma_f32_16x16x32_bf16 v[8:11], v[216:219], v[196:199], v[8:11]
	ds_read_b128 v[176:179], v210 offset:24576
	s_add_u32 m0, s41, 53248
	s_nop 0
	global_load_lds_dwordx4 v213, s[100:101]
	s_waitcnt lgkmcnt(8)
	v_mfma_f32_16x16x32_bf16 v[56:59], v[72:75], v[200:203], v[56:59]
	v_mfma_f32_16x16x32_bf16 v[32:35], v[216:219], v[200:203], v[32:35]
	ds_read_b128 v[180:183], v210 offset:26624
	s_add_u32 m0, s41, 57344
	s_nop 0
	global_load_lds_dwordx4 v214, s[100:101]
	s_waitcnt lgkmcnt(8)
	v_mfma_f32_16x16x32_bf16 v[12:15], v[72:75], v[204:207], v[12:15]
	v_mfma_f32_16x16x32_bf16 v[4:7], v[216:219], v[204:207], v[4:7]
	ds_read_b128 v[184:187], v210 offset:28672
	s_add_u32 m0, s41, 61440
	s_nop 0
	global_load_lds_dwordx4 v215, s[100:101]
	s_add_u32 s100, s100, 128
	s_addc_u32 s101, s101, 0
	s_waitcnt lgkmcnt(6)
	v_mfma_f32_16x16x32_bf16 v[44:47], v[64:67], v[160:163], v[44:47]
	v_mfma_f32_16x16x32_bf16 v[48:51], v[68:71], v[160:163], v[48:51]
	ds_read_b128 v[188:191], v210 offset:30720
	s_waitcnt lgkmcnt(6)
	v_mfma_f32_16x16x32_bf16 v[28:31], v[64:67], v[164:167], v[28:31]
	v_mfma_f32_16x16x32_bf16 v[16:19], v[68:71], v[164:167], v[16:19]
	ds_read_b128 v[72:75], v209 offset:0
	ds_read_b128 v[216:219], v209 offset:2048
	ds_read_b128 v[192:195], v211 offset:16384
	s_waitcnt lgkmcnt(8)
	v_mfma_f32_16x16x32_bf16 v[60:63], v[64:67], v[168:171], v[60:63]
	v_mfma_f32_16x16x32_bf16 v[40:43], v[68:71], v[168:171], v[40:43]
	ds_read_b128 v[196:199], v211 offset:18432
	s_waitcnt lgkmcnt(8)
	v_mfma_f32_16x16x32_bf16 v[20:23], v[64:67], v[172:175], v[20:23]
	v_mfma_f32_16x16x32_bf16 v[0:3], v[68:71], v[172:175], v[0:3]
	ds_read_b128 v[200:203], v211 offset:20480
	s_waitcnt lgkmcnt(8)
	v_mfma_f32_16x16x32_bf16 v[52:55], v[64:67], v[176:179], v[52:55]
	v_mfma_f32_16x16x32_bf16 v[36:39], v[68:71], v[176:179], v[36:39]
	ds_read_b128 v[204:207], v211 offset:22528
	s_waitcnt lgkmcnt(8)
	v_mfma_f32_16x16x32_bf16 v[24:27], v[64:67], v[180:183], v[24:27]
	v_mfma_f32_16x16x32_bf16 v[8:11], v[68:71], v[180:183], v[8:11]
	ds_read_b128 v[160:163], v211 offset:24576
	s_waitcnt lgkmcnt(8)
	v_mfma_f32_16x16x32_bf16 v[56:59], v[64:67], v[184:187], v[56:59]
	v_mfma_f32_16x16x32_bf16 v[32:35], v[68:71], v[184:187], v[32:35]
	ds_read_b128 v[164:167], v211 offset:26624
	s_waitcnt lgkmcnt(8)
	v_mfma_f32_16x16x32_bf16 v[12:15], v[64:67], v[188:191], v[12:15]
	v_mfma_f32_16x16x32_bf16 v[4:7], v[68:71], v[188:191], v[4:7]
	ds_read_b128 v[168:171], v211 offset:28672
	s_waitcnt lgkmcnt(6)
	v_mfma_f32_16x16x32_bf16 v[44:47], v[72:75], v[192:195], v[44:47]
	v_mfma_f32_16x16x32_bf16 v[48:51], v[216:219], v[192:195], v[48:51]
	ds_read_b128 v[172:175], v211 offset:30720
	s_waitcnt lgkmcnt(6)
	v_mfma_f32_16x16x32_bf16 v[28:31], v[72:75], v[196:199], v[28:31]
	v_mfma_f32_16x16x32_bf16 v[16:19], v[216:219], v[196:199], v[16:19]
	s_waitcnt lgkmcnt(5)
	v_mfma_f32_16x16x32_bf16 v[60:63], v[72:75], v[200:203], v[60:63]
	v_mfma_f32_16x16x32_bf16 v[40:43], v[216:219], v[200:203], v[40:43]
	s_waitcnt lgkmcnt(4)
	v_mfma_f32_16x16x32_bf16 v[20:23], v[72:75], v[204:207], v[20:23]
	v_mfma_f32_16x16x32_bf16 v[0:3], v[216:219], v[204:207], v[0:3]
	s_waitcnt lgkmcnt(3)
	v_mfma_f32_16x16x32_bf16 v[52:55], v[72:75], v[160:163], v[52:55]
	v_mfma_f32_16x16x32_bf16 v[36:39], v[216:219], v[160:163], v[36:39]
	s_waitcnt lgkmcnt(2)
	v_mfma_f32_16x16x32_bf16 v[24:27], v[72:75], v[164:167], v[24:27]
	v_mfma_f32_16x16x32_bf16 v[8:11], v[216:219], v[164:167], v[8:11]
	s_waitcnt lgkmcnt(1)
	v_mfma_f32_16x16x32_bf16 v[56:59], v[72:75], v[168:171], v[56:59]
	v_mfma_f32_16x16x32_bf16 v[32:35], v[216:219], v[168:171], v[32:35]
	s_waitcnt lgkmcnt(0)
	v_mfma_f32_16x16x32_bf16 v[12:15], v[72:75], v[172:175], v[12:15]
	v_mfma_f32_16x16x32_bf16 v[4:7], v[216:219], v[172:175], v[4:7]
	s_setprio 0
	s_mov_b32 s40, 0x8000
	v_add_u32_e32 v68, s40, v101
	v_add_u32_e32 v69, v68, v102
	s_waitcnt vmcnt(0)
	s_barrier
	ds_read_b128 v[64:67], v69
	v_add_u32_e32 v126, v68, v100
	ds_read_b128 v[72:75], v126 offset:16384
	ds_read_b128 v[118:121], v126 offset:20480
	ds_read_b128 v[122:125], v126 offset:24576
	s_ashr_i32 s39, s39, 5
	s_mul_hi_i32 s4, s39, 0x3000
	s_waitcnt lgkmcnt(0)
	v_mfma_f32_16x16x32_bf16 v[130:133], v[64:67], v[72:75], v[44:47]
	v_add_u32_e32 v128, 0x400, v105
	s_nop 1
	ds_read_b128 v[44:47], v69 offset:2048
	v_mfma_f32_16x16x32_bf16 v[134:137], v[64:67], v[118:121], v[60:63]
	ds_read_b128 v[68:71], v126 offset:18432
	v_mfma_f32_16x16x32_bf16 v[138:141], v[64:67], v[122:125], v[52:55]
	s_nop 2
	ds_read_b128 v[52:55], v126 offset:22528
	s_waitcnt lgkmcnt(0)
	v_mfma_f32_16x16x32_bf16 v[48:51], v[44:47], v[72:75], v[48:51]
	ds_read_b128 v[72:75], v126 offset:26624
	v_mfma_f32_16x16x32_bf16 v[118:121], v[44:47], v[118:121], v[40:43]
	ds_read_b128 v[142:145], v126 offset:28672
	s_waitcnt lgkmcnt(0)
	v_mfma_f32_16x16x32_bf16 v[56:59], v[64:67], v[142:145], v[56:59]
	ds_read_b128 v[40:43], v126 offset:30720
	v_mfma_f32_16x16x32_bf16 v[122:125], v[44:47], v[122:125], v[36:39]
	s_nop 2
	v_add_u32_e32 v36, s40, v103
	v_add_u32_e32 v37, v36, v102
	ds_read_b128 v[60:63], v37
	v_mfma_f32_16x16x32_bf16 v[142:145], v[44:47], v[142:145], v[32:35]
	v_add_u32_e32 v126, v36, v100
	s_mul_i32 s40, s39, 0x3000
	s_add_u32 s30, s33, s40
	ds_read_b128 v[32:35], v37 offset:2048
	v_mfma_f32_16x16x32_bf16 v[146:149], v[64:67], v[68:71], v[28:31]
	s_addc_u32 s31, s34, s4
	s_lshl_b32 s4, s38, 9
	s_add_u32 s30, s30, s4
	ds_read_b128 v[28:31], v126 offset:16384
	s_waitcnt lgkmcnt(0)
	v_mfma_f32_16x16x32_bf16 v[130:133], v[60:63], v[28:31], v[130:133]
	ds_read_b128 v[150:153], v126 offset:18432
	s_addc_u32 s31, s31, 0
	v_mfma_f32_16x16x32_bf16 v[28:31], v[32:35], v[28:31], v[48:51]
	ds_read_b128 v[36:39], v126 offset:20480
	s_waitcnt lgkmcnt(0)
	v_mfma_f32_16x16x32_bf16 v[134:137], v[60:63], v[36:39], v[134:137]
	ds_read_b128 v[154:157], v126 offset:22528
	v_mfma_f32_16x16x32_bf16 v[36:39], v[32:35], v[36:39], v[118:121]
	ds_read_b128 v[48:51], v126 offset:24576
	s_waitcnt lgkmcnt(0)
	v_mfma_f32_16x16x32_bf16 v[118:121], v[60:63], v[48:51], v[138:141]
	s_nop 2
	ds_read_b128 v[138:141], v126 offset:26624
	v_mfma_f32_16x16x32_bf16 v[48:51], v[32:35], v[48:51], v[122:125]
	s_nop 2
	ds_read_b128 v[122:125], v126 offset:28672
	s_waitcnt lgkmcnt(0)
	v_mfma_f32_16x16x32_bf16 v[158:161], v[60:63], v[122:125], v[56:59]
	ds_read_b128 v[162:165], v126 offset:30720
	s_barrier
	v_mfma_f32_16x16x32_bf16 v[56:59], v[32:35], v[122:125], v[142:145]
	v_mfma_f32_16x16x32_bf16 v[24:27], v[64:67], v[72:75], v[24:27]
	v_mfma_f32_16x16x32_bf16 v[16:19], v[44:47], v[68:71], v[16:19]
	v_mfma_f32_16x16x32_bf16 v[8:11], v[44:47], v[72:75], v[8:11]
	v_mfma_f32_16x16x32_bf16 v[68:71], v[60:63], v[150:153], v[146:149]
	v_mfma_f32_16x16x32_bf16 v[24:27], v[60:63], v[138:141], v[24:27]
	v_mfma_f32_16x16x32_bf16 v[16:19], v[32:35], v[150:153], v[16:19]
	v_mfma_f32_16x16x32_bf16 v[8:11], v[32:35], v[138:141], v[8:11]
	v_mfma_f32_16x16x32_bf16 v[20:23], v[64:67], v[52:55], v[20:23]
	v_mfma_f32_16x16x32_bf16 v[12:15], v[64:67], v[40:43], v[12:15]
	v_lshl_add_u64 v[64:65], s[30:31], 0, v[76:77]
	s_add_i32 s30, s39, 4
	s_add_i32 s31, s40, 0xc000
	s_mul_hi_i32 s30, s30, 0x3000
	s_add_u32 s31, s33, s31
	s_addc_u32 s38, s34, s30
	v_lshl_add_u64 v[66:67], v[64:65], 0, s[26:27]
	v_add_co_u32_e32 v64, vcc, s37, v64
	s_add_u32 s30, s31, s4
	s_nop 0
	v_addc_co_u32_e32 v65, vcc, 0, v65, vcc
	s_addc_u32 s31, s38, 0
	v_mfma_f32_16x16x32_bf16 v[20:23], v[60:63], v[154:157], v[20:23]
	s_waitcnt lgkmcnt(0)
	v_mfma_f32_16x16x32_bf16 v[12:15], v[60:63], v[162:165], v[12:15]
	ds_write2_b32 v105, v130, v68 offset1:16
	global_load_dwordx4 v[60:63], v[64:65], off
	ds_write2_b32 v105, v131, v69 offset0:128 offset1:144
	v_lshl_add_u64 v[68:69], s[30:31], 0, v[76:77]
	s_add_i32 s30, s39, 8
	s_add_i32 s31, s40, 0x18000
	s_mul_hi_i32 s30, s30, 0x3000
	s_add_u32 s31, s33, s31
	s_addc_u32 s38, s34, s30
	v_lshl_add_u64 v[122:123], v[68:69], 0, s[26:27]
	v_add_co_u32_e32 v68, vcc, s37, v68
	s_add_u32 s30, s31, s4
	s_nop 0
	v_addc_co_u32_e32 v69, vcc, 0, v69, vcc
	s_addc_u32 s31, s38, 0
	global_load_dwordx4 v[64:67], v[66:67], off offset:16
	ds_write2_b32 v128, v132, v70 offset1:16
	global_load_dwordx4 v[72:75], v[68:69], off
	ds_write2_b32 v128, v133, v71 offset0:128 offset1:144
	global_load_dwordx4 v[68:71], v[122:123], off offset:16
	v_lshl_add_u64 v[122:123], s[30:31], 0, v[76:77]
	s_add_i32 s30, s39, 12
	s_add_i32 s31, s40, 0x24000
	s_mul_hi_i32 s30, s30, 0x3000
	s_add_u32 s31, s33, s31
	s_addc_u32 s38, s34, s30
	v_lshl_add_u64 v[126:127], v[122:123], 0, s[26:27]
	v_add_co_u32_e32 v122, vcc, s37, v122
	s_add_u32 s30, s31, s4
	s_nop 0
	v_addc_co_u32_e32 v123, vcc, 0, v123, vcc
	s_addc_u32 s31, s38, 0
	ds_write2_b32 v105, v134, v20 offset0:32 offset1:48
	global_load_dwordx4 v[122:125], v[122:123], off
	ds_write2_b32 v105, v135, v21 offset0:160 offset1:176
	v_lshl_add_u64 v[20:21], s[30:31], 0, v[76:77]
	s_add_i32 s30, s39, 16
	s_add_i32 s31, s40, 0x30000
	s_mul_hi_i32 s30, s30, 0x3000
	s_add_u32 s31, s33, s31
	s_addc_u32 s38, s34, s30
	global_load_dwordx4 v[130:133], v[126:127], off offset:16
	v_lshl_add_u64 v[126:127], v[20:21], 0, s[26:27]
	v_add_co_u32_e32 v20, vcc, s37, v20
	s_add_u32 s30, s31, s4
	s_nop 0
	v_addc_co_u32_e32 v21, vcc, 0, v21, vcc
	s_addc_u32 s31, s38, 0
	ds_write2_b32 v128, v136, v22 offset0:32 offset1:48
	global_load_dwordx4 v[138:141], v[20:21], off
	ds_write2_b32 v128, v137, v23 offset0:160 offset1:176
	global_load_dwordx4 v[20:23], v[126:127], off offset:16
	v_lshl_add_u64 v[126:127], s[30:31], 0, v[76:77]
	s_add_i32 s30, s39, 20
	s_add_i32 s31, s40, 0x3c000
	s_mul_hi_i32 s30, s30, 0x3000
	s_add_u32 s31, s33, s31
	s_addc_u32 s38, s34, s30
	v_lshl_add_u64 v[142:143], v[126:127], 0, s[26:27]
	v_add_co_u32_e32 v126, vcc, s37, v126
	s_add_u32 s30, s31, s4
	s_nop 0
	v_addc_co_u32_e32 v127, vcc, 0, v127, vcc
	s_addc_u32 s31, s38, 0
	ds_write2_b32 v105, v118, v24 offset0:64 offset1:80
	global_load_dwordx4 v[134:137], v[126:127], off
	ds_write2_b32 v105, v119, v25 offset0:192 offset1:208
	v_lshl_add_u64 v[24:25], s[30:31], 0, v[76:77]
	s_add_i32 s30, s39, 24
	s_add_i32 s31, s40, 0x48000
	s_mul_hi_i32 s30, s30, 0x3000
	s_add_u32 s31, s33, s31
	s_addc_u32 s38, s34, s30
	v_lshl_add_u64 v[118:119], v[24:25], 0, s[26:27]
	v_add_co_u32_e32 v24, vcc, s37, v24
	s_add_u32 s30, s31, s4
	s_nop 0
	v_addc_co_u32_e32 v25, vcc, 0, v25, vcc
	s_addc_u32 s31, s38, 0
	s_add_i32 s39, s39, 28
	s_add_i32 s40, s40, 0x54000
	global_load_dwordx4 v[142:145], v[142:143], off offset:16
	ds_write2_b32 v128, v120, v26 offset0:64 offset1:80
	global_load_dwordx4 v[146:149], v[24:25], off
	ds_write2_b32 v128, v121, v27 offset0:192 offset1:208
	global_load_dwordx4 v[24:27], v[118:119], off offset:16
	v_lshl_add_u64 v[118:119], s[30:31], 0, v[76:77]
	s_mul_hi_i32 s30, s39, 0x3000
	s_add_u32 s31, s33, s40
	s_addc_u32 s38, s34, s30
	v_lshl_add_u64 v[126:127], v[118:119], 0, s[26:27]
	v_add_co_u32_e32 v118, vcc, s37, v118
	s_add_u32 s30, s31, s4
	s_nop 0
	v_addc_co_u32_e32 v119, vcc, 0, v119, vcc
	s_addc_u32 s31, s38, 0
	ds_write2st64_b32 v106, v158, v159 offset1:2
	global_load_dwordx4 v[118:121], v[118:119], off
	ds_write2st64_b32 v106, v160, v161 offset0:4 offset1:6
	global_load_dwordx4 v[150:153], v[126:127], off offset:16
	v_lshl_add_u64 v[126:127], s[30:31], 0, v[76:77]
	v_lshl_add_u64 v[166:167], v[126:127], 0, s[26:27]
	v_add_co_u32_e32 v126, vcc, s37, v126
	ds_write2st64_b32 v107, v12, v13 offset1:2
	s_nop 0
	v_addc_co_u32_e32 v127, vcc, 0, v127, vcc
	global_load_dwordx4 v[158:161], v[126:127], off
	ds_write2st64_b32 v107, v14, v15 offset0:4 offset1:6
	global_load_dwordx4 v[12:15], v[166:167], off offset:16
	v_mfma_f32_16x16x32_bf16 v[0:3], v[44:47], v[52:55], v[0:3]
	v_lshl_add_u64 v[126:127], v[82:83], 0, s[28:29]
	v_lshl_add_u64 v[126:127], v[126:127], 0, s[4:5]
	v_mfma_f32_16x16x32_bf16 v[4:7], v[44:47], v[40:43], v[4:7]
	s_waitcnt vmcnt(0)
	v_pk_add_f32 v[62:63], v[62:63], 0 op_sel_hi:[1,0]
	v_pk_add_f32 v[60:61], v[60:61], 0 op_sel_hi:[1,0]
	v_pk_add_f32 v[66:67], v[66:67], 0 op_sel_hi:[1,0]
	v_mfma_f32_16x16x32_bf16 v[0:3], v[32:35], v[154:157], v[0:3]
	v_add_f32_e64 v64, v64, 0
	v_add_f32_e64 v65, v65, 0
	v_pk_add_f32 v[62:63], v[62:63], v[74:75]
	v_pk_add_f32 v[60:61], v[60:61], v[72:73]
	v_mfma_f32_16x16x32_bf16 v[4:7], v[32:35], v[162:165], v[4:7]
	ds_read_b128 v[32:35], v104
	ds_read_b128 v[154:157], v104 offset:16
	ds_read_b128 v[174:177], v108
	ds_read_b128 v[166:169], v110 offset:16
	ds_read_b128 v[170:173], v110
	ds_read_b128 v[52:55], v109 offset:16
	ds_read_b128 v[40:43], v109
	ds_read_b128 v[44:47], v108 offset:16
	global_load_dwordx4 v[162:165], v[126:127], off offset:16 nt
	global_load_dwordx4 v[178:181], v[126:127], off nt
	v_pk_add_f32 v[66:67], v[66:67], v[70:71]
	v_pk_add_f32 v[64:65], v[64:65], v[68:69]
	v_pk_add_f32 v[62:63], v[62:63], v[124:125]
	v_pk_add_f32 v[60:61], v[60:61], v[122:123]
	v_pk_add_f32 v[66:67], v[66:67], v[132:133]
	v_pk_add_f32 v[64:65], v[64:65], v[130:131]
	v_pk_add_f32 v[62:63], v[62:63], v[140:141]
	v_pk_add_f32 v[60:61], v[60:61], v[138:139]
	v_pk_add_f32 v[22:23], v[66:67], v[22:23]
	v_pk_add_f32 v[20:21], v[64:65], v[20:21]
	v_pk_add_f32 v[62:63], v[62:63], v[136:137]
	v_pk_add_f32 v[60:61], v[60:61], v[134:135]
	s_add_i32 s2, s2, s3
	s_add_i32 s35, s35, s36
	s_cmpk_gt_i32 s2, 0x3ff
	v_pk_add_f32 v[22:23], v[22:23], v[144:145]
	v_pk_add_f32 v[20:21], v[20:21], v[142:143]
	v_pk_add_f32 v[62:63], v[62:63], v[148:149]
	v_pk_add_f32 v[60:61], v[60:61], v[146:147]
	v_pk_add_f32 v[22:23], v[22:23], v[26:27]
	v_pk_add_f32 v[20:21], v[20:21], v[24:25]
	v_pk_add_f32 v[24:25], v[62:63], v[120:121]
	v_pk_add_f32 v[26:27], v[60:61], v[118:119]
	v_pk_add_f32 v[22:23], v[22:23], v[152:153]
	v_pk_add_f32 v[20:21], v[20:21], v[150:151]
	v_pk_add_f32 v[60:61], v[24:25], v[160:161]
	v_pk_add_f32 v[62:63], v[26:27], v[158:159]
	v_pk_add_f32 v[64:65], v[22:23], v[14:15]
	v_pk_add_f32 v[66:67], v[20:21], v[12:13]
	v_lshl_add_u64 v[26:27], v[88:89], 0, s[28:29]
	v_lshl_add_u64 v[26:27], v[26:27], 0, s[4:5]
	s_waitcnt vmcnt(1) lgkmcnt(6)
	v_pk_fma_f32 v[22:23], v[64:65], v[156:157], v[164:165]
	s_waitcnt vmcnt(0)
	v_pk_fma_f32 v[14:15], v[60:61], v[34:35], v[180:181]
	v_pk_fma_f32 v[12:13], v[62:63], v[32:33], v[178:179]
	v_pk_fma_f32 v[20:21], v[66:67], v[154:155], v[162:163]
	global_store_dwordx4 v[126:127], v[12:15], off
	global_store_dwordx4 v[126:127], v[20:23], off offset:16
	s_nop 0
	v_lshl_add_u64 v[12:13], v[84:85], 0, s[28:29]
	v_lshl_add_u64 v[24:25], v[12:13], 0, s[4:5]
	global_load_dwordx4 v[12:15], v[24:25], off offset:16 nt
	global_load_dwordx4 v[20:23], v[24:25], off nt
	s_waitcnt vmcnt(1) lgkmcnt(0)
	v_pk_fma_f32 v[14:15], v[64:65], v[46:47], v[14:15]
	v_pk_fma_f32 v[12:13], v[66:67], v[44:45], v[12:13]
	s_waitcnt vmcnt(0)
	v_pk_fma_f32 v[22:23], v[60:61], v[176:177], v[22:23]
	v_pk_fma_f32 v[20:21], v[62:63], v[174:175], v[20:21]
	global_store_dwordx4 v[24:25], v[12:15], off offset:16
	global_store_dwordx4 v[24:25], v[20:23], off
	s_nop 0
	v_lshl_add_u64 v[12:13], v[86:87], 0, s[28:29]
	v_lshl_add_u64 v[24:25], v[12:13], 0, s[4:5]
	global_load_dwordx4 v[12:15], v[24:25], off offset:16 nt
	global_load_dwordx4 v[20:23], v[24:25], off nt
	s_waitcnt vmcnt(1)
	v_pk_fma_f32 v[14:15], v[64:65], v[54:55], v[14:15]
	s_waitcnt vmcnt(0)
	v_pk_fma_f32 v[22:23], v[60:61], v[42:43], v[22:23]
	v_pk_fma_f32 v[20:21], v[62:63], v[40:41], v[20:21]
	v_pk_fma_f32 v[12:13], v[66:67], v[52:53], v[12:13]
	global_store_dwordx4 v[24:25], v[20:23], off
	global_store_dwordx4 v[24:25], v[12:15], off offset:16
	global_load_dwordx4 v[12:15], v[26:27], off offset:16 nt
	v_lshl_add_u64 v[24:25], v[90:91], 0, s[28:29]
	global_load_dwordx4 v[20:23], v[26:27], off nt
	v_lshl_add_u64 v[40:41], v[24:25], 0, s[4:5]
	v_lshl_add_u64 v[42:43], v[92:93], 0, s[28:29]
	v_lshl_add_u64 v[42:43], v[42:43], 0, s[4:5]
	s_waitcnt vmcnt(1)
	v_pk_fma_f32 v[14:15], v[64:65], v[168:169], v[14:15]
	v_pk_fma_f32 v[12:13], v[66:67], v[166:167], v[12:13]
	s_waitcnt vmcnt(0)
	v_pk_fma_f32 v[22:23], v[60:61], v[172:173], v[22:23]
	v_pk_fma_f32 v[20:21], v[62:63], v[170:171], v[20:21]
	global_store_dwordx4 v[26:27], v[20:23], off
	global_store_dwordx4 v[26:27], v[12:15], off offset:16
	ds_write2_b32 v105, v28, v16 offset1:16
	ds_write2_b32 v105, v29, v17 offset0:128 offset1:144
	ds_write2_b32 v128, v30, v18 offset1:16
	ds_write2_b32 v128, v31, v19 offset0:128 offset1:144
	ds_write2_b32 v105, v36, v0 offset0:32 offset1:48
	ds_write2_b32 v105, v37, v1 offset0:160 offset1:176
	ds_write2_b32 v128, v38, v2 offset0:32 offset1:48
	ds_write2_b32 v128, v39, v3 offset0:160 offset1:176
	ds_write2_b32 v105, v48, v8 offset0:64 offset1:80
	ds_write2_b32 v105, v49, v9 offset0:192 offset1:208
	ds_write2_b32 v128, v50, v10 offset0:64 offset1:80
	ds_write2_b32 v128, v51, v11 offset0:192 offset1:208
	ds_write2st64_b32 v106, v56, v57 offset1:2
	ds_write2st64_b32 v106, v58, v59 offset0:4 offset1:6
	ds_write2st64_b32 v107, v4, v5 offset1:2
	ds_write2st64_b32 v107, v6, v7 offset0:4 offset1:6
	ds_read_b128 v[28:31], v104
	ds_read_b128 v[24:27], v104 offset:16
	ds_read_b128 v[20:23], v108
	ds_read_b128 v[16:19], v108 offset:16
	ds_read_b128 v[12:15], v109
	ds_read_b128 v[8:11], v109 offset:16
	ds_read_b128 v[4:7], v110
	ds_read_b128 v[0:3], v110 offset:16
	global_load_dwordx4 v[32:35], v[40:41], off offset:16 nt
	global_load_dwordx4 v[36:39], v[40:41], off nt
	s_waitcnt vmcnt(1) lgkmcnt(6)
	v_pk_fma_f32 v[26:27], v[64:65], v[26:27], v[34:35]
	s_waitcnt vmcnt(0)
	v_pk_fma_f32 v[30:31], v[60:61], v[30:31], v[38:39]
	v_pk_fma_f32 v[28:29], v[62:63], v[28:29], v[36:37]
	v_pk_fma_f32 v[24:25], v[66:67], v[24:25], v[32:33]
	global_store_dwordx4 v[40:41], v[28:31], off
	global_store_dwordx4 v[40:41], v[24:27], off offset:16
	global_load_dwordx4 v[24:27], v[42:43], off offset:16 nt
	v_lshl_add_u64 v[32:33], v[94:95], 0, s[28:29]
	global_load_dwordx4 v[28:31], v[42:43], off nt
	v_lshl_add_u64 v[32:33], v[32:33], 0, s[4:5]
	s_waitcnt vmcnt(1) lgkmcnt(4)
	v_pk_fma_f32 v[18:19], v[64:65], v[18:19], v[26:27]
	v_pk_fma_f32 v[16:17], v[66:67], v[16:17], v[24:25]
	s_waitcnt vmcnt(0)
	v_pk_fma_f32 v[22:23], v[60:61], v[22:23], v[30:31]
	v_pk_fma_f32 v[20:21], v[62:63], v[20:21], v[28:29]
	global_store_dwordx4 v[42:43], v[20:23], off
	global_store_dwordx4 v[42:43], v[16:19], off offset:16
	global_load_dwordx4 v[16:19], v[32:33], off offset:16 nt
	v_lshl_add_u64 v[24:25], v[96:97], 0, s[28:29]
	global_load_dwordx4 v[20:23], v[32:33], off nt
	v_lshl_add_u64 v[24:25], v[24:25], 0, s[4:5]
	s_waitcnt vmcnt(1) lgkmcnt(2)
	v_pk_fma_f32 v[10:11], v[64:65], v[10:11], v[18:19]
	v_pk_fma_f32 v[8:9], v[66:67], v[8:9], v[16:17]
	s_waitcnt vmcnt(0)
	v_pk_fma_f32 v[14:15], v[60:61], v[14:15], v[22:23]
	v_pk_fma_f32 v[12:13], v[62:63], v[12:13], v[20:21]
	global_store_dwordx4 v[32:33], v[12:15], off
	global_store_dwordx4 v[32:33], v[8:11], off offset:16
	global_load_dwordx4 v[8:11], v[24:25], off offset:16 nt
	s_waitcnt vmcnt(0) lgkmcnt(0)
	v_pk_fma_f32 v[2:3], v[64:65], v[2:3], v[10:11]
	global_load_dwordx4 v[12:15], v[24:25], off nt
	v_pk_fma_f32 v[0:1], v[66:67], v[0:1], v[8:9]
	global_store_dwordx4 v[24:25], v[0:3], off offset:16
	s_waitcnt vmcnt(1)
	v_pk_fma_f32 v[6:7], v[60:61], v[6:7], v[14:15]
	v_pk_fma_f32 v[4:5], v[62:63], v[4:5], v[12:13]
	global_store_dwordx4 v[24:25], v[4:7], off
	s_cbranch_scc0 .LBB0_686
